# GEMM K loops: 121 LDS-DMA loads use the SGPR-base + 32-bit lane-offset form instead of a per-load 64-bit VALU address add
# speedup vs baseline: 1.0100x; 1.0052x over previous
.LBB0_155:
	s_mov_b64 s[10:11], 0x80
	s_and_b32 s16, s2, 3
	s_add_i32 m0, s39, 0x18000
	v_lshl_add_u64 v[6:7], v[6:7], 0, s[10:11]
	s_lshl_b32 s2, s3, 13
	s_lshl_b32 s17, s16, 5
	s_lshl_b32 s12, s16, 12
	s_waitcnt vmcnt(2)
	s_barrier
	global_load_lds_dwordx4 v[6:7], off
	v_lshl_add_u64 v[4:5], v[4:5], 0, s[10:11]
	s_add_i32 m0, s39, 0x1a000
	s_add_i32 s43, s39, 0x8000
	s_add_i32 s44, s39, 0xa000
	global_load_lds_dwordx4 v[4:5], off
	v_lshl_add_u64 v[0:1], v[0:1], 0, s[10:11]
	s_mov_b32 m0, s43
	s_add_u32 s4, s30, 0x40080
	global_load_lds_dwordx4 v[0:1], off
	v_lshl_add_u64 v[0:1], v[2:3], 0, s[10:11]
	s_mov_b32 m0, s44
	s_addc_u32 s5, s31, 0
	global_load_lds_dwordx4 v[0:1], off
	s_add_i32 m0, s39, 0x1c000
	s_nop 0
	global_load_lds_dwordx4 v130, s[4:5]
	v_lshl_add_u64 v[0:1], s[4:5], 0, v[134:135]
	s_add_i32 m0, s39, 0x1e000
	v_bfe_u32 v2, v8, 4, 2
	global_load_lds_dwordx4 v[0:1], off
	v_and_b32_e32 v1, 15, v8
	v_lshlrev_b32_e32 v138, 4, v2
	v_lshlrev_b32_e32 v3, 2, v8
	v_lshl_or_b32 v139, s3, 6, v1
	v_lshl_or_b32 v1, v1, 6, v138
	v_and_b32_e32 v3, 32, v3
	v_bitop3_b32 v4, v1, s2, v3 bitop3:0xde
	v_bitop3_b32 v141, v1, s12, v3 bitop3:0xde
	v_lshlrev_b32_e32 v1, 14, v9
	v_and_b32_e32 v1, 0xffff8000, v1
	v_lshlrev_b32_e32 v0, 3, v2
	v_cmp_eq_u32_e64 s[2:3], 0, v2
	v_lshlrev_b32_e32 v140, 5, v2
	v_lshl_add_u32 v1, v10, 11, v1
	v_and_b32_e32 v2, 1, v9
	v_lshl_or_b32 v1, v2, 6, v1
	v_lshl_add_u32 v144, v11, 1, v1
	v_lshlrev_b32_e32 v1, 14, v12
	s_cmpk_lt_u32 s6, 0x100
	v_and_b32_e32 v1, 0xffff8000, v1
	s_waitcnt vmcnt(6)
	s_cselect_b64 s[12:13], -1, 0
	s_cmp_eq_u32 s16, 0
	v_lshl_add_u32 v1, v13, 11, v1
	v_and_b32_e32 v2, 1, v12
	s_cselect_b64 s[14:15], -1, 0
	v_lshl_or_b32 v1, v2, 6, v1
	s_add_i32 s49, 0, 0x10000
	s_add_i32 s50, 0, 0x14000
	v_lshlrev_b32_e32 v136, 1, v0
	v_mbcnt_lo_u32_b32 v0, -1, 0
	s_ashr_i32 s45, s96, 31
	s_ashr_i32 s46, s33, 31
	s_lshl_b32 s47, s16, 2
	v_lshl_or_b32 v142, s16, 6, v138
	v_mov_b32_e32 v145, v137
	v_lshl_add_u32 v146, v14, 1, v1
	v_mov_b32_e32 v147, v137
	v_mov_b64_e32 v[148:149], 0xb00
	v_mov_b64_e32 v[150:151], 0xaff
	s_movk_i32 s48, 0x161
	v_add_u32_e32 v143, s49, v141
	v_add_u32_e32 v158, s50, v141
	v_add_u32_e32 v159, 0, v4
	v_mov_b32_e32 v160, 0x358637bd
	s_movk_i32 s51, 0x1600
	s_lshl_b32 s6, s17, 1
	v_mbcnt_hi_u32_b32 v161, -1, v0
	s_mov_b32 s52, s7
	s_barrier
	s_branch .LBB0_158

.LBB0_161:
	ds_read_b128 v[152:155], v143
	ds_read_b128 v[162:165], v143 offset:1024
	ds_read_b128 v[166:169], v143 offset:2048
	ds_read_b128 v[170:173], v143 offset:3072
	ds_read_b128 v[174:177], v158
	ds_read_b128 v[178:181], v158 offset:1024
	ds_read_b128 v[182:185], v158 offset:2048
	ds_read_b128 v[186:189], v158 offset:3072
	s_add_u32 s30, s28, 0xfffc0080
	s_addc_u32 s31, s29, -1
	s_cmp_eq_u32 s55, 12
	s_cselect_b32 s35, s19, s31
	s_cselect_b32 s34, s25, s30
	s_cselect_b32 s31, s17, s54
	s_cselect_b32 s30, s27, s53
	s_waitcnt lgkmcnt(0)
	s_add_i32 m0, s39, 0xc000
	ds_read_b128 v[190:193], v159
	ds_read_b128 v[194:197], v159 offset:1024
	ds_read_b128 v[198:201], v159 offset:2048
	ds_read_b128 v[202:205], v159 offset:3072
	ds_read_b128 v[206:209], v159 offset:4096
	ds_read_b128 v[210:213], v159 offset:5120
	ds_read_b128 v[214:217], v159 offset:6144
	ds_read_b128 v[218:221], v159 offset:7168
	global_load_lds_dwordx4 v144, s[28:29]
	s_add_i32 m0, s39, 0xe000
	s_nop 0
	global_load_lds_dwordx4 v146, s[28:29]
	s_waitcnt vmcnt(8)
	s_waitcnt lgkmcnt(0)
	s_barrier
	s_setprio 1
	s_waitcnt lgkmcnt(0)
	v_mfma_f32_16x16x32_bf16 v[116:119], v[152:155], v[190:193], v[116:119]
	v_mfma_f32_16x16x32_bf16 v[112:115], v[166:169], v[190:193], v[112:115]
	v_mfma_f32_16x16x32_bf16 v[100:103], v[152:155], v[198:201], v[100:103]
	v_mfma_f32_16x16x32_bf16 v[96:99], v[166:169], v[198:201], v[96:99]
	v_mfma_f32_16x16x32_bf16 v[88:91], v[152:155], v[206:209], v[88:91]
	v_mfma_f32_16x16x32_bf16 v[84:87], v[166:169], v[206:209], v[84:87]
	v_mfma_f32_16x16x32_bf16 v[72:75], v[152:155], v[214:217], v[72:75]
	v_mfma_f32_16x16x32_bf16 v[68:71], v[166:169], v[214:217], v[68:71]
	v_mfma_f32_16x16x32_bf16 v[116:119], v[162:165], v[194:197], v[116:119]
	v_mfma_f32_16x16x32_bf16 v[112:115], v[170:173], v[194:197], v[112:115]
	v_mfma_f32_16x16x32_bf16 v[100:103], v[162:165], v[202:205], v[100:103]
	v_mfma_f32_16x16x32_bf16 v[96:99], v[170:173], v[202:205], v[96:99]
	v_mfma_f32_16x16x32_bf16 v[88:91], v[162:165], v[210:213], v[88:91]
	v_mfma_f32_16x16x32_bf16 v[84:87], v[170:173], v[210:213], v[84:87]
	v_mfma_f32_16x16x32_bf16 v[72:75], v[162:165], v[218:221], v[72:75]
	v_mfma_f32_16x16x32_bf16 v[68:71], v[170:173], v[218:221], v[68:71]
	s_setprio 0
	s_setprio 1
	v_mfma_f32_16x16x32_bf16 v[124:127], v[174:177], v[190:193], v[124:127]
	v_mfma_f32_16x16x32_bf16 v[120:123], v[182:185], v[190:193], v[120:123]
	v_mfma_f32_16x16x32_bf16 v[108:111], v[174:177], v[198:201], v[108:111]
	v_mfma_f32_16x16x32_bf16 v[104:107], v[182:185], v[198:201], v[104:107]
	v_mfma_f32_16x16x32_bf16 v[92:95], v[174:177], v[206:209], v[92:95]
	v_mfma_f32_16x16x32_bf16 v[80:83], v[182:185], v[206:209], v[80:83]
	v_mfma_f32_16x16x32_bf16 v[76:79], v[174:177], v[214:217], v[76:79]
	v_mfma_f32_16x16x32_bf16 v[64:67], v[182:185], v[214:217], v[64:67]
	v_mfma_f32_16x16x32_bf16 v[124:127], v[178:181], v[194:197], v[124:127]
	v_mfma_f32_16x16x32_bf16 v[120:123], v[186:189], v[194:197], v[120:123]
	v_mfma_f32_16x16x32_bf16 v[108:111], v[178:181], v[202:205], v[108:111]
	v_mfma_f32_16x16x32_bf16 v[104:107], v[186:189], v[202:205], v[104:107]
	v_mfma_f32_16x16x32_bf16 v[92:95], v[178:181], v[210:213], v[92:95]
	v_mfma_f32_16x16x32_bf16 v[80:83], v[186:189], v[210:213], v[80:83]
	v_mfma_f32_16x16x32_bf16 v[76:79], v[178:181], v[218:221], v[76:79]
	v_mfma_f32_16x16x32_bf16 v[64:67], v[186:189], v[218:221], v[64:67]
	s_setprio 0
	s_barrier
	s_add_i32 s56, s49, s36
	v_lshl_add_u64 v[156:157], s[30:31], 0, v[130:131]
	s_mov_b32 m0, s56
	ds_read_b128 v[190:193], v159 offset:16384
	ds_read_b128 v[194:197], v159 offset:17408
	ds_read_b128 v[198:201], v159 offset:18432
	ds_read_b128 v[202:205], v159 offset:19456
	ds_read_b128 v[206:209], v159 offset:20480
	ds_read_b128 v[210:213], v159 offset:21504
	ds_read_b128 v[214:217], v159 offset:22528
	ds_read_b128 v[218:221], v159 offset:23552
	global_load_lds_dwordx4 v[156:157], off
	s_add_i32 m0, s56, 0x2000
	s_add_u32 s56, s30, 0x40000
	v_lshl_add_u64 v[222:223], s[30:31], 0, v[134:135]
	s_addc_u32 s57, s31, 0
	s_add_i32 s58, s50, s36
	global_load_lds_dwordx4 v[222:223], off
	s_mov_b32 m0, s58
	v_lshl_add_u64 v[226:227], s[34:35], 0, v[132:133]
	global_load_lds_dwordx4 v130, s[56:57]
	s_add_i32 m0, s58, 0x2000
	s_nop 0
	global_load_lds_dwordx4 v134, s[56:57]
	v_lshl_add_u64 v[224:225], s[34:35], 0, v[128:129]
	s_mov_b32 m0, s39
	s_nop 0
	global_load_lds_dwordx4 v[224:225], off
	s_mov_b32 m0, s40
	s_nop 0
	global_load_lds_dwordx4 v[226:227], off
	s_waitcnt vmcnt(8)
	s_waitcnt lgkmcnt(0)
	s_barrier
	s_setprio 1
	s_waitcnt lgkmcnt(0)
	v_mfma_f32_16x16x32_bf16 v[56:59], v[152:155], v[190:193], v[56:59]
	v_mfma_f32_16x16x32_bf16 v[52:55], v[166:169], v[190:193], v[52:55]
	v_mfma_f32_16x16x32_bf16 v[40:43], v[152:155], v[198:201], v[40:43]
	v_mfma_f32_16x16x32_bf16 v[36:39], v[166:169], v[198:201], v[36:39]
	v_mfma_f32_16x16x32_bf16 v[24:27], v[152:155], v[206:209], v[24:27]
	v_mfma_f32_16x16x32_bf16 v[20:23], v[166:169], v[206:209], v[20:23]
	v_mfma_f32_16x16x32_bf16 v[8:11], v[152:155], v[214:217], v[8:11]
	v_mfma_f32_16x16x32_bf16 v[4:7], v[166:169], v[214:217], v[4:7]
	v_mfma_f32_16x16x32_bf16 v[56:59], v[162:165], v[194:197], v[56:59]
	v_mfma_f32_16x16x32_bf16 v[52:55], v[170:173], v[194:197], v[52:55]
	v_mfma_f32_16x16x32_bf16 v[40:43], v[162:165], v[202:205], v[40:43]
	v_mfma_f32_16x16x32_bf16 v[36:39], v[170:173], v[202:205], v[36:39]
	v_mfma_f32_16x16x32_bf16 v[24:27], v[162:165], v[210:213], v[24:27]
	v_mfma_f32_16x16x32_bf16 v[20:23], v[170:173], v[210:213], v[20:23]
	v_mfma_f32_16x16x32_bf16 v[8:11], v[162:165], v[218:221], v[8:11]
	v_mfma_f32_16x16x32_bf16 v[4:7], v[170:173], v[218:221], v[4:7]
	s_setprio 0
	s_setprio 1
	v_mfma_f32_16x16x32_bf16 v[60:63], v[174:177], v[190:193], v[60:63]
	v_mfma_f32_16x16x32_bf16 v[48:51], v[182:185], v[190:193], v[48:51]
	v_mfma_f32_16x16x32_bf16 v[44:47], v[174:177], v[198:201], v[44:47]
	v_mfma_f32_16x16x32_bf16 v[32:35], v[182:185], v[198:201], v[32:35]
	v_mfma_f32_16x16x32_bf16 v[28:31], v[174:177], v[206:209], v[28:31]
	v_mfma_f32_16x16x32_bf16 v[16:19], v[182:185], v[206:209], v[16:19]
	v_mfma_f32_16x16x32_bf16 v[12:15], v[174:177], v[214:217], v[12:15]
	v_mfma_f32_16x16x32_bf16 v[0:3], v[182:185], v[214:217], v[0:3]
	v_mfma_f32_16x16x32_bf16 v[60:63], v[178:181], v[194:197], v[60:63]
	v_mfma_f32_16x16x32_bf16 v[48:51], v[186:189], v[194:197], v[48:51]
	v_mfma_f32_16x16x32_bf16 v[44:47], v[178:181], v[202:205], v[44:47]
	v_mfma_f32_16x16x32_bf16 v[32:35], v[186:189], v[202:205], v[32:35]
	v_mfma_f32_16x16x32_bf16 v[28:31], v[178:181], v[210:213], v[28:31]
	v_mfma_f32_16x16x32_bf16 v[16:19], v[186:189], v[210:213], v[16:19]
	v_mfma_f32_16x16x32_bf16 v[12:15], v[178:181], v[218:221], v[12:15]
	v_mfma_f32_16x16x32_bf16 v[0:3], v[186:189], v[218:221], v[0:3]
	s_setprio 0
	s_barrier
	s_add_i32 s56, 0, 0x18000
	s_add_i32 s57, 0, 0x1c000
	v_add_u32_e32 v170, s56, v141
	v_add_u32_e32 v186, s57, v141
	ds_read_b128 v[152:155], v170
	ds_read_b128 v[162:165], v170 offset:1024
	ds_read_b128 v[166:169], v170 offset:2048
	ds_read_b128 v[170:173], v170 offset:3072
	ds_read_b128 v[174:177], v186
	ds_read_b128 v[178:181], v186 offset:1024
	ds_read_b128 v[182:185], v186 offset:2048
	ds_read_b128 v[186:189], v186 offset:3072
	s_add_u32 s34, s34, 0x40000
	s_addc_u32 s35, s35, 0
	s_mov_b32 m0, s41
	ds_read_b128 v[190:193], v159 offset:32768
	ds_read_b128 v[194:197], v159 offset:33792
	ds_read_b128 v[198:201], v159 offset:34816
	ds_read_b128 v[202:205], v159 offset:35840
	ds_read_b128 v[206:209], v159 offset:36864
	ds_read_b128 v[210:213], v159 offset:37888
	ds_read_b128 v[214:217], v159 offset:38912
	ds_read_b128 v[218:221], v159 offset:39936
	global_load_lds_dwordx4 v128, s[34:35]
	v_lshl_add_u64 v[228:229], s[34:35], 0, v[132:133]
	s_mov_b32 m0, s42
	s_nop 0
	global_load_lds_dwordx4 v[228:229], off
	s_waitcnt vmcnt(8)
	s_waitcnt lgkmcnt(0)
	s_barrier
	s_setprio 1
	s_waitcnt lgkmcnt(0)
	v_mfma_f32_16x16x32_bf16 v[116:119], v[152:155], v[190:193], v[116:119]
	v_mfma_f32_16x16x32_bf16 v[112:115], v[166:169], v[190:193], v[112:115]
	v_mfma_f32_16x16x32_bf16 v[100:103], v[152:155], v[198:201], v[100:103]
	v_mfma_f32_16x16x32_bf16 v[96:99], v[166:169], v[198:201], v[96:99]
	v_mfma_f32_16x16x32_bf16 v[88:91], v[152:155], v[206:209], v[88:91]
	v_mfma_f32_16x16x32_bf16 v[84:87], v[166:169], v[206:209], v[84:87]
	v_mfma_f32_16x16x32_bf16 v[72:75], v[152:155], v[214:217], v[72:75]
	v_mfma_f32_16x16x32_bf16 v[68:71], v[166:169], v[214:217], v[68:71]
	v_mfma_f32_16x16x32_bf16 v[116:119], v[162:165], v[194:197], v[116:119]
	v_mfma_f32_16x16x32_bf16 v[112:115], v[170:173], v[194:197], v[112:115]
	v_mfma_f32_16x16x32_bf16 v[100:103], v[162:165], v[202:205], v[100:103]
	v_mfma_f32_16x16x32_bf16 v[96:99], v[170:173], v[202:205], v[96:99]
	v_mfma_f32_16x16x32_bf16 v[88:91], v[162:165], v[210:213], v[88:91]
	v_mfma_f32_16x16x32_bf16 v[84:87], v[170:173], v[210:213], v[84:87]
	v_mfma_f32_16x16x32_bf16 v[72:75], v[162:165], v[218:221], v[72:75]
	v_mfma_f32_16x16x32_bf16 v[68:71], v[170:173], v[218:221], v[68:71]
	s_setprio 0
	s_setprio 1
	v_mfma_f32_16x16x32_bf16 v[124:127], v[174:177], v[190:193], v[124:127]
	v_mfma_f32_16x16x32_bf16 v[120:123], v[182:185], v[190:193], v[120:123]
	v_mfma_f32_16x16x32_bf16 v[108:111], v[174:177], v[198:201], v[108:111]
	v_mfma_f32_16x16x32_bf16 v[104:107], v[182:185], v[198:201], v[104:107]
	v_mfma_f32_16x16x32_bf16 v[92:95], v[174:177], v[206:209], v[92:95]
	v_mfma_f32_16x16x32_bf16 v[80:83], v[182:185], v[206:209], v[80:83]
	v_mfma_f32_16x16x32_bf16 v[76:79], v[174:177], v[214:217], v[76:79]
	v_mfma_f32_16x16x32_bf16 v[64:67], v[182:185], v[214:217], v[64:67]
	v_mfma_f32_16x16x32_bf16 v[124:127], v[178:181], v[194:197], v[124:127]
	v_mfma_f32_16x16x32_bf16 v[120:123], v[186:189], v[194:197], v[120:123]
	v_mfma_f32_16x16x32_bf16 v[108:111], v[178:181], v[202:205], v[108:111]
	v_mfma_f32_16x16x32_bf16 v[104:107], v[186:189], v[202:205], v[104:107]
	v_mfma_f32_16x16x32_bf16 v[92:95], v[178:181], v[210:213], v[92:95]
	v_mfma_f32_16x16x32_bf16 v[80:83], v[186:189], v[210:213], v[80:83]
	v_mfma_f32_16x16x32_bf16 v[76:79], v[178:181], v[218:221], v[76:79]
	v_mfma_f32_16x16x32_bf16 v[64:67], v[186:189], v[218:221], v[64:67]
	s_setprio 0
	s_barrier
	s_add_i32 s34, s56, s36
	v_lshl_add_u64 v[156:157], v[156:157], 0, s[10:11]
	s_mov_b32 m0, s34
	ds_read_b128 v[190:193], v159 offset:49152
	ds_read_b128 v[194:197], v159 offset:50176
	ds_read_b128 v[198:201], v159 offset:51200
	ds_read_b128 v[202:205], v159 offset:52224
	ds_read_b128 v[206:209], v159 offset:53248
	ds_read_b128 v[210:213], v159 offset:54272
	ds_read_b128 v[214:217], v159 offset:55296
	ds_read_b128 v[218:221], v159 offset:56320
	global_load_lds_dwordx4 v[156:157], off
	s_add_i32 m0, s34, 0x2000
	s_add_u32 s30, s30, 0x40080
	v_lshl_add_u64 v[156:157], v[222:223], 0, s[10:11]
	s_addc_u32 s31, s31, 0
	s_add_i32 s34, s57, s36
	global_load_lds_dwordx4 v[156:157], off
	s_mov_b32 m0, s34
	s_nop 0
	global_load_lds_dwordx4 v130, s[30:31]
	s_add_i32 m0, s34, 0x2000
	s_nop 0
	global_load_lds_dwordx4 v134, s[30:31]
	v_lshl_add_u64 v[156:157], v[224:225], 0, s[10:11]
	s_mov_b32 m0, s43
	s_nop 0
	global_load_lds_dwordx4 v[156:157], off
	v_lshl_add_u64 v[156:157], v[226:227], 0, s[10:11]
	s_mov_b32 m0, s44
	s_nop 0
	global_load_lds_dwordx4 v[156:157], off
	s_waitcnt vmcnt(8)
	s_waitcnt lgkmcnt(0)
	s_barrier
	s_setprio 1
	s_waitcnt lgkmcnt(0)
	v_mfma_f32_16x16x32_bf16 v[56:59], v[152:155], v[190:193], v[56:59]
	v_mfma_f32_16x16x32_bf16 v[52:55], v[166:169], v[190:193], v[52:55]
	v_mfma_f32_16x16x32_bf16 v[40:43], v[152:155], v[198:201], v[40:43]
	v_mfma_f32_16x16x32_bf16 v[36:39], v[166:169], v[198:201], v[36:39]
	v_mfma_f32_16x16x32_bf16 v[24:27], v[152:155], v[206:209], v[24:27]
	v_mfma_f32_16x16x32_bf16 v[20:23], v[166:169], v[206:209], v[20:23]
	v_mfma_f32_16x16x32_bf16 v[8:11], v[152:155], v[214:217], v[8:11]
	v_mfma_f32_16x16x32_bf16 v[4:7], v[166:169], v[214:217], v[4:7]
	v_mfma_f32_16x16x32_bf16 v[56:59], v[162:165], v[194:197], v[56:59]
	v_mfma_f32_16x16x32_bf16 v[52:55], v[170:173], v[194:197], v[52:55]
	v_mfma_f32_16x16x32_bf16 v[40:43], v[162:165], v[202:205], v[40:43]
	v_mfma_f32_16x16x32_bf16 v[36:39], v[170:173], v[202:205], v[36:39]
	v_mfma_f32_16x16x32_bf16 v[24:27], v[162:165], v[210:213], v[24:27]
	v_mfma_f32_16x16x32_bf16 v[20:23], v[170:173], v[210:213], v[20:23]
	v_mfma_f32_16x16x32_bf16 v[8:11], v[162:165], v[218:221], v[8:11]
	v_mfma_f32_16x16x32_bf16 v[4:7], v[170:173], v[218:221], v[4:7]
	s_setprio 0
	s_setprio 1
	v_mfma_f32_16x16x32_bf16 v[60:63], v[174:177], v[190:193], v[60:63]
	v_mfma_f32_16x16x32_bf16 v[48:51], v[182:185], v[190:193], v[48:51]
	v_mfma_f32_16x16x32_bf16 v[44:47], v[174:177], v[198:201], v[44:47]
	v_mfma_f32_16x16x32_bf16 v[32:35], v[182:185], v[198:201], v[32:35]
	v_mfma_f32_16x16x32_bf16 v[28:31], v[174:177], v[206:209], v[28:31]
	v_mfma_f32_16x16x32_bf16 v[16:19], v[182:185], v[206:209], v[16:19]
	v_mfma_f32_16x16x32_bf16 v[12:15], v[174:177], v[214:217], v[12:15]
	v_mfma_f32_16x16x32_bf16 v[0:3], v[182:185], v[214:217], v[0:3]
	v_mfma_f32_16x16x32_bf16 v[60:63], v[178:181], v[194:197], v[60:63]
	v_mfma_f32_16x16x32_bf16 v[48:51], v[186:189], v[194:197], v[48:51]
	v_mfma_f32_16x16x32_bf16 v[44:47], v[178:181], v[202:205], v[44:47]
	v_mfma_f32_16x16x32_bf16 v[32:35], v[186:189], v[202:205], v[32:35]
	v_mfma_f32_16x16x32_bf16 v[28:31], v[178:181], v[210:213], v[28:31]
	v_mfma_f32_16x16x32_bf16 v[16:19], v[186:189], v[210:213], v[16:19]
	v_mfma_f32_16x16x32_bf16 v[12:15], v[178:181], v[218:221], v[12:15]
	v_mfma_f32_16x16x32_bf16 v[0:3], v[186:189], v[218:221], v[0:3]
	s_setprio 0
	s_barrier
	s_add_i32 s55, s55, 2
	s_add_u32 s28, s28, 0x100
	s_addc_u32 s29, s29, 0
	s_add_u32 s53, s53, 0x100
	s_addc_u32 s54, s54, 0
	s_cmp_gt_u32 s55, 13
	s_cbranch_scc0 .LBB0_161
	s_and_b64 vcc, exec, s[12:13]
	s_cbranch_vccz .LBB0_166
	s_barrier
	v_lshl_add_u32 v152, s26, 8, v139
	s_cmp_gt_i32 s24, 21
	s_mov_b64 s[26:27], -1
	s_cbranch_scc1 .LBB0_167

.LBB0_247:
	ds_read_b128 v[148:151], v145
	ds_read_b128 v[152:155], v145 offset:1024
	ds_read_b128 v[156:159], v145 offset:2048
	ds_read_b128 v[160:163], v145 offset:3072
	ds_read_b128 v[164:167], v146
	ds_read_b128 v[168:171], v146 offset:1024
	ds_read_b128 v[172:175], v146 offset:2048
	ds_read_b128 v[176:179], v146 offset:3072
	s_add_u32 s28, s26, 0x100
	s_addc_u32 s29, s27, 0
	s_cmp_eq_u32 s56, 40
	s_cselect_b32 s35, s5, s29
	s_cselect_b32 s34, s4, s28
	s_cselect_b32 s31, s25, s55
	s_cselect_b32 s30, s24, s54
	v_lshl_add_u64 v[140:141], s[26:27], 0, v[132:133]
	s_add_i32 m0, s40, 0xc000
	ds_read_b128 v[180:183], v147
	ds_read_b128 v[184:187], v147 offset:1024
	ds_read_b128 v[188:191], v147 offset:2048
	ds_read_b128 v[192:195], v147 offset:3072
	ds_read_b128 v[196:199], v147 offset:4096
	ds_read_b128 v[200:203], v147 offset:5120
	ds_read_b128 v[204:207], v147 offset:6144
	ds_read_b128 v[208:211], v147 offset:7168
	global_load_lds_dwordx4 v[140:141], off
	v_lshl_add_u64 v[140:141], s[26:27], 0, v[134:135]
	s_add_i32 m0, s40, 0xe000
	s_nop 0
	global_load_lds_dwordx4 v[140:141], off
	s_waitcnt vmcnt(8)
	s_waitcnt lgkmcnt(0)
	s_barrier
	s_setprio 1
	s_waitcnt lgkmcnt(0)
	v_mfma_f32_16x16x32_bf16 v[124:127], v[148:151], v[180:183], v[124:127]
	v_mfma_f32_16x16x32_bf16 v[120:123], v[156:159], v[180:183], v[120:123]
	v_mfma_f32_16x16x32_bf16 v[112:115], v[148:151], v[188:191], v[112:115]
	v_mfma_f32_16x16x32_bf16 v[108:111], v[156:159], v[188:191], v[108:111]
	v_mfma_f32_16x16x32_bf16 v[96:99], v[148:151], v[196:199], v[96:99]
	v_mfma_f32_16x16x32_bf16 v[92:95], v[156:159], v[196:199], v[92:95]
	v_mfma_f32_16x16x32_bf16 v[80:83], v[148:151], v[204:207], v[80:83]
	v_mfma_f32_16x16x32_bf16 v[76:79], v[156:159], v[204:207], v[76:79]
	v_mfma_f32_16x16x32_bf16 v[124:127], v[152:155], v[184:187], v[124:127]
	v_mfma_f32_16x16x32_bf16 v[120:123], v[160:163], v[184:187], v[120:123]
	v_mfma_f32_16x16x32_bf16 v[112:115], v[152:155], v[192:195], v[112:115]
	v_mfma_f32_16x16x32_bf16 v[108:111], v[160:163], v[192:195], v[108:111]
	v_mfma_f32_16x16x32_bf16 v[96:99], v[152:155], v[200:203], v[96:99]
	v_mfma_f32_16x16x32_bf16 v[92:95], v[160:163], v[200:203], v[92:95]
	v_mfma_f32_16x16x32_bf16 v[80:83], v[152:155], v[208:211], v[80:83]
	v_mfma_f32_16x16x32_bf16 v[76:79], v[160:163], v[208:211], v[76:79]
	s_setprio 0
	s_setprio 1
	v_mfma_f32_16x16x32_bf16 v[116:119], v[164:167], v[180:183], v[116:119]
	v_mfma_f32_16x16x32_bf16 v[104:107], v[172:175], v[180:183], v[104:107]
	v_mfma_f32_16x16x32_bf16 v[100:103], v[164:167], v[188:191], v[100:103]
	v_mfma_f32_16x16x32_bf16 v[88:91], v[172:175], v[188:191], v[88:91]
	v_mfma_f32_16x16x32_bf16 v[84:87], v[164:167], v[196:199], v[84:87]
	v_mfma_f32_16x16x32_bf16 v[72:75], v[172:175], v[196:199], v[72:75]
	v_mfma_f32_16x16x32_bf16 v[68:71], v[164:167], v[204:207], v[68:71]
	v_mfma_f32_16x16x32_bf16 v[64:67], v[172:175], v[204:207], v[64:67]
	v_mfma_f32_16x16x32_bf16 v[116:119], v[168:171], v[184:187], v[116:119]
	v_mfma_f32_16x16x32_bf16 v[104:107], v[176:179], v[184:187], v[104:107]
	v_mfma_f32_16x16x32_bf16 v[100:103], v[168:171], v[192:195], v[100:103]
	v_mfma_f32_16x16x32_bf16 v[88:91], v[176:179], v[192:195], v[88:91]
	v_mfma_f32_16x16x32_bf16 v[84:87], v[168:171], v[200:203], v[84:87]
	v_mfma_f32_16x16x32_bf16 v[72:75], v[176:179], v[200:203], v[72:75]
	v_mfma_f32_16x16x32_bf16 v[68:71], v[168:171], v[208:211], v[68:71]
	v_mfma_f32_16x16x32_bf16 v[64:67], v[176:179], v[208:211], v[64:67]
	s_setprio 0
	s_barrier
	s_add_i32 s26, s48, s37
	v_lshl_add_u64 v[140:141], s[30:31], 0, v[128:129]
	s_mov_b32 m0, s26
	ds_read_b128 v[180:183], v147 offset:16384
	ds_read_b128 v[184:187], v147 offset:17408
	ds_read_b128 v[188:191], v147 offset:18432
	ds_read_b128 v[192:195], v147 offset:19456
	ds_read_b128 v[196:199], v147 offset:20480
	ds_read_b128 v[200:203], v147 offset:21504
	ds_read_b128 v[204:207], v147 offset:22528
	ds_read_b128 v[208:211], v147 offset:23552
	global_load_lds_dwordx4 v[140:141], off
	s_add_i32 m0, s26, 0x2000
	s_add_u32 s26, s30, 0xb0000
	v_lshl_add_u64 v[212:213], s[30:31], 0, v[130:131]
	s_addc_u32 s27, s31, 0
	s_add_i32 s57, s49, s37
	global_load_lds_dwordx4 v[212:213], off
	v_lshl_add_u64 v[214:215], s[26:27], 0, v[128:129]
	s_mov_b32 m0, s57
	v_lshl_add_u64 v[216:217], s[34:35], 0, v[130:131]
	global_load_lds_dwordx4 v[214:215], off
	s_add_i32 m0, s57, 0x2000
	s_nop 0
	global_load_lds_dwordx4 v130, s[26:27]
	v_lshl_add_u64 v[214:215], s[34:35], 0, v[128:129]
	s_mov_b32 m0, s40
	s_nop 0
	global_load_lds_dwordx4 v[214:215], off
	s_mov_b32 m0, s41
	s_nop 0
	global_load_lds_dwordx4 v[216:217], off
	s_waitcnt vmcnt(8)
	s_waitcnt lgkmcnt(0)
	s_barrier
	s_setprio 1
	s_waitcnt lgkmcnt(0)
	v_mfma_f32_16x16x32_bf16 v[60:63], v[148:151], v[180:183], v[60:63]
	v_mfma_f32_16x16x32_bf16 v[56:59], v[156:159], v[180:183], v[56:59]
	v_mfma_f32_16x16x32_bf16 v[48:51], v[148:151], v[188:191], v[48:51]
	v_mfma_f32_16x16x32_bf16 v[44:47], v[156:159], v[188:191], v[44:47]
	v_mfma_f32_16x16x32_bf16 v[32:35], v[148:151], v[196:199], v[32:35]
	v_mfma_f32_16x16x32_bf16 v[28:31], v[156:159], v[196:199], v[28:31]
	v_mfma_f32_16x16x32_bf16 v[16:19], v[148:151], v[204:207], v[16:19]
	v_mfma_f32_16x16x32_bf16 v[12:15], v[156:159], v[204:207], v[12:15]
	v_mfma_f32_16x16x32_bf16 v[60:63], v[152:155], v[184:187], v[60:63]
	v_mfma_f32_16x16x32_bf16 v[56:59], v[160:163], v[184:187], v[56:59]
	v_mfma_f32_16x16x32_bf16 v[48:51], v[152:155], v[192:195], v[48:51]
	v_mfma_f32_16x16x32_bf16 v[44:47], v[160:163], v[192:195], v[44:47]
	v_mfma_f32_16x16x32_bf16 v[32:35], v[152:155], v[200:203], v[32:35]
	v_mfma_f32_16x16x32_bf16 v[28:31], v[160:163], v[200:203], v[28:31]
	v_mfma_f32_16x16x32_bf16 v[16:19], v[152:155], v[208:211], v[16:19]
	v_mfma_f32_16x16x32_bf16 v[12:15], v[160:163], v[208:211], v[12:15]
	s_setprio 0
	s_setprio 1
	v_mfma_f32_16x16x32_bf16 v[52:55], v[164:167], v[180:183], v[52:55]
	v_mfma_f32_16x16x32_bf16 v[40:43], v[172:175], v[180:183], v[40:43]
	v_mfma_f32_16x16x32_bf16 v[36:39], v[164:167], v[188:191], v[36:39]
	v_mfma_f32_16x16x32_bf16 v[24:27], v[172:175], v[188:191], v[24:27]
	v_mfma_f32_16x16x32_bf16 v[20:23], v[164:167], v[196:199], v[20:23]
	v_mfma_f32_16x16x32_bf16 v[8:11], v[172:175], v[196:199], v[8:11]
	v_mfma_f32_16x16x32_bf16 v[4:7], v[164:167], v[204:207], v[4:7]
	v_mfma_f32_16x16x32_bf16 v[0:3], v[172:175], v[204:207], v[0:3]
	v_mfma_f32_16x16x32_bf16 v[52:55], v[168:171], v[184:187], v[52:55]
	v_mfma_f32_16x16x32_bf16 v[40:43], v[176:179], v[184:187], v[40:43]
	v_mfma_f32_16x16x32_bf16 v[36:39], v[168:171], v[192:195], v[36:39]
	v_mfma_f32_16x16x32_bf16 v[24:27], v[176:179], v[192:195], v[24:27]
	v_mfma_f32_16x16x32_bf16 v[20:23], v[168:171], v[200:203], v[20:23]
	v_mfma_f32_16x16x32_bf16 v[8:11], v[176:179], v[200:203], v[8:11]
	v_mfma_f32_16x16x32_bf16 v[4:7], v[168:171], v[208:211], v[4:7]
	v_mfma_f32_16x16x32_bf16 v[0:3], v[176:179], v[208:211], v[0:3]
	s_setprio 0
	s_barrier
	s_add_i32 s57, 0, 0x18000
	s_add_i32 s58, 0, 0x1c000
	v_add_u32_e32 v160, s57, v143
	v_add_u32_e32 v176, s58, v143
	ds_read_b128 v[148:151], v160
	ds_read_b128 v[152:155], v160 offset:1024
	ds_read_b128 v[156:159], v160 offset:2048
	ds_read_b128 v[160:163], v160 offset:3072
	ds_read_b128 v[164:167], v176
	ds_read_b128 v[168:171], v176 offset:1024
	ds_read_b128 v[172:175], v176 offset:2048
	ds_read_b128 v[176:179], v176 offset:3072
	s_add_u32 s26, s34, 0xb0000
	s_addc_u32 s27, s35, 0
	s_mov_b32 m0, s42
	v_lshl_add_u64 v[218:219], s[26:27], 0, v[128:129]
	ds_read_b128 v[180:183], v147 offset:32768
	ds_read_b128 v[184:187], v147 offset:33792
	ds_read_b128 v[188:191], v147 offset:34816
	ds_read_b128 v[192:195], v147 offset:35840
	ds_read_b128 v[196:199], v147 offset:36864
	ds_read_b128 v[200:203], v147 offset:37888
	ds_read_b128 v[204:207], v147 offset:38912
	ds_read_b128 v[208:211], v147 offset:39936
	global_load_lds_dwordx4 v[218:219], off
	v_lshl_add_u64 v[218:219], s[26:27], 0, v[130:131]
	s_mov_b32 m0, s43
	s_nop 0
	global_load_lds_dwordx4 v[218:219], off
	s_waitcnt vmcnt(8)
	s_waitcnt lgkmcnt(0)
	s_barrier
	s_setprio 1
	s_waitcnt lgkmcnt(0)
	v_mfma_f32_16x16x32_bf16 v[124:127], v[148:151], v[180:183], v[124:127]
	v_mfma_f32_16x16x32_bf16 v[120:123], v[156:159], v[180:183], v[120:123]
	v_mfma_f32_16x16x32_bf16 v[112:115], v[148:151], v[188:191], v[112:115]
	v_mfma_f32_16x16x32_bf16 v[108:111], v[156:159], v[188:191], v[108:111]
	v_mfma_f32_16x16x32_bf16 v[96:99], v[148:151], v[196:199], v[96:99]
	v_mfma_f32_16x16x32_bf16 v[92:95], v[156:159], v[196:199], v[92:95]
	v_mfma_f32_16x16x32_bf16 v[80:83], v[148:151], v[204:207], v[80:83]
	v_mfma_f32_16x16x32_bf16 v[76:79], v[156:159], v[204:207], v[76:79]
	v_mfma_f32_16x16x32_bf16 v[124:127], v[152:155], v[184:187], v[124:127]
	v_mfma_f32_16x16x32_bf16 v[120:123], v[160:163], v[184:187], v[120:123]
	v_mfma_f32_16x16x32_bf16 v[112:115], v[152:155], v[192:195], v[112:115]
	v_mfma_f32_16x16x32_bf16 v[108:111], v[160:163], v[192:195], v[108:111]
	v_mfma_f32_16x16x32_bf16 v[96:99], v[152:155], v[200:203], v[96:99]
	v_mfma_f32_16x16x32_bf16 v[92:95], v[160:163], v[200:203], v[92:95]
	v_mfma_f32_16x16x32_bf16 v[80:83], v[152:155], v[208:211], v[80:83]
	v_mfma_f32_16x16x32_bf16 v[76:79], v[160:163], v[208:211], v[76:79]
	s_setprio 0
	s_setprio 1
	v_mfma_f32_16x16x32_bf16 v[116:119], v[164:167], v[180:183], v[116:119]
	v_mfma_f32_16x16x32_bf16 v[104:107], v[172:175], v[180:183], v[104:107]
	v_mfma_f32_16x16x32_bf16 v[100:103], v[164:167], v[188:191], v[100:103]
	v_mfma_f32_16x16x32_bf16 v[88:91], v[172:175], v[188:191], v[88:91]
	v_mfma_f32_16x16x32_bf16 v[84:87], v[164:167], v[196:199], v[84:87]
	v_mfma_f32_16x16x32_bf16 v[72:75], v[172:175], v[196:199], v[72:75]
	v_mfma_f32_16x16x32_bf16 v[68:71], v[164:167], v[204:207], v[68:71]
	v_mfma_f32_16x16x32_bf16 v[64:67], v[172:175], v[204:207], v[64:67]
	v_mfma_f32_16x16x32_bf16 v[116:119], v[168:171], v[184:187], v[116:119]
	v_mfma_f32_16x16x32_bf16 v[104:107], v[176:179], v[184:187], v[104:107]
	v_mfma_f32_16x16x32_bf16 v[100:103], v[168:171], v[192:195], v[100:103]
	v_mfma_f32_16x16x32_bf16 v[88:91], v[176:179], v[192:195], v[88:91]
	v_mfma_f32_16x16x32_bf16 v[84:87], v[168:171], v[200:203], v[84:87]
	v_mfma_f32_16x16x32_bf16 v[72:75], v[176:179], v[200:203], v[72:75]
	v_mfma_f32_16x16x32_bf16 v[68:71], v[168:171], v[208:211], v[68:71]
	v_mfma_f32_16x16x32_bf16 v[64:67], v[176:179], v[208:211], v[64:67]
	s_setprio 0
	s_barrier
	s_add_i32 s26, s57, s37
	v_lshl_add_u64 v[140:141], v[140:141], 0, s[14:15]
	s_mov_b32 m0, s26
	ds_read_b128 v[180:183], v147 offset:49152
	ds_read_b128 v[184:187], v147 offset:50176
	ds_read_b128 v[188:191], v147 offset:51200
	ds_read_b128 v[192:195], v147 offset:52224
	ds_read_b128 v[196:199], v147 offset:53248
	ds_read_b128 v[200:203], v147 offset:54272
	ds_read_b128 v[204:207], v147 offset:55296
	ds_read_b128 v[208:211], v147 offset:56320
	global_load_lds_dwordx4 v[140:141], off
	s_add_i32 m0, s26, 0x2000
	s_add_u32 s26, s30, 0xb0080
	v_lshl_add_u64 v[140:141], v[212:213], 0, s[14:15]
	s_addc_u32 s27, s31, 0
	s_add_i32 s30, s58, s37
	global_load_lds_dwordx4 v[140:141], off
	v_lshl_add_u64 v[140:141], s[26:27], 0, v[128:129]
	s_mov_b32 m0, s30
	s_nop 0
	global_load_lds_dwordx4 v[140:141], off
	s_add_i32 m0, s30, 0x2000
	s_nop 0
	global_load_lds_dwordx4 v130, s[26:27]
	v_lshl_add_u64 v[140:141], v[214:215], 0, s[14:15]
	s_mov_b32 m0, s45
	s_nop 0
	global_load_lds_dwordx4 v[140:141], off
	v_lshl_add_u64 v[140:141], v[216:217], 0, s[14:15]
	s_mov_b32 m0, s46
	s_nop 0
	global_load_lds_dwordx4 v[140:141], off
	s_waitcnt vmcnt(8)
	s_waitcnt lgkmcnt(0)
	s_barrier
	s_setprio 1
	s_waitcnt lgkmcnt(0)
	v_mfma_f32_16x16x32_bf16 v[60:63], v[148:151], v[180:183], v[60:63]
	v_mfma_f32_16x16x32_bf16 v[56:59], v[156:159], v[180:183], v[56:59]
	v_mfma_f32_16x16x32_bf16 v[48:51], v[148:151], v[188:191], v[48:51]
	v_mfma_f32_16x16x32_bf16 v[44:47], v[156:159], v[188:191], v[44:47]
	v_mfma_f32_16x16x32_bf16 v[32:35], v[148:151], v[196:199], v[32:35]
	v_mfma_f32_16x16x32_bf16 v[28:31], v[156:159], v[196:199], v[28:31]
	v_mfma_f32_16x16x32_bf16 v[16:19], v[148:151], v[204:207], v[16:19]
	v_mfma_f32_16x16x32_bf16 v[12:15], v[156:159], v[204:207], v[12:15]
	v_mfma_f32_16x16x32_bf16 v[60:63], v[152:155], v[184:187], v[60:63]
	v_mfma_f32_16x16x32_bf16 v[56:59], v[160:163], v[184:187], v[56:59]
	v_mfma_f32_16x16x32_bf16 v[48:51], v[152:155], v[192:195], v[48:51]
	v_mfma_f32_16x16x32_bf16 v[44:47], v[160:163], v[192:195], v[44:47]
	v_mfma_f32_16x16x32_bf16 v[32:35], v[152:155], v[200:203], v[32:35]
	v_mfma_f32_16x16x32_bf16 v[28:31], v[160:163], v[200:203], v[28:31]
	v_mfma_f32_16x16x32_bf16 v[16:19], v[152:155], v[208:211], v[16:19]
	v_mfma_f32_16x16x32_bf16 v[12:15], v[160:163], v[208:211], v[12:15]
	s_setprio 0
	s_setprio 1
	v_mfma_f32_16x16x32_bf16 v[52:55], v[164:167], v[180:183], v[52:55]
	v_mfma_f32_16x16x32_bf16 v[40:43], v[172:175], v[180:183], v[40:43]
	v_mfma_f32_16x16x32_bf16 v[36:39], v[164:167], v[188:191], v[36:39]
	v_mfma_f32_16x16x32_bf16 v[24:27], v[172:175], v[188:191], v[24:27]
	v_mfma_f32_16x16x32_bf16 v[20:23], v[164:167], v[196:199], v[20:23]
	v_mfma_f32_16x16x32_bf16 v[8:11], v[172:175], v[196:199], v[8:11]
	v_mfma_f32_16x16x32_bf16 v[4:7], v[164:167], v[204:207], v[4:7]
	v_mfma_f32_16x16x32_bf16 v[0:3], v[172:175], v[204:207], v[0:3]
	v_mfma_f32_16x16x32_bf16 v[52:55], v[168:171], v[184:187], v[52:55]
	v_mfma_f32_16x16x32_bf16 v[40:43], v[176:179], v[184:187], v[40:43]
	v_mfma_f32_16x16x32_bf16 v[36:39], v[168:171], v[192:195], v[36:39]
	v_mfma_f32_16x16x32_bf16 v[24:27], v[176:179], v[192:195], v[24:27]
	v_mfma_f32_16x16x32_bf16 v[20:23], v[168:171], v[200:203], v[20:23]
	v_mfma_f32_16x16x32_bf16 v[8:11], v[176:179], v[200:203], v[8:11]
	v_mfma_f32_16x16x32_bf16 v[4:7], v[168:171], v[208:211], v[4:7]
	v_mfma_f32_16x16x32_bf16 v[0:3], v[176:179], v[208:211], v[0:3]
	s_setprio 0
	s_barrier
	s_add_i32 s56, s56, 2
	s_add_u32 s54, s54, 0x100
	s_addc_u32 s55, s55, 0
	s_cmp_gt_u32 s56, 41
	s_mov_b64 s[26:27], s[28:29]
	s_cbranch_scc0 .LBB0_247
	s_and_b64 vcc, exec, s[16:17]
	s_cbranch_vccz .LBB0_250
	s_barrier

.LBB0_328:
	s_add_u32 s8, s70, 0x15c00000
	s_addc_u32 s9, s71, 0
	s_and_b32 s16, s10, 3
	s_mov_b64 s[10:11], 0x80
	s_add_i32 m0, s56, 0x18000
	v_lshl_add_u64 v[4:5], v[4:5], 0, s[10:11]
	s_lshl_b32 s17, s13, 13
	s_lshl_b32 s18, s16, 12
	s_waitcnt vmcnt(2)
	s_barrier
	global_load_lds_dwordx4 v[4:5], off
	v_lshl_add_u64 v[0:1], v[0:1], 0, s[10:11]
	s_add_i32 m0, s56, 0x1a000
	s_add_i32 s63, s56, 0x8000
	s_add_i32 s64, s56, 0xa000
	global_load_lds_dwordx4 v[0:1], off
	v_lshl_add_u64 v[0:1], v[2:3], 0, s[10:11]
	s_mov_b32 m0, s63
	s_add_u32 s14, s48, 0x80080
	global_load_lds_dwordx4 v[0:1], off
	v_lshl_add_u64 v[0:1], v[6:7], 0, s[10:11]
	s_mov_b32 m0, s64
	s_addc_u32 s15, s49, 0
	global_load_lds_dwordx4 v[0:1], off
	s_add_i32 m0, s56, 0x1c000
	s_nop 0
	global_load_lds_dwordx4 v134, s[14:15]
	v_lshl_add_u64 v[0:1], s[14:15], 0, v[138:139]
	s_add_i32 m0, s56, 0x1e000
	s_cmpk_lt_u32 s12, 0x100
	global_load_lds_dwordx4 v[0:1], off
	v_lshrrev_b32_e32 v1, 1, v9
	v_and_b32_e32 v1, 24, v1
	v_and_b32_e32 v0, 15, v9
	v_lshlrev_b32_e32 v2, 1, v1
	v_lshl_or_b32 v160, s13, 6, v0
	v_lshl_or_b32 v0, v0, 6, v2
	v_lshlrev_b32_e32 v2, 2, v9
	v_and_b32_e32 v2, 32, v2
	v_bitop3_b32 v3, v0, s17, v2 bitop3:0xde
	v_bitop3_b32 v161, v0, s18, v2 bitop3:0xde
	v_lshl_or_b32 v0, s16, 5, v1
	v_lshlrev_b32_e32 v142, 1, v0
	v_mov_b32_e32 v143, v141
	s_cselect_b64 s[12:13], -1, 0
	s_cmp_lt_u32 s16, 2
	v_lshl_add_u64 v[0:1], s[70:71], 0, v[142:143]
	s_mov_b64 s[16:17], 0x19c00000
	v_lshl_add_u64 v[144:145], v[0:1], 0, s[16:17]
	v_lshlrev_b32_e32 v0, 15, v8
	v_and_b32_e32 v0, 0xffff0000, v0
	v_lshl_add_u32 v0, v10, 12, v0
	v_and_b32_e32 v1, 1, v8
	v_lshl_or_b32 v0, v1, 6, v0
	v_lshl_add_u32 v146, v11, 1, v0
	v_lshlrev_b32_e32 v0, 15, v12
	v_and_b32_e32 v0, 0xffff0000, v0
	s_waitcnt vmcnt(6)
	v_lshl_add_u32 v0, v13, 12, v0
	v_and_b32_e32 v1, 1, v12
	s_cselect_b64 s[14:15], -1, 0
	v_lshl_or_b32 v0, v1, 6, v0
	s_add_i32 s65, 0, 0x10000
	s_add_i32 s66, 0, 0x14000
	v_mov_b32_e32 v147, v141
	v_lshl_add_u32 v148, v14, 1, v0
	v_mov_b32_e32 v149, v141
	v_add_u32_e32 v143, s65, v161
	v_add_u32_e32 v162, s66, v161
	v_add_u32_e32 v163, 0, v3
	s_mov_b64 s[16:17], 0x10000
	s_mov_b64 s[18:19], 0x12000
	s_mov_b64 s[20:21], 0x14000
	s_mov_b64 s[22:23], 0x16000
	s_mov_b64 s[24:25], 0x40000
	s_mov_b32 s67, 0x40000
	s_mov_b64 s[26:27], 0x48000
	s_mov_b32 s68, 0x48000
	s_mov_b64 s[28:29], 0x50000
	s_mov_b32 s69, 0x50000
	s_mov_b64 s[30:31], 0x58000
	s_mov_b32 s78, 0x58000
	s_barrier
	s_branch .LBB0_331

.LBB0_340:
	ds_read_b128 v[128:131], v143
	ds_read_b128 v[150:153], v143 offset:1024
	ds_read_b128 v[154:157], v143 offset:2048
	ds_read_b128 v[164:167], v143 offset:3072
	ds_read_b128 v[168:171], v162
	ds_read_b128 v[172:175], v162 offset:1024
	ds_read_b128 v[176:179], v162 offset:2048
	ds_read_b128 v[180:183], v162 offset:3072
	s_add_i32 s86, s48, 2
	s_add_u32 s49, s46, 0xfff80080
	s_addc_u32 s50, s47, -1
	s_cmp_eq_u32 s83, s48
	s_cselect_b32 s48, s81, s84
	s_cselect_b32 s51, s3, s50
	s_cselect_b32 s50, s35, s49
	s_cselect_b32 s49, s37, s85
	s_add_i32 m0, s56, 0xc000
	ds_read_b128 v[184:187], v163
	ds_read_b128 v[188:191], v163 offset:1024
	ds_read_b128 v[192:195], v163 offset:2048
	ds_read_b128 v[196:199], v163 offset:3072
	ds_read_b128 v[200:203], v163 offset:4096
	ds_read_b128 v[204:207], v163 offset:5120
	ds_read_b128 v[208:211], v163 offset:6144
	ds_read_b128 v[212:215], v163 offset:7168
	global_load_lds_dwordx4 v146, s[46:47]
	s_add_i32 m0, s56, 0xe000
	s_nop 0
	global_load_lds_dwordx4 v148, s[46:47]
	s_waitcnt vmcnt(8)
	s_waitcnt lgkmcnt(0)
	s_barrier
	s_setprio 1
	s_waitcnt lgkmcnt(0)
	v_mfma_f32_16x16x32_bf16 v[124:127], v[128:131], v[184:187], v[124:127]
	v_mfma_f32_16x16x32_bf16 v[120:123], v[154:157], v[184:187], v[120:123]
	v_mfma_f32_16x16x32_bf16 v[116:119], v[128:131], v[192:195], v[116:119]
	v_mfma_f32_16x16x32_bf16 v[108:111], v[154:157], v[192:195], v[108:111]
	v_mfma_f32_16x16x32_bf16 v[100:103], v[128:131], v[200:203], v[100:103]
	v_mfma_f32_16x16x32_bf16 v[92:95], v[154:157], v[200:203], v[92:95]
	v_mfma_f32_16x16x32_bf16 v[84:87], v[128:131], v[208:211], v[84:87]
	v_mfma_f32_16x16x32_bf16 v[76:79], v[154:157], v[208:211], v[76:79]
	v_mfma_f32_16x16x32_bf16 v[124:127], v[150:153], v[188:191], v[124:127]
	v_mfma_f32_16x16x32_bf16 v[120:123], v[164:167], v[188:191], v[120:123]
	v_mfma_f32_16x16x32_bf16 v[116:119], v[150:153], v[196:199], v[116:119]
	v_mfma_f32_16x16x32_bf16 v[108:111], v[164:167], v[196:199], v[108:111]
	v_mfma_f32_16x16x32_bf16 v[100:103], v[150:153], v[204:207], v[100:103]
	v_mfma_f32_16x16x32_bf16 v[92:95], v[164:167], v[204:207], v[92:95]
	v_mfma_f32_16x16x32_bf16 v[84:87], v[150:153], v[212:215], v[84:87]
	v_mfma_f32_16x16x32_bf16 v[76:79], v[164:167], v[212:215], v[76:79]
	s_setprio 0
	s_setprio 1
	v_mfma_f32_16x16x32_bf16 v[112:115], v[168:171], v[184:187], v[112:115]
	v_mfma_f32_16x16x32_bf16 v[104:107], v[176:179], v[184:187], v[104:107]
	v_mfma_f32_16x16x32_bf16 v[96:99], v[168:171], v[192:195], v[96:99]
	v_mfma_f32_16x16x32_bf16 v[88:91], v[176:179], v[192:195], v[88:91]
	v_mfma_f32_16x16x32_bf16 v[80:83], v[168:171], v[200:203], v[80:83]
	v_mfma_f32_16x16x32_bf16 v[72:75], v[176:179], v[200:203], v[72:75]
	v_mfma_f32_16x16x32_bf16 v[68:71], v[168:171], v[208:211], v[68:71]
	v_mfma_f32_16x16x32_bf16 v[64:67], v[176:179], v[208:211], v[64:67]
	v_mfma_f32_16x16x32_bf16 v[112:115], v[172:175], v[188:191], v[112:115]
	v_mfma_f32_16x16x32_bf16 v[104:107], v[180:183], v[188:191], v[104:107]
	v_mfma_f32_16x16x32_bf16 v[96:99], v[172:175], v[196:199], v[96:99]
	v_mfma_f32_16x16x32_bf16 v[88:91], v[180:183], v[196:199], v[88:91]
	v_mfma_f32_16x16x32_bf16 v[80:83], v[172:175], v[204:207], v[80:83]
	v_mfma_f32_16x16x32_bf16 v[72:75], v[180:183], v[204:207], v[72:75]
	v_mfma_f32_16x16x32_bf16 v[68:71], v[172:175], v[212:215], v[68:71]
	v_mfma_f32_16x16x32_bf16 v[64:67], v[180:183], v[212:215], v[64:67]
	s_setprio 0
	s_barrier
	s_add_i32 s87, s65, s55
	v_lshl_add_u64 v[158:159], s[48:49], 0, v[134:135]
	s_mov_b32 m0, s87
	ds_read_b128 v[184:187], v163 offset:16384
	ds_read_b128 v[188:191], v163 offset:17408
	ds_read_b128 v[192:195], v163 offset:18432
	ds_read_b128 v[196:199], v163 offset:19456
	ds_read_b128 v[200:203], v163 offset:20480
	ds_read_b128 v[204:207], v163 offset:21504
	ds_read_b128 v[208:211], v163 offset:22528
	ds_read_b128 v[212:215], v163 offset:23552
	global_load_lds_dwordx4 v[158:159], off
	s_add_i32 m0, s87, 0x2000
	s_add_u32 s88, s48, 0x80000
	v_lshl_add_u64 v[216:217], s[48:49], 0, v[138:139]
	s_addc_u32 s89, s49, 0
	s_add_i32 s87, s66, s55
	global_load_lds_dwordx4 v[216:217], off
	s_mov_b32 m0, s87
	v_lshl_add_u64 v[220:221], s[50:51], 0, v[136:137]
	global_load_lds_dwordx4 v134, s[88:89]
	s_add_i32 m0, s87, 0x2000
	s_nop 0
	global_load_lds_dwordx4 v138, s[88:89]
	v_lshl_add_u64 v[218:219], s[50:51], 0, v[132:133]
	s_mov_b32 m0, s56
	s_nop 0
	global_load_lds_dwordx4 v[218:219], off
	s_mov_b32 m0, s57
	s_nop 0
	global_load_lds_dwordx4 v[220:221], off
	s_waitcnt vmcnt(8)
	s_waitcnt lgkmcnt(0)
	s_barrier
	s_setprio 1
	s_waitcnt lgkmcnt(0)
	v_mfma_f32_16x16x32_bf16 v[60:63], v[128:131], v[184:187], v[60:63]
	v_mfma_f32_16x16x32_bf16 v[56:59], v[154:157], v[184:187], v[56:59]
	v_mfma_f32_16x16x32_bf16 v[52:55], v[128:131], v[192:195], v[52:55]
	v_mfma_f32_16x16x32_bf16 v[44:47], v[154:157], v[192:195], v[44:47]
	v_mfma_f32_16x16x32_bf16 v[36:39], v[128:131], v[200:203], v[36:39]
	v_mfma_f32_16x16x32_bf16 v[28:31], v[154:157], v[200:203], v[28:31]
	v_mfma_f32_16x16x32_bf16 v[20:23], v[128:131], v[208:211], v[20:23]
	v_mfma_f32_16x16x32_bf16 v[12:15], v[154:157], v[208:211], v[12:15]
	v_mfma_f32_16x16x32_bf16 v[60:63], v[150:153], v[188:191], v[60:63]
	v_mfma_f32_16x16x32_bf16 v[56:59], v[164:167], v[188:191], v[56:59]
	v_mfma_f32_16x16x32_bf16 v[52:55], v[150:153], v[196:199], v[52:55]
	v_mfma_f32_16x16x32_bf16 v[44:47], v[164:167], v[196:199], v[44:47]
	v_mfma_f32_16x16x32_bf16 v[36:39], v[150:153], v[204:207], v[36:39]
	v_mfma_f32_16x16x32_bf16 v[28:31], v[164:167], v[204:207], v[28:31]
	v_mfma_f32_16x16x32_bf16 v[20:23], v[150:153], v[212:215], v[20:23]
	v_mfma_f32_16x16x32_bf16 v[12:15], v[164:167], v[212:215], v[12:15]
	s_setprio 0
	s_setprio 1
	v_mfma_f32_16x16x32_bf16 v[48:51], v[168:171], v[184:187], v[48:51]
	v_mfma_f32_16x16x32_bf16 v[40:43], v[176:179], v[184:187], v[40:43]
	v_mfma_f32_16x16x32_bf16 v[32:35], v[168:171], v[192:195], v[32:35]
	v_mfma_f32_16x16x32_bf16 v[24:27], v[176:179], v[192:195], v[24:27]
	v_mfma_f32_16x16x32_bf16 v[16:19], v[168:171], v[200:203], v[16:19]
	v_mfma_f32_16x16x32_bf16 v[8:11], v[176:179], v[200:203], v[8:11]
	v_mfma_f32_16x16x32_bf16 v[4:7], v[168:171], v[208:211], v[4:7]
	v_mfma_f32_16x16x32_bf16 v[0:3], v[176:179], v[208:211], v[0:3]
	v_mfma_f32_16x16x32_bf16 v[48:51], v[172:175], v[188:191], v[48:51]
	v_mfma_f32_16x16x32_bf16 v[40:43], v[180:183], v[188:191], v[40:43]
	v_mfma_f32_16x16x32_bf16 v[32:35], v[172:175], v[196:199], v[32:35]
	v_mfma_f32_16x16x32_bf16 v[24:27], v[180:183], v[196:199], v[24:27]
	v_mfma_f32_16x16x32_bf16 v[16:19], v[172:175], v[204:207], v[16:19]
	v_mfma_f32_16x16x32_bf16 v[8:11], v[180:183], v[204:207], v[8:11]
	v_mfma_f32_16x16x32_bf16 v[4:7], v[172:175], v[212:215], v[4:7]
	v_mfma_f32_16x16x32_bf16 v[0:3], v[180:183], v[212:215], v[0:3]
	s_setprio 0
	s_barrier
	s_add_i32 s87, 0, 0x18000
	v_add_u32_e32 v140, s87, v161
	s_add_i32 s88, 0, 0x1c000
	ds_read_b128 v[128:131], v140
	ds_read_b128 v[150:153], v140 offset:1024
	ds_read_b128 v[154:157], v140 offset:2048
	ds_read_b128 v[164:167], v140 offset:3072
	v_add_u32_e32 v140, s88, v161
	ds_read_b128 v[168:171], v140
	ds_read_b128 v[172:175], v140 offset:1024
	ds_read_b128 v[176:179], v140 offset:2048
	ds_read_b128 v[180:183], v140 offset:3072
	s_add_u32 s50, s50, 0x80000
	s_addc_u32 s51, s51, 0
	s_mov_b32 m0, s58
	ds_read_b128 v[184:187], v163 offset:32768
	ds_read_b128 v[188:191], v163 offset:33792
	ds_read_b128 v[192:195], v163 offset:34816
	ds_read_b128 v[196:199], v163 offset:35840
	ds_read_b128 v[200:203], v163 offset:36864
	ds_read_b128 v[204:207], v163 offset:37888
	ds_read_b128 v[208:211], v163 offset:38912
	ds_read_b128 v[212:215], v163 offset:39936
	global_load_lds_dwordx4 v132, s[50:51]
	v_lshl_add_u64 v[222:223], s[50:51], 0, v[136:137]
	s_mov_b32 m0, s59
	s_nop 0
	global_load_lds_dwordx4 v[222:223], off
	s_waitcnt vmcnt(8)
	s_waitcnt lgkmcnt(0)
	s_barrier
	s_setprio 1
	s_waitcnt lgkmcnt(0)
	v_mfma_f32_16x16x32_bf16 v[124:127], v[128:131], v[184:187], v[124:127]
	v_mfma_f32_16x16x32_bf16 v[120:123], v[154:157], v[184:187], v[120:123]
	v_mfma_f32_16x16x32_bf16 v[116:119], v[128:131], v[192:195], v[116:119]
	v_mfma_f32_16x16x32_bf16 v[108:111], v[154:157], v[192:195], v[108:111]
	v_mfma_f32_16x16x32_bf16 v[100:103], v[128:131], v[200:203], v[100:103]
	v_mfma_f32_16x16x32_bf16 v[92:95], v[154:157], v[200:203], v[92:95]
	v_mfma_f32_16x16x32_bf16 v[84:87], v[128:131], v[208:211], v[84:87]
	v_mfma_f32_16x16x32_bf16 v[76:79], v[154:157], v[208:211], v[76:79]
	v_mfma_f32_16x16x32_bf16 v[124:127], v[150:153], v[188:191], v[124:127]
	v_mfma_f32_16x16x32_bf16 v[120:123], v[164:167], v[188:191], v[120:123]
	v_mfma_f32_16x16x32_bf16 v[116:119], v[150:153], v[196:199], v[116:119]
	v_mfma_f32_16x16x32_bf16 v[108:111], v[164:167], v[196:199], v[108:111]
	v_mfma_f32_16x16x32_bf16 v[100:103], v[150:153], v[204:207], v[100:103]
	v_mfma_f32_16x16x32_bf16 v[92:95], v[164:167], v[204:207], v[92:95]
	v_mfma_f32_16x16x32_bf16 v[84:87], v[150:153], v[212:215], v[84:87]
	v_mfma_f32_16x16x32_bf16 v[76:79], v[164:167], v[212:215], v[76:79]
	s_setprio 0
	s_setprio 1
	v_mfma_f32_16x16x32_bf16 v[112:115], v[168:171], v[184:187], v[112:115]
	v_mfma_f32_16x16x32_bf16 v[104:107], v[176:179], v[184:187], v[104:107]
	v_mfma_f32_16x16x32_bf16 v[96:99], v[168:171], v[192:195], v[96:99]
	v_mfma_f32_16x16x32_bf16 v[88:91], v[176:179], v[192:195], v[88:91]
	v_mfma_f32_16x16x32_bf16 v[80:83], v[168:171], v[200:203], v[80:83]
	v_mfma_f32_16x16x32_bf16 v[72:75], v[176:179], v[200:203], v[72:75]
	v_mfma_f32_16x16x32_bf16 v[68:71], v[168:171], v[208:211], v[68:71]
	v_mfma_f32_16x16x32_bf16 v[64:67], v[176:179], v[208:211], v[64:67]
	v_mfma_f32_16x16x32_bf16 v[112:115], v[172:175], v[188:191], v[112:115]
	v_mfma_f32_16x16x32_bf16 v[104:107], v[180:183], v[188:191], v[104:107]
	v_mfma_f32_16x16x32_bf16 v[96:99], v[172:175], v[196:199], v[96:99]
	v_mfma_f32_16x16x32_bf16 v[88:91], v[180:183], v[196:199], v[88:91]
	v_mfma_f32_16x16x32_bf16 v[80:83], v[172:175], v[204:207], v[80:83]
	v_mfma_f32_16x16x32_bf16 v[72:75], v[180:183], v[204:207], v[72:75]
	v_mfma_f32_16x16x32_bf16 v[68:71], v[172:175], v[212:215], v[68:71]
	v_mfma_f32_16x16x32_bf16 v[64:67], v[180:183], v[212:215], v[64:67]
	s_setprio 0
	s_barrier
	s_add_i32 s50, s87, s55
	v_lshl_add_u64 v[158:159], v[158:159], 0, s[10:11]
	s_mov_b32 m0, s50
	ds_read_b128 v[184:187], v163 offset:49152
	ds_read_b128 v[188:191], v163 offset:50176
	ds_read_b128 v[192:195], v163 offset:51200
	ds_read_b128 v[196:199], v163 offset:52224
	ds_read_b128 v[200:203], v163 offset:53248
	ds_read_b128 v[204:207], v163 offset:54272
	ds_read_b128 v[208:211], v163 offset:55296
	ds_read_b128 v[212:215], v163 offset:56320
	global_load_lds_dwordx4 v[158:159], off
	s_add_i32 m0, s50, 0x2000
	s_add_u32 s48, s48, 0x80080
	v_lshl_add_u64 v[158:159], v[216:217], 0, s[10:11]
	s_addc_u32 s49, s49, 0
	s_add_i32 s50, s88, s55
	global_load_lds_dwordx4 v[158:159], off
	s_mov_b32 m0, s50
	s_nop 0
	global_load_lds_dwordx4 v134, s[48:49]
	s_add_i32 m0, s50, 0x2000
	s_nop 0
	global_load_lds_dwordx4 v138, s[48:49]
	v_lshl_add_u64 v[158:159], v[218:219], 0, s[10:11]
	s_mov_b32 m0, s63
	s_nop 0
	global_load_lds_dwordx4 v[158:159], off
	v_lshl_add_u64 v[158:159], v[220:221], 0, s[10:11]
	s_mov_b32 m0, s64
	s_nop 0
	global_load_lds_dwordx4 v[158:159], off
	s_waitcnt vmcnt(8)
	s_waitcnt lgkmcnt(0)
	s_barrier
	s_setprio 1
	s_waitcnt lgkmcnt(0)
	v_mfma_f32_16x16x32_bf16 v[60:63], v[128:131], v[184:187], v[60:63]
	v_mfma_f32_16x16x32_bf16 v[56:59], v[154:157], v[184:187], v[56:59]
	v_mfma_f32_16x16x32_bf16 v[52:55], v[128:131], v[192:195], v[52:55]
	v_mfma_f32_16x16x32_bf16 v[44:47], v[154:157], v[192:195], v[44:47]
	v_mfma_f32_16x16x32_bf16 v[36:39], v[128:131], v[200:203], v[36:39]
	v_mfma_f32_16x16x32_bf16 v[28:31], v[154:157], v[200:203], v[28:31]
	v_mfma_f32_16x16x32_bf16 v[20:23], v[128:131], v[208:211], v[20:23]
	v_mfma_f32_16x16x32_bf16 v[12:15], v[154:157], v[208:211], v[12:15]
	v_mfma_f32_16x16x32_bf16 v[60:63], v[150:153], v[188:191], v[60:63]
	v_mfma_f32_16x16x32_bf16 v[56:59], v[164:167], v[188:191], v[56:59]
	v_mfma_f32_16x16x32_bf16 v[52:55], v[150:153], v[196:199], v[52:55]
	v_mfma_f32_16x16x32_bf16 v[44:47], v[164:167], v[196:199], v[44:47]
	v_mfma_f32_16x16x32_bf16 v[36:39], v[150:153], v[204:207], v[36:39]
	v_mfma_f32_16x16x32_bf16 v[28:31], v[164:167], v[204:207], v[28:31]
	v_mfma_f32_16x16x32_bf16 v[20:23], v[150:153], v[212:215], v[20:23]
	v_mfma_f32_16x16x32_bf16 v[12:15], v[164:167], v[212:215], v[12:15]
	s_setprio 0
	s_setprio 1
	v_mfma_f32_16x16x32_bf16 v[48:51], v[168:171], v[184:187], v[48:51]
	v_mfma_f32_16x16x32_bf16 v[40:43], v[176:179], v[184:187], v[40:43]
	v_mfma_f32_16x16x32_bf16 v[32:35], v[168:171], v[192:195], v[32:35]
	v_mfma_f32_16x16x32_bf16 v[24:27], v[176:179], v[192:195], v[24:27]
	v_mfma_f32_16x16x32_bf16 v[16:19], v[168:171], v[200:203], v[16:19]
	v_mfma_f32_16x16x32_bf16 v[8:11], v[176:179], v[200:203], v[8:11]
	v_mfma_f32_16x16x32_bf16 v[4:7], v[168:171], v[208:211], v[4:7]
	v_mfma_f32_16x16x32_bf16 v[0:3], v[176:179], v[208:211], v[0:3]
	v_mfma_f32_16x16x32_bf16 v[48:51], v[172:175], v[188:191], v[48:51]
	v_mfma_f32_16x16x32_bf16 v[40:43], v[180:183], v[188:191], v[40:43]
	v_mfma_f32_16x16x32_bf16 v[32:35], v[172:175], v[196:199], v[32:35]
	v_mfma_f32_16x16x32_bf16 v[24:27], v[180:183], v[196:199], v[24:27]
	v_mfma_f32_16x16x32_bf16 v[16:19], v[172:175], v[204:207], v[16:19]
	v_mfma_f32_16x16x32_bf16 v[8:11], v[180:183], v[204:207], v[8:11]
	v_mfma_f32_16x16x32_bf16 v[4:7], v[172:175], v[212:215], v[4:7]
	v_mfma_f32_16x16x32_bf16 v[0:3], v[180:183], v[212:215], v[0:3]
	s_setprio 0
	s_barrier
	s_add_u32 s46, s46, 0x100
	s_addc_u32 s47, s47, 0
	s_add_u32 s84, s84, 0x100
	s_addc_u32 s85, s85, 0
	s_cmp_ge_u32 s86, s82
	s_mov_b32 s48, s86
	s_cbranch_scc0 .LBB0_340
	s_and_b64 vcc, exec, s[12:13]
	s_cbranch_vccz .LBB0_343
	s_barrier

.LBB0_416:
	ds_read_b128 v[152:155], v149
	ds_read_b128 v[156:159], v149 offset:1024
	ds_read_b128 v[160:163], v149 offset:2048
	ds_read_b128 v[164:167], v149 offset:3072
	ds_read_b128 v[168:171], v150
	ds_read_b128 v[172:175], v150 offset:1024
	ds_read_b128 v[176:179], v150 offset:2048
	ds_read_b128 v[180:183], v150 offset:3072
	s_add_u32 s34, s30, 0xfffc0080
	s_addc_u32 s35, s31, -1
	s_cmp_eq_u32 s62, 12
	s_cselect_b32 s37, s23, s35
	s_cselect_b32 s36, s58, s34
	s_cselect_b32 s35, s21, s61
	s_cselect_b32 s34, s59, s60
	s_add_i32 m0, s29, 0xc000
	ds_read_b128 v[184:187], v151
	ds_read_b128 v[188:191], v151 offset:1024
	ds_read_b128 v[192:195], v151 offset:2048
	ds_read_b128 v[196:199], v151 offset:3072
	ds_read_b128 v[200:203], v151 offset:4096
	ds_read_b128 v[204:207], v151 offset:5120
	ds_read_b128 v[208:211], v151 offset:6144
	ds_read_b128 v[212:215], v151 offset:7168
	global_load_lds_dwordx4 v136, s[30:31]
	s_add_i32 m0, s29, 0xe000
	s_nop 0
	global_load_lds_dwordx4 v138, s[30:31]
	s_waitcnt vmcnt(8)
	s_waitcnt lgkmcnt(0)
	s_barrier
	s_setprio 1
	s_waitcnt lgkmcnt(0)
	v_mfma_f32_16x16x32_bf16 v[124:127], v[152:155], v[184:187], v[124:127]
	v_mfma_f32_16x16x32_bf16 v[120:123], v[160:163], v[184:187], v[120:123]
	v_mfma_f32_16x16x32_bf16 v[116:119], v[152:155], v[192:195], v[116:119]
	v_mfma_f32_16x16x32_bf16 v[108:111], v[160:163], v[192:195], v[108:111]
	v_mfma_f32_16x16x32_bf16 v[100:103], v[152:155], v[200:203], v[100:103]
	v_mfma_f32_16x16x32_bf16 v[92:95], v[160:163], v[200:203], v[92:95]
	v_mfma_f32_16x16x32_bf16 v[84:87], v[152:155], v[208:211], v[84:87]
	v_mfma_f32_16x16x32_bf16 v[76:79], v[160:163], v[208:211], v[76:79]
	v_mfma_f32_16x16x32_bf16 v[124:127], v[156:159], v[188:191], v[124:127]
	v_mfma_f32_16x16x32_bf16 v[120:123], v[164:167], v[188:191], v[120:123]
	v_mfma_f32_16x16x32_bf16 v[116:119], v[156:159], v[196:199], v[116:119]
	v_mfma_f32_16x16x32_bf16 v[108:111], v[164:167], v[196:199], v[108:111]
	v_mfma_f32_16x16x32_bf16 v[100:103], v[156:159], v[204:207], v[100:103]
	v_mfma_f32_16x16x32_bf16 v[92:95], v[164:167], v[204:207], v[92:95]
	v_mfma_f32_16x16x32_bf16 v[84:87], v[156:159], v[212:215], v[84:87]
	v_mfma_f32_16x16x32_bf16 v[76:79], v[164:167], v[212:215], v[76:79]
	s_setprio 0
	s_setprio 1
	v_mfma_f32_16x16x32_bf16 v[112:115], v[168:171], v[184:187], v[112:115]
	v_mfma_f32_16x16x32_bf16 v[104:107], v[176:179], v[184:187], v[104:107]
	v_mfma_f32_16x16x32_bf16 v[96:99], v[168:171], v[192:195], v[96:99]
	v_mfma_f32_16x16x32_bf16 v[88:91], v[176:179], v[192:195], v[88:91]
	v_mfma_f32_16x16x32_bf16 v[80:83], v[168:171], v[200:203], v[80:83]
	v_mfma_f32_16x16x32_bf16 v[72:75], v[176:179], v[200:203], v[72:75]
	v_mfma_f32_16x16x32_bf16 v[68:71], v[168:171], v[208:211], v[68:71]
	v_mfma_f32_16x16x32_bf16 v[64:67], v[176:179], v[208:211], v[64:67]
	v_mfma_f32_16x16x32_bf16 v[112:115], v[172:175], v[188:191], v[112:115]
	v_mfma_f32_16x16x32_bf16 v[104:107], v[180:183], v[188:191], v[104:107]
	v_mfma_f32_16x16x32_bf16 v[96:99], v[172:175], v[196:199], v[96:99]
	v_mfma_f32_16x16x32_bf16 v[88:91], v[180:183], v[196:199], v[88:91]
	v_mfma_f32_16x16x32_bf16 v[80:83], v[172:175], v[204:207], v[80:83]
	v_mfma_f32_16x16x32_bf16 v[72:75], v[180:183], v[204:207], v[72:75]
	v_mfma_f32_16x16x32_bf16 v[68:71], v[172:175], v[212:215], v[68:71]
	v_mfma_f32_16x16x32_bf16 v[64:67], v[180:183], v[212:215], v[64:67]
	s_setprio 0
	s_barrier
	s_add_i32 s63, s51, s43
	v_lshl_add_u64 v[144:145], s[34:35], 0, v[130:131]
	s_mov_b32 m0, s63
	ds_read_b128 v[184:187], v151 offset:16384
	ds_read_b128 v[188:191], v151 offset:17408
	ds_read_b128 v[192:195], v151 offset:18432
	ds_read_b128 v[196:199], v151 offset:19456
	ds_read_b128 v[200:203], v151 offset:20480
	ds_read_b128 v[204:207], v151 offset:21504
	ds_read_b128 v[208:211], v151 offset:22528
	ds_read_b128 v[212:215], v151 offset:23552
	global_load_lds_dwordx4 v[144:145], off
	s_add_i32 m0, s63, 0x2000
	s_add_u32 s64, s34, 0x40000
	v_lshl_add_u64 v[216:217], s[34:35], 0, v[134:135]
	s_addc_u32 s65, s35, 0
	s_add_i32 s63, s52, s43
	global_load_lds_dwordx4 v[216:217], off
	v_lshl_add_u64 v[218:219], s[64:65], 0, v[130:131]
	s_mov_b32 m0, s63
	v_lshl_add_u64 v[220:221], s[36:37], 0, v[132:133]
	global_load_lds_dwordx4 v[218:219], off
	s_add_i32 m0, s63, 0x2000
	s_nop 0
	global_load_lds_dwordx4 v134, s[64:65]
	v_lshl_add_u64 v[218:219], s[36:37], 0, v[128:129]
	s_mov_b32 m0, s29
	s_nop 0
	global_load_lds_dwordx4 v[218:219], off
	s_mov_b32 m0, s44
	s_nop 0
	global_load_lds_dwordx4 v[220:221], off
	s_waitcnt vmcnt(8)
	s_waitcnt lgkmcnt(0)
	s_barrier
	s_setprio 1
	s_waitcnt lgkmcnt(0)
	v_mfma_f32_16x16x32_bf16 v[60:63], v[152:155], v[184:187], v[60:63]
	v_mfma_f32_16x16x32_bf16 v[56:59], v[160:163], v[184:187], v[56:59]
	v_mfma_f32_16x16x32_bf16 v[52:55], v[152:155], v[192:195], v[52:55]
	v_mfma_f32_16x16x32_bf16 v[44:47], v[160:163], v[192:195], v[44:47]
	v_mfma_f32_16x16x32_bf16 v[36:39], v[152:155], v[200:203], v[36:39]
	v_mfma_f32_16x16x32_bf16 v[28:31], v[160:163], v[200:203], v[28:31]
	v_mfma_f32_16x16x32_bf16 v[20:23], v[152:155], v[208:211], v[20:23]
	v_mfma_f32_16x16x32_bf16 v[12:15], v[160:163], v[208:211], v[12:15]
	v_mfma_f32_16x16x32_bf16 v[60:63], v[156:159], v[188:191], v[60:63]
	v_mfma_f32_16x16x32_bf16 v[56:59], v[164:167], v[188:191], v[56:59]
	v_mfma_f32_16x16x32_bf16 v[52:55], v[156:159], v[196:199], v[52:55]
	v_mfma_f32_16x16x32_bf16 v[44:47], v[164:167], v[196:199], v[44:47]
	v_mfma_f32_16x16x32_bf16 v[36:39], v[156:159], v[204:207], v[36:39]
	v_mfma_f32_16x16x32_bf16 v[28:31], v[164:167], v[204:207], v[28:31]
	v_mfma_f32_16x16x32_bf16 v[20:23], v[156:159], v[212:215], v[20:23]
	v_mfma_f32_16x16x32_bf16 v[12:15], v[164:167], v[212:215], v[12:15]
	s_setprio 0
	s_setprio 1
	v_mfma_f32_16x16x32_bf16 v[48:51], v[168:171], v[184:187], v[48:51]
	v_mfma_f32_16x16x32_bf16 v[40:43], v[176:179], v[184:187], v[40:43]
	v_mfma_f32_16x16x32_bf16 v[32:35], v[168:171], v[192:195], v[32:35]
	v_mfma_f32_16x16x32_bf16 v[24:27], v[176:179], v[192:195], v[24:27]
	v_mfma_f32_16x16x32_bf16 v[16:19], v[168:171], v[200:203], v[16:19]
	v_mfma_f32_16x16x32_bf16 v[8:11], v[176:179], v[200:203], v[8:11]
	v_mfma_f32_16x16x32_bf16 v[4:7], v[168:171], v[208:211], v[4:7]
	v_mfma_f32_16x16x32_bf16 v[0:3], v[176:179], v[208:211], v[0:3]
	v_mfma_f32_16x16x32_bf16 v[48:51], v[172:175], v[188:191], v[48:51]
	v_mfma_f32_16x16x32_bf16 v[40:43], v[180:183], v[188:191], v[40:43]
	v_mfma_f32_16x16x32_bf16 v[32:35], v[172:175], v[196:199], v[32:35]
	v_mfma_f32_16x16x32_bf16 v[24:27], v[180:183], v[196:199], v[24:27]
	v_mfma_f32_16x16x32_bf16 v[16:19], v[172:175], v[204:207], v[16:19]
	v_mfma_f32_16x16x32_bf16 v[8:11], v[180:183], v[204:207], v[8:11]
	v_mfma_f32_16x16x32_bf16 v[4:7], v[172:175], v[212:215], v[4:7]
	v_mfma_f32_16x16x32_bf16 v[0:3], v[180:183], v[212:215], v[0:3]
	s_setprio 0
	s_barrier
	s_add_i32 s63, 0, 0x18000
	s_add_i32 s64, 0, 0x1c000
	v_add_u32_e32 v164, s63, v147
	v_add_u32_e32 v180, s64, v147
	ds_read_b128 v[152:155], v164
	ds_read_b128 v[156:159], v164 offset:1024
	ds_read_b128 v[160:163], v164 offset:2048
	ds_read_b128 v[164:167], v164 offset:3072
	ds_read_b128 v[168:171], v180
	ds_read_b128 v[172:175], v180 offset:1024
	ds_read_b128 v[176:179], v180 offset:2048
	ds_read_b128 v[180:183], v180 offset:3072
	s_add_u32 s36, s36, 0x40000
	s_addc_u32 s37, s37, 0
	s_mov_b32 m0, s45
	ds_read_b128 v[184:187], v151 offset:32768
	ds_read_b128 v[188:191], v151 offset:33792
	ds_read_b128 v[192:195], v151 offset:34816
	ds_read_b128 v[196:199], v151 offset:35840
	ds_read_b128 v[200:203], v151 offset:36864
	ds_read_b128 v[204:207], v151 offset:37888
	ds_read_b128 v[208:211], v151 offset:38912
	ds_read_b128 v[212:215], v151 offset:39936
	global_load_lds_dwordx4 v128, s[36:37]
	v_lshl_add_u64 v[222:223], s[36:37], 0, v[132:133]
	s_mov_b32 m0, s46
	s_nop 0
	global_load_lds_dwordx4 v[222:223], off
	s_waitcnt vmcnt(8)
	s_waitcnt lgkmcnt(0)
	s_barrier
	s_setprio 1
	s_waitcnt lgkmcnt(0)
	v_mfma_f32_16x16x32_bf16 v[124:127], v[152:155], v[184:187], v[124:127]
	v_mfma_f32_16x16x32_bf16 v[120:123], v[160:163], v[184:187], v[120:123]
	v_mfma_f32_16x16x32_bf16 v[116:119], v[152:155], v[192:195], v[116:119]
	v_mfma_f32_16x16x32_bf16 v[108:111], v[160:163], v[192:195], v[108:111]
	v_mfma_f32_16x16x32_bf16 v[100:103], v[152:155], v[200:203], v[100:103]
	v_mfma_f32_16x16x32_bf16 v[92:95], v[160:163], v[200:203], v[92:95]
	v_mfma_f32_16x16x32_bf16 v[84:87], v[152:155], v[208:211], v[84:87]
	v_mfma_f32_16x16x32_bf16 v[76:79], v[160:163], v[208:211], v[76:79]
	v_mfma_f32_16x16x32_bf16 v[124:127], v[156:159], v[188:191], v[124:127]
	v_mfma_f32_16x16x32_bf16 v[120:123], v[164:167], v[188:191], v[120:123]
	v_mfma_f32_16x16x32_bf16 v[116:119], v[156:159], v[196:199], v[116:119]
	v_mfma_f32_16x16x32_bf16 v[108:111], v[164:167], v[196:199], v[108:111]
	v_mfma_f32_16x16x32_bf16 v[100:103], v[156:159], v[204:207], v[100:103]
	v_mfma_f32_16x16x32_bf16 v[92:95], v[164:167], v[204:207], v[92:95]
	v_mfma_f32_16x16x32_bf16 v[84:87], v[156:159], v[212:215], v[84:87]
	v_mfma_f32_16x16x32_bf16 v[76:79], v[164:167], v[212:215], v[76:79]
	s_setprio 0
	s_setprio 1
	v_mfma_f32_16x16x32_bf16 v[112:115], v[168:171], v[184:187], v[112:115]
	v_mfma_f32_16x16x32_bf16 v[104:107], v[176:179], v[184:187], v[104:107]
	v_mfma_f32_16x16x32_bf16 v[96:99], v[168:171], v[192:195], v[96:99]
	v_mfma_f32_16x16x32_bf16 v[88:91], v[176:179], v[192:195], v[88:91]
	v_mfma_f32_16x16x32_bf16 v[80:83], v[168:171], v[200:203], v[80:83]
	v_mfma_f32_16x16x32_bf16 v[72:75], v[176:179], v[200:203], v[72:75]
	v_mfma_f32_16x16x32_bf16 v[68:71], v[168:171], v[208:211], v[68:71]
	v_mfma_f32_16x16x32_bf16 v[64:67], v[176:179], v[208:211], v[64:67]
	v_mfma_f32_16x16x32_bf16 v[112:115], v[172:175], v[188:191], v[112:115]
	v_mfma_f32_16x16x32_bf16 v[104:107], v[180:183], v[188:191], v[104:107]
	v_mfma_f32_16x16x32_bf16 v[96:99], v[172:175], v[196:199], v[96:99]
	v_mfma_f32_16x16x32_bf16 v[88:91], v[180:183], v[196:199], v[88:91]
	v_mfma_f32_16x16x32_bf16 v[80:83], v[172:175], v[204:207], v[80:83]
	v_mfma_f32_16x16x32_bf16 v[72:75], v[180:183], v[204:207], v[72:75]
	v_mfma_f32_16x16x32_bf16 v[68:71], v[172:175], v[212:215], v[68:71]
	v_mfma_f32_16x16x32_bf16 v[64:67], v[180:183], v[212:215], v[64:67]
	s_setprio 0
	s_barrier
	s_add_i32 s36, s63, s43
	v_lshl_add_u64 v[144:145], v[144:145], 0, s[10:11]
	s_mov_b32 m0, s36
	ds_read_b128 v[184:187], v151 offset:49152
	ds_read_b128 v[188:191], v151 offset:50176
	ds_read_b128 v[192:195], v151 offset:51200
	ds_read_b128 v[196:199], v151 offset:52224
	ds_read_b128 v[200:203], v151 offset:53248
	ds_read_b128 v[204:207], v151 offset:54272
	ds_read_b128 v[208:211], v151 offset:55296
	ds_read_b128 v[212:215], v151 offset:56320
	global_load_lds_dwordx4 v[144:145], off
	s_add_i32 m0, s36, 0x2000
	s_add_u32 s34, s34, 0x40080
	v_lshl_add_u64 v[144:145], v[216:217], 0, s[10:11]
	s_addc_u32 s35, s35, 0
	s_add_i32 s36, s64, s43
	global_load_lds_dwordx4 v[144:145], off
	v_lshl_add_u64 v[144:145], s[34:35], 0, v[130:131]
	s_mov_b32 m0, s36
	s_nop 0
	global_load_lds_dwordx4 v[144:145], off
	s_add_i32 m0, s36, 0x2000
	s_nop 0
	global_load_lds_dwordx4 v134, s[34:35]
	v_lshl_add_u64 v[144:145], v[218:219], 0, s[10:11]
	s_mov_b32 m0, s48
	s_nop 0
	global_load_lds_dwordx4 v[144:145], off
	v_lshl_add_u64 v[144:145], v[220:221], 0, s[10:11]
	s_mov_b32 m0, s49
	s_nop 0
	global_load_lds_dwordx4 v[144:145], off
	s_waitcnt vmcnt(8)
	s_waitcnt lgkmcnt(0)
	s_barrier
	s_setprio 1
	s_waitcnt lgkmcnt(0)
	v_mfma_f32_16x16x32_bf16 v[60:63], v[152:155], v[184:187], v[60:63]
	v_mfma_f32_16x16x32_bf16 v[56:59], v[160:163], v[184:187], v[56:59]
	v_mfma_f32_16x16x32_bf16 v[52:55], v[152:155], v[192:195], v[52:55]
	v_mfma_f32_16x16x32_bf16 v[44:47], v[160:163], v[192:195], v[44:47]
	v_mfma_f32_16x16x32_bf16 v[36:39], v[152:155], v[200:203], v[36:39]
	v_mfma_f32_16x16x32_bf16 v[28:31], v[160:163], v[200:203], v[28:31]
	v_mfma_f32_16x16x32_bf16 v[20:23], v[152:155], v[208:211], v[20:23]
	v_mfma_f32_16x16x32_bf16 v[12:15], v[160:163], v[208:211], v[12:15]
	v_mfma_f32_16x16x32_bf16 v[60:63], v[156:159], v[188:191], v[60:63]
	v_mfma_f32_16x16x32_bf16 v[56:59], v[164:167], v[188:191], v[56:59]
	v_mfma_f32_16x16x32_bf16 v[52:55], v[156:159], v[196:199], v[52:55]
	v_mfma_f32_16x16x32_bf16 v[44:47], v[164:167], v[196:199], v[44:47]
	v_mfma_f32_16x16x32_bf16 v[36:39], v[156:159], v[204:207], v[36:39]
	v_mfma_f32_16x16x32_bf16 v[28:31], v[164:167], v[204:207], v[28:31]
	v_mfma_f32_16x16x32_bf16 v[20:23], v[156:159], v[212:215], v[20:23]
	v_mfma_f32_16x16x32_bf16 v[12:15], v[164:167], v[212:215], v[12:15]
	s_setprio 0
	s_setprio 1
	v_mfma_f32_16x16x32_bf16 v[48:51], v[168:171], v[184:187], v[48:51]
	v_mfma_f32_16x16x32_bf16 v[40:43], v[176:179], v[184:187], v[40:43]
	v_mfma_f32_16x16x32_bf16 v[32:35], v[168:171], v[192:195], v[32:35]
	v_mfma_f32_16x16x32_bf16 v[24:27], v[176:179], v[192:195], v[24:27]
	v_mfma_f32_16x16x32_bf16 v[16:19], v[168:171], v[200:203], v[16:19]
	v_mfma_f32_16x16x32_bf16 v[8:11], v[176:179], v[200:203], v[8:11]
	v_mfma_f32_16x16x32_bf16 v[4:7], v[168:171], v[208:211], v[4:7]
	v_mfma_f32_16x16x32_bf16 v[0:3], v[176:179], v[208:211], v[0:3]
	v_mfma_f32_16x16x32_bf16 v[48:51], v[172:175], v[188:191], v[48:51]
	v_mfma_f32_16x16x32_bf16 v[40:43], v[180:183], v[188:191], v[40:43]
	v_mfma_f32_16x16x32_bf16 v[32:35], v[172:175], v[196:199], v[32:35]
	v_mfma_f32_16x16x32_bf16 v[24:27], v[180:183], v[196:199], v[24:27]
	v_mfma_f32_16x16x32_bf16 v[16:19], v[172:175], v[204:207], v[16:19]
	v_mfma_f32_16x16x32_bf16 v[8:11], v[180:183], v[204:207], v[8:11]
	v_mfma_f32_16x16x32_bf16 v[4:7], v[172:175], v[212:215], v[4:7]
	v_mfma_f32_16x16x32_bf16 v[0:3], v[180:183], v[212:215], v[0:3]
	s_setprio 0
	s_barrier
	s_add_i32 s62, s62, 2
	s_add_u32 s30, s30, 0x100
	s_addc_u32 s31, s31, 0
	s_add_u32 s60, s60, 0x100
	s_addc_u32 s61, s61, 0
	s_cmp_gt_u32 s62, 13
	s_cbranch_scc0 .LBB0_416
	s_and_b64 vcc, exec, s[12:13]
	s_cbranch_vccz .LBB0_419
	s_barrier

.LBB0_440:
	ds_read_b128 v[152:155], v149
	ds_read_b128 v[156:159], v149 offset:1024
	ds_read_b128 v[160:163], v149 offset:2048
	ds_read_b128 v[164:167], v149 offset:3072
	ds_read_b128 v[168:171], v150
	ds_read_b128 v[172:175], v150 offset:1024
	ds_read_b128 v[176:179], v150 offset:2048
	ds_read_b128 v[180:183], v150 offset:3072
	s_add_u32 s30, s28, 0xfffc0080
	s_addc_u32 s31, s29, -1
	s_cmp_eq_u32 s60, 12
	s_cselect_b32 s35, s21, s31
	s_cselect_b32 s34, s56, s30
	s_cselect_b32 s31, s19, s59
	s_cselect_b32 s30, s57, s58
	s_add_i32 m0, s27, 0xc000
	ds_read_b128 v[184:187], v151
	ds_read_b128 v[188:191], v151 offset:1024
	ds_read_b128 v[192:195], v151 offset:2048
	ds_read_b128 v[196:199], v151 offset:3072
	ds_read_b128 v[200:203], v151 offset:4096
	ds_read_b128 v[204:207], v151 offset:5120
	ds_read_b128 v[208:211], v151 offset:6144
	ds_read_b128 v[212:215], v151 offset:7168
	global_load_lds_dwordx4 v136, s[28:29]
	s_add_i32 m0, s27, 0xe000
	s_nop 0
	global_load_lds_dwordx4 v138, s[28:29]
	s_waitcnt vmcnt(8)
	s_waitcnt lgkmcnt(0)
	s_barrier
	s_setprio 1
	s_waitcnt lgkmcnt(0)
	v_mfma_f32_16x16x32_bf16 v[124:127], v[152:155], v[184:187], v[124:127]
	v_mfma_f32_16x16x32_bf16 v[120:123], v[160:163], v[184:187], v[120:123]
	v_mfma_f32_16x16x32_bf16 v[116:119], v[152:155], v[192:195], v[116:119]
	v_mfma_f32_16x16x32_bf16 v[108:111], v[160:163], v[192:195], v[108:111]
	v_mfma_f32_16x16x32_bf16 v[100:103], v[152:155], v[200:203], v[100:103]
	v_mfma_f32_16x16x32_bf16 v[92:95], v[160:163], v[200:203], v[92:95]
	v_mfma_f32_16x16x32_bf16 v[84:87], v[152:155], v[208:211], v[84:87]
	v_mfma_f32_16x16x32_bf16 v[76:79], v[160:163], v[208:211], v[76:79]
	v_mfma_f32_16x16x32_bf16 v[124:127], v[156:159], v[188:191], v[124:127]
	v_mfma_f32_16x16x32_bf16 v[120:123], v[164:167], v[188:191], v[120:123]
	v_mfma_f32_16x16x32_bf16 v[116:119], v[156:159], v[196:199], v[116:119]
	v_mfma_f32_16x16x32_bf16 v[108:111], v[164:167], v[196:199], v[108:111]
	v_mfma_f32_16x16x32_bf16 v[100:103], v[156:159], v[204:207], v[100:103]
	v_mfma_f32_16x16x32_bf16 v[92:95], v[164:167], v[204:207], v[92:95]
	v_mfma_f32_16x16x32_bf16 v[84:87], v[156:159], v[212:215], v[84:87]
	v_mfma_f32_16x16x32_bf16 v[76:79], v[164:167], v[212:215], v[76:79]
	s_setprio 0
	s_setprio 1
	v_mfma_f32_16x16x32_bf16 v[112:115], v[168:171], v[184:187], v[112:115]
	v_mfma_f32_16x16x32_bf16 v[104:107], v[176:179], v[184:187], v[104:107]
	v_mfma_f32_16x16x32_bf16 v[96:99], v[168:171], v[192:195], v[96:99]
	v_mfma_f32_16x16x32_bf16 v[88:91], v[176:179], v[192:195], v[88:91]
	v_mfma_f32_16x16x32_bf16 v[80:83], v[168:171], v[200:203], v[80:83]
	v_mfma_f32_16x16x32_bf16 v[72:75], v[176:179], v[200:203], v[72:75]
	v_mfma_f32_16x16x32_bf16 v[68:71], v[168:171], v[208:211], v[68:71]
	v_mfma_f32_16x16x32_bf16 v[64:67], v[176:179], v[208:211], v[64:67]
	v_mfma_f32_16x16x32_bf16 v[112:115], v[172:175], v[188:191], v[112:115]
	v_mfma_f32_16x16x32_bf16 v[104:107], v[180:183], v[188:191], v[104:107]
	v_mfma_f32_16x16x32_bf16 v[96:99], v[172:175], v[196:199], v[96:99]
	v_mfma_f32_16x16x32_bf16 v[88:91], v[180:183], v[196:199], v[88:91]
	v_mfma_f32_16x16x32_bf16 v[80:83], v[172:175], v[204:207], v[80:83]
	v_mfma_f32_16x16x32_bf16 v[72:75], v[180:183], v[204:207], v[72:75]
	v_mfma_f32_16x16x32_bf16 v[68:71], v[172:175], v[212:215], v[68:71]
	v_mfma_f32_16x16x32_bf16 v[64:67], v[180:183], v[212:215], v[64:67]
	s_setprio 0
	s_barrier
	s_add_i32 s61, s49, s41
	v_lshl_add_u64 v[144:145], s[30:31], 0, v[130:131]
	s_mov_b32 m0, s61
	ds_read_b128 v[184:187], v151 offset:16384
	ds_read_b128 v[188:191], v151 offset:17408
	ds_read_b128 v[192:195], v151 offset:18432
	ds_read_b128 v[196:199], v151 offset:19456
	ds_read_b128 v[200:203], v151 offset:20480
	ds_read_b128 v[204:207], v151 offset:21504
	ds_read_b128 v[208:211], v151 offset:22528
	ds_read_b128 v[212:215], v151 offset:23552
	global_load_lds_dwordx4 v[144:145], off
	s_add_i32 m0, s61, 0x2000
	s_add_u32 s62, s30, 0x40000
	v_lshl_add_u64 v[216:217], s[30:31], 0, v[134:135]
	s_addc_u32 s63, s31, 0
	s_add_i32 s61, s50, s41
	global_load_lds_dwordx4 v[216:217], off
	v_lshl_add_u64 v[218:219], s[62:63], 0, v[130:131]
	s_mov_b32 m0, s61
	v_lshl_add_u64 v[220:221], s[34:35], 0, v[132:133]
	global_load_lds_dwordx4 v[218:219], off
	s_add_i32 m0, s61, 0x2000
	s_nop 0
	global_load_lds_dwordx4 v134, s[62:63]
	v_lshl_add_u64 v[218:219], s[34:35], 0, v[128:129]
	s_mov_b32 m0, s27
	s_nop 0
	global_load_lds_dwordx4 v[218:219], off
	s_mov_b32 m0, s42
	s_nop 0
	global_load_lds_dwordx4 v[220:221], off
	s_waitcnt vmcnt(8)
	s_waitcnt lgkmcnt(0)
	s_barrier
	s_setprio 1
	s_waitcnt lgkmcnt(0)
	v_mfma_f32_16x16x32_bf16 v[60:63], v[152:155], v[184:187], v[60:63]
	v_mfma_f32_16x16x32_bf16 v[56:59], v[160:163], v[184:187], v[56:59]
	v_mfma_f32_16x16x32_bf16 v[52:55], v[152:155], v[192:195], v[52:55]
	v_mfma_f32_16x16x32_bf16 v[44:47], v[160:163], v[192:195], v[44:47]
	v_mfma_f32_16x16x32_bf16 v[36:39], v[152:155], v[200:203], v[36:39]
	v_mfma_f32_16x16x32_bf16 v[28:31], v[160:163], v[200:203], v[28:31]
	v_mfma_f32_16x16x32_bf16 v[20:23], v[152:155], v[208:211], v[20:23]
	v_mfma_f32_16x16x32_bf16 v[12:15], v[160:163], v[208:211], v[12:15]
	v_mfma_f32_16x16x32_bf16 v[60:63], v[156:159], v[188:191], v[60:63]
	v_mfma_f32_16x16x32_bf16 v[56:59], v[164:167], v[188:191], v[56:59]
	v_mfma_f32_16x16x32_bf16 v[52:55], v[156:159], v[196:199], v[52:55]
	v_mfma_f32_16x16x32_bf16 v[44:47], v[164:167], v[196:199], v[44:47]
	v_mfma_f32_16x16x32_bf16 v[36:39], v[156:159], v[204:207], v[36:39]
	v_mfma_f32_16x16x32_bf16 v[28:31], v[164:167], v[204:207], v[28:31]
	v_mfma_f32_16x16x32_bf16 v[20:23], v[156:159], v[212:215], v[20:23]
	v_mfma_f32_16x16x32_bf16 v[12:15], v[164:167], v[212:215], v[12:15]
	s_setprio 0
	s_setprio 1
	v_mfma_f32_16x16x32_bf16 v[48:51], v[168:171], v[184:187], v[48:51]
	v_mfma_f32_16x16x32_bf16 v[40:43], v[176:179], v[184:187], v[40:43]
	v_mfma_f32_16x16x32_bf16 v[32:35], v[168:171], v[192:195], v[32:35]
	v_mfma_f32_16x16x32_bf16 v[24:27], v[176:179], v[192:195], v[24:27]
	v_mfma_f32_16x16x32_bf16 v[16:19], v[168:171], v[200:203], v[16:19]
	v_mfma_f32_16x16x32_bf16 v[8:11], v[176:179], v[200:203], v[8:11]
	v_mfma_f32_16x16x32_bf16 v[4:7], v[168:171], v[208:211], v[4:7]
	v_mfma_f32_16x16x32_bf16 v[0:3], v[176:179], v[208:211], v[0:3]
	v_mfma_f32_16x16x32_bf16 v[48:51], v[172:175], v[188:191], v[48:51]
	v_mfma_f32_16x16x32_bf16 v[40:43], v[180:183], v[188:191], v[40:43]
	v_mfma_f32_16x16x32_bf16 v[32:35], v[172:175], v[196:199], v[32:35]
	v_mfma_f32_16x16x32_bf16 v[24:27], v[180:183], v[196:199], v[24:27]
	v_mfma_f32_16x16x32_bf16 v[16:19], v[172:175], v[204:207], v[16:19]
	v_mfma_f32_16x16x32_bf16 v[8:11], v[180:183], v[204:207], v[8:11]
	v_mfma_f32_16x16x32_bf16 v[4:7], v[172:175], v[212:215], v[4:7]
	v_mfma_f32_16x16x32_bf16 v[0:3], v[180:183], v[212:215], v[0:3]
	s_setprio 0
	s_barrier
	s_add_i32 s61, 0, 0x18000
	s_add_i32 s62, 0, 0x1c000
	v_add_u32_e32 v164, s61, v147
	v_add_u32_e32 v180, s62, v147
	ds_read_b128 v[152:155], v164
	ds_read_b128 v[156:159], v164 offset:1024
	ds_read_b128 v[160:163], v164 offset:2048
	ds_read_b128 v[164:167], v164 offset:3072
	ds_read_b128 v[168:171], v180
	ds_read_b128 v[172:175], v180 offset:1024
	ds_read_b128 v[176:179], v180 offset:2048
	ds_read_b128 v[180:183], v180 offset:3072
	s_add_u32 s34, s34, 0x40000
	s_addc_u32 s35, s35, 0
	s_mov_b32 m0, s43
	ds_read_b128 v[184:187], v151 offset:32768
	ds_read_b128 v[188:191], v151 offset:33792
	ds_read_b128 v[192:195], v151 offset:34816
	ds_read_b128 v[196:199], v151 offset:35840
	ds_read_b128 v[200:203], v151 offset:36864
	ds_read_b128 v[204:207], v151 offset:37888
	ds_read_b128 v[208:211], v151 offset:38912
	ds_read_b128 v[212:215], v151 offset:39936
	global_load_lds_dwordx4 v128, s[34:35]
	v_lshl_add_u64 v[222:223], s[34:35], 0, v[132:133]
	s_mov_b32 m0, s44
	s_nop 0
	global_load_lds_dwordx4 v[222:223], off
	s_waitcnt vmcnt(8)
	s_waitcnt lgkmcnt(0)
	s_barrier
	s_setprio 1
	s_waitcnt lgkmcnt(0)
	v_mfma_f32_16x16x32_bf16 v[124:127], v[152:155], v[184:187], v[124:127]
	v_mfma_f32_16x16x32_bf16 v[120:123], v[160:163], v[184:187], v[120:123]
	v_mfma_f32_16x16x32_bf16 v[116:119], v[152:155], v[192:195], v[116:119]
	v_mfma_f32_16x16x32_bf16 v[108:111], v[160:163], v[192:195], v[108:111]
	v_mfma_f32_16x16x32_bf16 v[100:103], v[152:155], v[200:203], v[100:103]
	v_mfma_f32_16x16x32_bf16 v[92:95], v[160:163], v[200:203], v[92:95]
	v_mfma_f32_16x16x32_bf16 v[84:87], v[152:155], v[208:211], v[84:87]
	v_mfma_f32_16x16x32_bf16 v[76:79], v[160:163], v[208:211], v[76:79]
	v_mfma_f32_16x16x32_bf16 v[124:127], v[156:159], v[188:191], v[124:127]
	v_mfma_f32_16x16x32_bf16 v[120:123], v[164:167], v[188:191], v[120:123]
	v_mfma_f32_16x16x32_bf16 v[116:119], v[156:159], v[196:199], v[116:119]
	v_mfma_f32_16x16x32_bf16 v[108:111], v[164:167], v[196:199], v[108:111]
	v_mfma_f32_16x16x32_bf16 v[100:103], v[156:159], v[204:207], v[100:103]
	v_mfma_f32_16x16x32_bf16 v[92:95], v[164:167], v[204:207], v[92:95]
	v_mfma_f32_16x16x32_bf16 v[84:87], v[156:159], v[212:215], v[84:87]
	v_mfma_f32_16x16x32_bf16 v[76:79], v[164:167], v[212:215], v[76:79]
	s_setprio 0
	s_setprio 1
	v_mfma_f32_16x16x32_bf16 v[112:115], v[168:171], v[184:187], v[112:115]
	v_mfma_f32_16x16x32_bf16 v[104:107], v[176:179], v[184:187], v[104:107]
	v_mfma_f32_16x16x32_bf16 v[96:99], v[168:171], v[192:195], v[96:99]
	v_mfma_f32_16x16x32_bf16 v[88:91], v[176:179], v[192:195], v[88:91]
	v_mfma_f32_16x16x32_bf16 v[80:83], v[168:171], v[200:203], v[80:83]
	v_mfma_f32_16x16x32_bf16 v[72:75], v[176:179], v[200:203], v[72:75]
	v_mfma_f32_16x16x32_bf16 v[68:71], v[168:171], v[208:211], v[68:71]
	v_mfma_f32_16x16x32_bf16 v[64:67], v[176:179], v[208:211], v[64:67]
	v_mfma_f32_16x16x32_bf16 v[112:115], v[172:175], v[188:191], v[112:115]
	v_mfma_f32_16x16x32_bf16 v[104:107], v[180:183], v[188:191], v[104:107]
	v_mfma_f32_16x16x32_bf16 v[96:99], v[172:175], v[196:199], v[96:99]
	v_mfma_f32_16x16x32_bf16 v[88:91], v[180:183], v[196:199], v[88:91]
	v_mfma_f32_16x16x32_bf16 v[80:83], v[172:175], v[204:207], v[80:83]
	v_mfma_f32_16x16x32_bf16 v[72:75], v[180:183], v[204:207], v[72:75]
	v_mfma_f32_16x16x32_bf16 v[68:71], v[172:175], v[212:215], v[68:71]
	v_mfma_f32_16x16x32_bf16 v[64:67], v[180:183], v[212:215], v[64:67]
	s_setprio 0
	s_barrier
	s_add_i32 s34, s61, s41
	v_lshl_add_u64 v[144:145], v[144:145], 0, s[8:9]
	s_mov_b32 m0, s34
	ds_read_b128 v[184:187], v151 offset:49152
	ds_read_b128 v[188:191], v151 offset:50176
	ds_read_b128 v[192:195], v151 offset:51200
	ds_read_b128 v[196:199], v151 offset:52224
	ds_read_b128 v[200:203], v151 offset:53248
	ds_read_b128 v[204:207], v151 offset:54272
	ds_read_b128 v[208:211], v151 offset:55296
	ds_read_b128 v[212:215], v151 offset:56320
	global_load_lds_dwordx4 v[144:145], off
	s_add_i32 m0, s34, 0x2000
	s_add_u32 s30, s30, 0x40080
	v_lshl_add_u64 v[144:145], v[216:217], 0, s[8:9]
	s_addc_u32 s31, s31, 0
	s_add_i32 s34, s62, s41
	global_load_lds_dwordx4 v[144:145], off
	v_lshl_add_u64 v[144:145], s[30:31], 0, v[130:131]
	s_mov_b32 m0, s34
	s_nop 0
	global_load_lds_dwordx4 v[144:145], off
	s_add_i32 m0, s34, 0x2000
	s_nop 0
	global_load_lds_dwordx4 v134, s[30:31]
	v_lshl_add_u64 v[144:145], v[218:219], 0, s[8:9]
	s_mov_b32 m0, s46
	s_nop 0
	global_load_lds_dwordx4 v[144:145], off
	v_lshl_add_u64 v[144:145], v[220:221], 0, s[8:9]
	s_mov_b32 m0, s47
	s_nop 0
	global_load_lds_dwordx4 v[144:145], off
	s_waitcnt vmcnt(8)
	s_waitcnt lgkmcnt(0)
	s_barrier
	s_setprio 1
	s_waitcnt lgkmcnt(0)
	v_mfma_f32_16x16x32_bf16 v[60:63], v[152:155], v[184:187], v[60:63]
	v_mfma_f32_16x16x32_bf16 v[56:59], v[160:163], v[184:187], v[56:59]
	v_mfma_f32_16x16x32_bf16 v[52:55], v[152:155], v[192:195], v[52:55]
	v_mfma_f32_16x16x32_bf16 v[44:47], v[160:163], v[192:195], v[44:47]
	v_mfma_f32_16x16x32_bf16 v[36:39], v[152:155], v[200:203], v[36:39]
	v_mfma_f32_16x16x32_bf16 v[28:31], v[160:163], v[200:203], v[28:31]
	v_mfma_f32_16x16x32_bf16 v[20:23], v[152:155], v[208:211], v[20:23]
	v_mfma_f32_16x16x32_bf16 v[12:15], v[160:163], v[208:211], v[12:15]
	v_mfma_f32_16x16x32_bf16 v[60:63], v[156:159], v[188:191], v[60:63]
	v_mfma_f32_16x16x32_bf16 v[56:59], v[164:167], v[188:191], v[56:59]
	v_mfma_f32_16x16x32_bf16 v[52:55], v[156:159], v[196:199], v[52:55]
	v_mfma_f32_16x16x32_bf16 v[44:47], v[164:167], v[196:199], v[44:47]
	v_mfma_f32_16x16x32_bf16 v[36:39], v[156:159], v[204:207], v[36:39]
	v_mfma_f32_16x16x32_bf16 v[28:31], v[164:167], v[204:207], v[28:31]
	v_mfma_f32_16x16x32_bf16 v[20:23], v[156:159], v[212:215], v[20:23]
	v_mfma_f32_16x16x32_bf16 v[12:15], v[164:167], v[212:215], v[12:15]
	s_setprio 0
	s_setprio 1
	v_mfma_f32_16x16x32_bf16 v[48:51], v[168:171], v[184:187], v[48:51]
	v_mfma_f32_16x16x32_bf16 v[40:43], v[176:179], v[184:187], v[40:43]
	v_mfma_f32_16x16x32_bf16 v[32:35], v[168:171], v[192:195], v[32:35]
	v_mfma_f32_16x16x32_bf16 v[24:27], v[176:179], v[192:195], v[24:27]
	v_mfma_f32_16x16x32_bf16 v[16:19], v[168:171], v[200:203], v[16:19]
	v_mfma_f32_16x16x32_bf16 v[8:11], v[176:179], v[200:203], v[8:11]
	v_mfma_f32_16x16x32_bf16 v[4:7], v[168:171], v[208:211], v[4:7]
	v_mfma_f32_16x16x32_bf16 v[0:3], v[176:179], v[208:211], v[0:3]
	v_mfma_f32_16x16x32_bf16 v[48:51], v[172:175], v[188:191], v[48:51]
	v_mfma_f32_16x16x32_bf16 v[40:43], v[180:183], v[188:191], v[40:43]
	v_mfma_f32_16x16x32_bf16 v[32:35], v[172:175], v[196:199], v[32:35]
	v_mfma_f32_16x16x32_bf16 v[24:27], v[180:183], v[196:199], v[24:27]
	v_mfma_f32_16x16x32_bf16 v[16:19], v[172:175], v[204:207], v[16:19]
	v_mfma_f32_16x16x32_bf16 v[8:11], v[180:183], v[204:207], v[8:11]
	v_mfma_f32_16x16x32_bf16 v[4:7], v[172:175], v[212:215], v[4:7]
	v_mfma_f32_16x16x32_bf16 v[0:3], v[180:183], v[212:215], v[0:3]
	s_setprio 0
	s_barrier
	s_add_i32 s60, s60, 2
	s_add_u32 s28, s28, 0x100
	s_addc_u32 s29, s29, 0
	s_add_u32 s58, s58, 0x100
	s_addc_u32 s59, s59, 0
	s_cmp_gt_u32 s60, 13
	s_cbranch_scc0 .LBB0_440
	s_and_b64 vcc, exec, s[10:11]
	s_cbranch_vccz .LBB0_443
	s_barrier

.LBB0_456:
	s_lshl_b32 s3, s3, 5
	s_mov_b64 s[12:13], 0x80
	s_and_b32 s3, s3, 0x60
	s_add_i32 m0, s55, 0x18000
	v_lshl_add_u64 v[6:7], v[6:7], 0, s[12:13]
	s_lshl_b32 s5, s2, 13
	s_lshl_b32 s15, s3, 7
	s_waitcnt vmcnt(2)
	s_barrier
	global_load_lds_dwordx4 v[6:7], off
	v_lshl_add_u64 v[4:5], v[4:5], 0, s[12:13]
	s_add_i32 m0, s55, 0x1a000
	s_add_i32 s59, s55, 0x8000
	s_add_i32 s60, s55, 0xa000
	global_load_lds_dwordx4 v[4:5], off
	v_lshl_add_u64 v[0:1], v[0:1], 0, s[12:13]
	s_mov_b32 m0, s59
	s_add_u32 s16, s44, 0x10080
	global_load_lds_dwordx4 v[0:1], off
	v_lshl_add_u64 v[0:1], v[2:3], 0, s[12:13]
	s_mov_b32 m0, s60
	s_addc_u32 s17, s45, 0
	global_load_lds_dwordx4 v[0:1], off
	s_add_i32 m0, s55, 0x1c000
	s_nop 0
	global_load_lds_dwordx4 v130, s[16:17]
	v_lshl_add_u64 v[0:1], s[16:17], 0, v[134:135]
	s_add_i32 m0, s55, 0x1e000
	s_cmpk_lt_u32 s14, 0x100
	global_load_lds_dwordx4 v[0:1], off
	v_lshrrev_b32_e32 v1, 1, v8
	v_and_b32_e32 v1, 24, v1
	v_and_b32_e32 v0, 15, v8
	v_lshlrev_b32_e32 v2, 1, v1
	v_lshl_or_b32 v143, s2, 6, v0
	v_lshl_or_b32 v0, v0, 6, v2
	v_lshlrev_b32_e32 v2, 2, v8
	v_and_b32_e32 v2, 32, v2
	v_bitop3_b32 v152, v0, s15, v2 bitop3:0xde
	s_cselect_b64 s[14:15], -1, 0
	s_ashr_i32 s61, s96, 31
	s_ashr_i32 s2, s33, 31
	s_waitcnt vmcnt(6)
	s_add_u32 s16, s33, s96
	v_bitop3_b32 v3, v0, s5, v2 bitop3:0xde
	s_addc_u32 s17, s2, s61
	s_add_i32 s62, 0, 0x10000
	s_add_i32 s63, 0, 0x14000
	v_or_b32_e32 v153, s3, v1
	v_add_u32_e32 v154, s62, v152
	v_add_u32_e32 v155, s63, v152
	v_add_u32_e32 v156, 0, v3
	s_add_i32 s64, s55, 0xc000
	s_add_i32 s65, s55, 0xe000
	s_mov_b64 s[18:19], 0x100
	s_mov_b64 s[20:21], 0x180
	s_mov_b32 s66, 0xdc00000
	s_mov_b64 s[22:23], 0x40000
	s_mov_b64 s[24:25], 0x48000
	s_mov_b64 s[26:27], 0x50000
	s_mov_b64 s[28:29], 0x58000
	v_mov_b32_e32 v157, 0x3f1b4598
	s_barrier
	s_branch .LBB0_459

.LBB0_465:
	s_ashr_i32 s35, s34, 31
	s_lshl_b64 s[36:37], s[34:35], 17
	s_add_u32 s36, s50, s36
	s_addc_u32 s37, s51, s37
	s_and_b64 s[38:39], s[2:3], exec
	s_cselect_b32 s49, s37, s43
	s_cselect_b32 s48, s36, s42
	s_ashr_i32 s31, s30, 31
	s_lshl_b64 s[38:39], s[30:31], 17
	s_add_u32 s38, s52, s38
	s_addc_u32 s39, s53, s39
	s_and_b64 s[46:47], s[2:3], exec
	s_cselect_b32 s47, s39, s45
	s_cselect_b32 s46, s38, s44
	s_add_u32 s68, s42, 0x10080
	s_addc_u32 s69, s43, 0
	v_lshl_add_u64 v[64:65], s[68:69], 0, v[128:129]
	v_lshl_add_u64 v[64:65], s[68:69], 0, v[132:133]
	s_add_i32 s41, s62, s54
	v_lshl_add_u64 v[214:215], s[44:45], 0, v[130:131]
	s_add_i32 s5, s41, 0x2000
	v_lshl_add_u64 v[144:145], v[214:215], 0, s[18:19]
	v_lshl_add_u64 v[216:217], s[44:45], 0, v[134:135]
	s_add_u32 s68, s44, 0x10100
	v_lshl_add_u64 v[144:145], v[216:217], 0, s[18:19]
	s_addc_u32 s69, s45, 0
	s_add_i32 s31, s63, s54
	v_lshl_add_u64 v[144:145], s[68:69], 0, v[130:131]
	s_add_i32 s35, s31, 0x2000
	v_lshl_add_u64 v[144:145], s[68:69], 0, v[134:135]
	v_lshl_add_u64 v[218:219], s[42:43], 0, v[128:129]
	v_lshl_add_u64 v[144:145], v[218:219], 0, s[18:19]
	v_lshl_add_u64 v[220:221], s[42:43], 0, v[132:133]
	v_lshl_add_u64 v[144:145], v[220:221], 0, s[18:19]
	s_add_i32 s67, 0, 0x18000
	s_add_i32 s80, 0, 0x1c000
	v_add_u32_e32 v136, s67, v152
	v_add_u32_e32 v142, s80, v152
	s_add_u32 s68, s42, 0x10100
	s_addc_u32 s69, s43, 0
	v_lshl_add_u64 v[222:223], s[68:69], 0, v[128:129]
	v_lshl_add_u64 v[222:223], s[68:69], 0, v[132:133]
	s_add_i32 s68, s67, s54
	s_add_i32 s67, s68, 0x2000
	v_lshl_add_u64 v[214:215], v[214:215], 0, s[20:21]
	s_add_u32 s78, s44, 0x10180
	v_lshl_add_u64 v[214:215], v[216:217], 0, s[20:21]
	s_addc_u32 s79, s45, 0
	s_add_i32 s44, s80, s54
	v_lshl_add_u64 v[214:215], s[78:79], 0, v[130:131]
	s_add_i32 s45, s44, 0x2000
	v_lshl_add_u64 v[214:215], s[78:79], 0, v[134:135]
	v_lshl_add_u64 v[214:215], v[218:219], 0, s[20:21]
	v_lshl_add_u64 v[214:215], v[220:221], 0, s[20:21]
	ds_read_b128 v[104:107], v154
	ds_read_b128 v[108:111], v154 offset:1024
	ds_read_b128 v[112:115], v154 offset:2048
	ds_read_b128 v[116:119], v154 offset:3072
	ds_read_b128 v[120:123], v155
	ds_read_b128 v[124:127], v155 offset:1024
	ds_read_b128 v[174:177], v155 offset:2048
	ds_read_b128 v[178:181], v155 offset:3072
	s_add_u32 s42, s42, 0x10080
	s_addc_u32 s43, s43, 0
	s_mov_b32 m0, s64
	ds_read_b128 v[182:185], v156
	ds_read_b128 v[186:189], v156 offset:1024
	ds_read_b128 v[190:193], v156 offset:2048
	ds_read_b128 v[194:197], v156 offset:3072
	ds_read_b128 v[198:201], v156 offset:4096
	ds_read_b128 v[202:205], v156 offset:5120
	ds_read_b128 v[206:209], v156 offset:6144
	ds_read_b128 v[210:213], v156 offset:7168
	global_load_lds_dwordx4 v128, s[42:43]
	s_mov_b32 m0, s65
	s_nop 0
	global_load_lds_dwordx4 v132, s[42:43]
	s_waitcnt vmcnt(8)
	s_waitcnt lgkmcnt(0)
	s_barrier
	s_setprio 1
	s_waitcnt lgkmcnt(0)
	v_mfma_f32_16x16x32_bf16 v[64:67], v[104:107], v[182:185], 0
	v_mfma_f32_16x16x32_bf16 v[68:71], v[112:115], v[182:185], 0
	v_mfma_f32_16x16x32_bf16 v[72:75], v[104:107], v[190:193], 0
	v_mfma_f32_16x16x32_bf16 v[76:79], v[112:115], v[190:193], 0
	v_mfma_f32_16x16x32_bf16 v[80:83], v[104:107], v[198:201], 0
	v_mfma_f32_16x16x32_bf16 v[84:87], v[112:115], v[198:201], 0
	v_mfma_f32_16x16x32_bf16 v[88:91], v[104:107], v[206:209], 0
	v_mfma_f32_16x16x32_bf16 v[64:67], v[108:111], v[186:189], v[64:67]
	v_mfma_f32_16x16x32_bf16 v[68:71], v[116:119], v[186:189], v[68:71]
	v_mfma_f32_16x16x32_bf16 v[72:75], v[108:111], v[194:197], v[72:75]
	v_mfma_f32_16x16x32_bf16 v[76:79], v[116:119], v[194:197], v[76:79]
	v_mfma_f32_16x16x32_bf16 v[80:83], v[108:111], v[202:205], v[80:83]
	v_mfma_f32_16x16x32_bf16 v[84:87], v[116:119], v[202:205], v[84:87]
	v_mfma_f32_16x16x32_bf16 v[214:217], v[108:111], v[210:213], v[88:91]
	v_mfma_f32_16x16x32_bf16 v[88:91], v[112:115], v[206:209], 0
	v_mfma_f32_16x16x32_bf16 v[218:221], v[116:119], v[210:213], v[88:91]
	s_setprio 0
	s_setprio 1
	v_mfma_f32_16x16x32_bf16 v[88:91], v[120:123], v[182:185], 0
	v_mfma_f32_16x16x32_bf16 v[32:35], v[174:177], v[182:185], 0
	v_mfma_f32_16x16x32_bf16 v[36:39], v[120:123], v[190:193], 0
	v_mfma_f32_16x16x32_bf16 v[40:43], v[174:177], v[190:193], 0
	v_mfma_f32_16x16x32_bf16 v[44:47], v[120:123], v[198:201], 0
	v_mfma_f32_16x16x32_bf16 v[48:51], v[174:177], v[198:201], 0
	v_mfma_f32_16x16x32_bf16 v[52:55], v[120:123], v[206:209], 0
	v_mfma_f32_16x16x32_bf16 v[56:59], v[174:177], v[206:209], 0
	v_mfma_f32_16x16x32_bf16 v[96:99], v[124:127], v[186:189], v[88:91]
	v_mfma_f32_16x16x32_bf16 v[32:35], v[178:181], v[186:189], v[32:35]
	v_mfma_f32_16x16x32_bf16 v[36:39], v[124:127], v[194:197], v[36:39]
	v_mfma_f32_16x16x32_bf16 v[40:43], v[178:181], v[194:197], v[40:43]
	v_mfma_f32_16x16x32_bf16 v[44:47], v[124:127], v[202:205], v[44:47]
	v_mfma_f32_16x16x32_bf16 v[48:51], v[178:181], v[202:205], v[48:51]
	v_mfma_f32_16x16x32_bf16 v[52:55], v[124:127], v[210:213], v[52:55]
	v_mfma_f32_16x16x32_bf16 v[56:59], v[178:181], v[210:213], v[56:59]
	s_setprio 0
	s_barrier
	s_mov_b32 m0, s41
	v_lshl_add_u64 v[250:251], s[46:47], 0, v[130:131]
	s_add_u32 s42, s46, 0x10000
	ds_read_b128 v[88:91], v156 offset:16384
	ds_read_b128 v[92:95], v156 offset:17408
	ds_read_b128 v[182:185], v156 offset:18432
	ds_read_b128 v[186:189], v156 offset:19456
	ds_read_b128 v[190:193], v156 offset:20480
	ds_read_b128 v[194:197], v156 offset:21504
	ds_read_b128 v[198:201], v156 offset:22528
	ds_read_b128 v[202:205], v156 offset:23552
	global_load_lds_dwordx4 v[250:251], off
	v_lshl_add_u64 v[252:253], s[46:47], 0, v[134:135]
	s_mov_b32 m0, s5
	s_addc_u32 s43, s47, 0
	global_load_lds_dwordx4 v[252:253], off
	s_mov_b32 m0, s31
	v_lshl_add_u64 v[138:139], s[48:49], 0, v[128:129]
	global_load_lds_dwordx4 v130, s[42:43]
	s_mov_b32 m0, s35
	v_lshl_add_u64 v[140:141], s[48:49], 0, v[132:133]
	global_load_lds_dwordx4 v134, s[42:43]
	s_mov_b32 m0, s55
	s_nop 0
	global_load_lds_dwordx4 v[138:139], off
	s_mov_b32 m0, s56
	s_nop 0
	global_load_lds_dwordx4 v[140:141], off
	s_waitcnt vmcnt(8)
	s_waitcnt lgkmcnt(0)
	s_barrier
	s_setprio 1
	s_waitcnt lgkmcnt(0)
	v_mfma_f32_16x16x32_bf16 v[0:3], v[104:107], v[198:201], 0
	v_mfma_f32_16x16x32_bf16 v[4:7], v[112:115], v[198:201], 0
	v_mfma_f32_16x16x32_bf16 v[144:147], v[104:107], v[88:91], 0
	v_mfma_f32_16x16x32_bf16 v[148:151], v[112:115], v[88:91], 0
	v_mfma_f32_16x16x32_bf16 v[158:161], v[104:107], v[182:185], 0
	v_mfma_f32_16x16x32_bf16 v[162:165], v[112:115], v[182:185], 0
	v_mfma_f32_16x16x32_bf16 v[166:169], v[104:107], v[190:193], 0
	v_mfma_f32_16x16x32_bf16 v[170:173], v[112:115], v[190:193], 0
	v_mfma_f32_16x16x32_bf16 v[0:3], v[108:111], v[202:205], v[0:3]
	v_mfma_f32_16x16x32_bf16 v[4:7], v[116:119], v[202:205], v[4:7]
	v_mfma_f32_16x16x32_bf16 v[144:147], v[108:111], v[92:95], v[144:147]
	v_mfma_f32_16x16x32_bf16 v[148:151], v[116:119], v[92:95], v[148:151]
	v_mfma_f32_16x16x32_bf16 v[158:161], v[108:111], v[186:189], v[158:161]
	v_mfma_f32_16x16x32_bf16 v[162:165], v[116:119], v[186:189], v[162:165]
	v_mfma_f32_16x16x32_bf16 v[166:169], v[108:111], v[194:197], v[166:169]
	v_mfma_f32_16x16x32_bf16 v[170:173], v[116:119], v[194:197], v[170:173]
	s_setprio 0
	s_setprio 1
	v_mfma_f32_16x16x32_bf16 v[8:11], v[120:123], v[88:91], 0
	v_mfma_f32_16x16x32_bf16 v[206:209], v[124:127], v[92:95], v[8:11]
	v_mfma_f32_16x16x32_bf16 v[8:11], v[174:177], v[88:91], 0
	v_mfma_f32_16x16x32_bf16 v[210:213], v[178:181], v[92:95], v[8:11]
	v_mfma_f32_16x16x32_bf16 v[8:11], v[120:123], v[182:185], 0
	v_mfma_f32_16x16x32_bf16 v[222:225], v[124:127], v[186:189], v[8:11]
	v_mfma_f32_16x16x32_bf16 v[8:11], v[174:177], v[182:185], 0
	v_mfma_f32_16x16x32_bf16 v[182:185], v[178:181], v[186:189], v[8:11]
	v_mfma_f32_16x16x32_bf16 v[8:11], v[120:123], v[190:193], 0
	v_mfma_f32_16x16x32_bf16 v[186:189], v[124:127], v[194:197], v[8:11]
	v_mfma_f32_16x16x32_bf16 v[8:11], v[174:177], v[190:193], 0
	v_mfma_f32_16x16x32_bf16 v[190:193], v[178:181], v[194:197], v[8:11]
	v_mfma_f32_16x16x32_bf16 v[8:11], v[120:123], v[198:201], 0
	v_mfma_f32_16x16x32_bf16 v[194:197], v[124:127], v[202:205], v[8:11]
	v_mfma_f32_16x16x32_bf16 v[8:11], v[174:177], v[198:201], 0
	v_mfma_f32_16x16x32_bf16 v[174:177], v[178:181], v[202:205], v[8:11]
	s_setprio 0
	s_barrier
	s_nop 4
	ds_read_b128 v[8:11], v136
	ds_read_b128 v[12:15], v136 offset:1024
	ds_read_b128 v[16:19], v136 offset:2048
	ds_read_b128 v[20:23], v136 offset:3072
	ds_read_b128 v[178:181], v142
	ds_read_b128 v[198:201], v142 offset:1024
	ds_read_b128 v[202:205], v142 offset:2048
	ds_read_b128 v[226:229], v142 offset:3072
	s_add_u32 s42, s48, 0x10000
	s_addc_u32 s43, s49, 0
	s_mov_b32 m0, s57
	ds_read_b128 v[24:27], v156 offset:32768
	ds_read_b128 v[28:31], v156 offset:33792
	ds_read_b128 v[60:63], v156 offset:34816
	ds_read_b128 v[230:233], v156 offset:35840
	ds_read_b128 v[234:237], v156 offset:36864
	ds_read_b128 v[238:241], v156 offset:37888
	ds_read_b128 v[242:245], v156 offset:38912
	ds_read_b128 v[246:249], v156 offset:39936
	global_load_lds_dwordx4 v128, s[42:43]
	s_mov_b32 m0, s58
	s_nop 0
	global_load_lds_dwordx4 v132, s[42:43]
	s_waitcnt vmcnt(8)
	s_waitcnt lgkmcnt(0)
	s_barrier
	s_setprio 1
	s_waitcnt lgkmcnt(0)
	v_mfma_f32_16x16x32_bf16 v[64:67], v[8:11], v[24:27], v[64:67]
	v_mfma_f32_16x16x32_bf16 v[124:127], v[12:15], v[28:31], v[64:67]
	v_mfma_f32_16x16x32_bf16 v[64:67], v[16:19], v[24:27], v[68:71]
	v_mfma_f32_16x16x32_bf16 v[120:123], v[20:23], v[28:31], v[64:67]
	v_mfma_f32_16x16x32_bf16 v[64:67], v[8:11], v[60:63], v[72:75]
	v_mfma_f32_16x16x32_bf16 v[108:111], v[12:15], v[230:233], v[64:67]
	v_mfma_f32_16x16x32_bf16 v[64:67], v[16:19], v[60:63], v[76:79]
	v_mfma_f32_16x16x32_bf16 v[104:107], v[20:23], v[230:233], v[64:67]
	v_mfma_f32_16x16x32_bf16 v[64:67], v[8:11], v[234:237], v[80:83]
	v_mfma_f32_16x16x32_bf16 v[92:95], v[12:15], v[238:241], v[64:67]
	v_mfma_f32_16x16x32_bf16 v[64:67], v[16:19], v[234:237], v[84:87]
	v_mfma_f32_16x16x32_bf16 v[88:91], v[20:23], v[238:241], v[64:67]
	v_mfma_f32_16x16x32_bf16 v[64:67], v[8:11], v[242:245], v[214:217]
	v_mfma_f32_16x16x32_bf16 v[76:79], v[12:15], v[246:249], v[64:67]
	v_mfma_f32_16x16x32_bf16 v[64:67], v[16:19], v[242:245], v[218:221]
	v_mfma_f32_16x16x32_bf16 v[72:75], v[20:23], v[246:249], v[64:67]
	s_setprio 0
	s_setprio 1
	v_mfma_f32_16x16x32_bf16 v[64:67], v[178:181], v[24:27], v[96:99]
	v_mfma_f32_16x16x32_bf16 v[24:27], v[202:205], v[24:27], v[32:35]
	v_mfma_f32_16x16x32_bf16 v[112:115], v[226:229], v[28:31], v[24:27]
	v_mfma_f32_16x16x32_bf16 v[24:27], v[178:181], v[60:63], v[36:39]
	v_mfma_f32_16x16x32_bf16 v[100:103], v[198:201], v[230:233], v[24:27]
	v_mfma_f32_16x16x32_bf16 v[24:27], v[202:205], v[60:63], v[40:43]
	v_mfma_f32_16x16x32_bf16 v[96:99], v[226:229], v[230:233], v[24:27]
	v_mfma_f32_16x16x32_bf16 v[24:27], v[178:181], v[234:237], v[44:47]
	v_mfma_f32_16x16x32_bf16 v[84:87], v[198:201], v[238:241], v[24:27]
	v_mfma_f32_16x16x32_bf16 v[24:27], v[202:205], v[234:237], v[48:51]
	v_mfma_f32_16x16x32_bf16 v[80:83], v[226:229], v[238:241], v[24:27]
	v_mfma_f32_16x16x32_bf16 v[24:27], v[178:181], v[242:245], v[52:55]
	v_mfma_f32_16x16x32_bf16 v[68:71], v[198:201], v[246:249], v[24:27]
	v_mfma_f32_16x16x32_bf16 v[24:27], v[202:205], v[242:245], v[56:59]
	v_mfma_f32_16x16x32_bf16 v[116:119], v[198:201], v[28:31], v[64:67]
	v_mfma_f32_16x16x32_bf16 v[64:67], v[226:229], v[246:249], v[24:27]
	s_setprio 0
	s_barrier
	s_mov_b32 m0, s68
	s_nop 2
	v_lshl_add_u64 v[24:25], v[250:251], 0, s[12:13]
	s_add_u32 s42, s46, 0x10080
	ds_read_b128 v[32:35], v156 offset:49152
	ds_read_b128 v[36:39], v156 offset:50176
	ds_read_b128 v[214:217], v156 offset:51200
	ds_read_b128 v[218:221], v156 offset:52224
	ds_read_b128 v[230:233], v156 offset:53248
	ds_read_b128 v[234:237], v156 offset:54272
	ds_read_b128 v[238:241], v156 offset:55296
	ds_read_b128 v[242:245], v156 offset:56320
	global_load_lds_dwordx4 v[24:25], off
	v_lshl_add_u64 v[24:25], v[252:253], 0, s[12:13]
	s_mov_b32 m0, s67
	s_addc_u32 s43, s47, 0
	global_load_lds_dwordx4 v[24:25], off
	s_mov_b32 m0, s44
	s_nop 0
	global_load_lds_dwordx4 v130, s[42:43]
	s_mov_b32 m0, s45
	s_nop 0
	global_load_lds_dwordx4 v134, s[42:43]
	v_lshl_add_u64 v[24:25], v[138:139], 0, s[12:13]
	s_mov_b32 m0, s59
	s_nop 0
	global_load_lds_dwordx4 v[24:25], off
	v_lshl_add_u64 v[24:25], v[140:141], 0, s[12:13]
	s_mov_b32 m0, s60
	s_nop 0
	global_load_lds_dwordx4 v[24:25], off
	s_waitcnt vmcnt(8)
	s_waitcnt lgkmcnt(0)
	s_barrier
	s_setprio 1
	s_waitcnt lgkmcnt(0)
	v_mfma_f32_16x16x32_bf16 v[24:27], v[8:11], v[32:35], v[144:147]
	v_mfma_f32_16x16x32_bf16 v[60:63], v[12:15], v[36:39], v[24:27]
	v_mfma_f32_16x16x32_bf16 v[24:27], v[16:19], v[32:35], v[148:151]
	v_mfma_f32_16x16x32_bf16 v[56:59], v[20:23], v[36:39], v[24:27]
	v_mfma_f32_16x16x32_bf16 v[24:27], v[8:11], v[214:217], v[158:161]
	v_mfma_f32_16x16x32_bf16 v[44:47], v[12:15], v[218:221], v[24:27]
	v_mfma_f32_16x16x32_bf16 v[24:27], v[16:19], v[214:217], v[162:165]
	v_mfma_f32_16x16x32_bf16 v[40:43], v[20:23], v[218:221], v[24:27]
	v_mfma_f32_16x16x32_bf16 v[24:27], v[8:11], v[230:233], v[166:169]
	v_mfma_f32_16x16x32_bf16 v[0:3], v[8:11], v[238:241], v[0:3]
	v_mfma_f32_16x16x32_bf16 v[28:31], v[12:15], v[234:237], v[24:27]
	v_mfma_f32_16x16x32_bf16 v[24:27], v[16:19], v[230:233], v[170:173]
	v_mfma_f32_16x16x32_bf16 v[12:15], v[12:15], v[242:245], v[0:3]
	v_mfma_f32_16x16x32_bf16 v[0:3], v[16:19], v[238:241], v[4:7]
	v_mfma_f32_16x16x32_bf16 v[24:27], v[20:23], v[234:237], v[24:27]
	v_mfma_f32_16x16x32_bf16 v[8:11], v[20:23], v[242:245], v[0:3]
	s_setprio 0
	s_setprio 1
	v_mfma_f32_16x16x32_bf16 v[0:3], v[178:181], v[32:35], v[206:209]
	v_mfma_f32_16x16x32_bf16 v[52:55], v[198:201], v[36:39], v[0:3]
	v_mfma_f32_16x16x32_bf16 v[0:3], v[202:205], v[32:35], v[210:213]
	v_mfma_f32_16x16x32_bf16 v[48:51], v[226:229], v[36:39], v[0:3]
	v_mfma_f32_16x16x32_bf16 v[0:3], v[178:181], v[214:217], v[222:225]
	v_mfma_f32_16x16x32_bf16 v[36:39], v[198:201], v[218:221], v[0:3]
	v_mfma_f32_16x16x32_bf16 v[0:3], v[202:205], v[214:217], v[182:185]
	v_mfma_f32_16x16x32_bf16 v[32:35], v[226:229], v[218:221], v[0:3]
	v_mfma_f32_16x16x32_bf16 v[0:3], v[178:181], v[230:233], v[186:189]
	v_mfma_f32_16x16x32_bf16 v[20:23], v[198:201], v[234:237], v[0:3]
	v_mfma_f32_16x16x32_bf16 v[0:3], v[202:205], v[230:233], v[190:193]
	v_mfma_f32_16x16x32_bf16 v[16:19], v[226:229], v[234:237], v[0:3]
	v_mfma_f32_16x16x32_bf16 v[0:3], v[178:181], v[238:241], v[194:197]
	v_mfma_f32_16x16x32_bf16 v[4:7], v[198:201], v[242:245], v[0:3]
	v_mfma_f32_16x16x32_bf16 v[0:3], v[202:205], v[238:241], v[174:177]
	v_mfma_f32_16x16x32_bf16 v[0:3], v[226:229], v[242:245], v[0:3]
	s_setprio 0
	s_barrier
	s_andn2_b64 vcc, exec, s[14:15]
	s_cbranch_vccnz .LBB0_467
	s_barrier

.LBB0_776:
	s_lshl_b32 s3, s3, 5
	s_mov_b64 s[12:13], 0x80
	s_and_b32 s3, s3, 0x60
	s_add_i32 m0, s55, 0x18000
	v_lshl_add_u64 v[6:7], v[6:7], 0, s[12:13]
	s_lshl_b32 s5, s2, 13
	s_lshl_b32 s15, s3, 7
	s_waitcnt vmcnt(2)
	s_barrier
	global_load_lds_dwordx4 v[6:7], off
	v_lshl_add_u64 v[4:5], v[4:5], 0, s[12:13]
	s_add_i32 m0, s55, 0x1a000
	s_add_i32 s59, s55, 0x8000
	s_add_i32 s60, s55, 0xa000
	global_load_lds_dwordx4 v[4:5], off
	v_lshl_add_u64 v[0:1], v[0:1], 0, s[12:13]
	s_mov_b32 m0, s59
	s_add_u32 s16, s44, 0x10080
	global_load_lds_dwordx4 v[0:1], off
	v_lshl_add_u64 v[0:1], v[2:3], 0, s[12:13]
	s_mov_b32 m0, s60
	s_addc_u32 s17, s45, 0
	global_load_lds_dwordx4 v[0:1], off
	s_add_i32 m0, s55, 0x1c000
	s_nop 0
	global_load_lds_dwordx4 v130, s[16:17]
	v_lshl_add_u64 v[0:1], s[16:17], 0, v[134:135]
	s_add_i32 m0, s55, 0x1e000
	s_cmpk_lt_u32 s14, 0x100
	global_load_lds_dwordx4 v[0:1], off
	v_lshrrev_b32_e32 v1, 1, v8
	v_and_b32_e32 v1, 24, v1
	v_and_b32_e32 v0, 15, v8
	v_lshlrev_b32_e32 v2, 1, v1
	v_lshl_or_b32 v143, s2, 6, v0
	v_lshl_or_b32 v0, v0, 6, v2
	v_lshlrev_b32_e32 v2, 2, v8
	v_and_b32_e32 v2, 32, v2
	v_bitop3_b32 v152, v0, s15, v2 bitop3:0xde
	s_cselect_b64 s[14:15], -1, 0
	s_ashr_i32 s61, s96, 31
	s_ashr_i32 s2, s33, 31
	s_waitcnt vmcnt(6)
	s_add_u32 s16, s33, s96
	v_bitop3_b32 v3, v0, s5, v2 bitop3:0xde
	s_addc_u32 s17, s2, s61
	s_add_i32 s62, 0, 0x10000
	s_add_i32 s63, 0, 0x14000
	v_or_b32_e32 v153, s3, v1
	v_add_u32_e32 v154, s62, v152
	v_add_u32_e32 v155, s63, v152
	v_add_u32_e32 v156, 0, v3
	s_add_i32 s64, s55, 0xc000
	s_add_i32 s65, s55, 0xe000
	s_mov_b64 s[18:19], 0x100
	s_mov_b64 s[20:21], 0x180
	s_mov_b32 s66, 0x11c00000
	s_mov_b64 s[22:23], 0x40000
	s_mov_b64 s[24:25], 0x48000
	s_mov_b64 s[26:27], 0x50000
	s_mov_b64 s[28:29], 0x58000
	v_mov_b32_e32 v157, 0x3f1b4598
	s_barrier
	s_branch .LBB0_779

.LBB0_911:
	ds_read_b128 v[140:143], v147
	ds_read_b128 v[152:155], v147 offset:1024
	ds_read_b128 v[156:159], v147 offset:2048
	ds_read_b128 v[160:163], v147 offset:3072
	ds_read_b128 v[164:167], v148
	ds_read_b128 v[168:171], v148 offset:1024
	ds_read_b128 v[172:175], v148 offset:2048
	ds_read_b128 v[176:179], v148 offset:3072
	s_add_u32 s30, s28, 0xfffc0080
	s_addc_u32 s31, s29, -1
	s_cmp_eq_u32 s56, 12
	s_cselect_b32 s35, s21, s31
	s_cselect_b32 s34, s27, s30
	s_cselect_b32 s31, s19, s55
	s_cselect_b32 s30, s53, s54
	s_add_i32 m0, s41, 0xc000
	ds_read_b128 v[180:183], v149
	ds_read_b128 v[184:187], v149 offset:1024
	ds_read_b128 v[188:191], v149 offset:2048
	ds_read_b128 v[192:195], v149 offset:3072
	ds_read_b128 v[196:199], v149 offset:4096
	ds_read_b128 v[200:203], v149 offset:5120
	ds_read_b128 v[204:207], v149 offset:6144
	ds_read_b128 v[208:211], v149 offset:7168
	global_load_lds_dwordx4 v132, s[28:29]
	s_add_i32 m0, s41, 0xe000
	s_nop 0
	global_load_lds_dwordx4 v134, s[28:29]
	s_waitcnt vmcnt(8)
	s_waitcnt lgkmcnt(0)
	s_barrier
	s_setprio 1
	s_waitcnt lgkmcnt(0)
	v_mfma_f32_16x16x32_bf16 v[124:127], v[140:143], v[180:183], v[124:127]
	v_mfma_f32_16x16x32_bf16 v[120:123], v[156:159], v[180:183], v[120:123]
	v_mfma_f32_16x16x32_bf16 v[108:111], v[140:143], v[188:191], v[108:111]
	v_mfma_f32_16x16x32_bf16 v[104:107], v[156:159], v[188:191], v[104:107]
	v_mfma_f32_16x16x32_bf16 v[92:95], v[140:143], v[196:199], v[92:95]
	v_mfma_f32_16x16x32_bf16 v[88:91], v[156:159], v[196:199], v[88:91]
	v_mfma_f32_16x16x32_bf16 v[76:79], v[140:143], v[204:207], v[76:79]
	v_mfma_f32_16x16x32_bf16 v[72:75], v[156:159], v[204:207], v[72:75]
	v_mfma_f32_16x16x32_bf16 v[124:127], v[152:155], v[184:187], v[124:127]
	v_mfma_f32_16x16x32_bf16 v[120:123], v[160:163], v[184:187], v[120:123]
	v_mfma_f32_16x16x32_bf16 v[108:111], v[152:155], v[192:195], v[108:111]
	v_mfma_f32_16x16x32_bf16 v[104:107], v[160:163], v[192:195], v[104:107]
	v_mfma_f32_16x16x32_bf16 v[92:95], v[152:155], v[200:203], v[92:95]
	v_mfma_f32_16x16x32_bf16 v[88:91], v[160:163], v[200:203], v[88:91]
	v_mfma_f32_16x16x32_bf16 v[76:79], v[152:155], v[208:211], v[76:79]
	v_mfma_f32_16x16x32_bf16 v[72:75], v[160:163], v[208:211], v[72:75]
	s_setprio 0
	s_setprio 1
	v_mfma_f32_16x16x32_bf16 v[116:119], v[164:167], v[180:183], v[116:119]
	v_mfma_f32_16x16x32_bf16 v[112:115], v[172:175], v[180:183], v[112:115]
	v_mfma_f32_16x16x32_bf16 v[100:103], v[164:167], v[188:191], v[100:103]
	v_mfma_f32_16x16x32_bf16 v[96:99], v[172:175], v[188:191], v[96:99]
	v_mfma_f32_16x16x32_bf16 v[84:87], v[164:167], v[196:199], v[84:87]
	v_mfma_f32_16x16x32_bf16 v[80:83], v[172:175], v[196:199], v[80:83]
	v_mfma_f32_16x16x32_bf16 v[68:71], v[164:167], v[204:207], v[68:71]
	v_mfma_f32_16x16x32_bf16 v[64:67], v[172:175], v[204:207], v[64:67]
	v_mfma_f32_16x16x32_bf16 v[116:119], v[168:171], v[184:187], v[116:119]
	v_mfma_f32_16x16x32_bf16 v[112:115], v[176:179], v[184:187], v[112:115]
	v_mfma_f32_16x16x32_bf16 v[100:103], v[168:171], v[192:195], v[100:103]
	v_mfma_f32_16x16x32_bf16 v[96:99], v[176:179], v[192:195], v[96:99]
	v_mfma_f32_16x16x32_bf16 v[84:87], v[168:171], v[200:203], v[84:87]
	v_mfma_f32_16x16x32_bf16 v[80:83], v[176:179], v[200:203], v[80:83]
	v_mfma_f32_16x16x32_bf16 v[68:71], v[168:171], v[208:211], v[68:71]
	v_mfma_f32_16x16x32_bf16 v[64:67], v[176:179], v[208:211], v[64:67]
	s_setprio 0
	s_barrier
	s_add_i32 s57, s50, s40
	v_lshl_add_u64 v[212:213], s[30:31], 0, v[128:129]
	s_mov_b32 m0, s57
	ds_read_b128 v[180:183], v149 offset:16384
	ds_read_b128 v[184:187], v149 offset:17408
	ds_read_b128 v[188:191], v149 offset:18432
	ds_read_b128 v[192:195], v149 offset:19456
	ds_read_b128 v[196:199], v149 offset:20480
	ds_read_b128 v[200:203], v149 offset:21504
	ds_read_b128 v[204:207], v149 offset:22528
	ds_read_b128 v[208:211], v149 offset:23552
	global_load_lds_dwordx4 v[212:213], off
	s_add_i32 m0, s57, 0x2000
	s_add_u32 s58, s30, 0x40000
	v_lshl_add_u64 v[214:215], s[30:31], 0, v[130:131]
	s_addc_u32 s59, s31, 0
	s_add_i32 s57, s51, s40
	global_load_lds_dwordx4 v[214:215], off
	v_lshl_add_u64 v[216:217], s[58:59], 0, v[128:129]
	s_mov_b32 m0, s57
	v_lshl_add_u64 v[218:219], s[34:35], 0, v[130:131]
	global_load_lds_dwordx4 v[216:217], off
	s_add_i32 m0, s57, 0x2000
	s_nop 0
	global_load_lds_dwordx4 v130, s[58:59]
	v_lshl_add_u64 v[216:217], s[34:35], 0, v[128:129]
	s_mov_b32 m0, s41
	s_nop 0
	global_load_lds_dwordx4 v[216:217], off
	s_mov_b32 m0, s42
	s_nop 0
	global_load_lds_dwordx4 v[218:219], off
	s_waitcnt vmcnt(8)
	s_waitcnt lgkmcnt(0)
	s_barrier
	s_setprio 1
	s_waitcnt lgkmcnt(0)
	v_mfma_f32_16x16x32_bf16 v[60:63], v[140:143], v[180:183], v[60:63]
	v_mfma_f32_16x16x32_bf16 v[56:59], v[156:159], v[180:183], v[56:59]
	v_mfma_f32_16x16x32_bf16 v[44:47], v[140:143], v[188:191], v[44:47]
	v_mfma_f32_16x16x32_bf16 v[40:43], v[156:159], v[188:191], v[40:43]
	v_mfma_f32_16x16x32_bf16 v[28:31], v[140:143], v[196:199], v[28:31]
	v_mfma_f32_16x16x32_bf16 v[24:27], v[156:159], v[196:199], v[24:27]
	v_mfma_f32_16x16x32_bf16 v[12:15], v[140:143], v[204:207], v[12:15]
	v_mfma_f32_16x16x32_bf16 v[8:11], v[156:159], v[204:207], v[8:11]
	v_mfma_f32_16x16x32_bf16 v[60:63], v[152:155], v[184:187], v[60:63]
	v_mfma_f32_16x16x32_bf16 v[56:59], v[160:163], v[184:187], v[56:59]
	v_mfma_f32_16x16x32_bf16 v[44:47], v[152:155], v[192:195], v[44:47]
	v_mfma_f32_16x16x32_bf16 v[40:43], v[160:163], v[192:195], v[40:43]
	v_mfma_f32_16x16x32_bf16 v[28:31], v[152:155], v[200:203], v[28:31]
	v_mfma_f32_16x16x32_bf16 v[24:27], v[160:163], v[200:203], v[24:27]
	v_mfma_f32_16x16x32_bf16 v[12:15], v[152:155], v[208:211], v[12:15]
	v_mfma_f32_16x16x32_bf16 v[8:11], v[160:163], v[208:211], v[8:11]
	s_setprio 0
	s_setprio 1
	v_mfma_f32_16x16x32_bf16 v[52:55], v[164:167], v[180:183], v[52:55]
	v_mfma_f32_16x16x32_bf16 v[48:51], v[172:175], v[180:183], v[48:51]
	v_mfma_f32_16x16x32_bf16 v[36:39], v[164:167], v[188:191], v[36:39]
	v_mfma_f32_16x16x32_bf16 v[32:35], v[172:175], v[188:191], v[32:35]
	v_mfma_f32_16x16x32_bf16 v[20:23], v[164:167], v[196:199], v[20:23]
	v_mfma_f32_16x16x32_bf16 v[16:19], v[172:175], v[196:199], v[16:19]
	v_mfma_f32_16x16x32_bf16 v[4:7], v[164:167], v[204:207], v[4:7]
	v_mfma_f32_16x16x32_bf16 v[0:3], v[172:175], v[204:207], v[0:3]
	v_mfma_f32_16x16x32_bf16 v[52:55], v[168:171], v[184:187], v[52:55]
	v_mfma_f32_16x16x32_bf16 v[48:51], v[176:179], v[184:187], v[48:51]
	v_mfma_f32_16x16x32_bf16 v[36:39], v[168:171], v[192:195], v[36:39]
	v_mfma_f32_16x16x32_bf16 v[32:35], v[176:179], v[192:195], v[32:35]
	v_mfma_f32_16x16x32_bf16 v[20:23], v[168:171], v[200:203], v[20:23]
	v_mfma_f32_16x16x32_bf16 v[16:19], v[176:179], v[200:203], v[16:19]
	v_mfma_f32_16x16x32_bf16 v[4:7], v[168:171], v[208:211], v[4:7]
	v_mfma_f32_16x16x32_bf16 v[0:3], v[176:179], v[208:211], v[0:3]
	s_setprio 0
	s_barrier
	s_add_i32 s57, 0, 0x18000
	v_add_u32_e32 v151, s57, v145
	s_add_i32 s58, 0, 0x1c000
	ds_read_b128 v[140:143], v151
	ds_read_b128 v[152:155], v151 offset:1024
	ds_read_b128 v[156:159], v151 offset:2048
	ds_read_b128 v[160:163], v151 offset:3072
	v_add_u32_e32 v151, s58, v145
	ds_read_b128 v[164:167], v151
	ds_read_b128 v[168:171], v151 offset:1024
	ds_read_b128 v[172:175], v151 offset:2048
	ds_read_b128 v[176:179], v151 offset:3072
	s_add_u32 s34, s34, 0x40000
	s_addc_u32 s35, s35, 0
	s_mov_b32 m0, s43
	v_lshl_add_u64 v[220:221], s[34:35], 0, v[128:129]
	ds_read_b128 v[180:183], v149 offset:32768
	ds_read_b128 v[184:187], v149 offset:33792
	ds_read_b128 v[188:191], v149 offset:34816
	ds_read_b128 v[192:195], v149 offset:35840
	ds_read_b128 v[196:199], v149 offset:36864
	ds_read_b128 v[200:203], v149 offset:37888
	ds_read_b128 v[204:207], v149 offset:38912
	ds_read_b128 v[208:211], v149 offset:39936
	global_load_lds_dwordx4 v[220:221], off
	v_lshl_add_u64 v[220:221], s[34:35], 0, v[130:131]
	s_mov_b32 m0, s44
	s_nop 0
	global_load_lds_dwordx4 v[220:221], off
	s_waitcnt vmcnt(8)
	s_waitcnt lgkmcnt(0)
	s_barrier
	s_setprio 1
	s_waitcnt lgkmcnt(0)
	v_mfma_f32_16x16x32_bf16 v[124:127], v[140:143], v[180:183], v[124:127]
	v_mfma_f32_16x16x32_bf16 v[120:123], v[156:159], v[180:183], v[120:123]
	v_mfma_f32_16x16x32_bf16 v[108:111], v[140:143], v[188:191], v[108:111]
	v_mfma_f32_16x16x32_bf16 v[104:107], v[156:159], v[188:191], v[104:107]
	v_mfma_f32_16x16x32_bf16 v[92:95], v[140:143], v[196:199], v[92:95]
	v_mfma_f32_16x16x32_bf16 v[88:91], v[156:159], v[196:199], v[88:91]
	v_mfma_f32_16x16x32_bf16 v[76:79], v[140:143], v[204:207], v[76:79]
	v_mfma_f32_16x16x32_bf16 v[72:75], v[156:159], v[204:207], v[72:75]
	v_mfma_f32_16x16x32_bf16 v[124:127], v[152:155], v[184:187], v[124:127]
	v_mfma_f32_16x16x32_bf16 v[120:123], v[160:163], v[184:187], v[120:123]
	v_mfma_f32_16x16x32_bf16 v[108:111], v[152:155], v[192:195], v[108:111]
	v_mfma_f32_16x16x32_bf16 v[104:107], v[160:163], v[192:195], v[104:107]
	v_mfma_f32_16x16x32_bf16 v[92:95], v[152:155], v[200:203], v[92:95]
	v_mfma_f32_16x16x32_bf16 v[88:91], v[160:163], v[200:203], v[88:91]
	v_mfma_f32_16x16x32_bf16 v[76:79], v[152:155], v[208:211], v[76:79]
	v_mfma_f32_16x16x32_bf16 v[72:75], v[160:163], v[208:211], v[72:75]
	s_setprio 0
	s_setprio 1
	v_mfma_f32_16x16x32_bf16 v[116:119], v[164:167], v[180:183], v[116:119]
	v_mfma_f32_16x16x32_bf16 v[112:115], v[172:175], v[180:183], v[112:115]
	v_mfma_f32_16x16x32_bf16 v[100:103], v[164:167], v[188:191], v[100:103]
	v_mfma_f32_16x16x32_bf16 v[96:99], v[172:175], v[188:191], v[96:99]
	v_mfma_f32_16x16x32_bf16 v[84:87], v[164:167], v[196:199], v[84:87]
	v_mfma_f32_16x16x32_bf16 v[80:83], v[172:175], v[196:199], v[80:83]
	v_mfma_f32_16x16x32_bf16 v[68:71], v[164:167], v[204:207], v[68:71]
	v_mfma_f32_16x16x32_bf16 v[64:67], v[172:175], v[204:207], v[64:67]
	v_mfma_f32_16x16x32_bf16 v[116:119], v[168:171], v[184:187], v[116:119]
	v_mfma_f32_16x16x32_bf16 v[112:115], v[176:179], v[184:187], v[112:115]
	v_mfma_f32_16x16x32_bf16 v[100:103], v[168:171], v[192:195], v[100:103]
	v_mfma_f32_16x16x32_bf16 v[96:99], v[176:179], v[192:195], v[96:99]
	v_mfma_f32_16x16x32_bf16 v[84:87], v[168:171], v[200:203], v[84:87]
	v_mfma_f32_16x16x32_bf16 v[80:83], v[176:179], v[200:203], v[80:83]
	v_mfma_f32_16x16x32_bf16 v[68:71], v[168:171], v[208:211], v[68:71]
	v_mfma_f32_16x16x32_bf16 v[64:67], v[176:179], v[208:211], v[64:67]
	s_setprio 0
	s_barrier
	s_add_i32 s34, s57, s40
	v_lshl_add_u64 v[212:213], v[212:213], 0, s[14:15]
	s_mov_b32 m0, s34
	ds_read_b128 v[180:183], v149 offset:49152
	ds_read_b128 v[184:187], v149 offset:50176
	ds_read_b128 v[188:191], v149 offset:51200
	ds_read_b128 v[192:195], v149 offset:52224
	ds_read_b128 v[196:199], v149 offset:53248
	ds_read_b128 v[200:203], v149 offset:54272
	ds_read_b128 v[204:207], v149 offset:55296
	ds_read_b128 v[208:211], v149 offset:56320
	global_load_lds_dwordx4 v[212:213], off
	s_add_i32 m0, s34, 0x2000
	s_add_u32 s30, s30, 0x40080
	v_lshl_add_u64 v[212:213], v[214:215], 0, s[14:15]
	s_addc_u32 s31, s31, 0
	s_add_i32 s34, s58, s40
	global_load_lds_dwordx4 v[212:213], off
	v_lshl_add_u64 v[212:213], s[30:31], 0, v[128:129]
	s_mov_b32 m0, s34
	s_nop 0
	global_load_lds_dwordx4 v[212:213], off
	s_add_i32 m0, s34, 0x2000
	s_nop 0
	global_load_lds_dwordx4 v130, s[30:31]
	v_lshl_add_u64 v[212:213], v[216:217], 0, s[14:15]
	s_mov_b32 m0, s46
	s_nop 0
	global_load_lds_dwordx4 v[212:213], off
	v_lshl_add_u64 v[212:213], v[218:219], 0, s[14:15]
	s_mov_b32 m0, s47
	s_nop 0
	global_load_lds_dwordx4 v[212:213], off
	s_waitcnt vmcnt(8)
	s_waitcnt lgkmcnt(0)
	s_barrier
	s_setprio 1
	s_waitcnt lgkmcnt(0)
	v_mfma_f32_16x16x32_bf16 v[60:63], v[140:143], v[180:183], v[60:63]
	v_mfma_f32_16x16x32_bf16 v[56:59], v[156:159], v[180:183], v[56:59]
	v_mfma_f32_16x16x32_bf16 v[44:47], v[140:143], v[188:191], v[44:47]
	v_mfma_f32_16x16x32_bf16 v[40:43], v[156:159], v[188:191], v[40:43]
	v_mfma_f32_16x16x32_bf16 v[28:31], v[140:143], v[196:199], v[28:31]
	v_mfma_f32_16x16x32_bf16 v[24:27], v[156:159], v[196:199], v[24:27]
	v_mfma_f32_16x16x32_bf16 v[12:15], v[140:143], v[204:207], v[12:15]
	v_mfma_f32_16x16x32_bf16 v[8:11], v[156:159], v[204:207], v[8:11]
	v_mfma_f32_16x16x32_bf16 v[60:63], v[152:155], v[184:187], v[60:63]
	v_mfma_f32_16x16x32_bf16 v[56:59], v[160:163], v[184:187], v[56:59]
	v_mfma_f32_16x16x32_bf16 v[44:47], v[152:155], v[192:195], v[44:47]
	v_mfma_f32_16x16x32_bf16 v[40:43], v[160:163], v[192:195], v[40:43]
	v_mfma_f32_16x16x32_bf16 v[28:31], v[152:155], v[200:203], v[28:31]
	v_mfma_f32_16x16x32_bf16 v[24:27], v[160:163], v[200:203], v[24:27]
	v_mfma_f32_16x16x32_bf16 v[12:15], v[152:155], v[208:211], v[12:15]
	v_mfma_f32_16x16x32_bf16 v[8:11], v[160:163], v[208:211], v[8:11]
	s_setprio 0
	s_setprio 1
	v_mfma_f32_16x16x32_bf16 v[52:55], v[164:167], v[180:183], v[52:55]
	v_mfma_f32_16x16x32_bf16 v[48:51], v[172:175], v[180:183], v[48:51]
	v_mfma_f32_16x16x32_bf16 v[36:39], v[164:167], v[188:191], v[36:39]
	v_mfma_f32_16x16x32_bf16 v[32:35], v[172:175], v[188:191], v[32:35]
	v_mfma_f32_16x16x32_bf16 v[20:23], v[164:167], v[196:199], v[20:23]
	v_mfma_f32_16x16x32_bf16 v[16:19], v[172:175], v[196:199], v[16:19]
	v_mfma_f32_16x16x32_bf16 v[4:7], v[164:167], v[204:207], v[4:7]
	v_mfma_f32_16x16x32_bf16 v[0:3], v[172:175], v[204:207], v[0:3]
	v_mfma_f32_16x16x32_bf16 v[52:55], v[168:171], v[184:187], v[52:55]
	v_mfma_f32_16x16x32_bf16 v[48:51], v[176:179], v[184:187], v[48:51]
	v_mfma_f32_16x16x32_bf16 v[36:39], v[168:171], v[192:195], v[36:39]
	v_mfma_f32_16x16x32_bf16 v[32:35], v[176:179], v[192:195], v[32:35]
	v_mfma_f32_16x16x32_bf16 v[20:23], v[168:171], v[200:203], v[20:23]
	v_mfma_f32_16x16x32_bf16 v[16:19], v[176:179], v[200:203], v[16:19]
	v_mfma_f32_16x16x32_bf16 v[4:7], v[168:171], v[208:211], v[4:7]
	v_mfma_f32_16x16x32_bf16 v[0:3], v[176:179], v[208:211], v[0:3]
	s_setprio 0
	s_barrier
	s_add_i32 s56, s56, 2
	s_add_u32 s28, s28, 0x100
	s_addc_u32 s29, s29, 0
	s_add_u32 s54, s54, 0x100
	s_addc_u32 s55, s55, 0
	s_cmp_gt_u32 s56, 13
	s_cbranch_scc0 .LBB0_911
	s_and_b64 vcc, exec, s[16:17]
	s_cbranch_vccz .LBB0_914
	s_barrier

.LBB0_971:
	s_mov_b64 s[12:13], 0x80
	s_and_b32 s5, s2, 3
	s_add_i32 m0, s41, 0x18000
	v_lshl_add_u64 v[6:7], v[6:7], 0, s[12:13]
	s_lshl_b32 s2, s3, 13
	s_lshl_b32 s8, s5, 5
	s_lshl_b32 s16, s5, 12
	s_waitcnt vmcnt(2)
	s_barrier
	global_load_lds_dwordx4 v[6:7], off
	v_lshl_add_u64 v[4:5], v[4:5], 0, s[12:13]
	s_add_i32 m0, s41, 0x1a000
	s_add_i32 s45, s41, 0x8000
	s_add_i32 s46, s41, 0xa000
	global_load_lds_dwordx4 v[4:5], off
	v_lshl_add_u64 v[0:1], v[0:1], 0, s[12:13]
	s_mov_b32 m0, s45
	s_add_u32 s14, s34, 0x40080
	global_load_lds_dwordx4 v[0:1], off
	v_lshl_add_u64 v[0:1], v[2:3], 0, s[12:13]
	s_mov_b32 m0, s46
	s_addc_u32 s15, s35, 0
	global_load_lds_dwordx4 v[0:1], off
	s_add_i32 m0, s41, 0x1c000
	s_nop 0
	global_load_lds_dwordx4 v130, s[14:15]
	v_lshl_add_u64 v[0:1], s[14:15], 0, v[134:135]
	s_add_i32 m0, s41, 0x1e000
	v_bfe_u32 v2, v8, 4, 2
	global_load_lds_dwordx4 v[0:1], off
	v_and_b32_e32 v1, 15, v8
	v_lshlrev_b32_e32 v138, 4, v2
	v_lshlrev_b32_e32 v3, 2, v8
	v_lshl_or_b32 v139, s3, 6, v1
	v_lshl_or_b32 v1, v1, 6, v138
	v_and_b32_e32 v3, 32, v3
	v_bitop3_b32 v4, v1, s2, v3 bitop3:0xde
	v_bitop3_b32 v141, v1, s16, v3 bitop3:0xde
	v_lshlrev_b32_e32 v1, 14, v9
	v_and_b32_e32 v1, 0xffff8000, v1
	v_lshlrev_b32_e32 v0, 3, v2
	v_cmp_eq_u32_e64 s[2:3], 0, v2
	v_lshlrev_b32_e32 v140, 5, v2
	v_lshl_add_u32 v1, v10, 11, v1
	v_and_b32_e32 v2, 1, v9
	v_lshl_or_b32 v1, v2, 6, v1
	v_lshl_add_u32 v144, v11, 1, v1
	v_lshlrev_b32_e32 v1, 14, v12
	s_cmpk_lt_u32 s4, 0x100
	v_and_b32_e32 v1, 0xffff8000, v1
	s_waitcnt vmcnt(6)
	s_cselect_b64 s[14:15], -1, 0
	s_cmp_eq_u32 s5, 0
	v_lshl_add_u32 v1, v13, 11, v1
	v_and_b32_e32 v2, 1, v12
	s_cselect_b64 s[16:17], -1, 0
	v_lshl_or_b32 v1, v2, 6, v1
	s_add_i32 s51, 0, 0x10000
	s_add_i32 s52, 0, 0x14000
	v_lshlrev_b32_e32 v136, 1, v0
	v_mbcnt_lo_u32_b32 v0, -1, 0
	s_ashr_i32 s47, s96, 31
	s_ashr_i32 s48, s33, 31
	s_lshl_b32 s49, s5, 2
	v_lshl_or_b32 v142, s5, 6, v138
	v_mov_b32_e32 v145, v137
	v_lshl_add_u32 v146, v14, 1, v1
	v_mov_b32_e32 v147, v137
	v_mov_b64_e32 v[148:149], 0xb00
	v_mov_b64_e32 v[150:151], 0xaff
	s_movk_i32 s50, 0x161
	v_add_u32_e32 v143, s51, v141
	v_add_u32_e32 v158, s52, v141
	v_add_u32_e32 v159, 0, v4
	v_mov_b32_e32 v160, 0x358637bd
	s_movk_i32 s53, 0x1600
	s_lshl_b32 s8, s8, 1
	v_mbcnt_hi_u32_b32 v161, -1, v0
	s_mov_b32 s54, s9
	s_barrier
	s_branch .LBB0_974

.LBB0_977:
	ds_read_b128 v[152:155], v143
	ds_read_b128 v[162:165], v143 offset:1024
	ds_read_b128 v[166:169], v143 offset:2048
	ds_read_b128 v[170:173], v143 offset:3072
	ds_read_b128 v[174:177], v158
	ds_read_b128 v[178:181], v158 offset:1024
	ds_read_b128 v[182:185], v158 offset:2048
	ds_read_b128 v[186:189], v158 offset:3072
	s_add_u32 s34, s30, 0xfffc0080
	s_addc_u32 s35, s31, -1
	s_cmp_eq_u32 s57, 12
	s_cselect_b32 s37, s21, s35
	s_cselect_b32 s36, s27, s34
	s_cselect_b32 s35, s19, s56
	s_cselect_b32 s34, s29, s55
	s_waitcnt lgkmcnt(0)
	s_add_i32 m0, s41, 0xc000
	ds_read_b128 v[190:193], v159
	ds_read_b128 v[194:197], v159 offset:1024
	ds_read_b128 v[198:201], v159 offset:2048
	ds_read_b128 v[202:205], v159 offset:3072
	ds_read_b128 v[206:209], v159 offset:4096
	ds_read_b128 v[210:213], v159 offset:5120
	ds_read_b128 v[214:217], v159 offset:6144
	ds_read_b128 v[218:221], v159 offset:7168
	global_load_lds_dwordx4 v144, s[30:31]
	s_add_i32 m0, s41, 0xe000
	s_nop 0
	global_load_lds_dwordx4 v146, s[30:31]
	s_waitcnt vmcnt(8)
	s_waitcnt lgkmcnt(0)
	s_barrier
	s_setprio 1
	s_waitcnt lgkmcnt(0)
	v_mfma_f32_16x16x32_bf16 v[116:119], v[152:155], v[190:193], v[116:119]
	v_mfma_f32_16x16x32_bf16 v[112:115], v[166:169], v[190:193], v[112:115]
	v_mfma_f32_16x16x32_bf16 v[100:103], v[152:155], v[198:201], v[100:103]
	v_mfma_f32_16x16x32_bf16 v[96:99], v[166:169], v[198:201], v[96:99]
	v_mfma_f32_16x16x32_bf16 v[88:91], v[152:155], v[206:209], v[88:91]
	v_mfma_f32_16x16x32_bf16 v[84:87], v[166:169], v[206:209], v[84:87]
	v_mfma_f32_16x16x32_bf16 v[72:75], v[152:155], v[214:217], v[72:75]
	v_mfma_f32_16x16x32_bf16 v[68:71], v[166:169], v[214:217], v[68:71]
	v_mfma_f32_16x16x32_bf16 v[116:119], v[162:165], v[194:197], v[116:119]
	v_mfma_f32_16x16x32_bf16 v[112:115], v[170:173], v[194:197], v[112:115]
	v_mfma_f32_16x16x32_bf16 v[100:103], v[162:165], v[202:205], v[100:103]
	v_mfma_f32_16x16x32_bf16 v[96:99], v[170:173], v[202:205], v[96:99]
	v_mfma_f32_16x16x32_bf16 v[88:91], v[162:165], v[210:213], v[88:91]
	v_mfma_f32_16x16x32_bf16 v[84:87], v[170:173], v[210:213], v[84:87]
	v_mfma_f32_16x16x32_bf16 v[72:75], v[162:165], v[218:221], v[72:75]
	v_mfma_f32_16x16x32_bf16 v[68:71], v[170:173], v[218:221], v[68:71]
	s_setprio 0
	s_setprio 1
	v_mfma_f32_16x16x32_bf16 v[124:127], v[174:177], v[190:193], v[124:127]
	v_mfma_f32_16x16x32_bf16 v[120:123], v[182:185], v[190:193], v[120:123]
	v_mfma_f32_16x16x32_bf16 v[108:111], v[174:177], v[198:201], v[108:111]
	v_mfma_f32_16x16x32_bf16 v[104:107], v[182:185], v[198:201], v[104:107]
	v_mfma_f32_16x16x32_bf16 v[92:95], v[174:177], v[206:209], v[92:95]
	v_mfma_f32_16x16x32_bf16 v[80:83], v[182:185], v[206:209], v[80:83]
	v_mfma_f32_16x16x32_bf16 v[76:79], v[174:177], v[214:217], v[76:79]
	v_mfma_f32_16x16x32_bf16 v[64:67], v[182:185], v[214:217], v[64:67]
	v_mfma_f32_16x16x32_bf16 v[124:127], v[178:181], v[194:197], v[124:127]
	v_mfma_f32_16x16x32_bf16 v[120:123], v[186:189], v[194:197], v[120:123]
	v_mfma_f32_16x16x32_bf16 v[108:111], v[178:181], v[202:205], v[108:111]
	v_mfma_f32_16x16x32_bf16 v[104:107], v[186:189], v[202:205], v[104:107]
	v_mfma_f32_16x16x32_bf16 v[92:95], v[178:181], v[210:213], v[92:95]
	v_mfma_f32_16x16x32_bf16 v[80:83], v[186:189], v[210:213], v[80:83]
	v_mfma_f32_16x16x32_bf16 v[76:79], v[178:181], v[218:221], v[76:79]
	v_mfma_f32_16x16x32_bf16 v[64:67], v[186:189], v[218:221], v[64:67]
	s_setprio 0
	s_barrier
	s_add_i32 s58, s51, s40
	v_lshl_add_u64 v[156:157], s[34:35], 0, v[130:131]
	s_mov_b32 m0, s58
	ds_read_b128 v[190:193], v159 offset:16384
	ds_read_b128 v[194:197], v159 offset:17408
	ds_read_b128 v[198:201], v159 offset:18432
	ds_read_b128 v[202:205], v159 offset:19456
	ds_read_b128 v[206:209], v159 offset:20480
	ds_read_b128 v[210:213], v159 offset:21504
	ds_read_b128 v[214:217], v159 offset:22528
	ds_read_b128 v[218:221], v159 offset:23552
	global_load_lds_dwordx4 v[156:157], off
	s_add_i32 m0, s58, 0x2000
	s_add_u32 s58, s34, 0x40000
	v_lshl_add_u64 v[222:223], s[34:35], 0, v[134:135]
	s_addc_u32 s59, s35, 0
	s_add_i32 s60, s52, s40
	global_load_lds_dwordx4 v[222:223], off
	s_mov_b32 m0, s60
	v_lshl_add_u64 v[226:227], s[36:37], 0, v[132:133]
	global_load_lds_dwordx4 v130, s[58:59]
	s_add_i32 m0, s60, 0x2000
	s_nop 0
	global_load_lds_dwordx4 v134, s[58:59]
	v_lshl_add_u64 v[224:225], s[36:37], 0, v[128:129]
	s_mov_b32 m0, s41
	s_nop 0
	global_load_lds_dwordx4 v[224:225], off
	s_mov_b32 m0, s42
	s_nop 0
	global_load_lds_dwordx4 v[226:227], off
	s_waitcnt vmcnt(8)
	s_waitcnt lgkmcnt(0)
	s_barrier
	s_setprio 1
	s_waitcnt lgkmcnt(0)
	v_mfma_f32_16x16x32_bf16 v[56:59], v[152:155], v[190:193], v[56:59]
	v_mfma_f32_16x16x32_bf16 v[52:55], v[166:169], v[190:193], v[52:55]
	v_mfma_f32_16x16x32_bf16 v[40:43], v[152:155], v[198:201], v[40:43]
	v_mfma_f32_16x16x32_bf16 v[36:39], v[166:169], v[198:201], v[36:39]
	v_mfma_f32_16x16x32_bf16 v[24:27], v[152:155], v[206:209], v[24:27]
	v_mfma_f32_16x16x32_bf16 v[20:23], v[166:169], v[206:209], v[20:23]
	v_mfma_f32_16x16x32_bf16 v[8:11], v[152:155], v[214:217], v[8:11]
	v_mfma_f32_16x16x32_bf16 v[4:7], v[166:169], v[214:217], v[4:7]
	v_mfma_f32_16x16x32_bf16 v[56:59], v[162:165], v[194:197], v[56:59]
	v_mfma_f32_16x16x32_bf16 v[52:55], v[170:173], v[194:197], v[52:55]
	v_mfma_f32_16x16x32_bf16 v[40:43], v[162:165], v[202:205], v[40:43]
	v_mfma_f32_16x16x32_bf16 v[36:39], v[170:173], v[202:205], v[36:39]
	v_mfma_f32_16x16x32_bf16 v[24:27], v[162:165], v[210:213], v[24:27]
	v_mfma_f32_16x16x32_bf16 v[20:23], v[170:173], v[210:213], v[20:23]
	v_mfma_f32_16x16x32_bf16 v[8:11], v[162:165], v[218:221], v[8:11]
	v_mfma_f32_16x16x32_bf16 v[4:7], v[170:173], v[218:221], v[4:7]
	s_setprio 0
	s_setprio 1
	v_mfma_f32_16x16x32_bf16 v[60:63], v[174:177], v[190:193], v[60:63]
	v_mfma_f32_16x16x32_bf16 v[48:51], v[182:185], v[190:193], v[48:51]
	v_mfma_f32_16x16x32_bf16 v[44:47], v[174:177], v[198:201], v[44:47]
	v_mfma_f32_16x16x32_bf16 v[32:35], v[182:185], v[198:201], v[32:35]
	v_mfma_f32_16x16x32_bf16 v[28:31], v[174:177], v[206:209], v[28:31]
	v_mfma_f32_16x16x32_bf16 v[16:19], v[182:185], v[206:209], v[16:19]
	v_mfma_f32_16x16x32_bf16 v[12:15], v[174:177], v[214:217], v[12:15]
	v_mfma_f32_16x16x32_bf16 v[0:3], v[182:185], v[214:217], v[0:3]
	v_mfma_f32_16x16x32_bf16 v[60:63], v[178:181], v[194:197], v[60:63]
	v_mfma_f32_16x16x32_bf16 v[48:51], v[186:189], v[194:197], v[48:51]
	v_mfma_f32_16x16x32_bf16 v[44:47], v[178:181], v[202:205], v[44:47]
	v_mfma_f32_16x16x32_bf16 v[32:35], v[186:189], v[202:205], v[32:35]
	v_mfma_f32_16x16x32_bf16 v[28:31], v[178:181], v[210:213], v[28:31]
	v_mfma_f32_16x16x32_bf16 v[16:19], v[186:189], v[210:213], v[16:19]
	v_mfma_f32_16x16x32_bf16 v[12:15], v[178:181], v[218:221], v[12:15]
	v_mfma_f32_16x16x32_bf16 v[0:3], v[186:189], v[218:221], v[0:3]
	s_setprio 0
	s_barrier
	s_add_i32 s58, 0, 0x18000
	s_add_i32 s59, 0, 0x1c000
	v_add_u32_e32 v170, s58, v141
	v_add_u32_e32 v186, s59, v141
	ds_read_b128 v[152:155], v170
	ds_read_b128 v[162:165], v170 offset:1024
	ds_read_b128 v[166:169], v170 offset:2048
	ds_read_b128 v[170:173], v170 offset:3072
	ds_read_b128 v[174:177], v186
	ds_read_b128 v[178:181], v186 offset:1024
	ds_read_b128 v[182:185], v186 offset:2048
	ds_read_b128 v[186:189], v186 offset:3072
	s_add_u32 s36, s36, 0x40000
	s_addc_u32 s37, s37, 0
	s_mov_b32 m0, s43
	ds_read_b128 v[190:193], v159 offset:32768
	ds_read_b128 v[194:197], v159 offset:33792
	ds_read_b128 v[198:201], v159 offset:34816
	ds_read_b128 v[202:205], v159 offset:35840
	ds_read_b128 v[206:209], v159 offset:36864
	ds_read_b128 v[210:213], v159 offset:37888
	ds_read_b128 v[214:217], v159 offset:38912
	ds_read_b128 v[218:221], v159 offset:39936
	global_load_lds_dwordx4 v128, s[36:37]
	v_lshl_add_u64 v[228:229], s[36:37], 0, v[132:133]
	s_mov_b32 m0, s44
	s_nop 0
	global_load_lds_dwordx4 v[228:229], off
	s_waitcnt vmcnt(8)
	s_waitcnt lgkmcnt(0)
	s_barrier
	s_setprio 1
	s_waitcnt lgkmcnt(0)
	v_mfma_f32_16x16x32_bf16 v[116:119], v[152:155], v[190:193], v[116:119]
	v_mfma_f32_16x16x32_bf16 v[112:115], v[166:169], v[190:193], v[112:115]
	v_mfma_f32_16x16x32_bf16 v[100:103], v[152:155], v[198:201], v[100:103]
	v_mfma_f32_16x16x32_bf16 v[96:99], v[166:169], v[198:201], v[96:99]
	v_mfma_f32_16x16x32_bf16 v[88:91], v[152:155], v[206:209], v[88:91]
	v_mfma_f32_16x16x32_bf16 v[84:87], v[166:169], v[206:209], v[84:87]
	v_mfma_f32_16x16x32_bf16 v[72:75], v[152:155], v[214:217], v[72:75]
	v_mfma_f32_16x16x32_bf16 v[68:71], v[166:169], v[214:217], v[68:71]
	v_mfma_f32_16x16x32_bf16 v[116:119], v[162:165], v[194:197], v[116:119]
	v_mfma_f32_16x16x32_bf16 v[112:115], v[170:173], v[194:197], v[112:115]
	v_mfma_f32_16x16x32_bf16 v[100:103], v[162:165], v[202:205], v[100:103]
	v_mfma_f32_16x16x32_bf16 v[96:99], v[170:173], v[202:205], v[96:99]
	v_mfma_f32_16x16x32_bf16 v[88:91], v[162:165], v[210:213], v[88:91]
	v_mfma_f32_16x16x32_bf16 v[84:87], v[170:173], v[210:213], v[84:87]
	v_mfma_f32_16x16x32_bf16 v[72:75], v[162:165], v[218:221], v[72:75]
	v_mfma_f32_16x16x32_bf16 v[68:71], v[170:173], v[218:221], v[68:71]
	s_setprio 0
	s_setprio 1
	v_mfma_f32_16x16x32_bf16 v[124:127], v[174:177], v[190:193], v[124:127]
	v_mfma_f32_16x16x32_bf16 v[120:123], v[182:185], v[190:193], v[120:123]
	v_mfma_f32_16x16x32_bf16 v[108:111], v[174:177], v[198:201], v[108:111]
	v_mfma_f32_16x16x32_bf16 v[104:107], v[182:185], v[198:201], v[104:107]
	v_mfma_f32_16x16x32_bf16 v[92:95], v[174:177], v[206:209], v[92:95]
	v_mfma_f32_16x16x32_bf16 v[80:83], v[182:185], v[206:209], v[80:83]
	v_mfma_f32_16x16x32_bf16 v[76:79], v[174:177], v[214:217], v[76:79]
	v_mfma_f32_16x16x32_bf16 v[64:67], v[182:185], v[214:217], v[64:67]
	v_mfma_f32_16x16x32_bf16 v[124:127], v[178:181], v[194:197], v[124:127]
	v_mfma_f32_16x16x32_bf16 v[120:123], v[186:189], v[194:197], v[120:123]
	v_mfma_f32_16x16x32_bf16 v[108:111], v[178:181], v[202:205], v[108:111]
	v_mfma_f32_16x16x32_bf16 v[104:107], v[186:189], v[202:205], v[104:107]
	v_mfma_f32_16x16x32_bf16 v[92:95], v[178:181], v[210:213], v[92:95]
	v_mfma_f32_16x16x32_bf16 v[80:83], v[186:189], v[210:213], v[80:83]
	v_mfma_f32_16x16x32_bf16 v[76:79], v[178:181], v[218:221], v[76:79]
	v_mfma_f32_16x16x32_bf16 v[64:67], v[186:189], v[218:221], v[64:67]
	s_setprio 0
	s_barrier
	s_add_i32 s36, s58, s40
	v_lshl_add_u64 v[156:157], v[156:157], 0, s[12:13]
	s_mov_b32 m0, s36
	ds_read_b128 v[190:193], v159 offset:49152
	ds_read_b128 v[194:197], v159 offset:50176
	ds_read_b128 v[198:201], v159 offset:51200
	ds_read_b128 v[202:205], v159 offset:52224
	ds_read_b128 v[206:209], v159 offset:53248
	ds_read_b128 v[210:213], v159 offset:54272
	ds_read_b128 v[214:217], v159 offset:55296
	ds_read_b128 v[218:221], v159 offset:56320
	global_load_lds_dwordx4 v[156:157], off
	s_add_i32 m0, s36, 0x2000
	s_add_u32 s34, s34, 0x40080
	v_lshl_add_u64 v[156:157], v[222:223], 0, s[12:13]
	s_addc_u32 s35, s35, 0
	s_add_i32 s36, s59, s40
	global_load_lds_dwordx4 v[156:157], off
	s_mov_b32 m0, s36
	s_nop 0
	global_load_lds_dwordx4 v130, s[34:35]
	s_add_i32 m0, s36, 0x2000
	s_nop 0
	global_load_lds_dwordx4 v134, s[34:35]
	v_lshl_add_u64 v[156:157], v[224:225], 0, s[12:13]
	s_mov_b32 m0, s45
	s_nop 0
	global_load_lds_dwordx4 v[156:157], off
	v_lshl_add_u64 v[156:157], v[226:227], 0, s[12:13]
	s_mov_b32 m0, s46
	s_nop 0
	global_load_lds_dwordx4 v[156:157], off
	s_waitcnt vmcnt(8)
	s_waitcnt lgkmcnt(0)
	s_barrier
	s_setprio 1
	s_waitcnt lgkmcnt(0)
	v_mfma_f32_16x16x32_bf16 v[56:59], v[152:155], v[190:193], v[56:59]
	v_mfma_f32_16x16x32_bf16 v[52:55], v[166:169], v[190:193], v[52:55]
	v_mfma_f32_16x16x32_bf16 v[40:43], v[152:155], v[198:201], v[40:43]
	v_mfma_f32_16x16x32_bf16 v[36:39], v[166:169], v[198:201], v[36:39]
	v_mfma_f32_16x16x32_bf16 v[24:27], v[152:155], v[206:209], v[24:27]
	v_mfma_f32_16x16x32_bf16 v[20:23], v[166:169], v[206:209], v[20:23]
	v_mfma_f32_16x16x32_bf16 v[8:11], v[152:155], v[214:217], v[8:11]
	v_mfma_f32_16x16x32_bf16 v[4:7], v[166:169], v[214:217], v[4:7]
	v_mfma_f32_16x16x32_bf16 v[56:59], v[162:165], v[194:197], v[56:59]
	v_mfma_f32_16x16x32_bf16 v[52:55], v[170:173], v[194:197], v[52:55]
	v_mfma_f32_16x16x32_bf16 v[40:43], v[162:165], v[202:205], v[40:43]
	v_mfma_f32_16x16x32_bf16 v[36:39], v[170:173], v[202:205], v[36:39]
	v_mfma_f32_16x16x32_bf16 v[24:27], v[162:165], v[210:213], v[24:27]
	v_mfma_f32_16x16x32_bf16 v[20:23], v[170:173], v[210:213], v[20:23]
	v_mfma_f32_16x16x32_bf16 v[8:11], v[162:165], v[218:221], v[8:11]
	v_mfma_f32_16x16x32_bf16 v[4:7], v[170:173], v[218:221], v[4:7]
	s_setprio 0
	s_setprio 1
	v_mfma_f32_16x16x32_bf16 v[60:63], v[174:177], v[190:193], v[60:63]
	v_mfma_f32_16x16x32_bf16 v[48:51], v[182:185], v[190:193], v[48:51]
	v_mfma_f32_16x16x32_bf16 v[44:47], v[174:177], v[198:201], v[44:47]
	v_mfma_f32_16x16x32_bf16 v[32:35], v[182:185], v[198:201], v[32:35]
	v_mfma_f32_16x16x32_bf16 v[28:31], v[174:177], v[206:209], v[28:31]
	v_mfma_f32_16x16x32_bf16 v[16:19], v[182:185], v[206:209], v[16:19]
	v_mfma_f32_16x16x32_bf16 v[12:15], v[174:177], v[214:217], v[12:15]
	v_mfma_f32_16x16x32_bf16 v[0:3], v[182:185], v[214:217], v[0:3]
	v_mfma_f32_16x16x32_bf16 v[60:63], v[178:181], v[194:197], v[60:63]
	v_mfma_f32_16x16x32_bf16 v[48:51], v[186:189], v[194:197], v[48:51]
	v_mfma_f32_16x16x32_bf16 v[44:47], v[178:181], v[202:205], v[44:47]
	v_mfma_f32_16x16x32_bf16 v[32:35], v[186:189], v[202:205], v[32:35]
	v_mfma_f32_16x16x32_bf16 v[28:31], v[178:181], v[210:213], v[28:31]
	v_mfma_f32_16x16x32_bf16 v[16:19], v[186:189], v[210:213], v[16:19]
	v_mfma_f32_16x16x32_bf16 v[12:15], v[178:181], v[218:221], v[12:15]
	v_mfma_f32_16x16x32_bf16 v[0:3], v[186:189], v[218:221], v[0:3]
	s_setprio 0
	s_barrier
	s_add_i32 s57, s57, 2
	s_add_u32 s30, s30, 0x100
	s_addc_u32 s31, s31, 0
	s_add_u32 s55, s55, 0x100
	s_addc_u32 s56, s56, 0
	s_cmp_gt_u32 s57, 13
	s_cbranch_scc0 .LBB0_977
	s_and_b64 vcc, exec, s[14:15]
	s_cbranch_vccz .LBB0_982
	s_barrier
	v_lshl_add_u32 v152, s28, 8, v139
	s_cmp_gt_i32 s26, 21
	s_mov_b64 s[28:29], -1
	s_cbranch_scc1 .LBB0_983

.LBB0_1065:
	ds_read_b128 v[140:143], v147
	ds_read_b128 v[152:155], v147 offset:1024
	ds_read_b128 v[156:159], v147 offset:2048
	ds_read_b128 v[160:163], v147 offset:3072
	ds_read_b128 v[164:167], v148
	ds_read_b128 v[168:171], v148 offset:1024
	ds_read_b128 v[172:175], v148 offset:2048
	ds_read_b128 v[176:179], v148 offset:3072
	s_add_u32 s24, s22, 0x100
	s_addc_u32 s25, s23, 0
	s_cmp_eq_u32 s52, 40
	s_cselect_b32 s29, s7, s25
	s_cselect_b32 s28, s6, s24
	s_cselect_b32 s27, s21, s51
	s_cselect_b32 s26, s20, s50
	v_lshl_add_u64 v[212:213], s[22:23], 0, v[132:133]
	s_add_i32 m0, s35, 0xc000
	ds_read_b128 v[180:183], v149
	ds_read_b128 v[184:187], v149 offset:1024
	ds_read_b128 v[188:191], v149 offset:2048
	ds_read_b128 v[192:195], v149 offset:3072
	ds_read_b128 v[196:199], v149 offset:4096
	ds_read_b128 v[200:203], v149 offset:5120
	ds_read_b128 v[204:207], v149 offset:6144
	ds_read_b128 v[208:211], v149 offset:7168
	global_load_lds_dwordx4 v[212:213], off
	v_lshl_add_u64 v[212:213], s[22:23], 0, v[134:135]
	s_add_i32 m0, s35, 0xe000
	s_nop 0
	global_load_lds_dwordx4 v[212:213], off
	s_waitcnt vmcnt(8)
	s_waitcnt lgkmcnt(0)
	s_barrier
	s_setprio 1
	s_waitcnt lgkmcnt(0)
	v_mfma_f32_16x16x32_bf16 v[124:127], v[140:143], v[180:183], v[124:127]
	v_mfma_f32_16x16x32_bf16 v[120:123], v[156:159], v[180:183], v[120:123]
	v_mfma_f32_16x16x32_bf16 v[108:111], v[140:143], v[188:191], v[108:111]
	v_mfma_f32_16x16x32_bf16 v[104:107], v[156:159], v[188:191], v[104:107]
	v_mfma_f32_16x16x32_bf16 v[92:95], v[140:143], v[196:199], v[92:95]
	v_mfma_f32_16x16x32_bf16 v[88:91], v[156:159], v[196:199], v[88:91]
	v_mfma_f32_16x16x32_bf16 v[76:79], v[140:143], v[204:207], v[76:79]
	v_mfma_f32_16x16x32_bf16 v[72:75], v[156:159], v[204:207], v[72:75]
	v_mfma_f32_16x16x32_bf16 v[124:127], v[152:155], v[184:187], v[124:127]
	v_mfma_f32_16x16x32_bf16 v[120:123], v[160:163], v[184:187], v[120:123]
	v_mfma_f32_16x16x32_bf16 v[108:111], v[152:155], v[192:195], v[108:111]
	v_mfma_f32_16x16x32_bf16 v[104:107], v[160:163], v[192:195], v[104:107]
	v_mfma_f32_16x16x32_bf16 v[92:95], v[152:155], v[200:203], v[92:95]
	v_mfma_f32_16x16x32_bf16 v[88:91], v[160:163], v[200:203], v[88:91]
	v_mfma_f32_16x16x32_bf16 v[76:79], v[152:155], v[208:211], v[76:79]
	v_mfma_f32_16x16x32_bf16 v[72:75], v[160:163], v[208:211], v[72:75]
	s_setprio 0
	s_setprio 1
	v_mfma_f32_16x16x32_bf16 v[116:119], v[164:167], v[180:183], v[116:119]
	v_mfma_f32_16x16x32_bf16 v[112:115], v[172:175], v[180:183], v[112:115]
	v_mfma_f32_16x16x32_bf16 v[100:103], v[164:167], v[188:191], v[100:103]
	v_mfma_f32_16x16x32_bf16 v[96:99], v[172:175], v[188:191], v[96:99]
	v_mfma_f32_16x16x32_bf16 v[84:87], v[164:167], v[196:199], v[84:87]
	v_mfma_f32_16x16x32_bf16 v[80:83], v[172:175], v[196:199], v[80:83]
	v_mfma_f32_16x16x32_bf16 v[68:71], v[164:167], v[204:207], v[68:71]
	v_mfma_f32_16x16x32_bf16 v[64:67], v[172:175], v[204:207], v[64:67]
	v_mfma_f32_16x16x32_bf16 v[116:119], v[168:171], v[184:187], v[116:119]
	v_mfma_f32_16x16x32_bf16 v[112:115], v[176:179], v[184:187], v[112:115]
	v_mfma_f32_16x16x32_bf16 v[100:103], v[168:171], v[192:195], v[100:103]
	v_mfma_f32_16x16x32_bf16 v[96:99], v[176:179], v[192:195], v[96:99]
	v_mfma_f32_16x16x32_bf16 v[84:87], v[168:171], v[200:203], v[84:87]
	v_mfma_f32_16x16x32_bf16 v[80:83], v[176:179], v[200:203], v[80:83]
	v_mfma_f32_16x16x32_bf16 v[68:71], v[168:171], v[208:211], v[68:71]
	v_mfma_f32_16x16x32_bf16 v[64:67], v[176:179], v[208:211], v[64:67]
	s_setprio 0
	s_barrier
	s_add_i32 s22, s44, s34
	v_lshl_add_u64 v[212:213], s[26:27], 0, v[128:129]
	s_mov_b32 m0, s22
	ds_read_b128 v[180:183], v149 offset:16384
	ds_read_b128 v[184:187], v149 offset:17408
	ds_read_b128 v[188:191], v149 offset:18432
	ds_read_b128 v[192:195], v149 offset:19456
	ds_read_b128 v[196:199], v149 offset:20480
	ds_read_b128 v[200:203], v149 offset:21504
	ds_read_b128 v[204:207], v149 offset:22528
	ds_read_b128 v[208:211], v149 offset:23552
	global_load_lds_dwordx4 v[212:213], off
	s_add_i32 m0, s22, 0x2000
	s_add_u32 s22, s26, 0xb0000
	v_lshl_add_u64 v[214:215], s[26:27], 0, v[130:131]
	s_addc_u32 s23, s27, 0
	s_add_i32 s53, s45, s34
	global_load_lds_dwordx4 v[214:215], off
	v_lshl_add_u64 v[216:217], s[22:23], 0, v[128:129]
	s_mov_b32 m0, s53
	v_lshl_add_u64 v[218:219], s[28:29], 0, v[130:131]
	global_load_lds_dwordx4 v[216:217], off
	s_add_i32 m0, s53, 0x2000
	s_nop 0
	global_load_lds_dwordx4 v130, s[22:23]
	v_lshl_add_u64 v[216:217], s[28:29], 0, v[128:129]
	s_mov_b32 m0, s35
	s_nop 0
	global_load_lds_dwordx4 v[216:217], off
	s_mov_b32 m0, s36
	s_nop 0
	global_load_lds_dwordx4 v[218:219], off
	s_waitcnt vmcnt(8)
	s_waitcnt lgkmcnt(0)
	s_barrier
	s_setprio 1
	s_waitcnt lgkmcnt(0)
	v_mfma_f32_16x16x32_bf16 v[60:63], v[140:143], v[180:183], v[60:63]
	v_mfma_f32_16x16x32_bf16 v[56:59], v[156:159], v[180:183], v[56:59]
	v_mfma_f32_16x16x32_bf16 v[44:47], v[140:143], v[188:191], v[44:47]
	v_mfma_f32_16x16x32_bf16 v[40:43], v[156:159], v[188:191], v[40:43]
	v_mfma_f32_16x16x32_bf16 v[28:31], v[140:143], v[196:199], v[28:31]
	v_mfma_f32_16x16x32_bf16 v[24:27], v[156:159], v[196:199], v[24:27]
	v_mfma_f32_16x16x32_bf16 v[12:15], v[140:143], v[204:207], v[12:15]
	v_mfma_f32_16x16x32_bf16 v[8:11], v[156:159], v[204:207], v[8:11]
	v_mfma_f32_16x16x32_bf16 v[60:63], v[152:155], v[184:187], v[60:63]
	v_mfma_f32_16x16x32_bf16 v[56:59], v[160:163], v[184:187], v[56:59]
	v_mfma_f32_16x16x32_bf16 v[44:47], v[152:155], v[192:195], v[44:47]
	v_mfma_f32_16x16x32_bf16 v[40:43], v[160:163], v[192:195], v[40:43]
	v_mfma_f32_16x16x32_bf16 v[28:31], v[152:155], v[200:203], v[28:31]
	v_mfma_f32_16x16x32_bf16 v[24:27], v[160:163], v[200:203], v[24:27]
	v_mfma_f32_16x16x32_bf16 v[12:15], v[152:155], v[208:211], v[12:15]
	v_mfma_f32_16x16x32_bf16 v[8:11], v[160:163], v[208:211], v[8:11]
	s_setprio 0
	s_setprio 1
	v_mfma_f32_16x16x32_bf16 v[52:55], v[164:167], v[180:183], v[52:55]
	v_mfma_f32_16x16x32_bf16 v[48:51], v[172:175], v[180:183], v[48:51]
	v_mfma_f32_16x16x32_bf16 v[36:39], v[164:167], v[188:191], v[36:39]
	v_mfma_f32_16x16x32_bf16 v[32:35], v[172:175], v[188:191], v[32:35]
	v_mfma_f32_16x16x32_bf16 v[20:23], v[164:167], v[196:199], v[20:23]
	v_mfma_f32_16x16x32_bf16 v[16:19], v[172:175], v[196:199], v[16:19]
	v_mfma_f32_16x16x32_bf16 v[4:7], v[164:167], v[204:207], v[4:7]
	v_mfma_f32_16x16x32_bf16 v[0:3], v[172:175], v[204:207], v[0:3]
	v_mfma_f32_16x16x32_bf16 v[52:55], v[168:171], v[184:187], v[52:55]
	v_mfma_f32_16x16x32_bf16 v[48:51], v[176:179], v[184:187], v[48:51]
	v_mfma_f32_16x16x32_bf16 v[36:39], v[168:171], v[192:195], v[36:39]
	v_mfma_f32_16x16x32_bf16 v[32:35], v[176:179], v[192:195], v[32:35]
	v_mfma_f32_16x16x32_bf16 v[20:23], v[168:171], v[200:203], v[20:23]
	v_mfma_f32_16x16x32_bf16 v[16:19], v[176:179], v[200:203], v[16:19]
	v_mfma_f32_16x16x32_bf16 v[4:7], v[168:171], v[208:211], v[4:7]
	v_mfma_f32_16x16x32_bf16 v[0:3], v[176:179], v[208:211], v[0:3]
	s_setprio 0
	s_barrier
	s_add_i32 s53, 0, 0x18000
	v_add_u32_e32 v151, s53, v145
	s_add_i32 s54, 0, 0x1c000
	ds_read_b128 v[140:143], v151
	ds_read_b128 v[152:155], v151 offset:1024
	ds_read_b128 v[156:159], v151 offset:2048
	ds_read_b128 v[160:163], v151 offset:3072
	v_add_u32_e32 v151, s54, v145
	ds_read_b128 v[164:167], v151
	ds_read_b128 v[168:171], v151 offset:1024
	ds_read_b128 v[172:175], v151 offset:2048
	ds_read_b128 v[176:179], v151 offset:3072
	s_add_u32 s22, s28, 0xb0000
	s_addc_u32 s23, s29, 0
	s_mov_b32 m0, s37
	v_lshl_add_u64 v[220:221], s[22:23], 0, v[128:129]
	ds_read_b128 v[180:183], v149 offset:32768
	ds_read_b128 v[184:187], v149 offset:33792
	ds_read_b128 v[188:191], v149 offset:34816
	ds_read_b128 v[192:195], v149 offset:35840
	ds_read_b128 v[196:199], v149 offset:36864
	ds_read_b128 v[200:203], v149 offset:37888
	ds_read_b128 v[204:207], v149 offset:38912
	ds_read_b128 v[208:211], v149 offset:39936
	global_load_lds_dwordx4 v[220:221], off
	v_lshl_add_u64 v[220:221], s[22:23], 0, v[130:131]
	s_mov_b32 m0, s38
	s_nop 0
	global_load_lds_dwordx4 v[220:221], off
	s_waitcnt vmcnt(8)
	s_waitcnt lgkmcnt(0)
	s_barrier
	s_setprio 1
	s_waitcnt lgkmcnt(0)
	v_mfma_f32_16x16x32_bf16 v[124:127], v[140:143], v[180:183], v[124:127]
	v_mfma_f32_16x16x32_bf16 v[120:123], v[156:159], v[180:183], v[120:123]
	v_mfma_f32_16x16x32_bf16 v[108:111], v[140:143], v[188:191], v[108:111]
	v_mfma_f32_16x16x32_bf16 v[104:107], v[156:159], v[188:191], v[104:107]
	v_mfma_f32_16x16x32_bf16 v[92:95], v[140:143], v[196:199], v[92:95]
	v_mfma_f32_16x16x32_bf16 v[88:91], v[156:159], v[196:199], v[88:91]
	v_mfma_f32_16x16x32_bf16 v[76:79], v[140:143], v[204:207], v[76:79]
	v_mfma_f32_16x16x32_bf16 v[72:75], v[156:159], v[204:207], v[72:75]
	v_mfma_f32_16x16x32_bf16 v[124:127], v[152:155], v[184:187], v[124:127]
	v_mfma_f32_16x16x32_bf16 v[120:123], v[160:163], v[184:187], v[120:123]
	v_mfma_f32_16x16x32_bf16 v[108:111], v[152:155], v[192:195], v[108:111]
	v_mfma_f32_16x16x32_bf16 v[104:107], v[160:163], v[192:195], v[104:107]
	v_mfma_f32_16x16x32_bf16 v[92:95], v[152:155], v[200:203], v[92:95]
	v_mfma_f32_16x16x32_bf16 v[88:91], v[160:163], v[200:203], v[88:91]
	v_mfma_f32_16x16x32_bf16 v[76:79], v[152:155], v[208:211], v[76:79]
	v_mfma_f32_16x16x32_bf16 v[72:75], v[160:163], v[208:211], v[72:75]
	s_setprio 0
	s_setprio 1
	v_mfma_f32_16x16x32_bf16 v[116:119], v[164:167], v[180:183], v[116:119]
	v_mfma_f32_16x16x32_bf16 v[112:115], v[172:175], v[180:183], v[112:115]
	v_mfma_f32_16x16x32_bf16 v[100:103], v[164:167], v[188:191], v[100:103]
	v_mfma_f32_16x16x32_bf16 v[96:99], v[172:175], v[188:191], v[96:99]
	v_mfma_f32_16x16x32_bf16 v[84:87], v[164:167], v[196:199], v[84:87]
	v_mfma_f32_16x16x32_bf16 v[80:83], v[172:175], v[196:199], v[80:83]
	v_mfma_f32_16x16x32_bf16 v[68:71], v[164:167], v[204:207], v[68:71]
	v_mfma_f32_16x16x32_bf16 v[64:67], v[172:175], v[204:207], v[64:67]
	v_mfma_f32_16x16x32_bf16 v[116:119], v[168:171], v[184:187], v[116:119]
	v_mfma_f32_16x16x32_bf16 v[112:115], v[176:179], v[184:187], v[112:115]
	v_mfma_f32_16x16x32_bf16 v[100:103], v[168:171], v[192:195], v[100:103]
	v_mfma_f32_16x16x32_bf16 v[96:99], v[176:179], v[192:195], v[96:99]
	v_mfma_f32_16x16x32_bf16 v[84:87], v[168:171], v[200:203], v[84:87]
	v_mfma_f32_16x16x32_bf16 v[80:83], v[176:179], v[200:203], v[80:83]
	v_mfma_f32_16x16x32_bf16 v[68:71], v[168:171], v[208:211], v[68:71]
	v_mfma_f32_16x16x32_bf16 v[64:67], v[176:179], v[208:211], v[64:67]
	s_setprio 0
	s_barrier
	s_add_i32 s22, s53, s34
	v_lshl_add_u64 v[212:213], v[212:213], 0, s[16:17]
	s_mov_b32 m0, s22
	ds_read_b128 v[180:183], v149 offset:49152
	ds_read_b128 v[184:187], v149 offset:50176
	ds_read_b128 v[188:191], v149 offset:51200
	ds_read_b128 v[192:195], v149 offset:52224
	ds_read_b128 v[196:199], v149 offset:53248
	ds_read_b128 v[200:203], v149 offset:54272
	ds_read_b128 v[204:207], v149 offset:55296
	ds_read_b128 v[208:211], v149 offset:56320
	global_load_lds_dwordx4 v[212:213], off
	s_add_i32 m0, s22, 0x2000
	s_add_u32 s22, s26, 0xb0080
	v_lshl_add_u64 v[212:213], v[214:215], 0, s[16:17]
	s_addc_u32 s23, s27, 0
	s_add_i32 s26, s54, s34
	global_load_lds_dwordx4 v[212:213], off
	v_lshl_add_u64 v[212:213], s[22:23], 0, v[128:129]
	s_mov_b32 m0, s26
	s_nop 0
	global_load_lds_dwordx4 v[212:213], off
	s_add_i32 m0, s26, 0x2000
	s_nop 0
	global_load_lds_dwordx4 v130, s[22:23]
	v_lshl_add_u64 v[212:213], v[216:217], 0, s[16:17]
	s_mov_b32 m0, s40
	s_nop 0
	global_load_lds_dwordx4 v[212:213], off
	v_lshl_add_u64 v[212:213], v[218:219], 0, s[16:17]
	s_mov_b32 m0, s41
	s_nop 0
	global_load_lds_dwordx4 v[212:213], off
	s_waitcnt vmcnt(8)
	s_waitcnt lgkmcnt(0)
	s_barrier
	s_setprio 1
	s_waitcnt lgkmcnt(0)
	v_mfma_f32_16x16x32_bf16 v[60:63], v[140:143], v[180:183], v[60:63]
	v_mfma_f32_16x16x32_bf16 v[56:59], v[156:159], v[180:183], v[56:59]
	v_mfma_f32_16x16x32_bf16 v[44:47], v[140:143], v[188:191], v[44:47]
	v_mfma_f32_16x16x32_bf16 v[40:43], v[156:159], v[188:191], v[40:43]
	v_mfma_f32_16x16x32_bf16 v[28:31], v[140:143], v[196:199], v[28:31]
	v_mfma_f32_16x16x32_bf16 v[24:27], v[156:159], v[196:199], v[24:27]
	v_mfma_f32_16x16x32_bf16 v[12:15], v[140:143], v[204:207], v[12:15]
	v_mfma_f32_16x16x32_bf16 v[8:11], v[156:159], v[204:207], v[8:11]
	v_mfma_f32_16x16x32_bf16 v[60:63], v[152:155], v[184:187], v[60:63]
	v_mfma_f32_16x16x32_bf16 v[56:59], v[160:163], v[184:187], v[56:59]
	v_mfma_f32_16x16x32_bf16 v[44:47], v[152:155], v[192:195], v[44:47]
	v_mfma_f32_16x16x32_bf16 v[40:43], v[160:163], v[192:195], v[40:43]
	v_mfma_f32_16x16x32_bf16 v[28:31], v[152:155], v[200:203], v[28:31]
	v_mfma_f32_16x16x32_bf16 v[24:27], v[160:163], v[200:203], v[24:27]
	v_mfma_f32_16x16x32_bf16 v[12:15], v[152:155], v[208:211], v[12:15]
	v_mfma_f32_16x16x32_bf16 v[8:11], v[160:163], v[208:211], v[8:11]
	s_setprio 0
	s_setprio 1
	v_mfma_f32_16x16x32_bf16 v[52:55], v[164:167], v[180:183], v[52:55]
	v_mfma_f32_16x16x32_bf16 v[48:51], v[172:175], v[180:183], v[48:51]
	v_mfma_f32_16x16x32_bf16 v[36:39], v[164:167], v[188:191], v[36:39]
	v_mfma_f32_16x16x32_bf16 v[32:35], v[172:175], v[188:191], v[32:35]
	v_mfma_f32_16x16x32_bf16 v[20:23], v[164:167], v[196:199], v[20:23]
	v_mfma_f32_16x16x32_bf16 v[16:19], v[172:175], v[196:199], v[16:19]
	v_mfma_f32_16x16x32_bf16 v[4:7], v[164:167], v[204:207], v[4:7]
	v_mfma_f32_16x16x32_bf16 v[0:3], v[172:175], v[204:207], v[0:3]
	v_mfma_f32_16x16x32_bf16 v[52:55], v[168:171], v[184:187], v[52:55]
	v_mfma_f32_16x16x32_bf16 v[48:51], v[176:179], v[184:187], v[48:51]
	v_mfma_f32_16x16x32_bf16 v[36:39], v[168:171], v[192:195], v[36:39]
	v_mfma_f32_16x16x32_bf16 v[32:35], v[176:179], v[192:195], v[32:35]
	v_mfma_f32_16x16x32_bf16 v[20:23], v[168:171], v[200:203], v[20:23]
	v_mfma_f32_16x16x32_bf16 v[16:19], v[176:179], v[200:203], v[16:19]
	v_mfma_f32_16x16x32_bf16 v[4:7], v[168:171], v[208:211], v[4:7]
	v_mfma_f32_16x16x32_bf16 v[0:3], v[176:179], v[208:211], v[0:3]
	s_setprio 0
	s_barrier
	s_add_i32 s52, s52, 2
	s_add_u32 s50, s50, 0x100
	s_addc_u32 s51, s51, 0
	s_cmp_gt_u32 s52, 41
	s_mov_b64 s[22:23], s[24:25]
	s_cbranch_scc0 .LBB0_1065
	s_and_b64 vcc, exec, s[18:19]
	s_cbranch_vccz .LBB0_1068
	s_barrier

.LBB0_1125:
	s_mov_b64 s[12:13], 0x80
	s_and_b32 s8, s2, 3
	s_add_i32 m0, s43, 0x18000
	v_lshl_add_u64 v[6:7], v[6:7], 0, s[12:13]
	s_lshl_b32 s2, s3, 13
	s_lshl_b32 s20, s8, 5
	s_lshl_b32 s5, s8, 12
	s_waitcnt vmcnt(2)
	s_barrier
	global_load_lds_dwordx4 v[6:7], off
	v_lshl_add_u64 v[4:5], v[4:5], 0, s[12:13]
	s_add_i32 m0, s43, 0x1a000
	s_add_i32 s47, s43, 0x8000
	s_add_i32 s48, s43, 0xa000
	global_load_lds_dwordx4 v[4:5], off
	v_lshl_add_u64 v[0:1], v[0:1], 0, s[12:13]
	s_mov_b32 m0, s47
	s_add_u32 s14, s36, 0x40080
	global_load_lds_dwordx4 v[0:1], off
	v_lshl_add_u64 v[0:1], v[2:3], 0, s[12:13]
	s_mov_b32 m0, s48
	s_addc_u32 s15, s37, 0
	global_load_lds_dwordx4 v[0:1], off
	s_add_i32 m0, s43, 0x1c000
	s_nop 0
	global_load_lds_dwordx4 v130, s[14:15]
	v_lshl_add_u64 v[0:1], s[14:15], 0, v[134:135]
	s_add_i32 m0, s43, 0x1e000
	v_bfe_u32 v3, v8, 4, 2
	global_load_lds_dwordx4 v[0:1], off
	v_and_b32_e32 v1, 15, v8
	v_lshlrev_b32_e32 v2, 4, v3
	v_lshlrev_b32_e32 v4, 2, v8
	s_cmpk_lt_u32 s4, 0x100
	v_lshl_or_b32 v158, s3, 6, v1
	v_lshl_or_b32 v1, v1, 6, v2
	v_and_b32_e32 v4, 32, v4
	s_cselect_b64 s[14:15], -1, 0
	s_cmp_eq_u32 s8, 0
	v_lshlrev_b32_e32 v0, 3, v3
	v_bitop3_b32 v6, v1, s2, v4 bitop3:0xde
	s_cselect_b64 s[16:17], -1, 0
	v_cmp_eq_u32_e64 s[2:3], 0, v3
	s_ashr_i32 s49, s96, 31
	s_ashr_i32 s50, s33, 31
	v_lshlrev_b32_e32 v136, 5, v3
	s_lshl_b32 s4, s8, 2
	v_mov_b32_e32 v3, v137
	v_bitop3_b32 v159, v1, s5, v4 bitop3:0xde
	s_add_u32 s18, s82, s4
	v_lshl_add_u64 v[4:5], s[70:71], 0, v[2:3]
	s_mov_b64 s[4:5], 0x15c00000
	s_addc_u32 s19, s83, 0
	v_lshl_add_u64 v[142:143], v[4:5], 0, s[4:5]
	s_lshl_b32 s4, s8, 6
	s_add_u32 s4, s70, s4
	s_addc_u32 s5, s71, 0
	v_lshlrev_b32_e32 v1, 14, v9
	v_lshl_add_u64 v[2:3], s[4:5], 0, v[2:3]
	s_mov_b64 s[4:5], 0x14c00000
	v_and_b32_e32 v1, 0xffff8000, v1
	v_lshl_add_u64 v[144:145], v[2:3], 0, s[4:5]
	v_lshl_add_u32 v1, v10, 11, v1
	v_and_b32_e32 v2, 1, v9
	v_lshl_or_b32 v1, v2, 6, v1
	v_lshl_add_u32 v146, v11, 1, v1
	v_lshlrev_b32_e32 v1, 14, v12
	v_and_b32_e32 v1, 0xffff8000, v1
	s_waitcnt vmcnt(6)
	v_lshl_add_u32 v1, v13, 11, v1
	v_and_b32_e32 v2, 1, v12
	v_lshl_add_u64 v[138:139], s[78:79], 0, v[136:137]
	v_lshl_add_u64 v[140:141], s[80:81], 0, v[136:137]
	v_lshl_or_b32 v1, v2, 6, v1
	s_add_i32 s52, 0, 0x10000
	s_add_i32 s53, 0, 0x14000
	v_lshlrev_b32_e32 v136, 1, v0
	v_mbcnt_lo_u32_b32 v0, -1, 0
	v_mov_b32_e32 v147, v137
	v_lshl_add_u32 v148, v14, 1, v1
	v_mov_b32_e32 v149, v137
	v_mov_b64_e32 v[150:151], 0xc00
	v_mov_b64_e32 v[152:153], 0xbff
	s_movk_i32 s51, 0x181
	v_add_u32_e32 v160, s52, v159
	v_add_u32_e32 v161, s53, v159
	v_add_u32_e32 v162, 0, v6
	v_mov_b32_e32 v163, 0x358637bd
	s_movk_i32 s54, 0x1600
	s_lshl_b32 s8, s20, 1
	v_mbcnt_hi_u32_b32 v164, -1, v0
	s_mov_b32 s55, s9
	s_barrier
	s_branch .LBB0_1128

.LBB0_1131:
	ds_read_b128 v[154:157], v160
	ds_read_b128 v[166:169], v160 offset:1024
	ds_read_b128 v[170:173], v160 offset:2048
	ds_read_b128 v[174:177], v160 offset:3072
	ds_read_b128 v[178:181], v161
	ds_read_b128 v[182:185], v161 offset:1024
	ds_read_b128 v[186:189], v161 offset:2048
	ds_read_b128 v[190:193], v161 offset:3072
	s_add_u32 s36, s34, 0xfffc0080
	s_addc_u32 s37, s35, -1
	s_cmp_eq_u32 s58, 12
	s_cselect_b32 s39, s23, s37
	s_cselect_b32 s38, s29, s36
	s_cselect_b32 s37, s21, s57
	s_cselect_b32 s36, s31, s56
	s_add_i32 m0, s43, 0xc000
	ds_read_b128 v[194:197], v162
	ds_read_b128 v[198:201], v162 offset:1024
	ds_read_b128 v[202:205], v162 offset:2048
	ds_read_b128 v[206:209], v162 offset:3072
	ds_read_b128 v[210:213], v162 offset:4096
	ds_read_b128 v[214:217], v162 offset:5120
	ds_read_b128 v[218:221], v162 offset:6144
	ds_read_b128 v[222:225], v162 offset:7168
	global_load_lds_dwordx4 v146, s[34:35]
	s_add_i32 m0, s43, 0xe000
	s_nop 0
	global_load_lds_dwordx4 v148, s[34:35]
	s_waitcnt vmcnt(8)
	s_waitcnt lgkmcnt(0)
	s_barrier
	s_setprio 1
	s_waitcnt lgkmcnt(0)
	v_mfma_f32_16x16x32_bf16 v[116:119], v[154:157], v[194:197], v[116:119]
	v_mfma_f32_16x16x32_bf16 v[112:115], v[170:173], v[194:197], v[112:115]
	v_mfma_f32_16x16x32_bf16 v[100:103], v[154:157], v[202:205], v[100:103]
	v_mfma_f32_16x16x32_bf16 v[96:99], v[170:173], v[202:205], v[96:99]
	v_mfma_f32_16x16x32_bf16 v[88:91], v[154:157], v[210:213], v[88:91]
	v_mfma_f32_16x16x32_bf16 v[84:87], v[170:173], v[210:213], v[84:87]
	v_mfma_f32_16x16x32_bf16 v[72:75], v[154:157], v[218:221], v[72:75]
	v_mfma_f32_16x16x32_bf16 v[68:71], v[170:173], v[218:221], v[68:71]
	v_mfma_f32_16x16x32_bf16 v[116:119], v[166:169], v[198:201], v[116:119]
	v_mfma_f32_16x16x32_bf16 v[112:115], v[174:177], v[198:201], v[112:115]
	v_mfma_f32_16x16x32_bf16 v[100:103], v[166:169], v[206:209], v[100:103]
	v_mfma_f32_16x16x32_bf16 v[96:99], v[174:177], v[206:209], v[96:99]
	v_mfma_f32_16x16x32_bf16 v[88:91], v[166:169], v[214:217], v[88:91]
	v_mfma_f32_16x16x32_bf16 v[84:87], v[174:177], v[214:217], v[84:87]
	v_mfma_f32_16x16x32_bf16 v[72:75], v[166:169], v[222:225], v[72:75]
	v_mfma_f32_16x16x32_bf16 v[68:71], v[174:177], v[222:225], v[68:71]
	s_setprio 0
	s_setprio 1
	v_mfma_f32_16x16x32_bf16 v[124:127], v[178:181], v[194:197], v[124:127]
	v_mfma_f32_16x16x32_bf16 v[120:123], v[186:189], v[194:197], v[120:123]
	v_mfma_f32_16x16x32_bf16 v[108:111], v[178:181], v[202:205], v[108:111]
	v_mfma_f32_16x16x32_bf16 v[104:107], v[186:189], v[202:205], v[104:107]
	v_mfma_f32_16x16x32_bf16 v[92:95], v[178:181], v[210:213], v[92:95]
	v_mfma_f32_16x16x32_bf16 v[80:83], v[186:189], v[210:213], v[80:83]
	v_mfma_f32_16x16x32_bf16 v[76:79], v[178:181], v[218:221], v[76:79]
	v_mfma_f32_16x16x32_bf16 v[64:67], v[186:189], v[218:221], v[64:67]
	v_mfma_f32_16x16x32_bf16 v[124:127], v[182:185], v[198:201], v[124:127]
	v_mfma_f32_16x16x32_bf16 v[120:123], v[190:193], v[198:201], v[120:123]
	v_mfma_f32_16x16x32_bf16 v[108:111], v[182:185], v[206:209], v[108:111]
	v_mfma_f32_16x16x32_bf16 v[104:107], v[190:193], v[206:209], v[104:107]
	v_mfma_f32_16x16x32_bf16 v[92:95], v[182:185], v[214:217], v[92:95]
	v_mfma_f32_16x16x32_bf16 v[80:83], v[190:193], v[214:217], v[80:83]
	v_mfma_f32_16x16x32_bf16 v[76:79], v[182:185], v[222:225], v[76:79]
	v_mfma_f32_16x16x32_bf16 v[64:67], v[190:193], v[222:225], v[64:67]
	s_setprio 0
	s_barrier
	s_add_i32 s59, s52, s42
	v_lshl_add_u64 v[226:227], s[36:37], 0, v[130:131]
	s_mov_b32 m0, s59
	ds_read_b128 v[194:197], v162 offset:16384
	ds_read_b128 v[198:201], v162 offset:17408
	ds_read_b128 v[202:205], v162 offset:18432
	ds_read_b128 v[206:209], v162 offset:19456
	ds_read_b128 v[210:213], v162 offset:20480
	ds_read_b128 v[214:217], v162 offset:21504
	ds_read_b128 v[218:221], v162 offset:22528
	ds_read_b128 v[222:225], v162 offset:23552
	global_load_lds_dwordx4 v[226:227], off
	s_add_i32 m0, s59, 0x2000
	s_add_u32 s60, s36, 0x40000
	v_lshl_add_u64 v[228:229], s[36:37], 0, v[134:135]
	s_addc_u32 s61, s37, 0
	s_add_i32 s59, s53, s42
	global_load_lds_dwordx4 v[228:229], off
	s_mov_b32 m0, s59
	v_lshl_add_u64 v[232:233], s[38:39], 0, v[132:133]
	global_load_lds_dwordx4 v130, s[60:61]
	s_add_i32 m0, s59, 0x2000
	s_nop 0
	global_load_lds_dwordx4 v134, s[60:61]
	v_lshl_add_u64 v[230:231], s[38:39], 0, v[128:129]
	s_mov_b32 m0, s43
	s_nop 0
	global_load_lds_dwordx4 v[230:231], off
	s_mov_b32 m0, s44
	s_nop 0
	global_load_lds_dwordx4 v[232:233], off
	s_waitcnt vmcnt(8)
	s_waitcnt lgkmcnt(0)
	s_barrier
	s_setprio 1
	s_waitcnt lgkmcnt(0)
	v_mfma_f32_16x16x32_bf16 v[56:59], v[154:157], v[194:197], v[56:59]
	v_mfma_f32_16x16x32_bf16 v[52:55], v[170:173], v[194:197], v[52:55]
	v_mfma_f32_16x16x32_bf16 v[40:43], v[154:157], v[202:205], v[40:43]
	v_mfma_f32_16x16x32_bf16 v[36:39], v[170:173], v[202:205], v[36:39]
	v_mfma_f32_16x16x32_bf16 v[24:27], v[154:157], v[210:213], v[24:27]
	v_mfma_f32_16x16x32_bf16 v[20:23], v[170:173], v[210:213], v[20:23]
	v_mfma_f32_16x16x32_bf16 v[8:11], v[154:157], v[218:221], v[8:11]
	v_mfma_f32_16x16x32_bf16 v[4:7], v[170:173], v[218:221], v[4:7]
	v_mfma_f32_16x16x32_bf16 v[56:59], v[166:169], v[198:201], v[56:59]
	v_mfma_f32_16x16x32_bf16 v[52:55], v[174:177], v[198:201], v[52:55]
	v_mfma_f32_16x16x32_bf16 v[40:43], v[166:169], v[206:209], v[40:43]
	v_mfma_f32_16x16x32_bf16 v[36:39], v[174:177], v[206:209], v[36:39]
	v_mfma_f32_16x16x32_bf16 v[24:27], v[166:169], v[214:217], v[24:27]
	v_mfma_f32_16x16x32_bf16 v[20:23], v[174:177], v[214:217], v[20:23]
	v_mfma_f32_16x16x32_bf16 v[8:11], v[166:169], v[222:225], v[8:11]
	v_mfma_f32_16x16x32_bf16 v[4:7], v[174:177], v[222:225], v[4:7]
	s_setprio 0
	s_setprio 1
	v_mfma_f32_16x16x32_bf16 v[60:63], v[178:181], v[194:197], v[60:63]
	v_mfma_f32_16x16x32_bf16 v[48:51], v[186:189], v[194:197], v[48:51]
	v_mfma_f32_16x16x32_bf16 v[44:47], v[178:181], v[202:205], v[44:47]
	v_mfma_f32_16x16x32_bf16 v[32:35], v[186:189], v[202:205], v[32:35]
	v_mfma_f32_16x16x32_bf16 v[28:31], v[178:181], v[210:213], v[28:31]
	v_mfma_f32_16x16x32_bf16 v[16:19], v[186:189], v[210:213], v[16:19]
	v_mfma_f32_16x16x32_bf16 v[12:15], v[178:181], v[218:221], v[12:15]
	v_mfma_f32_16x16x32_bf16 v[0:3], v[186:189], v[218:221], v[0:3]
	v_mfma_f32_16x16x32_bf16 v[60:63], v[182:185], v[198:201], v[60:63]
	v_mfma_f32_16x16x32_bf16 v[48:51], v[190:193], v[198:201], v[48:51]
	v_mfma_f32_16x16x32_bf16 v[44:47], v[182:185], v[206:209], v[44:47]
	v_mfma_f32_16x16x32_bf16 v[32:35], v[190:193], v[206:209], v[32:35]
	v_mfma_f32_16x16x32_bf16 v[28:31], v[182:185], v[214:217], v[28:31]
	v_mfma_f32_16x16x32_bf16 v[16:19], v[190:193], v[214:217], v[16:19]
	v_mfma_f32_16x16x32_bf16 v[12:15], v[182:185], v[222:225], v[12:15]
	v_mfma_f32_16x16x32_bf16 v[0:3], v[190:193], v[222:225], v[0:3]
	s_setprio 0
	s_barrier
	s_add_i32 s59, 0, 0x18000
	v_add_u32_e32 v165, s59, v159
	s_add_i32 s60, 0, 0x1c000
	ds_read_b128 v[154:157], v165
	ds_read_b128 v[166:169], v165 offset:1024
	ds_read_b128 v[170:173], v165 offset:2048
	ds_read_b128 v[174:177], v165 offset:3072
	v_add_u32_e32 v165, s60, v159
	ds_read_b128 v[178:181], v165
	ds_read_b128 v[182:185], v165 offset:1024
	ds_read_b128 v[186:189], v165 offset:2048
	ds_read_b128 v[190:193], v165 offset:3072
	s_add_u32 s38, s38, 0x40000
	s_addc_u32 s39, s39, 0
	s_mov_b32 m0, s45
	ds_read_b128 v[194:197], v162 offset:32768
	ds_read_b128 v[198:201], v162 offset:33792
	ds_read_b128 v[202:205], v162 offset:34816
	ds_read_b128 v[206:209], v162 offset:35840
	ds_read_b128 v[210:213], v162 offset:36864
	ds_read_b128 v[214:217], v162 offset:37888
	ds_read_b128 v[218:221], v162 offset:38912
	ds_read_b128 v[222:225], v162 offset:39936
	global_load_lds_dwordx4 v128, s[38:39]
	v_lshl_add_u64 v[234:235], s[38:39], 0, v[132:133]
	s_mov_b32 m0, s46
	s_nop 0
	global_load_lds_dwordx4 v[234:235], off
	s_waitcnt vmcnt(8)
	s_waitcnt lgkmcnt(0)
	s_barrier
	s_setprio 1
	s_waitcnt lgkmcnt(0)
	v_mfma_f32_16x16x32_bf16 v[116:119], v[154:157], v[194:197], v[116:119]
	v_mfma_f32_16x16x32_bf16 v[112:115], v[170:173], v[194:197], v[112:115]
	v_mfma_f32_16x16x32_bf16 v[100:103], v[154:157], v[202:205], v[100:103]
	v_mfma_f32_16x16x32_bf16 v[96:99], v[170:173], v[202:205], v[96:99]
	v_mfma_f32_16x16x32_bf16 v[88:91], v[154:157], v[210:213], v[88:91]
	v_mfma_f32_16x16x32_bf16 v[84:87], v[170:173], v[210:213], v[84:87]
	v_mfma_f32_16x16x32_bf16 v[72:75], v[154:157], v[218:221], v[72:75]
	v_mfma_f32_16x16x32_bf16 v[68:71], v[170:173], v[218:221], v[68:71]
	v_mfma_f32_16x16x32_bf16 v[116:119], v[166:169], v[198:201], v[116:119]
	v_mfma_f32_16x16x32_bf16 v[112:115], v[174:177], v[198:201], v[112:115]
	v_mfma_f32_16x16x32_bf16 v[100:103], v[166:169], v[206:209], v[100:103]
	v_mfma_f32_16x16x32_bf16 v[96:99], v[174:177], v[206:209], v[96:99]
	v_mfma_f32_16x16x32_bf16 v[88:91], v[166:169], v[214:217], v[88:91]
	v_mfma_f32_16x16x32_bf16 v[84:87], v[174:177], v[214:217], v[84:87]
	v_mfma_f32_16x16x32_bf16 v[72:75], v[166:169], v[222:225], v[72:75]
	v_mfma_f32_16x16x32_bf16 v[68:71], v[174:177], v[222:225], v[68:71]
	s_setprio 0
	s_setprio 1
	v_mfma_f32_16x16x32_bf16 v[124:127], v[178:181], v[194:197], v[124:127]
	v_mfma_f32_16x16x32_bf16 v[120:123], v[186:189], v[194:197], v[120:123]
	v_mfma_f32_16x16x32_bf16 v[108:111], v[178:181], v[202:205], v[108:111]
	v_mfma_f32_16x16x32_bf16 v[104:107], v[186:189], v[202:205], v[104:107]
	v_mfma_f32_16x16x32_bf16 v[92:95], v[178:181], v[210:213], v[92:95]
	v_mfma_f32_16x16x32_bf16 v[80:83], v[186:189], v[210:213], v[80:83]
	v_mfma_f32_16x16x32_bf16 v[76:79], v[178:181], v[218:221], v[76:79]
	v_mfma_f32_16x16x32_bf16 v[64:67], v[186:189], v[218:221], v[64:67]
	v_mfma_f32_16x16x32_bf16 v[124:127], v[182:185], v[198:201], v[124:127]
	v_mfma_f32_16x16x32_bf16 v[120:123], v[190:193], v[198:201], v[120:123]
	v_mfma_f32_16x16x32_bf16 v[108:111], v[182:185], v[206:209], v[108:111]
	v_mfma_f32_16x16x32_bf16 v[104:107], v[190:193], v[206:209], v[104:107]
	v_mfma_f32_16x16x32_bf16 v[92:95], v[182:185], v[214:217], v[92:95]
	v_mfma_f32_16x16x32_bf16 v[80:83], v[190:193], v[214:217], v[80:83]
	v_mfma_f32_16x16x32_bf16 v[76:79], v[182:185], v[222:225], v[76:79]
	v_mfma_f32_16x16x32_bf16 v[64:67], v[190:193], v[222:225], v[64:67]
	s_setprio 0
	s_barrier
	s_add_i32 s38, s59, s42
	v_lshl_add_u64 v[226:227], v[226:227], 0, s[12:13]
	s_mov_b32 m0, s38
	ds_read_b128 v[194:197], v162 offset:49152
	ds_read_b128 v[198:201], v162 offset:50176
	ds_read_b128 v[202:205], v162 offset:51200
	ds_read_b128 v[206:209], v162 offset:52224
	ds_read_b128 v[210:213], v162 offset:53248
	ds_read_b128 v[214:217], v162 offset:54272
	ds_read_b128 v[218:221], v162 offset:55296
	ds_read_b128 v[222:225], v162 offset:56320
	global_load_lds_dwordx4 v[226:227], off
	s_add_i32 m0, s38, 0x2000
	s_add_u32 s36, s36, 0x40080
	v_lshl_add_u64 v[226:227], v[228:229], 0, s[12:13]
	s_addc_u32 s37, s37, 0
	s_add_i32 s38, s60, s42
	global_load_lds_dwordx4 v[226:227], off
	s_mov_b32 m0, s38
	s_nop 0
	global_load_lds_dwordx4 v130, s[36:37]
	s_add_i32 m0, s38, 0x2000
	s_nop 0
	global_load_lds_dwordx4 v134, s[36:37]
	v_lshl_add_u64 v[226:227], v[230:231], 0, s[12:13]
	s_mov_b32 m0, s47
	s_nop 0
	global_load_lds_dwordx4 v[226:227], off
	v_lshl_add_u64 v[226:227], v[232:233], 0, s[12:13]
	s_mov_b32 m0, s48
	s_nop 0
	global_load_lds_dwordx4 v[226:227], off
	s_waitcnt vmcnt(8)
	s_waitcnt lgkmcnt(0)
	s_barrier
	s_setprio 1
	s_waitcnt lgkmcnt(0)
	v_mfma_f32_16x16x32_bf16 v[56:59], v[154:157], v[194:197], v[56:59]
	v_mfma_f32_16x16x32_bf16 v[52:55], v[170:173], v[194:197], v[52:55]
	v_mfma_f32_16x16x32_bf16 v[40:43], v[154:157], v[202:205], v[40:43]
	v_mfma_f32_16x16x32_bf16 v[36:39], v[170:173], v[202:205], v[36:39]
	v_mfma_f32_16x16x32_bf16 v[24:27], v[154:157], v[210:213], v[24:27]
	v_mfma_f32_16x16x32_bf16 v[20:23], v[170:173], v[210:213], v[20:23]
	v_mfma_f32_16x16x32_bf16 v[8:11], v[154:157], v[218:221], v[8:11]
	v_mfma_f32_16x16x32_bf16 v[4:7], v[170:173], v[218:221], v[4:7]
	v_mfma_f32_16x16x32_bf16 v[56:59], v[166:169], v[198:201], v[56:59]
	v_mfma_f32_16x16x32_bf16 v[52:55], v[174:177], v[198:201], v[52:55]
	v_mfma_f32_16x16x32_bf16 v[40:43], v[166:169], v[206:209], v[40:43]
	v_mfma_f32_16x16x32_bf16 v[36:39], v[174:177], v[206:209], v[36:39]
	v_mfma_f32_16x16x32_bf16 v[24:27], v[166:169], v[214:217], v[24:27]
	v_mfma_f32_16x16x32_bf16 v[20:23], v[174:177], v[214:217], v[20:23]
	v_mfma_f32_16x16x32_bf16 v[8:11], v[166:169], v[222:225], v[8:11]
	v_mfma_f32_16x16x32_bf16 v[4:7], v[174:177], v[222:225], v[4:7]
	s_setprio 0
	s_setprio 1
	v_mfma_f32_16x16x32_bf16 v[60:63], v[178:181], v[194:197], v[60:63]
	v_mfma_f32_16x16x32_bf16 v[48:51], v[186:189], v[194:197], v[48:51]
	v_mfma_f32_16x16x32_bf16 v[44:47], v[178:181], v[202:205], v[44:47]
	v_mfma_f32_16x16x32_bf16 v[32:35], v[186:189], v[202:205], v[32:35]
	v_mfma_f32_16x16x32_bf16 v[28:31], v[178:181], v[210:213], v[28:31]
	v_mfma_f32_16x16x32_bf16 v[16:19], v[186:189], v[210:213], v[16:19]
	v_mfma_f32_16x16x32_bf16 v[12:15], v[178:181], v[218:221], v[12:15]
	v_mfma_f32_16x16x32_bf16 v[0:3], v[186:189], v[218:221], v[0:3]
	v_mfma_f32_16x16x32_bf16 v[60:63], v[182:185], v[198:201], v[60:63]
	v_mfma_f32_16x16x32_bf16 v[48:51], v[190:193], v[198:201], v[48:51]
	v_mfma_f32_16x16x32_bf16 v[44:47], v[182:185], v[206:209], v[44:47]
	v_mfma_f32_16x16x32_bf16 v[32:35], v[190:193], v[206:209], v[32:35]
	v_mfma_f32_16x16x32_bf16 v[28:31], v[182:185], v[214:217], v[28:31]
	v_mfma_f32_16x16x32_bf16 v[16:19], v[190:193], v[214:217], v[16:19]
	v_mfma_f32_16x16x32_bf16 v[12:15], v[182:185], v[222:225], v[12:15]
	v_mfma_f32_16x16x32_bf16 v[0:3], v[190:193], v[222:225], v[0:3]
	s_setprio 0
	s_barrier
	s_add_i32 s58, s58, 2
	s_add_u32 s34, s34, 0x100
	s_addc_u32 s35, s35, 0
	s_add_u32 s56, s56, 0x100
	s_addc_u32 s57, s57, 0
	s_cmp_gt_u32 s58, 13
	s_cbranch_scc0 .LBB0_1131
	s_and_b64 vcc, exec, s[14:15]
	s_cbranch_vccz .LBB0_1136
	s_barrier
	v_lshl_add_u32 v154, s30, 8, v158
	s_cmp_gt_i32 s28, 21
	s_mov_b64 s[30:31], -1
	s_cbranch_scc1 .LBB0_1137

.LBB0_1219:
	ds_read_b128 v[140:143], v147
	ds_read_b128 v[152:155], v147 offset:1024
	ds_read_b128 v[156:159], v147 offset:2048
	ds_read_b128 v[160:163], v147 offset:3072
	ds_read_b128 v[164:167], v148
	ds_read_b128 v[168:171], v148 offset:1024
	ds_read_b128 v[172:175], v148 offset:2048
	ds_read_b128 v[176:179], v148 offset:3072
	s_add_u32 s26, s24, 0x100
	s_addc_u32 s27, s25, 0
	s_cmp_eq_u32 s54, 40
	s_cselect_b32 s31, s9, s27
	s_cselect_b32 s30, s8, s26
	s_cselect_b32 s29, s23, s53
	s_cselect_b32 s28, s22, s52
	v_lshl_add_u64 v[212:213], s[24:25], 0, v[132:133]
	s_add_i32 m0, s37, 0xc000
	ds_read_b128 v[180:183], v149
	ds_read_b128 v[184:187], v149 offset:1024
	ds_read_b128 v[188:191], v149 offset:2048
	ds_read_b128 v[192:195], v149 offset:3072
	ds_read_b128 v[196:199], v149 offset:4096
	ds_read_b128 v[200:203], v149 offset:5120
	ds_read_b128 v[204:207], v149 offset:6144
	ds_read_b128 v[208:211], v149 offset:7168
	global_load_lds_dwordx4 v[212:213], off
	v_lshl_add_u64 v[212:213], s[24:25], 0, v[134:135]
	s_add_i32 m0, s37, 0xe000
	s_nop 0
	global_load_lds_dwordx4 v[212:213], off
	s_waitcnt vmcnt(8)
	s_waitcnt lgkmcnt(0)
	s_barrier
	s_setprio 1
	s_waitcnt lgkmcnt(0)
	v_mfma_f32_16x16x32_bf16 v[124:127], v[140:143], v[180:183], v[124:127]
	v_mfma_f32_16x16x32_bf16 v[120:123], v[156:159], v[180:183], v[120:123]
	v_mfma_f32_16x16x32_bf16 v[108:111], v[140:143], v[188:191], v[108:111]
	v_mfma_f32_16x16x32_bf16 v[104:107], v[156:159], v[188:191], v[104:107]
	v_mfma_f32_16x16x32_bf16 v[92:95], v[140:143], v[196:199], v[92:95]
	v_mfma_f32_16x16x32_bf16 v[88:91], v[156:159], v[196:199], v[88:91]
	v_mfma_f32_16x16x32_bf16 v[76:79], v[140:143], v[204:207], v[76:79]
	v_mfma_f32_16x16x32_bf16 v[72:75], v[156:159], v[204:207], v[72:75]
	v_mfma_f32_16x16x32_bf16 v[124:127], v[152:155], v[184:187], v[124:127]
	v_mfma_f32_16x16x32_bf16 v[120:123], v[160:163], v[184:187], v[120:123]
	v_mfma_f32_16x16x32_bf16 v[108:111], v[152:155], v[192:195], v[108:111]
	v_mfma_f32_16x16x32_bf16 v[104:107], v[160:163], v[192:195], v[104:107]
	v_mfma_f32_16x16x32_bf16 v[92:95], v[152:155], v[200:203], v[92:95]
	v_mfma_f32_16x16x32_bf16 v[88:91], v[160:163], v[200:203], v[88:91]
	v_mfma_f32_16x16x32_bf16 v[76:79], v[152:155], v[208:211], v[76:79]
	v_mfma_f32_16x16x32_bf16 v[72:75], v[160:163], v[208:211], v[72:75]
	s_setprio 0
	s_setprio 1
	v_mfma_f32_16x16x32_bf16 v[116:119], v[164:167], v[180:183], v[116:119]
	v_mfma_f32_16x16x32_bf16 v[112:115], v[172:175], v[180:183], v[112:115]
	v_mfma_f32_16x16x32_bf16 v[100:103], v[164:167], v[188:191], v[100:103]
	v_mfma_f32_16x16x32_bf16 v[96:99], v[172:175], v[188:191], v[96:99]
	v_mfma_f32_16x16x32_bf16 v[84:87], v[164:167], v[196:199], v[84:87]
	v_mfma_f32_16x16x32_bf16 v[80:83], v[172:175], v[196:199], v[80:83]
	v_mfma_f32_16x16x32_bf16 v[68:71], v[164:167], v[204:207], v[68:71]
	v_mfma_f32_16x16x32_bf16 v[64:67], v[172:175], v[204:207], v[64:67]
	v_mfma_f32_16x16x32_bf16 v[116:119], v[168:171], v[184:187], v[116:119]
	v_mfma_f32_16x16x32_bf16 v[112:115], v[176:179], v[184:187], v[112:115]
	v_mfma_f32_16x16x32_bf16 v[100:103], v[168:171], v[192:195], v[100:103]
	v_mfma_f32_16x16x32_bf16 v[96:99], v[176:179], v[192:195], v[96:99]
	v_mfma_f32_16x16x32_bf16 v[84:87], v[168:171], v[200:203], v[84:87]
	v_mfma_f32_16x16x32_bf16 v[80:83], v[176:179], v[200:203], v[80:83]
	v_mfma_f32_16x16x32_bf16 v[68:71], v[168:171], v[208:211], v[68:71]
	v_mfma_f32_16x16x32_bf16 v[64:67], v[176:179], v[208:211], v[64:67]
	s_setprio 0
	s_barrier
	s_add_i32 s24, s46, s36
	v_lshl_add_u64 v[212:213], s[28:29], 0, v[128:129]
	s_mov_b32 m0, s24
	ds_read_b128 v[180:183], v149 offset:16384
	ds_read_b128 v[184:187], v149 offset:17408
	ds_read_b128 v[188:191], v149 offset:18432
	ds_read_b128 v[192:195], v149 offset:19456
	ds_read_b128 v[196:199], v149 offset:20480
	ds_read_b128 v[200:203], v149 offset:21504
	ds_read_b128 v[204:207], v149 offset:22528
	ds_read_b128 v[208:211], v149 offset:23552
	global_load_lds_dwordx4 v[212:213], off
	s_add_i32 m0, s24, 0x2000
	s_add_u32 s24, s28, 0xb0000
	v_lshl_add_u64 v[214:215], s[28:29], 0, v[130:131]
	s_addc_u32 s25, s29, 0
	s_add_i32 s55, s47, s36
	global_load_lds_dwordx4 v[214:215], off
	v_lshl_add_u64 v[216:217], s[24:25], 0, v[128:129]
	s_mov_b32 m0, s55
	v_lshl_add_u64 v[218:219], s[30:31], 0, v[130:131]
	global_load_lds_dwordx4 v[216:217], off
	s_add_i32 m0, s55, 0x2000
	s_nop 0
	global_load_lds_dwordx4 v130, s[24:25]
	v_lshl_add_u64 v[216:217], s[30:31], 0, v[128:129]
	s_mov_b32 m0, s37
	s_nop 0
	global_load_lds_dwordx4 v[216:217], off
	s_mov_b32 m0, s38
	s_nop 0
	global_load_lds_dwordx4 v[218:219], off
	s_waitcnt vmcnt(8)
	s_waitcnt lgkmcnt(0)
	s_barrier
	s_setprio 1
	s_waitcnt lgkmcnt(0)
	v_mfma_f32_16x16x32_bf16 v[60:63], v[140:143], v[180:183], v[60:63]
	v_mfma_f32_16x16x32_bf16 v[56:59], v[156:159], v[180:183], v[56:59]
	v_mfma_f32_16x16x32_bf16 v[44:47], v[140:143], v[188:191], v[44:47]
	v_mfma_f32_16x16x32_bf16 v[40:43], v[156:159], v[188:191], v[40:43]
	v_mfma_f32_16x16x32_bf16 v[28:31], v[140:143], v[196:199], v[28:31]
	v_mfma_f32_16x16x32_bf16 v[24:27], v[156:159], v[196:199], v[24:27]
	v_mfma_f32_16x16x32_bf16 v[12:15], v[140:143], v[204:207], v[12:15]
	v_mfma_f32_16x16x32_bf16 v[8:11], v[156:159], v[204:207], v[8:11]
	v_mfma_f32_16x16x32_bf16 v[60:63], v[152:155], v[184:187], v[60:63]
	v_mfma_f32_16x16x32_bf16 v[56:59], v[160:163], v[184:187], v[56:59]
	v_mfma_f32_16x16x32_bf16 v[44:47], v[152:155], v[192:195], v[44:47]
	v_mfma_f32_16x16x32_bf16 v[40:43], v[160:163], v[192:195], v[40:43]
	v_mfma_f32_16x16x32_bf16 v[28:31], v[152:155], v[200:203], v[28:31]
	v_mfma_f32_16x16x32_bf16 v[24:27], v[160:163], v[200:203], v[24:27]
	v_mfma_f32_16x16x32_bf16 v[12:15], v[152:155], v[208:211], v[12:15]
	v_mfma_f32_16x16x32_bf16 v[8:11], v[160:163], v[208:211], v[8:11]
	s_setprio 0
	s_setprio 1
	v_mfma_f32_16x16x32_bf16 v[52:55], v[164:167], v[180:183], v[52:55]
	v_mfma_f32_16x16x32_bf16 v[48:51], v[172:175], v[180:183], v[48:51]
	v_mfma_f32_16x16x32_bf16 v[36:39], v[164:167], v[188:191], v[36:39]
	v_mfma_f32_16x16x32_bf16 v[32:35], v[172:175], v[188:191], v[32:35]
	v_mfma_f32_16x16x32_bf16 v[20:23], v[164:167], v[196:199], v[20:23]
	v_mfma_f32_16x16x32_bf16 v[16:19], v[172:175], v[196:199], v[16:19]
	v_mfma_f32_16x16x32_bf16 v[4:7], v[164:167], v[204:207], v[4:7]
	v_mfma_f32_16x16x32_bf16 v[0:3], v[172:175], v[204:207], v[0:3]
	v_mfma_f32_16x16x32_bf16 v[52:55], v[168:171], v[184:187], v[52:55]
	v_mfma_f32_16x16x32_bf16 v[48:51], v[176:179], v[184:187], v[48:51]
	v_mfma_f32_16x16x32_bf16 v[36:39], v[168:171], v[192:195], v[36:39]
	v_mfma_f32_16x16x32_bf16 v[32:35], v[176:179], v[192:195], v[32:35]
	v_mfma_f32_16x16x32_bf16 v[20:23], v[168:171], v[200:203], v[20:23]
	v_mfma_f32_16x16x32_bf16 v[16:19], v[176:179], v[200:203], v[16:19]
	v_mfma_f32_16x16x32_bf16 v[4:7], v[168:171], v[208:211], v[4:7]
	v_mfma_f32_16x16x32_bf16 v[0:3], v[176:179], v[208:211], v[0:3]
	s_setprio 0
	s_barrier
	s_add_i32 s55, 0, 0x18000
	v_add_u32_e32 v151, s55, v145
	s_add_i32 s56, 0, 0x1c000
	ds_read_b128 v[140:143], v151
	ds_read_b128 v[152:155], v151 offset:1024
	ds_read_b128 v[156:159], v151 offset:2048
	ds_read_b128 v[160:163], v151 offset:3072
	v_add_u32_e32 v151, s56, v145
	ds_read_b128 v[164:167], v151
	ds_read_b128 v[168:171], v151 offset:1024
	ds_read_b128 v[172:175], v151 offset:2048
	ds_read_b128 v[176:179], v151 offset:3072
	s_add_u32 s24, s30, 0xb0000
	s_addc_u32 s25, s31, 0
	s_mov_b32 m0, s39
	v_lshl_add_u64 v[220:221], s[24:25], 0, v[128:129]
	ds_read_b128 v[180:183], v149 offset:32768
	ds_read_b128 v[184:187], v149 offset:33792
	ds_read_b128 v[188:191], v149 offset:34816
	ds_read_b128 v[192:195], v149 offset:35840
	ds_read_b128 v[196:199], v149 offset:36864
	ds_read_b128 v[200:203], v149 offset:37888
	ds_read_b128 v[204:207], v149 offset:38912
	ds_read_b128 v[208:211], v149 offset:39936
	global_load_lds_dwordx4 v[220:221], off
	v_lshl_add_u64 v[220:221], s[24:25], 0, v[130:131]
	s_mov_b32 m0, s40
	s_nop 0
	global_load_lds_dwordx4 v[220:221], off
	s_waitcnt vmcnt(8)
	s_waitcnt lgkmcnt(0)
	s_barrier
	s_setprio 1
	s_waitcnt lgkmcnt(0)
	v_mfma_f32_16x16x32_bf16 v[124:127], v[140:143], v[180:183], v[124:127]
	v_mfma_f32_16x16x32_bf16 v[120:123], v[156:159], v[180:183], v[120:123]
	v_mfma_f32_16x16x32_bf16 v[108:111], v[140:143], v[188:191], v[108:111]
	v_mfma_f32_16x16x32_bf16 v[104:107], v[156:159], v[188:191], v[104:107]
	v_mfma_f32_16x16x32_bf16 v[92:95], v[140:143], v[196:199], v[92:95]
	v_mfma_f32_16x16x32_bf16 v[88:91], v[156:159], v[196:199], v[88:91]
	v_mfma_f32_16x16x32_bf16 v[76:79], v[140:143], v[204:207], v[76:79]
	v_mfma_f32_16x16x32_bf16 v[72:75], v[156:159], v[204:207], v[72:75]
	v_mfma_f32_16x16x32_bf16 v[124:127], v[152:155], v[184:187], v[124:127]
	v_mfma_f32_16x16x32_bf16 v[120:123], v[160:163], v[184:187], v[120:123]
	v_mfma_f32_16x16x32_bf16 v[108:111], v[152:155], v[192:195], v[108:111]
	v_mfma_f32_16x16x32_bf16 v[104:107], v[160:163], v[192:195], v[104:107]
	v_mfma_f32_16x16x32_bf16 v[92:95], v[152:155], v[200:203], v[92:95]
	v_mfma_f32_16x16x32_bf16 v[88:91], v[160:163], v[200:203], v[88:91]
	v_mfma_f32_16x16x32_bf16 v[76:79], v[152:155], v[208:211], v[76:79]
	v_mfma_f32_16x16x32_bf16 v[72:75], v[160:163], v[208:211], v[72:75]
	s_setprio 0
	s_setprio 1
	v_mfma_f32_16x16x32_bf16 v[116:119], v[164:167], v[180:183], v[116:119]
	v_mfma_f32_16x16x32_bf16 v[112:115], v[172:175], v[180:183], v[112:115]
	v_mfma_f32_16x16x32_bf16 v[100:103], v[164:167], v[188:191], v[100:103]
	v_mfma_f32_16x16x32_bf16 v[96:99], v[172:175], v[188:191], v[96:99]
	v_mfma_f32_16x16x32_bf16 v[84:87], v[164:167], v[196:199], v[84:87]
	v_mfma_f32_16x16x32_bf16 v[80:83], v[172:175], v[196:199], v[80:83]
	v_mfma_f32_16x16x32_bf16 v[68:71], v[164:167], v[204:207], v[68:71]
	v_mfma_f32_16x16x32_bf16 v[64:67], v[172:175], v[204:207], v[64:67]
	v_mfma_f32_16x16x32_bf16 v[116:119], v[168:171], v[184:187], v[116:119]
	v_mfma_f32_16x16x32_bf16 v[112:115], v[176:179], v[184:187], v[112:115]
	v_mfma_f32_16x16x32_bf16 v[100:103], v[168:171], v[192:195], v[100:103]
	v_mfma_f32_16x16x32_bf16 v[96:99], v[176:179], v[192:195], v[96:99]
	v_mfma_f32_16x16x32_bf16 v[84:87], v[168:171], v[200:203], v[84:87]
	v_mfma_f32_16x16x32_bf16 v[80:83], v[176:179], v[200:203], v[80:83]
	v_mfma_f32_16x16x32_bf16 v[68:71], v[168:171], v[208:211], v[68:71]
	v_mfma_f32_16x16x32_bf16 v[64:67], v[176:179], v[208:211], v[64:67]
	s_setprio 0
	s_barrier
	s_add_i32 s24, s55, s36
	v_lshl_add_u64 v[212:213], v[212:213], 0, s[18:19]
	s_mov_b32 m0, s24
	ds_read_b128 v[180:183], v149 offset:49152
	ds_read_b128 v[184:187], v149 offset:50176
	ds_read_b128 v[188:191], v149 offset:51200
	ds_read_b128 v[192:195], v149 offset:52224
	ds_read_b128 v[196:199], v149 offset:53248
	ds_read_b128 v[200:203], v149 offset:54272
	ds_read_b128 v[204:207], v149 offset:55296
	ds_read_b128 v[208:211], v149 offset:56320
	global_load_lds_dwordx4 v[212:213], off
	s_add_i32 m0, s24, 0x2000
	s_add_u32 s24, s28, 0xb0080
	v_lshl_add_u64 v[212:213], v[214:215], 0, s[18:19]
	s_addc_u32 s25, s29, 0
	s_add_i32 s28, s56, s36
	global_load_lds_dwordx4 v[212:213], off
	v_lshl_add_u64 v[212:213], s[24:25], 0, v[128:129]
	s_mov_b32 m0, s28
	s_nop 0
	global_load_lds_dwordx4 v[212:213], off
	s_add_i32 m0, s28, 0x2000
	s_nop 0
	global_load_lds_dwordx4 v130, s[24:25]
	v_lshl_add_u64 v[212:213], v[216:217], 0, s[18:19]
	s_mov_b32 m0, s42
	s_nop 0
	global_load_lds_dwordx4 v[212:213], off
	v_lshl_add_u64 v[212:213], v[218:219], 0, s[18:19]
	s_mov_b32 m0, s43
	s_nop 0
	global_load_lds_dwordx4 v[212:213], off
	s_waitcnt vmcnt(8)
	s_waitcnt lgkmcnt(0)
	s_barrier
	s_setprio 1
	s_waitcnt lgkmcnt(0)
	v_mfma_f32_16x16x32_bf16 v[60:63], v[140:143], v[180:183], v[60:63]
	v_mfma_f32_16x16x32_bf16 v[56:59], v[156:159], v[180:183], v[56:59]
	v_mfma_f32_16x16x32_bf16 v[44:47], v[140:143], v[188:191], v[44:47]
	v_mfma_f32_16x16x32_bf16 v[40:43], v[156:159], v[188:191], v[40:43]
	v_mfma_f32_16x16x32_bf16 v[28:31], v[140:143], v[196:199], v[28:31]
	v_mfma_f32_16x16x32_bf16 v[24:27], v[156:159], v[196:199], v[24:27]
	v_mfma_f32_16x16x32_bf16 v[12:15], v[140:143], v[204:207], v[12:15]
	v_mfma_f32_16x16x32_bf16 v[8:11], v[156:159], v[204:207], v[8:11]
	v_mfma_f32_16x16x32_bf16 v[60:63], v[152:155], v[184:187], v[60:63]
	v_mfma_f32_16x16x32_bf16 v[56:59], v[160:163], v[184:187], v[56:59]
	v_mfma_f32_16x16x32_bf16 v[44:47], v[152:155], v[192:195], v[44:47]
	v_mfma_f32_16x16x32_bf16 v[40:43], v[160:163], v[192:195], v[40:43]
	v_mfma_f32_16x16x32_bf16 v[28:31], v[152:155], v[200:203], v[28:31]
	v_mfma_f32_16x16x32_bf16 v[24:27], v[160:163], v[200:203], v[24:27]
	v_mfma_f32_16x16x32_bf16 v[12:15], v[152:155], v[208:211], v[12:15]
	v_mfma_f32_16x16x32_bf16 v[8:11], v[160:163], v[208:211], v[8:11]
	s_setprio 0
	s_setprio 1
	v_mfma_f32_16x16x32_bf16 v[52:55], v[164:167], v[180:183], v[52:55]
	v_mfma_f32_16x16x32_bf16 v[48:51], v[172:175], v[180:183], v[48:51]
	v_mfma_f32_16x16x32_bf16 v[36:39], v[164:167], v[188:191], v[36:39]
	v_mfma_f32_16x16x32_bf16 v[32:35], v[172:175], v[188:191], v[32:35]
	v_mfma_f32_16x16x32_bf16 v[20:23], v[164:167], v[196:199], v[20:23]
	v_mfma_f32_16x16x32_bf16 v[16:19], v[172:175], v[196:199], v[16:19]
	v_mfma_f32_16x16x32_bf16 v[4:7], v[164:167], v[204:207], v[4:7]
	v_mfma_f32_16x16x32_bf16 v[0:3], v[172:175], v[204:207], v[0:3]
	v_mfma_f32_16x16x32_bf16 v[52:55], v[168:171], v[184:187], v[52:55]
	v_mfma_f32_16x16x32_bf16 v[48:51], v[176:179], v[184:187], v[48:51]
	v_mfma_f32_16x16x32_bf16 v[36:39], v[168:171], v[192:195], v[36:39]
	v_mfma_f32_16x16x32_bf16 v[32:35], v[176:179], v[192:195], v[32:35]
	v_mfma_f32_16x16x32_bf16 v[20:23], v[168:171], v[200:203], v[20:23]
	v_mfma_f32_16x16x32_bf16 v[16:19], v[176:179], v[200:203], v[16:19]
	v_mfma_f32_16x16x32_bf16 v[4:7], v[168:171], v[208:211], v[4:7]
	v_mfma_f32_16x16x32_bf16 v[0:3], v[176:179], v[208:211], v[0:3]
	s_setprio 0
	s_barrier
	s_add_i32 s54, s54, 2
	s_add_u32 s52, s52, 0x100
	s_addc_u32 s53, s53, 0
	s_cmp_gt_u32 s54, 41
	s_mov_b64 s[24:25], s[26:27]
	s_cbranch_scc0 .LBB0_1219
	s_and_b64 vcc, exec, s[20:21]
	s_cbranch_vccz .LBB0_1222
	s_barrier

.LBB0_1258:
	ds_read_b128 v[0:3], v147
	ds_read_b128 v[4:7], v147 offset:1024
	ds_read_b128 v[8:11], v147 offset:2048
	ds_read_b128 v[12:15], v147 offset:3072
	ds_read_b128 v[16:19], v148
	ds_read_b128 v[20:23], v148 offset:1024
	ds_read_b128 v[24:27], v148 offset:2048
	ds_read_b128 v[28:31], v148 offset:3072
	s_ashr_i32 s25, s24, 31
	s_lshl_b64 s[26:27], s[24:25], 17
	s_add_u32 s26, s48, s26
	s_addc_u32 s27, s49, s27
	s_and_b64 s[28:29], s[4:5], exec
	s_cselect_b32 s41, s27, s35
	s_cselect_b32 s40, s26, s34
	s_ashr_i32 s23, s22, 31
	s_lshl_b64 s[28:29], s[22:23], 17
	s_add_u32 s28, s42, s28
	s_addc_u32 s29, s43, s29
	s_and_b64 s[38:39], s[4:5], exec
	s_cselect_b32 s39, s29, s37
	s_cselect_b32 s38, s28, s36
	s_add_u32 s58, s34, 0x10080
	s_addc_u32 s59, s35, 0
	s_mov_b32 m0, s55
	ds_read_b128 v[32:35], v149
	ds_read_b128 v[36:39], v149 offset:1024
	ds_read_b128 v[40:43], v149 offset:2048
	ds_read_b128 v[44:47], v149 offset:3072
	ds_read_b128 v[48:51], v149 offset:4096
	ds_read_b128 v[52:55], v149 offset:5120
	ds_read_b128 v[56:59], v149 offset:6144
	ds_read_b128 v[60:63], v149 offset:7168
	global_load_lds_dwordx4 v128, s[58:59]
	s_mov_b32 m0, s56
	s_nop 0
	global_load_lds_dwordx4 v132, s[58:59]
	s_waitcnt vmcnt(8)
	s_waitcnt lgkmcnt(0)
	s_barrier
	s_setprio 1
	s_waitcnt lgkmcnt(0)
	v_mfma_f32_16x16x32_bf16 v[64:67], v[0:3], v[32:35], 0
	v_mfma_f32_16x16x32_bf16 v[68:71], v[8:11], v[32:35], 0
	v_mfma_f32_16x16x32_bf16 v[72:75], v[0:3], v[40:43], 0
	v_mfma_f32_16x16x32_bf16 v[76:79], v[8:11], v[40:43], 0
	v_mfma_f32_16x16x32_bf16 v[80:83], v[0:3], v[48:51], 0
	v_mfma_f32_16x16x32_bf16 v[84:87], v[8:11], v[48:51], 0
	v_mfma_f32_16x16x32_bf16 v[88:91], v[0:3], v[56:59], 0
	v_mfma_f32_16x16x32_bf16 v[92:95], v[8:11], v[56:59], 0
	v_mfma_f32_16x16x32_bf16 v[64:67], v[4:7], v[36:39], v[64:67]
	v_mfma_f32_16x16x32_bf16 v[68:71], v[12:15], v[36:39], v[68:71]
	v_mfma_f32_16x16x32_bf16 v[72:75], v[4:7], v[44:47], v[72:75]
	v_mfma_f32_16x16x32_bf16 v[76:79], v[12:15], v[44:47], v[76:79]
	v_mfma_f32_16x16x32_bf16 v[80:83], v[4:7], v[52:55], v[80:83]
	v_mfma_f32_16x16x32_bf16 v[84:87], v[12:15], v[52:55], v[84:87]
	v_mfma_f32_16x16x32_bf16 v[88:91], v[4:7], v[60:63], v[88:91]
	v_mfma_f32_16x16x32_bf16 v[92:95], v[12:15], v[60:63], v[92:95]
	s_setprio 0
	s_setprio 1
	v_mfma_f32_16x16x32_bf16 v[96:99], v[16:19], v[32:35], 0
	v_mfma_f32_16x16x32_bf16 v[32:35], v[24:27], v[32:35], 0
	v_mfma_f32_16x16x32_bf16 v[96:99], v[20:23], v[36:39], v[96:99]
	v_mfma_f32_16x16x32_bf16 v[32:35], v[28:31], v[36:39], v[32:35]
	v_mfma_f32_16x16x32_bf16 v[36:39], v[16:19], v[40:43], 0
	v_mfma_f32_16x16x32_bf16 v[40:43], v[24:27], v[40:43], 0
	v_mfma_f32_16x16x32_bf16 v[36:39], v[20:23], v[44:47], v[36:39]
	v_mfma_f32_16x16x32_bf16 v[40:43], v[28:31], v[44:47], v[40:43]
	v_mfma_f32_16x16x32_bf16 v[44:47], v[16:19], v[48:51], 0
	v_mfma_f32_16x16x32_bf16 v[48:51], v[24:27], v[48:51], 0
	v_mfma_f32_16x16x32_bf16 v[44:47], v[20:23], v[52:55], v[44:47]
	v_mfma_f32_16x16x32_bf16 v[48:51], v[28:31], v[52:55], v[48:51]
	v_mfma_f32_16x16x32_bf16 v[52:55], v[16:19], v[56:59], 0
	v_mfma_f32_16x16x32_bf16 v[56:59], v[24:27], v[56:59], 0
	v_mfma_f32_16x16x32_bf16 v[52:55], v[20:23], v[60:63], v[52:55]
	v_mfma_f32_16x16x32_bf16 v[56:59], v[28:31], v[60:63], v[56:59]
	s_setprio 0
	s_barrier
	s_add_i32 s59, s53, s44
	v_lshl_add_u64 v[212:213], s[36:37], 0, v[130:131]
	s_add_i32 s23, s59, 0x2000
	v_lshl_add_u64 v[140:141], v[212:213], 0, s[18:19]
	s_mov_b32 m0, s59
	v_lshl_add_u64 v[214:215], s[36:37], 0, v[134:135]
	s_add_u32 s60, s36, 0x10100
	ds_read_b128 v[60:63], v149 offset:16384
	ds_read_b128 v[100:103], v149 offset:17408
	ds_read_b128 v[104:107], v149 offset:18432
	ds_read_b128 v[108:111], v149 offset:19456
	ds_read_b128 v[112:115], v149 offset:20480
	ds_read_b128 v[116:119], v149 offset:21504
	ds_read_b128 v[120:123], v149 offset:22528
	ds_read_b128 v[124:127], v149 offset:23552
	global_load_lds_dwordx4 v[140:141], off
	v_lshl_add_u64 v[140:141], v[214:215], 0, s[18:19]
	s_mov_b32 m0, s23
	s_addc_u32 s61, s37, 0
	s_add_i32 s25, s54, s44
	global_load_lds_dwordx4 v[140:141], off
	v_lshl_add_u64 v[140:141], s[60:61], 0, v[130:131]
	s_mov_b32 m0, s25
	s_add_i32 s58, s25, 0x2000
	global_load_lds_dwordx4 v[140:141], off
	s_mov_b32 m0, s58
	v_lshl_add_u64 v[216:217], s[34:35], 0, v[128:129]
	global_load_lds_dwordx4 v134, s[60:61]
	v_lshl_add_u64 v[140:141], v[216:217], 0, s[18:19]
	s_mov_b32 m0, s31
	v_lshl_add_u64 v[218:219], s[34:35], 0, v[132:133]
	global_load_lds_dwordx4 v[140:141], off
	v_lshl_add_u64 v[140:141], v[218:219], 0, s[18:19]
	s_mov_b32 m0, s45
	s_nop 0
	global_load_lds_dwordx4 v[140:141], off
	s_waitcnt vmcnt(8)
	s_waitcnt lgkmcnt(0)
	s_barrier
	s_setprio 1
	s_waitcnt lgkmcnt(0)
	v_mfma_f32_16x16x32_bf16 v[140:143], v[0:3], v[60:63], 0
	v_mfma_f32_16x16x32_bf16 v[156:159], v[0:3], v[104:107], 0
	v_mfma_f32_16x16x32_bf16 v[164:167], v[0:3], v[112:115], 0
	v_mfma_f32_16x16x32_bf16 v[0:3], v[0:3], v[120:123], 0
	v_mfma_f32_16x16x32_bf16 v[140:143], v[4:7], v[100:103], v[140:143]
	v_mfma_f32_16x16x32_bf16 v[156:159], v[4:7], v[108:111], v[156:159]
	v_mfma_f32_16x16x32_bf16 v[164:167], v[4:7], v[116:119], v[164:167]
	v_mfma_f32_16x16x32_bf16 v[0:3], v[4:7], v[124:127], v[0:3]
	v_mfma_f32_16x16x32_bf16 v[4:7], v[8:11], v[120:123], 0
	v_mfma_f32_16x16x32_bf16 v[152:155], v[8:11], v[60:63], 0
	v_mfma_f32_16x16x32_bf16 v[160:163], v[8:11], v[104:107], 0
	v_mfma_f32_16x16x32_bf16 v[168:171], v[8:11], v[112:115], 0
	v_mfma_f32_16x16x32_bf16 v[4:7], v[12:15], v[124:127], v[4:7]
	v_mfma_f32_16x16x32_bf16 v[152:155], v[12:15], v[100:103], v[152:155]
	v_mfma_f32_16x16x32_bf16 v[160:163], v[12:15], v[108:111], v[160:163]
	v_mfma_f32_16x16x32_bf16 v[168:171], v[12:15], v[116:119], v[168:171]
	s_setprio 0
	s_setprio 1
	v_mfma_f32_16x16x32_bf16 v[8:11], v[16:19], v[60:63], 0
	v_mfma_f32_16x16x32_bf16 v[12:15], v[24:27], v[60:63], 0
	v_mfma_f32_16x16x32_bf16 v[8:11], v[20:23], v[100:103], v[8:11]
	v_mfma_f32_16x16x32_bf16 v[12:15], v[28:31], v[100:103], v[12:15]
	v_mfma_f32_16x16x32_bf16 v[60:63], v[16:19], v[104:107], 0
	v_mfma_f32_16x16x32_bf16 v[100:103], v[24:27], v[104:107], 0
	v_mfma_f32_16x16x32_bf16 v[104:107], v[16:19], v[112:115], 0
	v_mfma_f32_16x16x32_bf16 v[16:19], v[16:19], v[120:123], 0
	v_mfma_f32_16x16x32_bf16 v[60:63], v[20:23], v[108:111], v[60:63]
	v_mfma_f32_16x16x32_bf16 v[100:103], v[28:31], v[108:111], v[100:103]
	v_mfma_f32_16x16x32_bf16 v[104:107], v[20:23], v[116:119], v[104:107]
	v_mfma_f32_16x16x32_bf16 v[108:111], v[24:27], v[112:115], 0
	v_mfma_f32_16x16x32_bf16 v[16:19], v[20:23], v[124:127], v[16:19]
	v_mfma_f32_16x16x32_bf16 v[20:23], v[24:27], v[120:123], 0
	v_mfma_f32_16x16x32_bf16 v[108:111], v[28:31], v[116:119], v[108:111]
	v_mfma_f32_16x16x32_bf16 v[20:23], v[28:31], v[124:127], v[20:23]
	s_setprio 0
	s_barrier
	s_add_i32 s62, 0, 0x18000
	s_add_i32 s64, 0, 0x1c000
	v_add_u32_e32 v151, s62, v145
	v_add_u32_e32 v222, s64, v145
	ds_read_b128 v[24:27], v151
	ds_read_b128 v[28:31], v151 offset:1024
	ds_read_b128 v[112:115], v151 offset:2048
	ds_read_b128 v[116:119], v151 offset:3072
	ds_read_b128 v[120:123], v222
	ds_read_b128 v[124:127], v222 offset:1024
	ds_read_b128 v[172:175], v222 offset:2048
	ds_read_b128 v[176:179], v222 offset:3072
	s_add_u32 s60, s34, 0x10100
	s_addc_u32 s61, s35, 0
	s_mov_b32 m0, s46
	ds_read_b128 v[180:183], v149 offset:32768
	ds_read_b128 v[184:187], v149 offset:33792
	ds_read_b128 v[188:191], v149 offset:34816
	ds_read_b128 v[192:195], v149 offset:35840
	ds_read_b128 v[196:199], v149 offset:36864
	ds_read_b128 v[200:203], v149 offset:37888
	ds_read_b128 v[204:207], v149 offset:38912
	ds_read_b128 v[208:211], v149 offset:39936
	global_load_lds_dwordx4 v128, s[60:61]
	s_mov_b32 m0, s47
	s_nop 0
	global_load_lds_dwordx4 v132, s[60:61]
	s_waitcnt vmcnt(8)
	s_waitcnt lgkmcnt(0)
	s_barrier
	s_setprio 1
	s_waitcnt lgkmcnt(0)
	v_mfma_f32_16x16x32_bf16 v[64:67], v[24:27], v[180:183], v[64:67]
	v_mfma_f32_16x16x32_bf16 v[68:71], v[112:115], v[180:183], v[68:71]
	v_mfma_f32_16x16x32_bf16 v[72:75], v[24:27], v[188:191], v[72:75]
	v_mfma_f32_16x16x32_bf16 v[76:79], v[112:115], v[188:191], v[76:79]
	v_mfma_f32_16x16x32_bf16 v[80:83], v[24:27], v[196:199], v[80:83]
	v_mfma_f32_16x16x32_bf16 v[84:87], v[112:115], v[196:199], v[84:87]
	v_mfma_f32_16x16x32_bf16 v[88:91], v[24:27], v[204:207], v[88:91]
	v_mfma_f32_16x16x32_bf16 v[92:95], v[112:115], v[204:207], v[92:95]
	v_mfma_f32_16x16x32_bf16 v[64:67], v[28:31], v[184:187], v[64:67]
	v_mfma_f32_16x16x32_bf16 v[68:71], v[116:119], v[184:187], v[68:71]
	v_mfma_f32_16x16x32_bf16 v[72:75], v[28:31], v[192:195], v[72:75]
	v_mfma_f32_16x16x32_bf16 v[76:79], v[116:119], v[192:195], v[76:79]
	v_mfma_f32_16x16x32_bf16 v[80:83], v[28:31], v[200:203], v[80:83]
	v_mfma_f32_16x16x32_bf16 v[84:87], v[116:119], v[200:203], v[84:87]
	v_mfma_f32_16x16x32_bf16 v[88:91], v[28:31], v[208:211], v[88:91]
	v_mfma_f32_16x16x32_bf16 v[92:95], v[116:119], v[208:211], v[92:95]
	s_setprio 0
	s_setprio 1
	v_mfma_f32_16x16x32_bf16 v[96:99], v[120:123], v[180:183], v[96:99]
	v_mfma_f32_16x16x32_bf16 v[32:35], v[172:175], v[180:183], v[32:35]
	v_mfma_f32_16x16x32_bf16 v[36:39], v[120:123], v[188:191], v[36:39]
	v_mfma_f32_16x16x32_bf16 v[40:43], v[172:175], v[188:191], v[40:43]
	v_mfma_f32_16x16x32_bf16 v[44:47], v[120:123], v[196:199], v[44:47]
	v_mfma_f32_16x16x32_bf16 v[48:51], v[172:175], v[196:199], v[48:51]
	v_mfma_f32_16x16x32_bf16 v[52:55], v[120:123], v[204:207], v[52:55]
	v_mfma_f32_16x16x32_bf16 v[56:59], v[172:175], v[204:207], v[56:59]
	v_mfma_f32_16x16x32_bf16 v[96:99], v[124:127], v[184:187], v[96:99]
	v_mfma_f32_16x16x32_bf16 v[32:35], v[176:179], v[184:187], v[32:35]
	v_mfma_f32_16x16x32_bf16 v[36:39], v[124:127], v[192:195], v[36:39]
	v_mfma_f32_16x16x32_bf16 v[40:43], v[176:179], v[192:195], v[40:43]
	v_mfma_f32_16x16x32_bf16 v[44:47], v[124:127], v[200:203], v[44:47]
	v_mfma_f32_16x16x32_bf16 v[48:51], v[176:179], v[200:203], v[48:51]
	v_mfma_f32_16x16x32_bf16 v[52:55], v[124:127], v[208:211], v[52:55]
	v_mfma_f32_16x16x32_bf16 v[56:59], v[176:179], v[208:211], v[56:59]
	s_setprio 0
	s_barrier
	s_add_i32 s61, s62, s44
	s_add_i32 s60, s61, 0x2000
	v_lshl_add_u64 v[212:213], v[212:213], 0, s[20:21]
	s_mov_b32 m0, s61
	s_add_u32 s62, s36, 0x10180
	ds_read_b128 v[180:183], v149 offset:49152
	ds_read_b128 v[184:187], v149 offset:50176
	ds_read_b128 v[188:191], v149 offset:51200
	ds_read_b128 v[192:195], v149 offset:52224
	ds_read_b128 v[196:199], v149 offset:53248
	ds_read_b128 v[200:203], v149 offset:54272
	ds_read_b128 v[204:207], v149 offset:55296
	ds_read_b128 v[208:211], v149 offset:56320
	global_load_lds_dwordx4 v[212:213], off
	v_lshl_add_u64 v[212:213], v[214:215], 0, s[20:21]
	s_mov_b32 m0, s60
	s_addc_u32 s63, s37, 0
	s_add_i32 s36, s64, s44
	global_load_lds_dwordx4 v[212:213], off
	v_lshl_add_u64 v[212:213], s[62:63], 0, v[130:131]
	s_mov_b32 m0, s36
	s_add_i32 s37, s36, 0x2000
	global_load_lds_dwordx4 v[212:213], off
	s_mov_b32 m0, s37
	s_nop 0
	global_load_lds_dwordx4 v134, s[62:63]
	v_lshl_add_u64 v[212:213], v[216:217], 0, s[20:21]
	s_mov_b32 m0, s50
	s_nop 0
	global_load_lds_dwordx4 v[212:213], off
	v_lshl_add_u64 v[212:213], v[218:219], 0, s[20:21]
	s_mov_b32 m0, s51
	s_nop 0
	global_load_lds_dwordx4 v[212:213], off
	s_waitcnt vmcnt(8)
	s_waitcnt lgkmcnt(0)
	s_barrier
	s_setprio 1
	s_waitcnt lgkmcnt(0)
	v_mfma_f32_16x16x32_bf16 v[0:3], v[24:27], v[204:207], v[0:3]
	v_mfma_f32_16x16x32_bf16 v[4:7], v[112:115], v[204:207], v[4:7]
	v_mfma_f32_16x16x32_bf16 v[140:143], v[24:27], v[180:183], v[140:143]
	v_mfma_f32_16x16x32_bf16 v[152:155], v[112:115], v[180:183], v[152:155]
	v_mfma_f32_16x16x32_bf16 v[156:159], v[24:27], v[188:191], v[156:159]
	v_mfma_f32_16x16x32_bf16 v[160:163], v[112:115], v[188:191], v[160:163]
	v_mfma_f32_16x16x32_bf16 v[164:167], v[24:27], v[196:199], v[164:167]
	v_mfma_f32_16x16x32_bf16 v[168:171], v[112:115], v[196:199], v[168:171]
	v_mfma_f32_16x16x32_bf16 v[0:3], v[28:31], v[208:211], v[0:3]
	v_mfma_f32_16x16x32_bf16 v[4:7], v[116:119], v[208:211], v[4:7]
	v_mfma_f32_16x16x32_bf16 v[140:143], v[28:31], v[184:187], v[140:143]
	v_mfma_f32_16x16x32_bf16 v[152:155], v[116:119], v[184:187], v[152:155]
	v_mfma_f32_16x16x32_bf16 v[156:159], v[28:31], v[192:195], v[156:159]
	v_mfma_f32_16x16x32_bf16 v[160:163], v[116:119], v[192:195], v[160:163]
	v_mfma_f32_16x16x32_bf16 v[164:167], v[28:31], v[200:203], v[164:167]
	v_mfma_f32_16x16x32_bf16 v[168:171], v[116:119], v[200:203], v[168:171]
	s_setprio 0
	s_setprio 1
	v_mfma_f32_16x16x32_bf16 v[8:11], v[120:123], v[180:183], v[8:11]
	v_mfma_f32_16x16x32_bf16 v[12:15], v[172:175], v[180:183], v[12:15]
	v_mfma_f32_16x16x32_bf16 v[24:27], v[120:123], v[188:191], v[60:63]
	v_mfma_f32_16x16x32_bf16 v[28:31], v[172:175], v[188:191], v[100:103]
	v_mfma_f32_16x16x32_bf16 v[60:63], v[120:123], v[196:199], v[104:107]
	v_mfma_f32_16x16x32_bf16 v[100:103], v[172:175], v[196:199], v[108:111]
	v_mfma_f32_16x16x32_bf16 v[16:19], v[120:123], v[204:207], v[16:19]
	v_mfma_f32_16x16x32_bf16 v[20:23], v[172:175], v[204:207], v[20:23]
	v_mfma_f32_16x16x32_bf16 v[8:11], v[124:127], v[184:187], v[8:11]
	v_mfma_f32_16x16x32_bf16 v[12:15], v[176:179], v[184:187], v[12:15]
	v_mfma_f32_16x16x32_bf16 v[24:27], v[124:127], v[192:195], v[24:27]
	v_mfma_f32_16x16x32_bf16 v[28:31], v[176:179], v[192:195], v[28:31]
	v_mfma_f32_16x16x32_bf16 v[60:63], v[124:127], v[200:203], v[60:63]
	v_mfma_f32_16x16x32_bf16 v[100:103], v[176:179], v[200:203], v[100:103]
	v_mfma_f32_16x16x32_bf16 v[16:19], v[124:127], v[208:211], v[16:19]
	v_mfma_f32_16x16x32_bf16 v[20:23], v[176:179], v[208:211], v[20:23]
	s_setprio 0
	s_barrier
	ds_read_b128 v[104:107], v147
	ds_read_b128 v[108:111], v147 offset:1024
	ds_read_b128 v[112:115], v147 offset:2048
	ds_read_b128 v[116:119], v147 offset:3072
	ds_read_b128 v[120:123], v148
	ds_read_b128 v[124:127], v148 offset:1024
	ds_read_b128 v[172:175], v148 offset:2048
	ds_read_b128 v[176:179], v148 offset:3072
	s_add_u32 s34, s34, 0x10180
	s_addc_u32 s35, s35, 0
	s_mov_b32 m0, s55
	ds_read_b128 v[180:183], v149
	ds_read_b128 v[184:187], v149 offset:1024
	ds_read_b128 v[188:191], v149 offset:2048
	ds_read_b128 v[192:195], v149 offset:3072
	ds_read_b128 v[196:199], v149 offset:4096
	ds_read_b128 v[200:203], v149 offset:5120
	ds_read_b128 v[204:207], v149 offset:6144
	ds_read_b128 v[208:211], v149 offset:7168
	global_load_lds_dwordx4 v128, s[34:35]
	s_mov_b32 m0, s56
	s_nop 0
	global_load_lds_dwordx4 v132, s[34:35]
	s_waitcnt vmcnt(8)
	s_waitcnt lgkmcnt(0)
	s_barrier
	s_setprio 1
	s_waitcnt lgkmcnt(0)
	v_mfma_f32_16x16x32_bf16 v[64:67], v[104:107], v[180:183], v[64:67]
	v_mfma_f32_16x16x32_bf16 v[68:71], v[112:115], v[180:183], v[68:71]
	v_mfma_f32_16x16x32_bf16 v[72:75], v[104:107], v[188:191], v[72:75]
	v_mfma_f32_16x16x32_bf16 v[76:79], v[112:115], v[188:191], v[76:79]
	v_mfma_f32_16x16x32_bf16 v[80:83], v[104:107], v[196:199], v[80:83]
	v_mfma_f32_16x16x32_bf16 v[84:87], v[112:115], v[196:199], v[84:87]
	v_mfma_f32_16x16x32_bf16 v[88:91], v[104:107], v[204:207], v[88:91]
	v_mfma_f32_16x16x32_bf16 v[92:95], v[112:115], v[204:207], v[92:95]
	v_mfma_f32_16x16x32_bf16 v[64:67], v[108:111], v[184:187], v[64:67]
	v_mfma_f32_16x16x32_bf16 v[68:71], v[116:119], v[184:187], v[68:71]
	v_mfma_f32_16x16x32_bf16 v[72:75], v[108:111], v[192:195], v[72:75]
	v_mfma_f32_16x16x32_bf16 v[76:79], v[116:119], v[192:195], v[76:79]
	v_mfma_f32_16x16x32_bf16 v[80:83], v[108:111], v[200:203], v[80:83]
	v_mfma_f32_16x16x32_bf16 v[84:87], v[116:119], v[200:203], v[84:87]
	v_mfma_f32_16x16x32_bf16 v[88:91], v[108:111], v[208:211], v[88:91]
	v_mfma_f32_16x16x32_bf16 v[92:95], v[116:119], v[208:211], v[92:95]
	s_setprio 0
	s_setprio 1
	v_mfma_f32_16x16x32_bf16 v[32:35], v[172:175], v[180:183], v[32:35]
	v_mfma_f32_16x16x32_bf16 v[36:39], v[120:123], v[188:191], v[36:39]
	v_mfma_f32_16x16x32_bf16 v[40:43], v[172:175], v[188:191], v[40:43]
	v_mfma_f32_16x16x32_bf16 v[44:47], v[120:123], v[196:199], v[44:47]
	v_mfma_f32_16x16x32_bf16 v[48:51], v[172:175], v[196:199], v[48:51]
	v_mfma_f32_16x16x32_bf16 v[52:55], v[120:123], v[204:207], v[52:55]
	v_mfma_f32_16x16x32_bf16 v[56:59], v[172:175], v[204:207], v[56:59]
	v_mfma_f32_16x16x32_bf16 v[96:99], v[120:123], v[180:183], v[96:99]
	v_mfma_f32_16x16x32_bf16 v[32:35], v[176:179], v[184:187], v[32:35]
	v_mfma_f32_16x16x32_bf16 v[36:39], v[124:127], v[192:195], v[36:39]
	v_mfma_f32_16x16x32_bf16 v[40:43], v[176:179], v[192:195], v[40:43]
	v_mfma_f32_16x16x32_bf16 v[44:47], v[124:127], v[200:203], v[44:47]
	v_mfma_f32_16x16x32_bf16 v[48:51], v[176:179], v[200:203], v[48:51]
	v_mfma_f32_16x16x32_bf16 v[52:55], v[124:127], v[208:211], v[52:55]
	v_mfma_f32_16x16x32_bf16 v[56:59], v[176:179], v[208:211], v[56:59]
	v_mfma_f32_16x16x32_bf16 v[212:215], v[124:127], v[184:187], v[96:99]
	s_setprio 0
	s_barrier
	s_mov_b32 m0, s59
	v_lshl_add_u64 v[240:241], s[38:39], 0, v[130:131]
	s_add_u32 s34, s38, 0x10000
	ds_read_b128 v[96:99], v149 offset:16384
	ds_read_b128 v[180:183], v149 offset:17408
	ds_read_b128 v[184:187], v149 offset:18432
	ds_read_b128 v[188:191], v149 offset:19456
	ds_read_b128 v[192:195], v149 offset:20480
	ds_read_b128 v[196:199], v149 offset:21504
	ds_read_b128 v[200:203], v149 offset:22528
	ds_read_b128 v[204:207], v149 offset:23552
	global_load_lds_dwordx4 v[240:241], off
	v_lshl_add_u64 v[242:243], s[38:39], 0, v[134:135]
	s_mov_b32 m0, s23
	s_addc_u32 s35, s39, 0
	global_load_lds_dwordx4 v[242:243], off
	v_lshl_add_u64 v[208:209], s[34:35], 0, v[130:131]
	s_mov_b32 m0, s25
	v_lshl_add_u64 v[244:245], s[40:41], 0, v[128:129]
	global_load_lds_dwordx4 v[208:209], off
	s_mov_b32 m0, s58
	v_lshl_add_u64 v[246:247], s[40:41], 0, v[132:133]
	global_load_lds_dwordx4 v134, s[34:35]
	s_mov_b32 m0, s31
	s_nop 0
	global_load_lds_dwordx4 v[244:245], off
	s_mov_b32 m0, s45
	s_nop 0
	global_load_lds_dwordx4 v[246:247], off
	s_waitcnt vmcnt(8)
	s_waitcnt lgkmcnt(0)
	s_barrier
	s_setprio 1
	s_waitcnt lgkmcnt(0)
	v_mfma_f32_16x16x32_bf16 v[0:3], v[104:107], v[200:203], v[0:3]
	v_mfma_f32_16x16x32_bf16 v[4:7], v[112:115], v[200:203], v[4:7]
	v_mfma_f32_16x16x32_bf16 v[140:143], v[104:107], v[96:99], v[140:143]
	v_mfma_f32_16x16x32_bf16 v[152:155], v[112:115], v[96:99], v[152:155]
	v_mfma_f32_16x16x32_bf16 v[156:159], v[104:107], v[184:187], v[156:159]
	v_mfma_f32_16x16x32_bf16 v[160:163], v[112:115], v[184:187], v[160:163]
	v_mfma_f32_16x16x32_bf16 v[164:167], v[104:107], v[192:195], v[164:167]
	v_mfma_f32_16x16x32_bf16 v[168:171], v[112:115], v[192:195], v[168:171]
	v_mfma_f32_16x16x32_bf16 v[0:3], v[108:111], v[204:207], v[0:3]
	v_mfma_f32_16x16x32_bf16 v[4:7], v[116:119], v[204:207], v[4:7]
	v_mfma_f32_16x16x32_bf16 v[140:143], v[108:111], v[180:183], v[140:143]
	v_mfma_f32_16x16x32_bf16 v[152:155], v[116:119], v[180:183], v[152:155]
	v_mfma_f32_16x16x32_bf16 v[156:159], v[108:111], v[188:191], v[156:159]
	v_mfma_f32_16x16x32_bf16 v[160:163], v[116:119], v[188:191], v[160:163]
	v_mfma_f32_16x16x32_bf16 v[164:167], v[108:111], v[196:199], v[164:167]
	v_mfma_f32_16x16x32_bf16 v[168:171], v[116:119], v[196:199], v[168:171]
	s_setprio 0
	s_setprio 1
	v_mfma_f32_16x16x32_bf16 v[8:11], v[120:123], v[96:99], v[8:11]
	v_mfma_f32_16x16x32_bf16 v[12:15], v[172:175], v[96:99], v[12:15]
	v_mfma_f32_16x16x32_bf16 v[24:27], v[120:123], v[184:187], v[24:27]
	v_mfma_f32_16x16x32_bf16 v[28:31], v[172:175], v[184:187], v[28:31]
	v_mfma_f32_16x16x32_bf16 v[60:63], v[120:123], v[192:195], v[60:63]
	v_mfma_f32_16x16x32_bf16 v[16:19], v[120:123], v[200:203], v[16:19]
	v_mfma_f32_16x16x32_bf16 v[8:11], v[124:127], v[180:183], v[8:11]
	v_mfma_f32_16x16x32_bf16 v[12:15], v[176:179], v[180:183], v[12:15]
	v_mfma_f32_16x16x32_bf16 v[24:27], v[124:127], v[188:191], v[24:27]
	v_mfma_f32_16x16x32_bf16 v[28:31], v[176:179], v[188:191], v[28:31]
	v_mfma_f32_16x16x32_bf16 v[180:183], v[124:127], v[196:199], v[60:63]
	v_mfma_f32_16x16x32_bf16 v[60:63], v[172:175], v[192:195], v[100:103]
	v_mfma_f32_16x16x32_bf16 v[188:191], v[124:127], v[204:207], v[16:19]
	v_mfma_f32_16x16x32_bf16 v[16:19], v[172:175], v[200:203], v[20:23]
	v_mfma_f32_16x16x32_bf16 v[184:187], v[176:179], v[196:199], v[60:63]
	v_mfma_f32_16x16x32_bf16 v[172:175], v[176:179], v[204:207], v[16:19]
	s_setprio 0
	s_barrier
	s_nop 1
	ds_read_b128 v[60:63], v151
	ds_read_b128 v[176:179], v151 offset:1024
	ds_read_b128 v[192:195], v151 offset:2048
	ds_read_b128 v[196:199], v151 offset:3072
	ds_read_b128 v[200:203], v222
	ds_read_b128 v[204:207], v222 offset:1024
	ds_read_b128 v[208:211], v222 offset:2048
	ds_read_b128 v[216:219], v222 offset:3072
	s_add_u32 s34, s40, 0x10000
	s_addc_u32 s35, s41, 0
	s_mov_b32 m0, s46
	ds_read_b128 v[16:19], v149 offset:32768
	ds_read_b128 v[20:23], v149 offset:33792
	ds_read_b128 v[108:111], v149 offset:34816
	ds_read_b128 v[220:223], v149 offset:35840
	ds_read_b128 v[224:227], v149 offset:36864
	ds_read_b128 v[228:231], v149 offset:37888
	ds_read_b128 v[232:235], v149 offset:38912
	ds_read_b128 v[236:239], v149 offset:39936
	global_load_lds_dwordx4 v128, s[34:35]
	s_mov_b32 m0, s47
	s_nop 0
	global_load_lds_dwordx4 v132, s[34:35]
	s_waitcnt vmcnt(8)
	s_waitcnt lgkmcnt(0)
	s_barrier
	s_setprio 1
	s_waitcnt lgkmcnt(0)
	v_mfma_f32_16x16x32_bf16 v[64:67], v[60:63], v[16:19], v[64:67]
	v_mfma_f32_16x16x32_bf16 v[112:115], v[176:179], v[20:23], v[64:67]
	v_mfma_f32_16x16x32_bf16 v[64:67], v[192:195], v[16:19], v[68:71]
	v_mfma_f32_16x16x32_bf16 v[116:119], v[196:199], v[20:23], v[64:67]
	v_mfma_f32_16x16x32_bf16 v[64:67], v[60:63], v[108:111], v[72:75]
	v_mfma_f32_16x16x32_bf16 v[96:99], v[176:179], v[220:223], v[64:67]
	v_mfma_f32_16x16x32_bf16 v[64:67], v[192:195], v[108:111], v[76:79]
	v_mfma_f32_16x16x32_bf16 v[100:103], v[196:199], v[220:223], v[64:67]
	v_mfma_f32_16x16x32_bf16 v[64:67], v[60:63], v[224:227], v[80:83]
	v_mfma_f32_16x16x32_bf16 v[80:83], v[176:179], v[228:231], v[64:67]
	v_mfma_f32_16x16x32_bf16 v[64:67], v[192:195], v[224:227], v[84:87]
	v_mfma_f32_16x16x32_bf16 v[84:87], v[196:199], v[228:231], v[64:67]
	v_mfma_f32_16x16x32_bf16 v[64:67], v[60:63], v[232:235], v[88:91]
	v_mfma_f32_16x16x32_bf16 v[68:71], v[192:195], v[232:235], v[92:95]
	v_mfma_f32_16x16x32_bf16 v[64:67], v[176:179], v[236:239], v[64:67]
	v_mfma_f32_16x16x32_bf16 v[68:71], v[196:199], v[236:239], v[68:71]
	s_setprio 0
	s_setprio 1
	v_mfma_f32_16x16x32_bf16 v[72:75], v[200:203], v[16:19], v[212:215]
	v_mfma_f32_16x16x32_bf16 v[16:19], v[208:211], v[16:19], v[32:35]
	v_mfma_f32_16x16x32_bf16 v[124:127], v[216:219], v[20:23], v[16:19]
	v_mfma_f32_16x16x32_bf16 v[16:19], v[200:203], v[108:111], v[36:39]
	v_mfma_f32_16x16x32_bf16 v[104:107], v[204:207], v[220:223], v[16:19]
	v_mfma_f32_16x16x32_bf16 v[16:19], v[208:211], v[108:111], v[40:43]
	v_mfma_f32_16x16x32_bf16 v[108:111], v[216:219], v[220:223], v[16:19]
	v_mfma_f32_16x16x32_bf16 v[16:19], v[200:203], v[224:227], v[44:47]
	v_mfma_f32_16x16x32_bf16 v[88:91], v[204:207], v[228:231], v[16:19]
	v_mfma_f32_16x16x32_bf16 v[16:19], v[208:211], v[224:227], v[48:51]
	v_mfma_f32_16x16x32_bf16 v[92:95], v[216:219], v[228:231], v[16:19]
	v_mfma_f32_16x16x32_bf16 v[16:19], v[200:203], v[232:235], v[52:55]
	v_mfma_f32_16x16x32_bf16 v[120:123], v[204:207], v[20:23], v[72:75]
	v_mfma_f32_16x16x32_bf16 v[72:75], v[204:207], v[236:239], v[16:19]
	v_mfma_f32_16x16x32_bf16 v[16:19], v[208:211], v[232:235], v[56:59]
	v_mfma_f32_16x16x32_bf16 v[76:79], v[216:219], v[236:239], v[16:19]
	s_setprio 0
	s_barrier
	s_mov_b32 m0, s61
	s_nop 3
	v_lshl_add_u64 v[16:17], v[240:241], 0, s[12:13]
	s_add_u32 s34, s38, 0x10080
	ds_read_b128 v[40:43], v149 offset:49152
	ds_read_b128 v[44:47], v149 offset:50176
	ds_read_b128 v[212:215], v149 offset:51200
	ds_read_b128 v[220:223], v149 offset:52224
	ds_read_b128 v[224:227], v149 offset:53248
	ds_read_b128 v[228:231], v149 offset:54272
	ds_read_b128 v[232:235], v149 offset:55296
	ds_read_b128 v[236:239], v149 offset:56320
	global_load_lds_dwordx4 v[16:17], off
	v_lshl_add_u64 v[16:17], v[242:243], 0, s[12:13]
	s_mov_b32 m0, s60
	s_addc_u32 s35, s39, 0
	global_load_lds_dwordx4 v[16:17], off
	v_lshl_add_u64 v[16:17], s[34:35], 0, v[130:131]
	s_mov_b32 m0, s36
	s_nop 0
	global_load_lds_dwordx4 v[16:17], off
	s_mov_b32 m0, s37
	s_nop 0
	global_load_lds_dwordx4 v134, s[34:35]
	v_lshl_add_u64 v[16:17], v[244:245], 0, s[12:13]
	s_mov_b32 m0, s50
	s_nop 0
	global_load_lds_dwordx4 v[16:17], off
	v_lshl_add_u64 v[16:17], v[246:247], 0, s[12:13]
	s_mov_b32 m0, s51
	s_nop 0
	global_load_lds_dwordx4 v[16:17], off
	s_waitcnt vmcnt(8)
	s_waitcnt lgkmcnt(0)
	s_barrier
	s_setprio 1
	s_waitcnt lgkmcnt(0)
	v_mfma_f32_16x16x32_bf16 v[16:19], v[60:63], v[40:43], v[140:143]
	v_mfma_f32_16x16x32_bf16 v[48:51], v[176:179], v[44:47], v[16:19]
	v_mfma_f32_16x16x32_bf16 v[16:19], v[192:195], v[40:43], v[152:155]
	v_mfma_f32_16x16x32_bf16 v[52:55], v[196:199], v[44:47], v[16:19]
	v_mfma_f32_16x16x32_bf16 v[16:19], v[60:63], v[212:215], v[156:159]
	v_mfma_f32_16x16x32_bf16 v[32:35], v[176:179], v[220:223], v[16:19]
	v_mfma_f32_16x16x32_bf16 v[16:19], v[192:195], v[212:215], v[160:163]
	v_mfma_f32_16x16x32_bf16 v[36:39], v[196:199], v[220:223], v[16:19]
	v_mfma_f32_16x16x32_bf16 v[16:19], v[60:63], v[224:227], v[164:167]
	v_mfma_f32_16x16x32_bf16 v[20:23], v[192:195], v[224:227], v[168:171]
	v_mfma_f32_16x16x32_bf16 v[0:3], v[60:63], v[232:235], v[0:3]
	v_mfma_f32_16x16x32_bf16 v[4:7], v[192:195], v[232:235], v[4:7]
	v_mfma_f32_16x16x32_bf16 v[16:19], v[176:179], v[228:231], v[16:19]
	v_mfma_f32_16x16x32_bf16 v[20:23], v[196:199], v[228:231], v[20:23]
	v_mfma_f32_16x16x32_bf16 v[0:3], v[176:179], v[236:239], v[0:3]
	v_mfma_f32_16x16x32_bf16 v[4:7], v[196:199], v[236:239], v[4:7]
	s_setprio 0
	s_setprio 1
	v_mfma_f32_16x16x32_bf16 v[8:11], v[200:203], v[40:43], v[8:11]
	v_mfma_f32_16x16x32_bf16 v[56:59], v[204:207], v[44:47], v[8:11]
	v_mfma_f32_16x16x32_bf16 v[8:11], v[208:211], v[40:43], v[12:15]
	v_mfma_f32_16x16x32_bf16 v[60:63], v[216:219], v[44:47], v[8:11]
	v_mfma_f32_16x16x32_bf16 v[8:11], v[200:203], v[212:215], v[24:27]
	v_mfma_f32_16x16x32_bf16 v[40:43], v[204:207], v[220:223], v[8:11]
	v_mfma_f32_16x16x32_bf16 v[8:11], v[208:211], v[212:215], v[28:31]
	v_mfma_f32_16x16x32_bf16 v[44:47], v[216:219], v[220:223], v[8:11]
	v_mfma_f32_16x16x32_bf16 v[8:11], v[200:203], v[224:227], v[180:183]
	v_mfma_f32_16x16x32_bf16 v[24:27], v[204:207], v[228:231], v[8:11]
	v_mfma_f32_16x16x32_bf16 v[8:11], v[208:211], v[224:227], v[184:187]
	v_mfma_f32_16x16x32_bf16 v[28:31], v[216:219], v[228:231], v[8:11]
	v_mfma_f32_16x16x32_bf16 v[8:11], v[200:203], v[232:235], v[188:191]
	v_mfma_f32_16x16x32_bf16 v[12:15], v[208:211], v[232:235], v[172:175]
	v_mfma_f32_16x16x32_bf16 v[8:11], v[204:207], v[236:239], v[8:11]
	v_mfma_f32_16x16x32_bf16 v[12:15], v[216:219], v[236:239], v[12:15]
	s_setprio 0
	s_barrier
	s_andn2_b64 vcc, exec, s[14:15]
	s_cbranch_vccnz .LBB0_1260
	s_barrier

.LBB0_1280:
	ds_read_b128 v[0:3], v161
	ds_read_b128 v[4:7], v161 offset:1024
	ds_read_b128 v[8:11], v161 offset:2048
	ds_read_b128 v[12:15], v161 offset:3072
	ds_read_b128 v[16:19], v162
	ds_read_b128 v[20:23], v162 offset:1024
	ds_read_b128 v[24:27], v162 offset:2048
	ds_read_b128 v[28:31], v162 offset:3072
	s_ashr_i32 s31, s30, 31
	s_lshl_b64 s[34:35], s[30:31], 17
	s_add_u32 s34, s50, s34
	s_addc_u32 s35, s51, s35
	s_and_b64 s[36:37], s[2:3], exec
	s_cselect_b32 s47, s35, s41
	s_cselect_b32 s46, s34, s40
	s_ashr_i32 s29, s28, 31
	s_lshl_b64 s[36:37], s[28:29], 17
	s_add_u32 s36, s48, s36
	s_addc_u32 s37, s49, s37
	s_and_b64 s[44:45], s[2:3], exec
	s_cselect_b32 s45, s37, s43
	s_cselect_b32 s44, s36, s42
	s_add_u32 s66, s40, 0x10080
	s_addc_u32 s67, s41, 0
	s_add_i32 s84, s39, 0xc000
	s_mov_b32 m0, s84
	s_add_i32 s29, s39, 0xe000
	ds_read_b128 v[32:35], v163
	ds_read_b128 v[36:39], v163 offset:1024
	ds_read_b128 v[40:43], v163 offset:2048
	ds_read_b128 v[44:47], v163 offset:3072
	ds_read_b128 v[48:51], v163 offset:4096
	ds_read_b128 v[52:55], v163 offset:5120
	ds_read_b128 v[56:59], v163 offset:6144
	ds_read_b128 v[60:63], v163 offset:7168
	global_load_lds_dwordx4 v128, s[66:67]
	s_mov_b32 m0, s29
	s_nop 0
	global_load_lds_dwordx4 v132, s[66:67]
	s_waitcnt vmcnt(8)
	s_waitcnt lgkmcnt(0)
	s_barrier
	s_setprio 1
	s_waitcnt lgkmcnt(0)
	v_mfma_f32_16x16x32_bf16 v[64:67], v[0:3], v[32:35], 0
	v_mfma_f32_16x16x32_bf16 v[68:71], v[8:11], v[32:35], 0
	v_mfma_f32_16x16x32_bf16 v[72:75], v[0:3], v[40:43], 0
	v_mfma_f32_16x16x32_bf16 v[76:79], v[8:11], v[40:43], 0
	v_mfma_f32_16x16x32_bf16 v[80:83], v[0:3], v[48:51], 0
	v_mfma_f32_16x16x32_bf16 v[84:87], v[8:11], v[48:51], 0
	v_mfma_f32_16x16x32_bf16 v[88:91], v[0:3], v[56:59], 0
	v_mfma_f32_16x16x32_bf16 v[92:95], v[8:11], v[56:59], 0
	v_mfma_f32_16x16x32_bf16 v[64:67], v[4:7], v[36:39], v[64:67]
	v_mfma_f32_16x16x32_bf16 v[68:71], v[12:15], v[36:39], v[68:71]
	v_mfma_f32_16x16x32_bf16 v[72:75], v[4:7], v[44:47], v[72:75]
	v_mfma_f32_16x16x32_bf16 v[76:79], v[12:15], v[44:47], v[76:79]
	v_mfma_f32_16x16x32_bf16 v[80:83], v[4:7], v[52:55], v[80:83]
	v_mfma_f32_16x16x32_bf16 v[84:87], v[12:15], v[52:55], v[84:87]
	v_mfma_f32_16x16x32_bf16 v[88:91], v[4:7], v[60:63], v[88:91]
	v_mfma_f32_16x16x32_bf16 v[92:95], v[12:15], v[60:63], v[92:95]
	s_setprio 0
	s_setprio 1
	v_mfma_f32_16x16x32_bf16 v[96:99], v[16:19], v[32:35], 0
	v_mfma_f32_16x16x32_bf16 v[32:35], v[24:27], v[32:35], 0
	v_mfma_f32_16x16x32_bf16 v[96:99], v[20:23], v[36:39], v[96:99]
	v_mfma_f32_16x16x32_bf16 v[32:35], v[28:31], v[36:39], v[32:35]
	v_mfma_f32_16x16x32_bf16 v[36:39], v[16:19], v[40:43], 0
	v_mfma_f32_16x16x32_bf16 v[40:43], v[24:27], v[40:43], 0
	v_mfma_f32_16x16x32_bf16 v[36:39], v[20:23], v[44:47], v[36:39]
	v_mfma_f32_16x16x32_bf16 v[40:43], v[28:31], v[44:47], v[40:43]
	v_mfma_f32_16x16x32_bf16 v[44:47], v[16:19], v[48:51], 0
	v_mfma_f32_16x16x32_bf16 v[48:51], v[24:27], v[48:51], 0
	v_mfma_f32_16x16x32_bf16 v[44:47], v[20:23], v[52:55], v[44:47]
	v_mfma_f32_16x16x32_bf16 v[48:51], v[28:31], v[52:55], v[48:51]
	v_mfma_f32_16x16x32_bf16 v[52:55], v[16:19], v[56:59], 0
	v_mfma_f32_16x16x32_bf16 v[56:59], v[24:27], v[56:59], 0
	v_mfma_f32_16x16x32_bf16 v[52:55], v[20:23], v[60:63], v[52:55]
	v_mfma_f32_16x16x32_bf16 v[56:59], v[28:31], v[60:63], v[56:59]
	s_setprio 0
	s_barrier
	s_add_i32 s68, s59, s52
	v_lshl_add_u64 v[156:157], s[42:43], 0, v[130:131]
	s_add_i32 s31, s68, 0x2000
	v_lshl_add_u64 v[140:141], v[156:157], 0, s[16:17]
	s_mov_b32 m0, s68
	v_lshl_add_u64 v[214:215], s[42:43], 0, v[134:135]
	s_add_u32 s86, s42, 0x10100
	ds_read_b128 v[60:63], v163 offset:16384
	ds_read_b128 v[100:103], v163 offset:17408
	ds_read_b128 v[104:107], v163 offset:18432
	ds_read_b128 v[108:111], v163 offset:19456
	ds_read_b128 v[112:115], v163 offset:20480
	ds_read_b128 v[116:119], v163 offset:21504
	ds_read_b128 v[120:123], v163 offset:22528
	ds_read_b128 v[124:127], v163 offset:23552
	global_load_lds_dwordx4 v[140:141], off
	v_lshl_add_u64 v[140:141], v[214:215], 0, s[16:17]
	s_mov_b32 m0, s31
	s_addc_u32 s87, s43, 0
	s_add_i32 s66, s60, s52
	global_load_lds_dwordx4 v[140:141], off
	v_lshl_add_u64 v[140:141], s[86:87], 0, v[130:131]
	s_mov_b32 m0, s66
	s_add_i32 s67, s66, 0x2000
	global_load_lds_dwordx4 v[140:141], off
	s_mov_b32 m0, s67
	v_lshl_add_u64 v[216:217], s[40:41], 0, v[128:129]
	global_load_lds_dwordx4 v134, s[86:87]
	v_lshl_add_u64 v[140:141], v[216:217], 0, s[16:17]
	s_mov_b32 m0, s39
	v_lshl_add_u64 v[218:219], s[40:41], 0, v[132:133]
	global_load_lds_dwordx4 v[140:141], off
	v_lshl_add_u64 v[140:141], v[218:219], 0, s[16:17]
	s_mov_b32 m0, s53
	s_nop 0
	global_load_lds_dwordx4 v[140:141], off
	s_waitcnt vmcnt(8)
	s_waitcnt lgkmcnt(0)
	s_barrier
	s_setprio 1
	s_waitcnt lgkmcnt(0)
	v_mfma_f32_16x16x32_bf16 v[140:143], v[0:3], v[60:63], 0
	v_mfma_f32_16x16x32_bf16 v[148:151], v[0:3], v[104:107], 0
	v_mfma_f32_16x16x32_bf16 v[166:169], v[0:3], v[112:115], 0
	v_mfma_f32_16x16x32_bf16 v[0:3], v[0:3], v[120:123], 0
	v_mfma_f32_16x16x32_bf16 v[140:143], v[4:7], v[100:103], v[140:143]
	v_mfma_f32_16x16x32_bf16 v[148:151], v[4:7], v[108:111], v[148:151]
	v_mfma_f32_16x16x32_bf16 v[166:169], v[4:7], v[116:119], v[166:169]
	v_mfma_f32_16x16x32_bf16 v[0:3], v[4:7], v[124:127], v[0:3]
	v_mfma_f32_16x16x32_bf16 v[4:7], v[8:11], v[120:123], 0
	v_mfma_f32_16x16x32_bf16 v[144:147], v[8:11], v[60:63], 0
	v_mfma_f32_16x16x32_bf16 v[152:155], v[8:11], v[104:107], 0
	v_mfma_f32_16x16x32_bf16 v[170:173], v[8:11], v[112:115], 0
	v_mfma_f32_16x16x32_bf16 v[4:7], v[12:15], v[124:127], v[4:7]
	v_mfma_f32_16x16x32_bf16 v[144:147], v[12:15], v[100:103], v[144:147]
	v_mfma_f32_16x16x32_bf16 v[152:155], v[12:15], v[108:111], v[152:155]
	v_mfma_f32_16x16x32_bf16 v[170:173], v[12:15], v[116:119], v[170:173]
	s_setprio 0
	s_setprio 1
	v_mfma_f32_16x16x32_bf16 v[8:11], v[16:19], v[60:63], 0
	v_mfma_f32_16x16x32_bf16 v[12:15], v[24:27], v[60:63], 0
	v_mfma_f32_16x16x32_bf16 v[8:11], v[20:23], v[100:103], v[8:11]
	v_mfma_f32_16x16x32_bf16 v[12:15], v[28:31], v[100:103], v[12:15]
	v_mfma_f32_16x16x32_bf16 v[60:63], v[16:19], v[104:107], 0
	v_mfma_f32_16x16x32_bf16 v[100:103], v[24:27], v[104:107], 0
	v_mfma_f32_16x16x32_bf16 v[104:107], v[16:19], v[112:115], 0
	v_mfma_f32_16x16x32_bf16 v[16:19], v[16:19], v[120:123], 0
	v_mfma_f32_16x16x32_bf16 v[60:63], v[20:23], v[108:111], v[60:63]
	v_mfma_f32_16x16x32_bf16 v[100:103], v[28:31], v[108:111], v[100:103]
	v_mfma_f32_16x16x32_bf16 v[104:107], v[20:23], v[116:119], v[104:107]
	v_mfma_f32_16x16x32_bf16 v[108:111], v[24:27], v[112:115], 0
	v_mfma_f32_16x16x32_bf16 v[16:19], v[20:23], v[124:127], v[16:19]
	v_mfma_f32_16x16x32_bf16 v[20:23], v[24:27], v[120:123], 0
	v_mfma_f32_16x16x32_bf16 v[108:111], v[28:31], v[116:119], v[108:111]
	v_mfma_f32_16x16x32_bf16 v[20:23], v[28:31], v[124:127], v[20:23]
	s_setprio 0
	s_barrier
	s_add_i32 s85, 0, 0x18000
	s_add_i32 s88, 0, 0x1c000
	v_add_u32_e32 v165, s85, v159
	v_add_u32_e32 v226, s88, v159
	ds_read_b128 v[24:27], v165
	ds_read_b128 v[28:31], v165 offset:1024
	ds_read_b128 v[112:115], v165 offset:2048
	ds_read_b128 v[116:119], v165 offset:3072
	ds_read_b128 v[120:123], v226
	ds_read_b128 v[124:127], v226 offset:1024
	ds_read_b128 v[174:177], v226 offset:2048
	ds_read_b128 v[178:181], v226 offset:3072
	s_add_u32 s86, s40, 0x10100
	s_addc_u32 s87, s41, 0
	s_mov_b32 m0, s54
	ds_read_b128 v[182:185], v163 offset:32768
	ds_read_b128 v[186:189], v163 offset:33792
	ds_read_b128 v[190:193], v163 offset:34816
	ds_read_b128 v[194:197], v163 offset:35840
	ds_read_b128 v[198:201], v163 offset:36864
	ds_read_b128 v[202:205], v163 offset:37888
	ds_read_b128 v[206:209], v163 offset:38912
	ds_read_b128 v[210:213], v163 offset:39936
	global_load_lds_dwordx4 v128, s[86:87]
	s_mov_b32 m0, s55
	s_nop 0
	global_load_lds_dwordx4 v132, s[86:87]
	s_waitcnt vmcnt(8)
	s_waitcnt lgkmcnt(0)
	s_barrier
	s_setprio 1
	s_waitcnt lgkmcnt(0)
	v_mfma_f32_16x16x32_bf16 v[64:67], v[24:27], v[182:185], v[64:67]
	v_mfma_f32_16x16x32_bf16 v[68:71], v[112:115], v[182:185], v[68:71]
	v_mfma_f32_16x16x32_bf16 v[72:75], v[24:27], v[190:193], v[72:75]
	v_mfma_f32_16x16x32_bf16 v[76:79], v[112:115], v[190:193], v[76:79]
	v_mfma_f32_16x16x32_bf16 v[80:83], v[24:27], v[198:201], v[80:83]
	v_mfma_f32_16x16x32_bf16 v[84:87], v[112:115], v[198:201], v[84:87]
	v_mfma_f32_16x16x32_bf16 v[88:91], v[24:27], v[206:209], v[88:91]
	v_mfma_f32_16x16x32_bf16 v[92:95], v[112:115], v[206:209], v[92:95]
	v_mfma_f32_16x16x32_bf16 v[64:67], v[28:31], v[186:189], v[64:67]
	v_mfma_f32_16x16x32_bf16 v[68:71], v[116:119], v[186:189], v[68:71]
	v_mfma_f32_16x16x32_bf16 v[72:75], v[28:31], v[194:197], v[72:75]
	v_mfma_f32_16x16x32_bf16 v[76:79], v[116:119], v[194:197], v[76:79]
	v_mfma_f32_16x16x32_bf16 v[80:83], v[28:31], v[202:205], v[80:83]
	v_mfma_f32_16x16x32_bf16 v[84:87], v[116:119], v[202:205], v[84:87]
	v_mfma_f32_16x16x32_bf16 v[88:91], v[28:31], v[210:213], v[88:91]
	v_mfma_f32_16x16x32_bf16 v[92:95], v[116:119], v[210:213], v[92:95]
	s_setprio 0
	s_setprio 1
	v_mfma_f32_16x16x32_bf16 v[96:99], v[120:123], v[182:185], v[96:99]
	v_mfma_f32_16x16x32_bf16 v[32:35], v[174:177], v[182:185], v[32:35]
	v_mfma_f32_16x16x32_bf16 v[36:39], v[120:123], v[190:193], v[36:39]
	v_mfma_f32_16x16x32_bf16 v[40:43], v[174:177], v[190:193], v[40:43]
	v_mfma_f32_16x16x32_bf16 v[44:47], v[120:123], v[198:201], v[44:47]
	v_mfma_f32_16x16x32_bf16 v[48:51], v[174:177], v[198:201], v[48:51]
	v_mfma_f32_16x16x32_bf16 v[52:55], v[120:123], v[206:209], v[52:55]
	v_mfma_f32_16x16x32_bf16 v[56:59], v[174:177], v[206:209], v[56:59]
	v_mfma_f32_16x16x32_bf16 v[96:99], v[124:127], v[186:189], v[96:99]
	v_mfma_f32_16x16x32_bf16 v[32:35], v[178:181], v[186:189], v[32:35]
	v_mfma_f32_16x16x32_bf16 v[36:39], v[124:127], v[194:197], v[36:39]
	v_mfma_f32_16x16x32_bf16 v[40:43], v[178:181], v[194:197], v[40:43]
	v_mfma_f32_16x16x32_bf16 v[44:47], v[124:127], v[202:205], v[44:47]
	v_mfma_f32_16x16x32_bf16 v[48:51], v[178:181], v[202:205], v[48:51]
	v_mfma_f32_16x16x32_bf16 v[52:55], v[124:127], v[210:213], v[52:55]
	v_mfma_f32_16x16x32_bf16 v[56:59], v[178:181], v[210:213], v[56:59]
	s_setprio 0
	s_barrier
	s_add_i32 s85, s85, s52
	s_add_i32 s69, s85, 0x2000
	v_lshl_add_u64 v[156:157], v[156:157], 0, s[18:19]
	s_mov_b32 m0, s85
	s_add_u32 s86, s42, 0x10180
	ds_read_b128 v[182:185], v163 offset:49152
	ds_read_b128 v[186:189], v163 offset:50176
	ds_read_b128 v[190:193], v163 offset:51200
	ds_read_b128 v[194:197], v163 offset:52224
	ds_read_b128 v[198:201], v163 offset:53248
	ds_read_b128 v[202:205], v163 offset:54272
	ds_read_b128 v[206:209], v163 offset:55296
	ds_read_b128 v[210:213], v163 offset:56320
	global_load_lds_dwordx4 v[156:157], off
	v_lshl_add_u64 v[156:157], v[214:215], 0, s[18:19]
	s_mov_b32 m0, s69
	s_addc_u32 s87, s43, 0
	s_add_i32 s42, s88, s52
	global_load_lds_dwordx4 v[156:157], off
	v_lshl_add_u64 v[156:157], s[86:87], 0, v[130:131]
	s_mov_b32 m0, s42
	s_add_i32 s43, s42, 0x2000
	global_load_lds_dwordx4 v[156:157], off
	s_mov_b32 m0, s43
	s_nop 0
	global_load_lds_dwordx4 v134, s[86:87]
	v_lshl_add_u64 v[156:157], v[216:217], 0, s[18:19]
	s_mov_b32 m0, s56
	s_nop 0
	global_load_lds_dwordx4 v[156:157], off
	v_lshl_add_u64 v[156:157], v[218:219], 0, s[18:19]
	s_mov_b32 m0, s57
	s_nop 0
	global_load_lds_dwordx4 v[156:157], off
	s_waitcnt vmcnt(8)
	s_waitcnt lgkmcnt(0)
	s_barrier
	s_setprio 1
	s_waitcnt lgkmcnt(0)
	v_mfma_f32_16x16x32_bf16 v[0:3], v[24:27], v[206:209], v[0:3]
	v_mfma_f32_16x16x32_bf16 v[4:7], v[112:115], v[206:209], v[4:7]
	v_mfma_f32_16x16x32_bf16 v[140:143], v[24:27], v[182:185], v[140:143]
	v_mfma_f32_16x16x32_bf16 v[144:147], v[112:115], v[182:185], v[144:147]
	v_mfma_f32_16x16x32_bf16 v[148:151], v[24:27], v[190:193], v[148:151]
	v_mfma_f32_16x16x32_bf16 v[152:155], v[112:115], v[190:193], v[152:155]
	v_mfma_f32_16x16x32_bf16 v[166:169], v[24:27], v[198:201], v[166:169]
	v_mfma_f32_16x16x32_bf16 v[170:173], v[112:115], v[198:201], v[170:173]
	v_mfma_f32_16x16x32_bf16 v[0:3], v[28:31], v[210:213], v[0:3]
	v_mfma_f32_16x16x32_bf16 v[4:7], v[116:119], v[210:213], v[4:7]
	v_mfma_f32_16x16x32_bf16 v[140:143], v[28:31], v[186:189], v[140:143]
	v_mfma_f32_16x16x32_bf16 v[144:147], v[116:119], v[186:189], v[144:147]
	v_mfma_f32_16x16x32_bf16 v[148:151], v[28:31], v[194:197], v[148:151]
	v_mfma_f32_16x16x32_bf16 v[152:155], v[116:119], v[194:197], v[152:155]
	v_mfma_f32_16x16x32_bf16 v[166:169], v[28:31], v[202:205], v[166:169]
	v_mfma_f32_16x16x32_bf16 v[170:173], v[116:119], v[202:205], v[170:173]
	s_setprio 0
	s_setprio 1
	v_mfma_f32_16x16x32_bf16 v[8:11], v[120:123], v[182:185], v[8:11]
	v_mfma_f32_16x16x32_bf16 v[12:15], v[174:177], v[182:185], v[12:15]
	v_mfma_f32_16x16x32_bf16 v[24:27], v[120:123], v[190:193], v[60:63]
	v_mfma_f32_16x16x32_bf16 v[28:31], v[174:177], v[190:193], v[100:103]
	v_mfma_f32_16x16x32_bf16 v[60:63], v[120:123], v[198:201], v[104:107]
	v_mfma_f32_16x16x32_bf16 v[100:103], v[174:177], v[198:201], v[108:111]
	v_mfma_f32_16x16x32_bf16 v[16:19], v[120:123], v[206:209], v[16:19]
	v_mfma_f32_16x16x32_bf16 v[20:23], v[174:177], v[206:209], v[20:23]
	v_mfma_f32_16x16x32_bf16 v[8:11], v[124:127], v[186:189], v[8:11]
	v_mfma_f32_16x16x32_bf16 v[12:15], v[178:181], v[186:189], v[12:15]
	v_mfma_f32_16x16x32_bf16 v[24:27], v[124:127], v[194:197], v[24:27]
	v_mfma_f32_16x16x32_bf16 v[28:31], v[178:181], v[194:197], v[28:31]
	v_mfma_f32_16x16x32_bf16 v[60:63], v[124:127], v[202:205], v[60:63]
	v_mfma_f32_16x16x32_bf16 v[100:103], v[178:181], v[202:205], v[100:103]
	v_mfma_f32_16x16x32_bf16 v[16:19], v[124:127], v[210:213], v[16:19]
	v_mfma_f32_16x16x32_bf16 v[20:23], v[178:181], v[210:213], v[20:23]
	s_setprio 0
	s_barrier
	ds_read_b128 v[104:107], v161
	ds_read_b128 v[108:111], v161 offset:1024
	ds_read_b128 v[112:115], v161 offset:2048
	ds_read_b128 v[116:119], v161 offset:3072
	ds_read_b128 v[120:123], v162
	ds_read_b128 v[124:127], v162 offset:1024
	ds_read_b128 v[174:177], v162 offset:2048
	ds_read_b128 v[178:181], v162 offset:3072
	s_add_u32 s40, s40, 0x10180
	s_addc_u32 s41, s41, 0
	s_mov_b32 m0, s84
	ds_read_b128 v[182:185], v163
	ds_read_b128 v[186:189], v163 offset:1024
	ds_read_b128 v[190:193], v163 offset:2048
	ds_read_b128 v[194:197], v163 offset:3072
	ds_read_b128 v[198:201], v163 offset:4096
	ds_read_b128 v[202:205], v163 offset:5120
	ds_read_b128 v[206:209], v163 offset:6144
	ds_read_b128 v[210:213], v163 offset:7168
	global_load_lds_dwordx4 v128, s[40:41]
	s_mov_b32 m0, s29
	s_nop 0
	global_load_lds_dwordx4 v132, s[40:41]
	s_waitcnt vmcnt(8)
	s_waitcnt lgkmcnt(0)
	s_barrier
	s_setprio 1
	s_waitcnt lgkmcnt(0)
	v_mfma_f32_16x16x32_bf16 v[64:67], v[104:107], v[182:185], v[64:67]
	v_mfma_f32_16x16x32_bf16 v[68:71], v[112:115], v[182:185], v[68:71]
	v_mfma_f32_16x16x32_bf16 v[72:75], v[104:107], v[190:193], v[72:75]
	v_mfma_f32_16x16x32_bf16 v[76:79], v[112:115], v[190:193], v[76:79]
	v_mfma_f32_16x16x32_bf16 v[80:83], v[104:107], v[198:201], v[80:83]
	v_mfma_f32_16x16x32_bf16 v[84:87], v[112:115], v[198:201], v[84:87]
	v_mfma_f32_16x16x32_bf16 v[88:91], v[104:107], v[206:209], v[88:91]
	v_mfma_f32_16x16x32_bf16 v[64:67], v[108:111], v[186:189], v[64:67]
	v_mfma_f32_16x16x32_bf16 v[68:71], v[116:119], v[186:189], v[68:71]
	v_mfma_f32_16x16x32_bf16 v[72:75], v[108:111], v[194:197], v[72:75]
	v_mfma_f32_16x16x32_bf16 v[76:79], v[116:119], v[194:197], v[76:79]
	v_mfma_f32_16x16x32_bf16 v[80:83], v[108:111], v[202:205], v[80:83]
	v_mfma_f32_16x16x32_bf16 v[84:87], v[116:119], v[202:205], v[84:87]
	v_mfma_f32_16x16x32_bf16 v[214:217], v[108:111], v[210:213], v[88:91]
	v_mfma_f32_16x16x32_bf16 v[88:91], v[112:115], v[206:209], v[92:95]
	v_mfma_f32_16x16x32_bf16 v[218:221], v[116:119], v[210:213], v[88:91]
	s_setprio 0
	s_setprio 1
	v_mfma_f32_16x16x32_bf16 v[88:91], v[120:123], v[182:185], v[96:99]
	v_mfma_f32_16x16x32_bf16 v[32:35], v[174:177], v[182:185], v[32:35]
	v_mfma_f32_16x16x32_bf16 v[36:39], v[120:123], v[190:193], v[36:39]
	v_mfma_f32_16x16x32_bf16 v[40:43], v[174:177], v[190:193], v[40:43]
	v_mfma_f32_16x16x32_bf16 v[44:47], v[120:123], v[198:201], v[44:47]
	v_mfma_f32_16x16x32_bf16 v[48:51], v[174:177], v[198:201], v[48:51]
	v_mfma_f32_16x16x32_bf16 v[52:55], v[120:123], v[206:209], v[52:55]
	v_mfma_f32_16x16x32_bf16 v[56:59], v[174:177], v[206:209], v[56:59]
	v_mfma_f32_16x16x32_bf16 v[96:99], v[124:127], v[186:189], v[88:91]
	v_mfma_f32_16x16x32_bf16 v[32:35], v[178:181], v[186:189], v[32:35]
	v_mfma_f32_16x16x32_bf16 v[36:39], v[124:127], v[194:197], v[36:39]
	v_mfma_f32_16x16x32_bf16 v[40:43], v[178:181], v[194:197], v[40:43]
	v_mfma_f32_16x16x32_bf16 v[44:47], v[124:127], v[202:205], v[44:47]
	v_mfma_f32_16x16x32_bf16 v[48:51], v[178:181], v[202:205], v[48:51]
	v_mfma_f32_16x16x32_bf16 v[52:55], v[124:127], v[210:213], v[52:55]
	v_mfma_f32_16x16x32_bf16 v[56:59], v[178:181], v[210:213], v[56:59]
	s_setprio 0
	s_barrier
	s_mov_b32 m0, s68
	v_lshl_add_u64 v[156:157], s[44:45], 0, v[130:131]
	s_add_u32 s40, s44, 0x10000
	ds_read_b128 v[88:91], v163 offset:16384
	ds_read_b128 v[92:95], v163 offset:17408
	ds_read_b128 v[182:185], v163 offset:18432
	ds_read_b128 v[186:189], v163 offset:19456
	ds_read_b128 v[190:193], v163 offset:20480
	ds_read_b128 v[194:197], v163 offset:21504
	ds_read_b128 v[198:201], v163 offset:22528
	ds_read_b128 v[202:205], v163 offset:23552
	global_load_lds_dwordx4 v[156:157], off
	v_lshl_add_u64 v[250:251], s[44:45], 0, v[134:135]
	s_mov_b32 m0, s31
	s_addc_u32 s41, s45, 0
	global_load_lds_dwordx4 v[250:251], off
	v_lshl_add_u64 v[206:207], s[40:41], 0, v[130:131]
	s_mov_b32 m0, s66
	v_lshl_add_u64 v[252:253], s[46:47], 0, v[128:129]
	global_load_lds_dwordx4 v[206:207], off
	s_mov_b32 m0, s67
	v_lshl_add_u64 v[136:137], s[46:47], 0, v[132:133]
	global_load_lds_dwordx4 v134, s[40:41]
	s_mov_b32 m0, s39
	s_nop 0
	global_load_lds_dwordx4 v[252:253], off
	s_mov_b32 m0, s53
	s_nop 0
	global_load_lds_dwordx4 v[136:137], off
	s_waitcnt vmcnt(8)
	s_waitcnt lgkmcnt(0)
	s_barrier
	s_setprio 1
	s_waitcnt lgkmcnt(0)
	v_mfma_f32_16x16x32_bf16 v[0:3], v[104:107], v[198:201], v[0:3]
	v_mfma_f32_16x16x32_bf16 v[4:7], v[112:115], v[198:201], v[4:7]
	v_mfma_f32_16x16x32_bf16 v[140:143], v[104:107], v[88:91], v[140:143]
	v_mfma_f32_16x16x32_bf16 v[144:147], v[112:115], v[88:91], v[144:147]
	v_mfma_f32_16x16x32_bf16 v[148:151], v[104:107], v[182:185], v[148:151]
	v_mfma_f32_16x16x32_bf16 v[152:155], v[112:115], v[182:185], v[152:155]
	v_mfma_f32_16x16x32_bf16 v[166:169], v[104:107], v[190:193], v[166:169]
	v_mfma_f32_16x16x32_bf16 v[170:173], v[112:115], v[190:193], v[170:173]
	v_mfma_f32_16x16x32_bf16 v[0:3], v[108:111], v[202:205], v[0:3]
	v_mfma_f32_16x16x32_bf16 v[4:7], v[116:119], v[202:205], v[4:7]
	v_mfma_f32_16x16x32_bf16 v[140:143], v[108:111], v[92:95], v[140:143]
	v_mfma_f32_16x16x32_bf16 v[144:147], v[116:119], v[92:95], v[144:147]
	v_mfma_f32_16x16x32_bf16 v[148:151], v[108:111], v[186:189], v[148:151]
	v_mfma_f32_16x16x32_bf16 v[152:155], v[116:119], v[186:189], v[152:155]
	v_mfma_f32_16x16x32_bf16 v[166:169], v[108:111], v[194:197], v[166:169]
	v_mfma_f32_16x16x32_bf16 v[170:173], v[116:119], v[194:197], v[170:173]
	s_setprio 0
	s_setprio 1
	v_mfma_f32_16x16x32_bf16 v[8:11], v[120:123], v[88:91], v[8:11]
	v_mfma_f32_16x16x32_bf16 v[206:209], v[124:127], v[92:95], v[8:11]
	v_mfma_f32_16x16x32_bf16 v[8:11], v[174:177], v[88:91], v[12:15]
	v_mfma_f32_16x16x32_bf16 v[210:213], v[178:181], v[92:95], v[8:11]
	v_mfma_f32_16x16x32_bf16 v[8:11], v[120:123], v[182:185], v[24:27]
	v_mfma_f32_16x16x32_bf16 v[222:225], v[124:127], v[186:189], v[8:11]
	v_mfma_f32_16x16x32_bf16 v[8:11], v[174:177], v[182:185], v[28:31]
	v_mfma_f32_16x16x32_bf16 v[182:185], v[178:181], v[186:189], v[8:11]
	v_mfma_f32_16x16x32_bf16 v[8:11], v[120:123], v[190:193], v[60:63]
	v_mfma_f32_16x16x32_bf16 v[186:189], v[124:127], v[194:197], v[8:11]
	v_mfma_f32_16x16x32_bf16 v[8:11], v[174:177], v[190:193], v[100:103]
	v_mfma_f32_16x16x32_bf16 v[190:193], v[178:181], v[194:197], v[8:11]
	v_mfma_f32_16x16x32_bf16 v[8:11], v[120:123], v[198:201], v[16:19]
	v_mfma_f32_16x16x32_bf16 v[194:197], v[124:127], v[202:205], v[8:11]
	v_mfma_f32_16x16x32_bf16 v[8:11], v[174:177], v[198:201], v[20:23]
	v_mfma_f32_16x16x32_bf16 v[174:177], v[178:181], v[202:205], v[8:11]
	s_setprio 0
	s_barrier
	s_nop 4
	ds_read_b128 v[8:11], v165
	ds_read_b128 v[12:15], v165 offset:1024
	ds_read_b128 v[16:19], v165 offset:2048
	ds_read_b128 v[20:23], v165 offset:3072
	ds_read_b128 v[178:181], v226
	ds_read_b128 v[198:201], v226 offset:1024
	ds_read_b128 v[202:205], v226 offset:2048
	ds_read_b128 v[226:229], v226 offset:3072
	s_add_u32 s40, s46, 0x10000
	s_addc_u32 s41, s47, 0
	s_mov_b32 m0, s54
	ds_read_b128 v[24:27], v163 offset:32768
	ds_read_b128 v[28:31], v163 offset:33792
	ds_read_b128 v[60:63], v163 offset:34816
	ds_read_b128 v[230:233], v163 offset:35840
	ds_read_b128 v[234:237], v163 offset:36864
	ds_read_b128 v[238:241], v163 offset:37888
	ds_read_b128 v[242:245], v163 offset:38912
	ds_read_b128 v[246:249], v163 offset:39936
	global_load_lds_dwordx4 v128, s[40:41]
	s_mov_b32 m0, s55
	s_nop 0
	global_load_lds_dwordx4 v132, s[40:41]
	s_waitcnt vmcnt(8)
	s_waitcnt lgkmcnt(0)
	s_barrier
	s_setprio 1
	s_waitcnt lgkmcnt(0)
	v_mfma_f32_16x16x32_bf16 v[64:67], v[8:11], v[24:27], v[64:67]
	v_mfma_f32_16x16x32_bf16 v[124:127], v[12:15], v[28:31], v[64:67]
	v_mfma_f32_16x16x32_bf16 v[64:67], v[16:19], v[24:27], v[68:71]
	v_mfma_f32_16x16x32_bf16 v[120:123], v[20:23], v[28:31], v[64:67]
	v_mfma_f32_16x16x32_bf16 v[64:67], v[8:11], v[60:63], v[72:75]
	v_mfma_f32_16x16x32_bf16 v[108:111], v[12:15], v[230:233], v[64:67]
	v_mfma_f32_16x16x32_bf16 v[64:67], v[16:19], v[60:63], v[76:79]
	v_mfma_f32_16x16x32_bf16 v[104:107], v[20:23], v[230:233], v[64:67]
	v_mfma_f32_16x16x32_bf16 v[64:67], v[8:11], v[234:237], v[80:83]
	v_mfma_f32_16x16x32_bf16 v[92:95], v[12:15], v[238:241], v[64:67]
	v_mfma_f32_16x16x32_bf16 v[64:67], v[16:19], v[234:237], v[84:87]
	v_mfma_f32_16x16x32_bf16 v[88:91], v[20:23], v[238:241], v[64:67]
	v_mfma_f32_16x16x32_bf16 v[64:67], v[8:11], v[242:245], v[214:217]
	v_mfma_f32_16x16x32_bf16 v[68:71], v[12:15], v[246:249], v[64:67]
	v_mfma_f32_16x16x32_bf16 v[64:67], v[16:19], v[242:245], v[218:221]
	v_mfma_f32_16x16x32_bf16 v[64:67], v[20:23], v[246:249], v[64:67]
	s_setprio 0
	s_setprio 1
	v_mfma_f32_16x16x32_bf16 v[72:75], v[178:181], v[24:27], v[96:99]
	v_mfma_f32_16x16x32_bf16 v[24:27], v[202:205], v[24:27], v[32:35]
	v_mfma_f32_16x16x32_bf16 v[112:115], v[226:229], v[28:31], v[24:27]
	v_mfma_f32_16x16x32_bf16 v[24:27], v[178:181], v[60:63], v[36:39]
	v_mfma_f32_16x16x32_bf16 v[100:103], v[198:201], v[230:233], v[24:27]
	v_mfma_f32_16x16x32_bf16 v[24:27], v[202:205], v[60:63], v[40:43]
	v_mfma_f32_16x16x32_bf16 v[96:99], v[226:229], v[230:233], v[24:27]
	v_mfma_f32_16x16x32_bf16 v[24:27], v[178:181], v[234:237], v[44:47]
	v_mfma_f32_16x16x32_bf16 v[84:87], v[198:201], v[238:241], v[24:27]
	v_mfma_f32_16x16x32_bf16 v[24:27], v[202:205], v[234:237], v[48:51]
	v_mfma_f32_16x16x32_bf16 v[80:83], v[226:229], v[238:241], v[24:27]
	v_mfma_f32_16x16x32_bf16 v[24:27], v[178:181], v[242:245], v[52:55]
	v_mfma_f32_16x16x32_bf16 v[52:55], v[198:201], v[246:249], v[24:27]
	v_mfma_f32_16x16x32_bf16 v[24:27], v[202:205], v[242:245], v[56:59]
	v_mfma_f32_16x16x32_bf16 v[116:119], v[198:201], v[28:31], v[72:75]
	v_mfma_f32_16x16x32_bf16 v[48:51], v[226:229], v[246:249], v[24:27]
	s_setprio 0
	s_barrier
	s_mov_b32 m0, s85
	s_nop 2
	v_lshl_add_u64 v[24:25], v[156:157], 0, s[8:9]
	s_add_u32 s40, s44, 0x10080
	ds_read_b128 v[32:35], v163 offset:49152
	ds_read_b128 v[36:39], v163 offset:50176
	ds_read_b128 v[214:217], v163 offset:51200
	ds_read_b128 v[218:221], v163 offset:52224
	ds_read_b128 v[230:233], v163 offset:53248
	ds_read_b128 v[234:237], v163 offset:54272
	ds_read_b128 v[238:241], v163 offset:55296
	ds_read_b128 v[242:245], v163 offset:56320
	global_load_lds_dwordx4 v[24:25], off
	v_lshl_add_u64 v[24:25], v[250:251], 0, s[8:9]
	s_mov_b32 m0, s69
	s_addc_u32 s41, s45, 0
	global_load_lds_dwordx4 v[24:25], off
	v_lshl_add_u64 v[24:25], s[40:41], 0, v[130:131]
	s_mov_b32 m0, s42
	s_nop 0
	global_load_lds_dwordx4 v[24:25], off
	s_mov_b32 m0, s43
	s_nop 0
	global_load_lds_dwordx4 v134, s[40:41]
	v_lshl_add_u64 v[24:25], v[252:253], 0, s[8:9]
	s_mov_b32 m0, s56
	s_nop 0
	global_load_lds_dwordx4 v[24:25], off
	v_lshl_add_u64 v[24:25], v[136:137], 0, s[8:9]
	s_mov_b32 m0, s57
	s_nop 0
	global_load_lds_dwordx4 v[24:25], off
	s_waitcnt vmcnt(8)
	s_waitcnt lgkmcnt(0)
	s_barrier
	s_setprio 1
	s_waitcnt lgkmcnt(0)
	v_mfma_f32_16x16x32_bf16 v[24:27], v[8:11], v[32:35], v[140:143]
	v_mfma_f32_16x16x32_bf16 v[76:79], v[12:15], v[36:39], v[24:27]
	v_mfma_f32_16x16x32_bf16 v[24:27], v[16:19], v[32:35], v[144:147]
	v_mfma_f32_16x16x32_bf16 v[72:75], v[20:23], v[36:39], v[24:27]
	v_mfma_f32_16x16x32_bf16 v[24:27], v[8:11], v[214:217], v[148:151]
	v_mfma_f32_16x16x32_bf16 v[44:47], v[12:15], v[218:221], v[24:27]
	v_mfma_f32_16x16x32_bf16 v[24:27], v[16:19], v[214:217], v[152:155]
	v_mfma_f32_16x16x32_bf16 v[40:43], v[20:23], v[218:221], v[24:27]
	v_mfma_f32_16x16x32_bf16 v[24:27], v[8:11], v[230:233], v[166:169]
	v_mfma_f32_16x16x32_bf16 v[0:3], v[8:11], v[238:241], v[0:3]
	v_mfma_f32_16x16x32_bf16 v[28:31], v[12:15], v[234:237], v[24:27]
	v_mfma_f32_16x16x32_bf16 v[24:27], v[16:19], v[230:233], v[170:173]
	v_mfma_f32_16x16x32_bf16 v[12:15], v[12:15], v[242:245], v[0:3]
	v_mfma_f32_16x16x32_bf16 v[0:3], v[16:19], v[238:241], v[4:7]
	v_mfma_f32_16x16x32_bf16 v[24:27], v[20:23], v[234:237], v[24:27]
	v_mfma_f32_16x16x32_bf16 v[8:11], v[20:23], v[242:245], v[0:3]
	s_setprio 0
	s_setprio 1
	v_mfma_f32_16x16x32_bf16 v[0:3], v[178:181], v[32:35], v[206:209]
	v_mfma_f32_16x16x32_bf16 v[60:63], v[198:201], v[36:39], v[0:3]
	v_mfma_f32_16x16x32_bf16 v[0:3], v[202:205], v[32:35], v[210:213]
	v_mfma_f32_16x16x32_bf16 v[56:59], v[226:229], v[36:39], v[0:3]
	v_mfma_f32_16x16x32_bf16 v[0:3], v[178:181], v[214:217], v[222:225]
	v_mfma_f32_16x16x32_bf16 v[36:39], v[198:201], v[218:221], v[0:3]
	v_mfma_f32_16x16x32_bf16 v[0:3], v[202:205], v[214:217], v[182:185]
	v_mfma_f32_16x16x32_bf16 v[32:35], v[226:229], v[218:221], v[0:3]
	v_mfma_f32_16x16x32_bf16 v[0:3], v[178:181], v[230:233], v[186:189]
	v_mfma_f32_16x16x32_bf16 v[20:23], v[198:201], v[234:237], v[0:3]
	v_mfma_f32_16x16x32_bf16 v[0:3], v[202:205], v[230:233], v[190:193]
	v_mfma_f32_16x16x32_bf16 v[16:19], v[226:229], v[234:237], v[0:3]
	v_mfma_f32_16x16x32_bf16 v[0:3], v[178:181], v[238:241], v[194:197]
	v_mfma_f32_16x16x32_bf16 v[4:7], v[198:201], v[242:245], v[0:3]
	v_mfma_f32_16x16x32_bf16 v[0:3], v[202:205], v[238:241], v[174:177]
	v_mfma_f32_16x16x32_bf16 v[0:3], v[226:229], v[242:245], v[0:3]
	s_setprio 0
	s_barrier
	s_andn2_b64 vcc, exec, s[12:13]
	s_cbranch_vccnz .LBB0_1282
	s_barrier

.LBB0_1337:
	ds_read_b128 v[144:147], v151
	ds_read_b128 v[156:159], v151 offset:1024
	ds_read_b128 v[160:163], v151 offset:2048
	ds_read_b128 v[164:167], v151 offset:3072
	ds_read_b128 v[168:171], v152
	ds_read_b128 v[172:175], v152 offset:1024
	ds_read_b128 v[176:179], v152 offset:2048
	ds_read_b128 v[180:183], v152 offset:3072
	s_add_u32 s26, s24, 0xfffc0080
	s_addc_u32 s27, s25, -1
	s_cmp_eq_u32 s50, 12
	s_cselect_b32 s29, s17, s27
	s_cselect_b32 s28, s23, s26
	s_cselect_b32 s27, s15, s49
	s_cselect_b32 s26, s47, s48
	s_add_i32 m0, s35, 0xc000
	ds_read_b128 v[184:187], v153
	ds_read_b128 v[188:191], v153 offset:1024
	ds_read_b128 v[192:195], v153 offset:2048
	ds_read_b128 v[196:199], v153 offset:3072
	ds_read_b128 v[200:203], v153 offset:4096
	ds_read_b128 v[204:207], v153 offset:5120
	ds_read_b128 v[208:211], v153 offset:6144
	ds_read_b128 v[212:215], v153 offset:7168
	global_load_lds_dwordx4 v136, s[24:25]
	s_add_i32 m0, s35, 0xe000
	s_nop 0
	global_load_lds_dwordx4 v138, s[24:25]
	s_waitcnt vmcnt(8)
	s_waitcnt lgkmcnt(0)
	s_barrier
	s_setprio 1
	s_waitcnt lgkmcnt(0)
	v_mfma_f32_16x16x32_bf16 v[124:127], v[144:147], v[184:187], v[124:127]
	v_mfma_f32_16x16x32_bf16 v[120:123], v[160:163], v[184:187], v[120:123]
	v_mfma_f32_16x16x32_bf16 v[108:111], v[144:147], v[192:195], v[108:111]
	v_mfma_f32_16x16x32_bf16 v[104:107], v[160:163], v[192:195], v[104:107]
	v_mfma_f32_16x16x32_bf16 v[92:95], v[144:147], v[200:203], v[92:95]
	v_mfma_f32_16x16x32_bf16 v[88:91], v[160:163], v[200:203], v[88:91]
	v_mfma_f32_16x16x32_bf16 v[76:79], v[144:147], v[208:211], v[76:79]
	v_mfma_f32_16x16x32_bf16 v[72:75], v[160:163], v[208:211], v[72:75]
	v_mfma_f32_16x16x32_bf16 v[124:127], v[156:159], v[188:191], v[124:127]
	v_mfma_f32_16x16x32_bf16 v[120:123], v[164:167], v[188:191], v[120:123]
	v_mfma_f32_16x16x32_bf16 v[108:111], v[156:159], v[196:199], v[108:111]
	v_mfma_f32_16x16x32_bf16 v[104:107], v[164:167], v[196:199], v[104:107]
	v_mfma_f32_16x16x32_bf16 v[92:95], v[156:159], v[204:207], v[92:95]
	v_mfma_f32_16x16x32_bf16 v[88:91], v[164:167], v[204:207], v[88:91]
	v_mfma_f32_16x16x32_bf16 v[76:79], v[156:159], v[212:215], v[76:79]
	v_mfma_f32_16x16x32_bf16 v[72:75], v[164:167], v[212:215], v[72:75]
	s_setprio 0
	s_setprio 1
	v_mfma_f32_16x16x32_bf16 v[116:119], v[168:171], v[184:187], v[116:119]
	v_mfma_f32_16x16x32_bf16 v[112:115], v[176:179], v[184:187], v[112:115]
	v_mfma_f32_16x16x32_bf16 v[100:103], v[168:171], v[192:195], v[100:103]
	v_mfma_f32_16x16x32_bf16 v[96:99], v[176:179], v[192:195], v[96:99]
	v_mfma_f32_16x16x32_bf16 v[84:87], v[168:171], v[200:203], v[84:87]
	v_mfma_f32_16x16x32_bf16 v[80:83], v[176:179], v[200:203], v[80:83]
	v_mfma_f32_16x16x32_bf16 v[68:71], v[168:171], v[208:211], v[68:71]
	v_mfma_f32_16x16x32_bf16 v[64:67], v[176:179], v[208:211], v[64:67]
	v_mfma_f32_16x16x32_bf16 v[116:119], v[172:175], v[188:191], v[116:119]
	v_mfma_f32_16x16x32_bf16 v[112:115], v[180:183], v[188:191], v[112:115]
	v_mfma_f32_16x16x32_bf16 v[100:103], v[172:175], v[196:199], v[100:103]
	v_mfma_f32_16x16x32_bf16 v[96:99], v[180:183], v[196:199], v[96:99]
	v_mfma_f32_16x16x32_bf16 v[84:87], v[172:175], v[204:207], v[84:87]
	v_mfma_f32_16x16x32_bf16 v[80:83], v[180:183], v[204:207], v[80:83]
	v_mfma_f32_16x16x32_bf16 v[68:71], v[172:175], v[212:215], v[68:71]
	v_mfma_f32_16x16x32_bf16 v[64:67], v[180:183], v[212:215], v[64:67]
	s_setprio 0
	s_barrier
	s_add_i32 s51, s44, s34
	v_lshl_add_u64 v[216:217], s[26:27], 0, v[130:131]
	s_mov_b32 m0, s51
	ds_read_b128 v[184:187], v153 offset:16384
	ds_read_b128 v[188:191], v153 offset:17408
	ds_read_b128 v[192:195], v153 offset:18432
	ds_read_b128 v[196:199], v153 offset:19456
	ds_read_b128 v[200:203], v153 offset:20480
	ds_read_b128 v[204:207], v153 offset:21504
	ds_read_b128 v[208:211], v153 offset:22528
	ds_read_b128 v[212:215], v153 offset:23552
	global_load_lds_dwordx4 v[216:217], off
	s_add_i32 m0, s51, 0x2000
	s_add_u32 s52, s26, 0x40000
	v_lshl_add_u64 v[218:219], s[26:27], 0, v[134:135]
	s_addc_u32 s53, s27, 0
	s_add_i32 s51, s45, s34
	global_load_lds_dwordx4 v[218:219], off
	v_lshl_add_u64 v[220:221], s[52:53], 0, v[130:131]
	s_mov_b32 m0, s51
	v_lshl_add_u64 v[222:223], s[28:29], 0, v[132:133]
	global_load_lds_dwordx4 v[220:221], off
	s_add_i32 m0, s51, 0x2000
	s_nop 0
	global_load_lds_dwordx4 v134, s[52:53]
	v_lshl_add_u64 v[220:221], s[28:29], 0, v[128:129]
	s_mov_b32 m0, s35
	s_nop 0
	global_load_lds_dwordx4 v[220:221], off
	s_mov_b32 m0, s36
	s_nop 0
	global_load_lds_dwordx4 v[222:223], off
	s_waitcnt vmcnt(8)
	s_waitcnt lgkmcnt(0)
	s_barrier
	s_setprio 1
	s_waitcnt lgkmcnt(0)
	v_mfma_f32_16x16x32_bf16 v[60:63], v[144:147], v[184:187], v[60:63]
	v_mfma_f32_16x16x32_bf16 v[56:59], v[160:163], v[184:187], v[56:59]
	v_mfma_f32_16x16x32_bf16 v[44:47], v[144:147], v[192:195], v[44:47]
	v_mfma_f32_16x16x32_bf16 v[40:43], v[160:163], v[192:195], v[40:43]
	v_mfma_f32_16x16x32_bf16 v[28:31], v[144:147], v[200:203], v[28:31]
	v_mfma_f32_16x16x32_bf16 v[24:27], v[160:163], v[200:203], v[24:27]
	v_mfma_f32_16x16x32_bf16 v[12:15], v[144:147], v[208:211], v[12:15]
	v_mfma_f32_16x16x32_bf16 v[8:11], v[160:163], v[208:211], v[8:11]
	v_mfma_f32_16x16x32_bf16 v[60:63], v[156:159], v[188:191], v[60:63]
	v_mfma_f32_16x16x32_bf16 v[56:59], v[164:167], v[188:191], v[56:59]
	v_mfma_f32_16x16x32_bf16 v[44:47], v[156:159], v[196:199], v[44:47]
	v_mfma_f32_16x16x32_bf16 v[40:43], v[164:167], v[196:199], v[40:43]
	v_mfma_f32_16x16x32_bf16 v[28:31], v[156:159], v[204:207], v[28:31]
	v_mfma_f32_16x16x32_bf16 v[24:27], v[164:167], v[204:207], v[24:27]
	v_mfma_f32_16x16x32_bf16 v[12:15], v[156:159], v[212:215], v[12:15]
	v_mfma_f32_16x16x32_bf16 v[8:11], v[164:167], v[212:215], v[8:11]
	s_setprio 0
	s_setprio 1
	v_mfma_f32_16x16x32_bf16 v[52:55], v[168:171], v[184:187], v[52:55]
	v_mfma_f32_16x16x32_bf16 v[48:51], v[176:179], v[184:187], v[48:51]
	v_mfma_f32_16x16x32_bf16 v[36:39], v[168:171], v[192:195], v[36:39]
	v_mfma_f32_16x16x32_bf16 v[32:35], v[176:179], v[192:195], v[32:35]
	v_mfma_f32_16x16x32_bf16 v[20:23], v[168:171], v[200:203], v[20:23]
	v_mfma_f32_16x16x32_bf16 v[16:19], v[176:179], v[200:203], v[16:19]
	v_mfma_f32_16x16x32_bf16 v[4:7], v[168:171], v[208:211], v[4:7]
	v_mfma_f32_16x16x32_bf16 v[0:3], v[176:179], v[208:211], v[0:3]
	v_mfma_f32_16x16x32_bf16 v[52:55], v[172:175], v[188:191], v[52:55]
	v_mfma_f32_16x16x32_bf16 v[48:51], v[180:183], v[188:191], v[48:51]
	v_mfma_f32_16x16x32_bf16 v[36:39], v[172:175], v[196:199], v[36:39]
	v_mfma_f32_16x16x32_bf16 v[32:35], v[180:183], v[196:199], v[32:35]
	v_mfma_f32_16x16x32_bf16 v[20:23], v[172:175], v[204:207], v[20:23]
	v_mfma_f32_16x16x32_bf16 v[16:19], v[180:183], v[204:207], v[16:19]
	v_mfma_f32_16x16x32_bf16 v[4:7], v[172:175], v[212:215], v[4:7]
	v_mfma_f32_16x16x32_bf16 v[0:3], v[180:183], v[212:215], v[0:3]
	s_setprio 0
	s_barrier
	s_add_i32 s51, 0, 0x18000
	s_add_i32 s52, 0, 0x1c000
	v_add_u32_e32 v164, s51, v149
	v_add_u32_e32 v180, s52, v149
	ds_read_b128 v[144:147], v164
	ds_read_b128 v[156:159], v164 offset:1024
	ds_read_b128 v[160:163], v164 offset:2048
	ds_read_b128 v[164:167], v164 offset:3072
	ds_read_b128 v[168:171], v180
	ds_read_b128 v[172:175], v180 offset:1024
	ds_read_b128 v[176:179], v180 offset:2048
	ds_read_b128 v[180:183], v180 offset:3072
	s_add_u32 s28, s28, 0x40000
	s_addc_u32 s29, s29, 0
	s_mov_b32 m0, s37
	ds_read_b128 v[184:187], v153 offset:32768
	ds_read_b128 v[188:191], v153 offset:33792
	ds_read_b128 v[192:195], v153 offset:34816
	ds_read_b128 v[196:199], v153 offset:35840
	ds_read_b128 v[200:203], v153 offset:36864
	ds_read_b128 v[204:207], v153 offset:37888
	ds_read_b128 v[208:211], v153 offset:38912
	ds_read_b128 v[212:215], v153 offset:39936
	global_load_lds_dwordx4 v128, s[28:29]
	v_lshl_add_u64 v[224:225], s[28:29], 0, v[132:133]
	s_mov_b32 m0, s38
	s_nop 0
	global_load_lds_dwordx4 v[224:225], off
	s_waitcnt vmcnt(8)
	s_waitcnt lgkmcnt(0)
	s_barrier
	s_setprio 1
	s_waitcnt lgkmcnt(0)
	v_mfma_f32_16x16x32_bf16 v[124:127], v[144:147], v[184:187], v[124:127]
	v_mfma_f32_16x16x32_bf16 v[120:123], v[160:163], v[184:187], v[120:123]
	v_mfma_f32_16x16x32_bf16 v[108:111], v[144:147], v[192:195], v[108:111]
	v_mfma_f32_16x16x32_bf16 v[104:107], v[160:163], v[192:195], v[104:107]
	v_mfma_f32_16x16x32_bf16 v[92:95], v[144:147], v[200:203], v[92:95]
	v_mfma_f32_16x16x32_bf16 v[88:91], v[160:163], v[200:203], v[88:91]
	v_mfma_f32_16x16x32_bf16 v[76:79], v[144:147], v[208:211], v[76:79]
	v_mfma_f32_16x16x32_bf16 v[72:75], v[160:163], v[208:211], v[72:75]
	v_mfma_f32_16x16x32_bf16 v[124:127], v[156:159], v[188:191], v[124:127]
	v_mfma_f32_16x16x32_bf16 v[120:123], v[164:167], v[188:191], v[120:123]
	v_mfma_f32_16x16x32_bf16 v[108:111], v[156:159], v[196:199], v[108:111]
	v_mfma_f32_16x16x32_bf16 v[104:107], v[164:167], v[196:199], v[104:107]
	v_mfma_f32_16x16x32_bf16 v[92:95], v[156:159], v[204:207], v[92:95]
	v_mfma_f32_16x16x32_bf16 v[88:91], v[164:167], v[204:207], v[88:91]
	v_mfma_f32_16x16x32_bf16 v[76:79], v[156:159], v[212:215], v[76:79]
	v_mfma_f32_16x16x32_bf16 v[72:75], v[164:167], v[212:215], v[72:75]
	s_setprio 0
	s_setprio 1
	v_mfma_f32_16x16x32_bf16 v[116:119], v[168:171], v[184:187], v[116:119]
	v_mfma_f32_16x16x32_bf16 v[112:115], v[176:179], v[184:187], v[112:115]
	v_mfma_f32_16x16x32_bf16 v[100:103], v[168:171], v[192:195], v[100:103]
	v_mfma_f32_16x16x32_bf16 v[96:99], v[176:179], v[192:195], v[96:99]
	v_mfma_f32_16x16x32_bf16 v[84:87], v[168:171], v[200:203], v[84:87]
	v_mfma_f32_16x16x32_bf16 v[80:83], v[176:179], v[200:203], v[80:83]
	v_mfma_f32_16x16x32_bf16 v[68:71], v[168:171], v[208:211], v[68:71]
	v_mfma_f32_16x16x32_bf16 v[64:67], v[176:179], v[208:211], v[64:67]
	v_mfma_f32_16x16x32_bf16 v[116:119], v[172:175], v[188:191], v[116:119]
	v_mfma_f32_16x16x32_bf16 v[112:115], v[180:183], v[188:191], v[112:115]
	v_mfma_f32_16x16x32_bf16 v[100:103], v[172:175], v[196:199], v[100:103]
	v_mfma_f32_16x16x32_bf16 v[96:99], v[180:183], v[196:199], v[96:99]
	v_mfma_f32_16x16x32_bf16 v[84:87], v[172:175], v[204:207], v[84:87]
	v_mfma_f32_16x16x32_bf16 v[80:83], v[180:183], v[204:207], v[80:83]
	v_mfma_f32_16x16x32_bf16 v[68:71], v[172:175], v[212:215], v[68:71]
	v_mfma_f32_16x16x32_bf16 v[64:67], v[180:183], v[212:215], v[64:67]
	s_setprio 0
	s_barrier
	s_add_i32 s28, s51, s34
	v_lshl_add_u64 v[216:217], v[216:217], 0, s[10:11]
	s_mov_b32 m0, s28
	ds_read_b128 v[184:187], v153 offset:49152
	ds_read_b128 v[188:191], v153 offset:50176
	ds_read_b128 v[192:195], v153 offset:51200
	ds_read_b128 v[196:199], v153 offset:52224
	ds_read_b128 v[200:203], v153 offset:53248
	ds_read_b128 v[204:207], v153 offset:54272
	ds_read_b128 v[208:211], v153 offset:55296
	ds_read_b128 v[212:215], v153 offset:56320
	global_load_lds_dwordx4 v[216:217], off
	s_add_i32 m0, s28, 0x2000
	s_add_u32 s26, s26, 0x40080
	v_lshl_add_u64 v[216:217], v[218:219], 0, s[10:11]
	s_addc_u32 s27, s27, 0
	s_add_i32 s28, s52, s34
	global_load_lds_dwordx4 v[216:217], off
	v_lshl_add_u64 v[216:217], s[26:27], 0, v[130:131]
	s_mov_b32 m0, s28
	s_nop 0
	global_load_lds_dwordx4 v[216:217], off
	s_add_i32 m0, s28, 0x2000
	s_nop 0
	global_load_lds_dwordx4 v134, s[26:27]
	v_lshl_add_u64 v[216:217], v[220:221], 0, s[10:11]
	s_mov_b32 m0, s40
	s_nop 0
	global_load_lds_dwordx4 v[216:217], off
	v_lshl_add_u64 v[216:217], v[222:223], 0, s[10:11]
	s_mov_b32 m0, s41
	s_nop 0
	global_load_lds_dwordx4 v[216:217], off
	s_waitcnt vmcnt(8)
	s_waitcnt lgkmcnt(0)
	s_barrier
	s_setprio 1
	s_waitcnt lgkmcnt(0)
	v_mfma_f32_16x16x32_bf16 v[60:63], v[144:147], v[184:187], v[60:63]
	v_mfma_f32_16x16x32_bf16 v[56:59], v[160:163], v[184:187], v[56:59]
	v_mfma_f32_16x16x32_bf16 v[44:47], v[144:147], v[192:195], v[44:47]
	v_mfma_f32_16x16x32_bf16 v[40:43], v[160:163], v[192:195], v[40:43]
	v_mfma_f32_16x16x32_bf16 v[28:31], v[144:147], v[200:203], v[28:31]
	v_mfma_f32_16x16x32_bf16 v[24:27], v[160:163], v[200:203], v[24:27]
	v_mfma_f32_16x16x32_bf16 v[12:15], v[144:147], v[208:211], v[12:15]
	v_mfma_f32_16x16x32_bf16 v[8:11], v[160:163], v[208:211], v[8:11]
	v_mfma_f32_16x16x32_bf16 v[60:63], v[156:159], v[188:191], v[60:63]
	v_mfma_f32_16x16x32_bf16 v[56:59], v[164:167], v[188:191], v[56:59]
	v_mfma_f32_16x16x32_bf16 v[44:47], v[156:159], v[196:199], v[44:47]
	v_mfma_f32_16x16x32_bf16 v[40:43], v[164:167], v[196:199], v[40:43]
	v_mfma_f32_16x16x32_bf16 v[28:31], v[156:159], v[204:207], v[28:31]
	v_mfma_f32_16x16x32_bf16 v[24:27], v[164:167], v[204:207], v[24:27]
	v_mfma_f32_16x16x32_bf16 v[12:15], v[156:159], v[212:215], v[12:15]
	v_mfma_f32_16x16x32_bf16 v[8:11], v[164:167], v[212:215], v[8:11]
	s_setprio 0
	s_setprio 1
	v_mfma_f32_16x16x32_bf16 v[52:55], v[168:171], v[184:187], v[52:55]
	v_mfma_f32_16x16x32_bf16 v[48:51], v[176:179], v[184:187], v[48:51]
	v_mfma_f32_16x16x32_bf16 v[36:39], v[168:171], v[192:195], v[36:39]
	v_mfma_f32_16x16x32_bf16 v[32:35], v[176:179], v[192:195], v[32:35]
	v_mfma_f32_16x16x32_bf16 v[20:23], v[168:171], v[200:203], v[20:23]
	v_mfma_f32_16x16x32_bf16 v[16:19], v[176:179], v[200:203], v[16:19]
	v_mfma_f32_16x16x32_bf16 v[4:7], v[168:171], v[208:211], v[4:7]
	v_mfma_f32_16x16x32_bf16 v[0:3], v[176:179], v[208:211], v[0:3]
	v_mfma_f32_16x16x32_bf16 v[52:55], v[172:175], v[188:191], v[52:55]
	v_mfma_f32_16x16x32_bf16 v[48:51], v[180:183], v[188:191], v[48:51]
	v_mfma_f32_16x16x32_bf16 v[36:39], v[172:175], v[196:199], v[36:39]
	v_mfma_f32_16x16x32_bf16 v[32:35], v[180:183], v[196:199], v[32:35]
	v_mfma_f32_16x16x32_bf16 v[20:23], v[172:175], v[204:207], v[20:23]
	v_mfma_f32_16x16x32_bf16 v[16:19], v[180:183], v[204:207], v[16:19]
	v_mfma_f32_16x16x32_bf16 v[4:7], v[172:175], v[212:215], v[4:7]
	v_mfma_f32_16x16x32_bf16 v[0:3], v[180:183], v[212:215], v[0:3]
	s_setprio 0
	s_barrier
	s_add_i32 s50, s50, 2
	s_add_u32 s24, s24, 0x100
	s_addc_u32 s25, s25, 0
	s_add_u32 s48, s48, 0x100
	s_addc_u32 s49, s49, 0
	s_cmp_gt_u32 s50, 13
	s_cbranch_scc0 .LBB0_1337
	s_and_b64 vcc, exec, s[12:13]
	s_cbranch_vccz .LBB0_1340
	s_barrier

.LBB0_1397:
	s_add_u32 s10, s70, 0xbc00000
	s_addc_u32 s11, s71, 0
	s_add_u32 s12, s70, 0xfc00000
	s_mov_b64 s[14:15], 0x80
	s_addc_u32 s13, s71, 0
	s_and_b32 s2, s2, 3
	s_add_i32 m0, s39, 0x18000
	v_lshl_add_u64 v[6:7], v[6:7], 0, s[14:15]
	s_lshl_b32 s5, s3, 13
	s_lshl_b32 s43, s2, 5
	s_lshl_b32 s17, s2, 12
	s_waitcnt vmcnt(2)
	s_barrier
	global_load_lds_dwordx4 v[6:7], off
	v_lshl_add_u64 v[4:5], v[4:5], 0, s[14:15]
	s_add_i32 m0, s39, 0x1a000
	s_add_i32 s44, s39, 0x8000
	s_add_i32 s45, s39, 0xa000
	global_load_lds_dwordx4 v[4:5], off
	v_lshl_add_u64 v[0:1], v[0:1], 0, s[14:15]
	s_mov_b32 m0, s44
	s_add_u32 s18, s30, 0x20080
	global_load_lds_dwordx4 v[0:1], off
	v_lshl_add_u64 v[0:1], v[2:3], 0, s[14:15]
	s_mov_b32 m0, s45
	s_addc_u32 s19, s31, 0
	global_load_lds_dwordx4 v[0:1], off
	s_add_i32 m0, s39, 0x1c000
	s_nop 0
	global_load_lds_dwordx4 v134, s[18:19]
	v_lshl_add_u64 v[0:1], s[18:19], 0, v[138:139]
	s_add_i32 m0, s39, 0x1e000
	s_cmpk_lt_u32 s16, 0x100
	global_load_lds_dwordx4 v[0:1], off
	v_lshrrev_b32_e32 v1, 1, v8
	v_and_b32_e32 v142, 24, v1
	v_and_b32_e32 v0, 15, v8
	v_lshlrev_b32_e32 v1, 1, v142
	v_lshl_or_b32 v143, s3, 6, v0
	v_lshl_or_b32 v0, v0, 6, v1
	v_lshlrev_b32_e32 v1, 2, v8
	v_and_b32_e32 v1, 32, v1
	v_bitop3_b32 v2, v0, s5, v1 bitop3:0xde
	v_bitop3_b32 v159, v0, s17, v1 bitop3:0xde
	v_lshlrev_b32_e32 v0, 13, v9
	v_and_b32_e32 v0, 0xffffc000, v0
	v_lshl_add_u32 v0, v10, 10, v0
	v_and_b32_e32 v1, 1, v9
	v_lshl_or_b32 v0, v1, 6, v0
	v_lshl_add_u32 v148, v11, 1, v0
	v_lshlrev_b32_e32 v0, 13, v12
	v_and_b32_e32 v0, 0xffffc000, v0
	s_waitcnt vmcnt(6)
	v_lshl_add_u32 v0, v13, 10, v0
	v_and_b32_e32 v1, 1, v12
	s_cselect_b64 s[16:17], -1, 0
	s_lshl_b32 s2, s2, 6
	v_lshlrev_b32_e32 v140, 2, v142
	v_lshl_or_b32 v0, v1, 6, v0
	s_add_i32 s50, 0, 0x10000
	s_add_i32 s51, 0, 0x14000
	s_or_b32 s46, s2, 0xfffffc00
	s_ashr_i32 s47, s96, 31
	s_ashr_i32 s48, s33, 31
	v_lshl_add_u64 v[144:145], s[78:79], 0, v[140:141]
	v_lshl_add_u64 v[146:147], s[80:81], 0, v[140:141]
	v_mov_b32_e32 v149, v141
	v_lshl_add_u32 v150, v14, 1, v0
	v_mov_b32_e32 v151, v141
	v_mov_b64_e32 v[152:153], 0x300
	v_mov_b64_e32 v[154:155], 0x2ff
	s_movk_i32 s49, 0x61
	s_mov_b64 s[18:19], 0x100
	v_add_u32_e32 v164, s50, v159
	v_add_u32_e32 v165, s51, v159
	v_add_u32_e32 v166, 0, v2
	v_mov_b32_e32 v167, 0x358637bd
	s_mov_b32 s52, 0
	s_barrier
	s_branch .LBB0_1400

.LBB0_1403:
	ds_read_b128 v[128:131], v164
	ds_read_b128 v[160:163], v164 offset:1024
	ds_read_b128 v[168:171], v164 offset:2048
	ds_read_b128 v[172:175], v164 offset:3072
	ds_read_b128 v[176:179], v165
	ds_read_b128 v[180:183], v165 offset:1024
	ds_read_b128 v[184:187], v165 offset:2048
	ds_read_b128 v[188:191], v165 offset:3072
	s_add_u32 s30, s28, 0xfffe0080
	s_addc_u32 s31, s29, -1
	s_cmp_eq_u32 s56, 4
	s_cselect_b32 s35, s5, s31
	s_cselect_b32 s34, s23, s30
	s_cselect_b32 s31, s21, s55
	s_cselect_b32 s30, s53, s54
	s_add_i32 m0, s39, 0xc000
	ds_read_b128 v[192:195], v166
	ds_read_b128 v[196:199], v166 offset:1024
	ds_read_b128 v[200:203], v166 offset:2048
	ds_read_b128 v[204:207], v166 offset:3072
	ds_read_b128 v[208:211], v166 offset:4096
	ds_read_b128 v[212:215], v166 offset:5120
	ds_read_b128 v[216:219], v166 offset:6144
	ds_read_b128 v[220:223], v166 offset:7168
	global_load_lds_dwordx4 v148, s[28:29]
	s_add_i32 m0, s39, 0xe000
	s_nop 0
	global_load_lds_dwordx4 v150, s[28:29]
	s_waitcnt vmcnt(8)
	s_waitcnt lgkmcnt(0)
	s_barrier
	s_setprio 1
	s_waitcnt lgkmcnt(0)
	v_mfma_f32_16x16x32_bf16 v[124:127], v[128:131], v[192:195], v[124:127]
	v_mfma_f32_16x16x32_bf16 v[120:123], v[168:171], v[192:195], v[120:123]
	v_mfma_f32_16x16x32_bf16 v[108:111], v[128:131], v[200:203], v[108:111]
	v_mfma_f32_16x16x32_bf16 v[104:107], v[168:171], v[200:203], v[104:107]
	v_mfma_f32_16x16x32_bf16 v[92:95], v[128:131], v[208:211], v[92:95]
	v_mfma_f32_16x16x32_bf16 v[88:91], v[168:171], v[208:211], v[88:91]
	v_mfma_f32_16x16x32_bf16 v[76:79], v[128:131], v[216:219], v[76:79]
	v_mfma_f32_16x16x32_bf16 v[72:75], v[168:171], v[216:219], v[72:75]
	v_mfma_f32_16x16x32_bf16 v[124:127], v[160:163], v[196:199], v[124:127]
	v_mfma_f32_16x16x32_bf16 v[120:123], v[172:175], v[196:199], v[120:123]
	v_mfma_f32_16x16x32_bf16 v[108:111], v[160:163], v[204:207], v[108:111]
	v_mfma_f32_16x16x32_bf16 v[104:107], v[172:175], v[204:207], v[104:107]
	v_mfma_f32_16x16x32_bf16 v[92:95], v[160:163], v[212:215], v[92:95]
	v_mfma_f32_16x16x32_bf16 v[88:91], v[172:175], v[212:215], v[88:91]
	v_mfma_f32_16x16x32_bf16 v[76:79], v[160:163], v[220:223], v[76:79]
	v_mfma_f32_16x16x32_bf16 v[72:75], v[172:175], v[220:223], v[72:75]
	s_setprio 0
	s_setprio 1
	v_mfma_f32_16x16x32_bf16 v[116:119], v[176:179], v[192:195], v[116:119]
	v_mfma_f32_16x16x32_bf16 v[112:115], v[184:187], v[192:195], v[112:115]
	v_mfma_f32_16x16x32_bf16 v[100:103], v[176:179], v[200:203], v[100:103]
	v_mfma_f32_16x16x32_bf16 v[96:99], v[184:187], v[200:203], v[96:99]
	v_mfma_f32_16x16x32_bf16 v[84:87], v[176:179], v[208:211], v[84:87]
	v_mfma_f32_16x16x32_bf16 v[80:83], v[184:187], v[208:211], v[80:83]
	v_mfma_f32_16x16x32_bf16 v[68:71], v[176:179], v[216:219], v[68:71]
	v_mfma_f32_16x16x32_bf16 v[64:67], v[184:187], v[216:219], v[64:67]
	v_mfma_f32_16x16x32_bf16 v[116:119], v[180:183], v[196:199], v[116:119]
	v_mfma_f32_16x16x32_bf16 v[112:115], v[188:191], v[196:199], v[112:115]
	v_mfma_f32_16x16x32_bf16 v[100:103], v[180:183], v[204:207], v[100:103]
	v_mfma_f32_16x16x32_bf16 v[96:99], v[188:191], v[204:207], v[96:99]
	v_mfma_f32_16x16x32_bf16 v[84:87], v[180:183], v[212:215], v[84:87]
	v_mfma_f32_16x16x32_bf16 v[80:83], v[188:191], v[212:215], v[80:83]
	v_mfma_f32_16x16x32_bf16 v[68:71], v[180:183], v[220:223], v[68:71]
	v_mfma_f32_16x16x32_bf16 v[64:67], v[188:191], v[220:223], v[64:67]
	s_setprio 0
	s_barrier
	s_add_i32 s57, s50, s38
	v_lshl_add_u64 v[156:157], s[30:31], 0, v[134:135]
	s_mov_b32 m0, s57
	ds_read_b128 v[192:195], v166 offset:16384
	ds_read_b128 v[196:199], v166 offset:17408
	ds_read_b128 v[200:203], v166 offset:18432
	ds_read_b128 v[204:207], v166 offset:19456
	ds_read_b128 v[208:211], v166 offset:20480
	ds_read_b128 v[212:215], v166 offset:21504
	ds_read_b128 v[216:219], v166 offset:22528
	ds_read_b128 v[220:223], v166 offset:23552
	global_load_lds_dwordx4 v[156:157], off
	s_add_i32 m0, s57, 0x2000
	s_add_u32 s58, s30, 0x20000
	v_lshl_add_u64 v[224:225], s[30:31], 0, v[138:139]
	s_addc_u32 s59, s31, 0
	s_add_i32 s57, s51, s38
	global_load_lds_dwordx4 v[224:225], off
	s_mov_b32 m0, s57
	v_lshl_add_u64 v[228:229], s[34:35], 0, v[136:137]
	global_load_lds_dwordx4 v134, s[58:59]
	s_add_i32 m0, s57, 0x2000
	s_nop 0
	global_load_lds_dwordx4 v138, s[58:59]
	v_lshl_add_u64 v[226:227], s[34:35], 0, v[132:133]
	s_mov_b32 m0, s39
	s_nop 0
	global_load_lds_dwordx4 v[226:227], off
	s_mov_b32 m0, s40
	s_nop 0
	global_load_lds_dwordx4 v[228:229], off
	s_waitcnt vmcnt(8)
	s_waitcnt lgkmcnt(0)
	s_barrier
	s_setprio 1
	s_waitcnt lgkmcnt(0)
	v_mfma_f32_16x16x32_bf16 v[60:63], v[128:131], v[192:195], v[60:63]
	v_mfma_f32_16x16x32_bf16 v[56:59], v[168:171], v[192:195], v[56:59]
	v_mfma_f32_16x16x32_bf16 v[44:47], v[128:131], v[200:203], v[44:47]
	v_mfma_f32_16x16x32_bf16 v[40:43], v[168:171], v[200:203], v[40:43]
	v_mfma_f32_16x16x32_bf16 v[28:31], v[128:131], v[208:211], v[28:31]
	v_mfma_f32_16x16x32_bf16 v[24:27], v[168:171], v[208:211], v[24:27]
	v_mfma_f32_16x16x32_bf16 v[12:15], v[128:131], v[216:219], v[12:15]
	v_mfma_f32_16x16x32_bf16 v[8:11], v[168:171], v[216:219], v[8:11]
	v_mfma_f32_16x16x32_bf16 v[60:63], v[160:163], v[196:199], v[60:63]
	v_mfma_f32_16x16x32_bf16 v[56:59], v[172:175], v[196:199], v[56:59]
	v_mfma_f32_16x16x32_bf16 v[44:47], v[160:163], v[204:207], v[44:47]
	v_mfma_f32_16x16x32_bf16 v[40:43], v[172:175], v[204:207], v[40:43]
	v_mfma_f32_16x16x32_bf16 v[28:31], v[160:163], v[212:215], v[28:31]
	v_mfma_f32_16x16x32_bf16 v[24:27], v[172:175], v[212:215], v[24:27]
	v_mfma_f32_16x16x32_bf16 v[12:15], v[160:163], v[220:223], v[12:15]
	v_mfma_f32_16x16x32_bf16 v[8:11], v[172:175], v[220:223], v[8:11]
	s_setprio 0
	s_setprio 1
	v_mfma_f32_16x16x32_bf16 v[52:55], v[176:179], v[192:195], v[52:55]
	v_mfma_f32_16x16x32_bf16 v[48:51], v[184:187], v[192:195], v[48:51]
	v_mfma_f32_16x16x32_bf16 v[36:39], v[176:179], v[200:203], v[36:39]
	v_mfma_f32_16x16x32_bf16 v[32:35], v[184:187], v[200:203], v[32:35]
	v_mfma_f32_16x16x32_bf16 v[20:23], v[176:179], v[208:211], v[20:23]
	v_mfma_f32_16x16x32_bf16 v[16:19], v[184:187], v[208:211], v[16:19]
	v_mfma_f32_16x16x32_bf16 v[4:7], v[176:179], v[216:219], v[4:7]
	v_mfma_f32_16x16x32_bf16 v[0:3], v[184:187], v[216:219], v[0:3]
	v_mfma_f32_16x16x32_bf16 v[52:55], v[180:183], v[196:199], v[52:55]
	v_mfma_f32_16x16x32_bf16 v[48:51], v[188:191], v[196:199], v[48:51]
	v_mfma_f32_16x16x32_bf16 v[36:39], v[180:183], v[204:207], v[36:39]
	v_mfma_f32_16x16x32_bf16 v[32:35], v[188:191], v[204:207], v[32:35]
	v_mfma_f32_16x16x32_bf16 v[20:23], v[180:183], v[212:215], v[20:23]
	v_mfma_f32_16x16x32_bf16 v[16:19], v[188:191], v[212:215], v[16:19]
	v_mfma_f32_16x16x32_bf16 v[4:7], v[180:183], v[220:223], v[4:7]
	v_mfma_f32_16x16x32_bf16 v[0:3], v[188:191], v[220:223], v[0:3]
	s_setprio 0
	s_barrier
	s_add_i32 s57, 0, 0x18000
	v_add_u32_e32 v140, s57, v159
	s_add_i32 s58, 0, 0x1c000
	ds_read_b128 v[128:131], v140
	ds_read_b128 v[160:163], v140 offset:1024
	ds_read_b128 v[168:171], v140 offset:2048
	ds_read_b128 v[172:175], v140 offset:3072
	v_add_u32_e32 v140, s58, v159
	ds_read_b128 v[176:179], v140
	ds_read_b128 v[180:183], v140 offset:1024
	ds_read_b128 v[184:187], v140 offset:2048
	ds_read_b128 v[188:191], v140 offset:3072
	s_add_u32 s34, s34, 0x20000
	s_addc_u32 s35, s35, 0
	s_mov_b32 m0, s41
	ds_read_b128 v[192:195], v166 offset:32768
	ds_read_b128 v[196:199], v166 offset:33792
	ds_read_b128 v[200:203], v166 offset:34816
	ds_read_b128 v[204:207], v166 offset:35840
	ds_read_b128 v[208:211], v166 offset:36864
	ds_read_b128 v[212:215], v166 offset:37888
	ds_read_b128 v[216:219], v166 offset:38912
	ds_read_b128 v[220:223], v166 offset:39936
	global_load_lds_dwordx4 v132, s[34:35]
	v_lshl_add_u64 v[230:231], s[34:35], 0, v[136:137]
	s_mov_b32 m0, s42
	s_nop 0
	global_load_lds_dwordx4 v[230:231], off
	s_waitcnt vmcnt(8)
	s_waitcnt lgkmcnt(0)
	s_barrier
	s_setprio 1
	s_waitcnt lgkmcnt(0)
	v_mfma_f32_16x16x32_bf16 v[124:127], v[128:131], v[192:195], v[124:127]
	v_mfma_f32_16x16x32_bf16 v[120:123], v[168:171], v[192:195], v[120:123]
	v_mfma_f32_16x16x32_bf16 v[108:111], v[128:131], v[200:203], v[108:111]
	v_mfma_f32_16x16x32_bf16 v[104:107], v[168:171], v[200:203], v[104:107]
	v_mfma_f32_16x16x32_bf16 v[92:95], v[128:131], v[208:211], v[92:95]
	v_mfma_f32_16x16x32_bf16 v[88:91], v[168:171], v[208:211], v[88:91]
	v_mfma_f32_16x16x32_bf16 v[76:79], v[128:131], v[216:219], v[76:79]
	v_mfma_f32_16x16x32_bf16 v[72:75], v[168:171], v[216:219], v[72:75]
	v_mfma_f32_16x16x32_bf16 v[124:127], v[160:163], v[196:199], v[124:127]
	v_mfma_f32_16x16x32_bf16 v[120:123], v[172:175], v[196:199], v[120:123]
	v_mfma_f32_16x16x32_bf16 v[108:111], v[160:163], v[204:207], v[108:111]
	v_mfma_f32_16x16x32_bf16 v[104:107], v[172:175], v[204:207], v[104:107]
	v_mfma_f32_16x16x32_bf16 v[92:95], v[160:163], v[212:215], v[92:95]
	v_mfma_f32_16x16x32_bf16 v[88:91], v[172:175], v[212:215], v[88:91]
	v_mfma_f32_16x16x32_bf16 v[76:79], v[160:163], v[220:223], v[76:79]
	v_mfma_f32_16x16x32_bf16 v[72:75], v[172:175], v[220:223], v[72:75]
	s_setprio 0
	s_setprio 1
	v_mfma_f32_16x16x32_bf16 v[116:119], v[176:179], v[192:195], v[116:119]
	v_mfma_f32_16x16x32_bf16 v[112:115], v[184:187], v[192:195], v[112:115]
	v_mfma_f32_16x16x32_bf16 v[100:103], v[176:179], v[200:203], v[100:103]
	v_mfma_f32_16x16x32_bf16 v[96:99], v[184:187], v[200:203], v[96:99]
	v_mfma_f32_16x16x32_bf16 v[84:87], v[176:179], v[208:211], v[84:87]
	v_mfma_f32_16x16x32_bf16 v[80:83], v[184:187], v[208:211], v[80:83]
	v_mfma_f32_16x16x32_bf16 v[68:71], v[176:179], v[216:219], v[68:71]
	v_mfma_f32_16x16x32_bf16 v[64:67], v[184:187], v[216:219], v[64:67]
	v_mfma_f32_16x16x32_bf16 v[116:119], v[180:183], v[196:199], v[116:119]
	v_mfma_f32_16x16x32_bf16 v[112:115], v[188:191], v[196:199], v[112:115]
	v_mfma_f32_16x16x32_bf16 v[100:103], v[180:183], v[204:207], v[100:103]
	v_mfma_f32_16x16x32_bf16 v[96:99], v[188:191], v[204:207], v[96:99]
	v_mfma_f32_16x16x32_bf16 v[84:87], v[180:183], v[212:215], v[84:87]
	v_mfma_f32_16x16x32_bf16 v[80:83], v[188:191], v[212:215], v[80:83]
	v_mfma_f32_16x16x32_bf16 v[68:71], v[180:183], v[220:223], v[68:71]
	v_mfma_f32_16x16x32_bf16 v[64:67], v[188:191], v[220:223], v[64:67]
	s_setprio 0
	s_barrier
	s_add_i32 s34, s57, s38
	v_lshl_add_u64 v[156:157], v[156:157], 0, s[14:15]
	s_mov_b32 m0, s34
	ds_read_b128 v[192:195], v166 offset:49152
	ds_read_b128 v[196:199], v166 offset:50176
	ds_read_b128 v[200:203], v166 offset:51200
	ds_read_b128 v[204:207], v166 offset:52224
	ds_read_b128 v[208:211], v166 offset:53248
	ds_read_b128 v[212:215], v166 offset:54272
	ds_read_b128 v[216:219], v166 offset:55296
	ds_read_b128 v[220:223], v166 offset:56320
	global_load_lds_dwordx4 v[156:157], off
	s_add_i32 m0, s34, 0x2000
	s_add_u32 s30, s30, 0x20080
	v_lshl_add_u64 v[156:157], v[224:225], 0, s[14:15]
	s_addc_u32 s31, s31, 0
	s_add_i32 s34, s58, s38
	global_load_lds_dwordx4 v[156:157], off
	s_mov_b32 m0, s34
	s_nop 0
	global_load_lds_dwordx4 v134, s[30:31]
	s_add_i32 m0, s34, 0x2000
	s_nop 0
	global_load_lds_dwordx4 v138, s[30:31]
	v_lshl_add_u64 v[156:157], v[226:227], 0, s[14:15]
	s_mov_b32 m0, s44
	s_nop 0
	global_load_lds_dwordx4 v[156:157], off
	v_lshl_add_u64 v[156:157], v[228:229], 0, s[14:15]
	s_mov_b32 m0, s45
	s_nop 0
	global_load_lds_dwordx4 v[156:157], off
	s_waitcnt vmcnt(8)
	s_waitcnt lgkmcnt(0)
	s_barrier
	s_setprio 1
	s_waitcnt lgkmcnt(0)
	v_mfma_f32_16x16x32_bf16 v[60:63], v[128:131], v[192:195], v[60:63]
	v_mfma_f32_16x16x32_bf16 v[56:59], v[168:171], v[192:195], v[56:59]
	v_mfma_f32_16x16x32_bf16 v[44:47], v[128:131], v[200:203], v[44:47]
	v_mfma_f32_16x16x32_bf16 v[40:43], v[168:171], v[200:203], v[40:43]
	v_mfma_f32_16x16x32_bf16 v[28:31], v[128:131], v[208:211], v[28:31]
	v_mfma_f32_16x16x32_bf16 v[24:27], v[168:171], v[208:211], v[24:27]
	v_mfma_f32_16x16x32_bf16 v[12:15], v[128:131], v[216:219], v[12:15]
	v_mfma_f32_16x16x32_bf16 v[8:11], v[168:171], v[216:219], v[8:11]
	v_mfma_f32_16x16x32_bf16 v[60:63], v[160:163], v[196:199], v[60:63]
	v_mfma_f32_16x16x32_bf16 v[56:59], v[172:175], v[196:199], v[56:59]
	v_mfma_f32_16x16x32_bf16 v[44:47], v[160:163], v[204:207], v[44:47]
	v_mfma_f32_16x16x32_bf16 v[40:43], v[172:175], v[204:207], v[40:43]
	v_mfma_f32_16x16x32_bf16 v[28:31], v[160:163], v[212:215], v[28:31]
	v_mfma_f32_16x16x32_bf16 v[24:27], v[172:175], v[212:215], v[24:27]
	v_mfma_f32_16x16x32_bf16 v[12:15], v[160:163], v[220:223], v[12:15]
	v_mfma_f32_16x16x32_bf16 v[8:11], v[172:175], v[220:223], v[8:11]
	s_setprio 0
	s_setprio 1
	v_mfma_f32_16x16x32_bf16 v[52:55], v[176:179], v[192:195], v[52:55]
	v_mfma_f32_16x16x32_bf16 v[48:51], v[184:187], v[192:195], v[48:51]
	v_mfma_f32_16x16x32_bf16 v[36:39], v[176:179], v[200:203], v[36:39]
	v_mfma_f32_16x16x32_bf16 v[32:35], v[184:187], v[200:203], v[32:35]
	v_mfma_f32_16x16x32_bf16 v[20:23], v[176:179], v[208:211], v[20:23]
	v_mfma_f32_16x16x32_bf16 v[16:19], v[184:187], v[208:211], v[16:19]
	v_mfma_f32_16x16x32_bf16 v[4:7], v[176:179], v[216:219], v[4:7]
	v_mfma_f32_16x16x32_bf16 v[0:3], v[184:187], v[216:219], v[0:3]
	v_mfma_f32_16x16x32_bf16 v[52:55], v[180:183], v[196:199], v[52:55]
	v_mfma_f32_16x16x32_bf16 v[48:51], v[188:191], v[196:199], v[48:51]
	v_mfma_f32_16x16x32_bf16 v[36:39], v[180:183], v[204:207], v[36:39]
	v_mfma_f32_16x16x32_bf16 v[32:35], v[188:191], v[204:207], v[32:35]
	v_mfma_f32_16x16x32_bf16 v[20:23], v[180:183], v[212:215], v[20:23]
	v_mfma_f32_16x16x32_bf16 v[16:19], v[188:191], v[212:215], v[16:19]
	v_mfma_f32_16x16x32_bf16 v[4:7], v[180:183], v[220:223], v[4:7]
	v_mfma_f32_16x16x32_bf16 v[0:3], v[188:191], v[220:223], v[0:3]
	s_setprio 0
	s_barrier
	s_add_i32 s56, s56, 2
	s_add_u32 s28, s28, 0x100
	s_addc_u32 s29, s29, 0
	s_add_u32 s54, s54, 0x100
	s_addc_u32 s55, s55, 0
	s_cmp_gt_u32 s56, 5
	s_cbranch_scc0 .LBB0_1403
	s_and_b64 vcc, exec, s[16:17]
	s_cbranch_vccz .LBB0_1406
	s_barrier

.LBB0_1553:
	ds_read_b128 v[140:143], v147
	ds_read_b128 v[152:155], v147 offset:1024
	ds_read_b128 v[156:159], v147 offset:2048
	ds_read_b128 v[160:163], v147 offset:3072
	ds_read_b128 v[164:167], v148
	ds_read_b128 v[168:171], v148 offset:1024
	ds_read_b128 v[172:175], v148 offset:2048
	ds_read_b128 v[176:179], v148 offset:3072
	s_add_u32 s28, s26, 0xfffc0080
	s_addc_u32 s29, s27, -1
	s_cmp_eq_u32 s54, 12
	s_cselect_b32 s31, s19, s29
	s_cselect_b32 s30, s25, s28
	s_cselect_b32 s29, s17, s53
	s_cselect_b32 s28, s51, s52
	s_add_i32 m0, s39, 0xc000
	ds_read_b128 v[180:183], v149
	ds_read_b128 v[184:187], v149 offset:1024
	ds_read_b128 v[188:191], v149 offset:2048
	ds_read_b128 v[192:195], v149 offset:3072
	ds_read_b128 v[196:199], v149 offset:4096
	ds_read_b128 v[200:203], v149 offset:5120
	ds_read_b128 v[204:207], v149 offset:6144
	ds_read_b128 v[208:211], v149 offset:7168
	global_load_lds_dwordx4 v132, s[26:27]
	s_add_i32 m0, s39, 0xe000
	s_nop 0
	global_load_lds_dwordx4 v134, s[26:27]
	s_waitcnt vmcnt(8)
	s_waitcnt lgkmcnt(0)
	s_barrier
	s_setprio 1
	s_waitcnt lgkmcnt(0)
	v_mfma_f32_16x16x32_bf16 v[124:127], v[140:143], v[180:183], v[124:127]
	v_mfma_f32_16x16x32_bf16 v[120:123], v[156:159], v[180:183], v[120:123]
	v_mfma_f32_16x16x32_bf16 v[108:111], v[140:143], v[188:191], v[108:111]
	v_mfma_f32_16x16x32_bf16 v[104:107], v[156:159], v[188:191], v[104:107]
	v_mfma_f32_16x16x32_bf16 v[92:95], v[140:143], v[196:199], v[92:95]
	v_mfma_f32_16x16x32_bf16 v[88:91], v[156:159], v[196:199], v[88:91]
	v_mfma_f32_16x16x32_bf16 v[76:79], v[140:143], v[204:207], v[76:79]
	v_mfma_f32_16x16x32_bf16 v[72:75], v[156:159], v[204:207], v[72:75]
	v_mfma_f32_16x16x32_bf16 v[124:127], v[152:155], v[184:187], v[124:127]
	v_mfma_f32_16x16x32_bf16 v[120:123], v[160:163], v[184:187], v[120:123]
	v_mfma_f32_16x16x32_bf16 v[108:111], v[152:155], v[192:195], v[108:111]
	v_mfma_f32_16x16x32_bf16 v[104:107], v[160:163], v[192:195], v[104:107]
	v_mfma_f32_16x16x32_bf16 v[92:95], v[152:155], v[200:203], v[92:95]
	v_mfma_f32_16x16x32_bf16 v[88:91], v[160:163], v[200:203], v[88:91]
	v_mfma_f32_16x16x32_bf16 v[76:79], v[152:155], v[208:211], v[76:79]
	v_mfma_f32_16x16x32_bf16 v[72:75], v[160:163], v[208:211], v[72:75]
	s_setprio 0
	s_setprio 1
	v_mfma_f32_16x16x32_bf16 v[116:119], v[164:167], v[180:183], v[116:119]
	v_mfma_f32_16x16x32_bf16 v[112:115], v[172:175], v[180:183], v[112:115]
	v_mfma_f32_16x16x32_bf16 v[100:103], v[164:167], v[188:191], v[100:103]
	v_mfma_f32_16x16x32_bf16 v[96:99], v[172:175], v[188:191], v[96:99]
	v_mfma_f32_16x16x32_bf16 v[84:87], v[164:167], v[196:199], v[84:87]
	v_mfma_f32_16x16x32_bf16 v[80:83], v[172:175], v[196:199], v[80:83]
	v_mfma_f32_16x16x32_bf16 v[68:71], v[164:167], v[204:207], v[68:71]
	v_mfma_f32_16x16x32_bf16 v[64:67], v[172:175], v[204:207], v[64:67]
	v_mfma_f32_16x16x32_bf16 v[116:119], v[168:171], v[184:187], v[116:119]
	v_mfma_f32_16x16x32_bf16 v[112:115], v[176:179], v[184:187], v[112:115]
	v_mfma_f32_16x16x32_bf16 v[100:103], v[168:171], v[192:195], v[100:103]
	v_mfma_f32_16x16x32_bf16 v[96:99], v[176:179], v[192:195], v[96:99]
	v_mfma_f32_16x16x32_bf16 v[84:87], v[168:171], v[200:203], v[84:87]
	v_mfma_f32_16x16x32_bf16 v[80:83], v[176:179], v[200:203], v[80:83]
	v_mfma_f32_16x16x32_bf16 v[68:71], v[168:171], v[208:211], v[68:71]
	v_mfma_f32_16x16x32_bf16 v[64:67], v[176:179], v[208:211], v[64:67]
	s_setprio 0
	s_barrier
	s_add_i32 s55, s48, s38
	v_lshl_add_u64 v[212:213], s[28:29], 0, v[128:129]
	s_mov_b32 m0, s55
	ds_read_b128 v[180:183], v149 offset:16384
	ds_read_b128 v[184:187], v149 offset:17408
	ds_read_b128 v[188:191], v149 offset:18432
	ds_read_b128 v[192:195], v149 offset:19456
	ds_read_b128 v[196:199], v149 offset:20480
	ds_read_b128 v[200:203], v149 offset:21504
	ds_read_b128 v[204:207], v149 offset:22528
	ds_read_b128 v[208:211], v149 offset:23552
	global_load_lds_dwordx4 v[212:213], off
	s_add_i32 m0, s55, 0x2000
	s_add_u32 s56, s28, 0x40000
	v_lshl_add_u64 v[214:215], s[28:29], 0, v[130:131]
	s_addc_u32 s57, s29, 0
	s_add_i32 s55, s49, s38
	global_load_lds_dwordx4 v[214:215], off
	v_lshl_add_u64 v[216:217], s[56:57], 0, v[128:129]
	s_mov_b32 m0, s55
	v_lshl_add_u64 v[218:219], s[30:31], 0, v[130:131]
	global_load_lds_dwordx4 v[216:217], off
	s_add_i32 m0, s55, 0x2000
	s_nop 0
	global_load_lds_dwordx4 v130, s[56:57]
	v_lshl_add_u64 v[216:217], s[30:31], 0, v[128:129]
	s_mov_b32 m0, s39
	s_nop 0
	global_load_lds_dwordx4 v[216:217], off
	s_mov_b32 m0, s40
	s_nop 0
	global_load_lds_dwordx4 v[218:219], off
	s_waitcnt vmcnt(8)
	s_waitcnt lgkmcnt(0)
	s_barrier
	s_setprio 1
	s_waitcnt lgkmcnt(0)
	v_mfma_f32_16x16x32_bf16 v[60:63], v[140:143], v[180:183], v[60:63]
	v_mfma_f32_16x16x32_bf16 v[56:59], v[156:159], v[180:183], v[56:59]
	v_mfma_f32_16x16x32_bf16 v[44:47], v[140:143], v[188:191], v[44:47]
	v_mfma_f32_16x16x32_bf16 v[40:43], v[156:159], v[188:191], v[40:43]
	v_mfma_f32_16x16x32_bf16 v[28:31], v[140:143], v[196:199], v[28:31]
	v_mfma_f32_16x16x32_bf16 v[24:27], v[156:159], v[196:199], v[24:27]
	v_mfma_f32_16x16x32_bf16 v[12:15], v[140:143], v[204:207], v[12:15]
	v_mfma_f32_16x16x32_bf16 v[8:11], v[156:159], v[204:207], v[8:11]
	v_mfma_f32_16x16x32_bf16 v[60:63], v[152:155], v[184:187], v[60:63]
	v_mfma_f32_16x16x32_bf16 v[56:59], v[160:163], v[184:187], v[56:59]
	v_mfma_f32_16x16x32_bf16 v[44:47], v[152:155], v[192:195], v[44:47]
	v_mfma_f32_16x16x32_bf16 v[40:43], v[160:163], v[192:195], v[40:43]
	v_mfma_f32_16x16x32_bf16 v[28:31], v[152:155], v[200:203], v[28:31]
	v_mfma_f32_16x16x32_bf16 v[24:27], v[160:163], v[200:203], v[24:27]
	v_mfma_f32_16x16x32_bf16 v[12:15], v[152:155], v[208:211], v[12:15]
	v_mfma_f32_16x16x32_bf16 v[8:11], v[160:163], v[208:211], v[8:11]
	s_setprio 0
	s_setprio 1
	v_mfma_f32_16x16x32_bf16 v[52:55], v[164:167], v[180:183], v[52:55]
	v_mfma_f32_16x16x32_bf16 v[48:51], v[172:175], v[180:183], v[48:51]
	v_mfma_f32_16x16x32_bf16 v[36:39], v[164:167], v[188:191], v[36:39]
	v_mfma_f32_16x16x32_bf16 v[32:35], v[172:175], v[188:191], v[32:35]
	v_mfma_f32_16x16x32_bf16 v[20:23], v[164:167], v[196:199], v[20:23]
	v_mfma_f32_16x16x32_bf16 v[16:19], v[172:175], v[196:199], v[16:19]
	v_mfma_f32_16x16x32_bf16 v[4:7], v[164:167], v[204:207], v[4:7]
	v_mfma_f32_16x16x32_bf16 v[0:3], v[172:175], v[204:207], v[0:3]
	v_mfma_f32_16x16x32_bf16 v[52:55], v[168:171], v[184:187], v[52:55]
	v_mfma_f32_16x16x32_bf16 v[48:51], v[176:179], v[184:187], v[48:51]
	v_mfma_f32_16x16x32_bf16 v[36:39], v[168:171], v[192:195], v[36:39]
	v_mfma_f32_16x16x32_bf16 v[32:35], v[176:179], v[192:195], v[32:35]
	v_mfma_f32_16x16x32_bf16 v[20:23], v[168:171], v[200:203], v[20:23]
	v_mfma_f32_16x16x32_bf16 v[16:19], v[176:179], v[200:203], v[16:19]
	v_mfma_f32_16x16x32_bf16 v[4:7], v[168:171], v[208:211], v[4:7]
	v_mfma_f32_16x16x32_bf16 v[0:3], v[176:179], v[208:211], v[0:3]
	s_setprio 0
	s_barrier
	s_add_i32 s55, 0, 0x18000
	v_add_u32_e32 v151, s55, v145
	s_add_i32 s56, 0, 0x1c000
	ds_read_b128 v[140:143], v151
	ds_read_b128 v[152:155], v151 offset:1024
	ds_read_b128 v[156:159], v151 offset:2048
	ds_read_b128 v[160:163], v151 offset:3072
	v_add_u32_e32 v151, s56, v145
	ds_read_b128 v[164:167], v151
	ds_read_b128 v[168:171], v151 offset:1024
	ds_read_b128 v[172:175], v151 offset:2048
	ds_read_b128 v[176:179], v151 offset:3072
	s_add_u32 s30, s30, 0x40000
	s_addc_u32 s31, s31, 0
	s_mov_b32 m0, s41
	v_lshl_add_u64 v[220:221], s[30:31], 0, v[128:129]
	ds_read_b128 v[180:183], v149 offset:32768
	ds_read_b128 v[184:187], v149 offset:33792
	ds_read_b128 v[188:191], v149 offset:34816
	ds_read_b128 v[192:195], v149 offset:35840
	ds_read_b128 v[196:199], v149 offset:36864
	ds_read_b128 v[200:203], v149 offset:37888
	ds_read_b128 v[204:207], v149 offset:38912
	ds_read_b128 v[208:211], v149 offset:39936
	global_load_lds_dwordx4 v[220:221], off
	v_lshl_add_u64 v[220:221], s[30:31], 0, v[130:131]
	s_mov_b32 m0, s42
	s_nop 0
	global_load_lds_dwordx4 v[220:221], off
	s_waitcnt vmcnt(8)
	s_waitcnt lgkmcnt(0)
	s_barrier
	s_setprio 1
	s_waitcnt lgkmcnt(0)
	v_mfma_f32_16x16x32_bf16 v[124:127], v[140:143], v[180:183], v[124:127]
	v_mfma_f32_16x16x32_bf16 v[120:123], v[156:159], v[180:183], v[120:123]
	v_mfma_f32_16x16x32_bf16 v[108:111], v[140:143], v[188:191], v[108:111]
	v_mfma_f32_16x16x32_bf16 v[104:107], v[156:159], v[188:191], v[104:107]
	v_mfma_f32_16x16x32_bf16 v[92:95], v[140:143], v[196:199], v[92:95]
	v_mfma_f32_16x16x32_bf16 v[88:91], v[156:159], v[196:199], v[88:91]
	v_mfma_f32_16x16x32_bf16 v[76:79], v[140:143], v[204:207], v[76:79]
	v_mfma_f32_16x16x32_bf16 v[72:75], v[156:159], v[204:207], v[72:75]
	v_mfma_f32_16x16x32_bf16 v[124:127], v[152:155], v[184:187], v[124:127]
	v_mfma_f32_16x16x32_bf16 v[120:123], v[160:163], v[184:187], v[120:123]
	v_mfma_f32_16x16x32_bf16 v[108:111], v[152:155], v[192:195], v[108:111]
	v_mfma_f32_16x16x32_bf16 v[104:107], v[160:163], v[192:195], v[104:107]
	v_mfma_f32_16x16x32_bf16 v[92:95], v[152:155], v[200:203], v[92:95]
	v_mfma_f32_16x16x32_bf16 v[88:91], v[160:163], v[200:203], v[88:91]
	v_mfma_f32_16x16x32_bf16 v[76:79], v[152:155], v[208:211], v[76:79]
	v_mfma_f32_16x16x32_bf16 v[72:75], v[160:163], v[208:211], v[72:75]
	s_setprio 0
	s_setprio 1
	v_mfma_f32_16x16x32_bf16 v[116:119], v[164:167], v[180:183], v[116:119]
	v_mfma_f32_16x16x32_bf16 v[112:115], v[172:175], v[180:183], v[112:115]
	v_mfma_f32_16x16x32_bf16 v[100:103], v[164:167], v[188:191], v[100:103]
	v_mfma_f32_16x16x32_bf16 v[96:99], v[172:175], v[188:191], v[96:99]
	v_mfma_f32_16x16x32_bf16 v[84:87], v[164:167], v[196:199], v[84:87]
	v_mfma_f32_16x16x32_bf16 v[80:83], v[172:175], v[196:199], v[80:83]
	v_mfma_f32_16x16x32_bf16 v[68:71], v[164:167], v[204:207], v[68:71]
	v_mfma_f32_16x16x32_bf16 v[64:67], v[172:175], v[204:207], v[64:67]
	v_mfma_f32_16x16x32_bf16 v[116:119], v[168:171], v[184:187], v[116:119]
	v_mfma_f32_16x16x32_bf16 v[112:115], v[176:179], v[184:187], v[112:115]
	v_mfma_f32_16x16x32_bf16 v[100:103], v[168:171], v[192:195], v[100:103]
	v_mfma_f32_16x16x32_bf16 v[96:99], v[176:179], v[192:195], v[96:99]
	v_mfma_f32_16x16x32_bf16 v[84:87], v[168:171], v[200:203], v[84:87]
	v_mfma_f32_16x16x32_bf16 v[80:83], v[176:179], v[200:203], v[80:83]
	v_mfma_f32_16x16x32_bf16 v[68:71], v[168:171], v[208:211], v[68:71]
	v_mfma_f32_16x16x32_bf16 v[64:67], v[176:179], v[208:211], v[64:67]
	s_setprio 0
	s_barrier
	s_add_i32 s30, s55, s38
	v_lshl_add_u64 v[212:213], v[212:213], 0, s[12:13]
	s_mov_b32 m0, s30
	ds_read_b128 v[180:183], v149 offset:49152
	ds_read_b128 v[184:187], v149 offset:50176
	ds_read_b128 v[188:191], v149 offset:51200
	ds_read_b128 v[192:195], v149 offset:52224
	ds_read_b128 v[196:199], v149 offset:53248
	ds_read_b128 v[200:203], v149 offset:54272
	ds_read_b128 v[204:207], v149 offset:55296
	ds_read_b128 v[208:211], v149 offset:56320
	global_load_lds_dwordx4 v[212:213], off
	s_add_i32 m0, s30, 0x2000
	s_add_u32 s28, s28, 0x40080
	v_lshl_add_u64 v[212:213], v[214:215], 0, s[12:13]
	s_addc_u32 s29, s29, 0
	s_add_i32 s30, s56, s38
	global_load_lds_dwordx4 v[212:213], off
	v_lshl_add_u64 v[212:213], s[28:29], 0, v[128:129]
	s_mov_b32 m0, s30
	s_nop 0
	global_load_lds_dwordx4 v[212:213], off
	s_add_i32 m0, s30, 0x2000
	s_nop 0
	global_load_lds_dwordx4 v130, s[28:29]
	v_lshl_add_u64 v[212:213], v[216:217], 0, s[12:13]
	s_mov_b32 m0, s44
	s_nop 0
	global_load_lds_dwordx4 v[212:213], off
	v_lshl_add_u64 v[212:213], v[218:219], 0, s[12:13]
	s_mov_b32 m0, s45
	s_nop 0
	global_load_lds_dwordx4 v[212:213], off
	s_waitcnt vmcnt(8)
	s_waitcnt lgkmcnt(0)
	s_barrier
	s_setprio 1
	s_waitcnt lgkmcnt(0)
	v_mfma_f32_16x16x32_bf16 v[60:63], v[140:143], v[180:183], v[60:63]
	v_mfma_f32_16x16x32_bf16 v[56:59], v[156:159], v[180:183], v[56:59]
	v_mfma_f32_16x16x32_bf16 v[44:47], v[140:143], v[188:191], v[44:47]
	v_mfma_f32_16x16x32_bf16 v[40:43], v[156:159], v[188:191], v[40:43]
	v_mfma_f32_16x16x32_bf16 v[28:31], v[140:143], v[196:199], v[28:31]
	v_mfma_f32_16x16x32_bf16 v[24:27], v[156:159], v[196:199], v[24:27]
	v_mfma_f32_16x16x32_bf16 v[12:15], v[140:143], v[204:207], v[12:15]
	v_mfma_f32_16x16x32_bf16 v[8:11], v[156:159], v[204:207], v[8:11]
	v_mfma_f32_16x16x32_bf16 v[60:63], v[152:155], v[184:187], v[60:63]
	v_mfma_f32_16x16x32_bf16 v[56:59], v[160:163], v[184:187], v[56:59]
	v_mfma_f32_16x16x32_bf16 v[44:47], v[152:155], v[192:195], v[44:47]
	v_mfma_f32_16x16x32_bf16 v[40:43], v[160:163], v[192:195], v[40:43]
	v_mfma_f32_16x16x32_bf16 v[28:31], v[152:155], v[200:203], v[28:31]
	v_mfma_f32_16x16x32_bf16 v[24:27], v[160:163], v[200:203], v[24:27]
	v_mfma_f32_16x16x32_bf16 v[12:15], v[152:155], v[208:211], v[12:15]
	v_mfma_f32_16x16x32_bf16 v[8:11], v[160:163], v[208:211], v[8:11]
	s_setprio 0
	s_setprio 1
	v_mfma_f32_16x16x32_bf16 v[52:55], v[164:167], v[180:183], v[52:55]
	v_mfma_f32_16x16x32_bf16 v[48:51], v[172:175], v[180:183], v[48:51]
	v_mfma_f32_16x16x32_bf16 v[36:39], v[164:167], v[188:191], v[36:39]
	v_mfma_f32_16x16x32_bf16 v[32:35], v[172:175], v[188:191], v[32:35]
	v_mfma_f32_16x16x32_bf16 v[20:23], v[164:167], v[196:199], v[20:23]
	v_mfma_f32_16x16x32_bf16 v[16:19], v[172:175], v[196:199], v[16:19]
	v_mfma_f32_16x16x32_bf16 v[4:7], v[164:167], v[204:207], v[4:7]
	v_mfma_f32_16x16x32_bf16 v[0:3], v[172:175], v[204:207], v[0:3]
	v_mfma_f32_16x16x32_bf16 v[52:55], v[168:171], v[184:187], v[52:55]
	v_mfma_f32_16x16x32_bf16 v[48:51], v[176:179], v[184:187], v[48:51]
	v_mfma_f32_16x16x32_bf16 v[36:39], v[168:171], v[192:195], v[36:39]
	v_mfma_f32_16x16x32_bf16 v[32:35], v[176:179], v[192:195], v[32:35]
	v_mfma_f32_16x16x32_bf16 v[20:23], v[168:171], v[200:203], v[20:23]
	v_mfma_f32_16x16x32_bf16 v[16:19], v[176:179], v[200:203], v[16:19]
	v_mfma_f32_16x16x32_bf16 v[4:7], v[168:171], v[208:211], v[4:7]
	v_mfma_f32_16x16x32_bf16 v[0:3], v[176:179], v[208:211], v[0:3]
	s_setprio 0
	s_barrier
	s_add_i32 s54, s54, 2
	s_add_u32 s26, s26, 0x100
	s_addc_u32 s27, s27, 0
	s_add_u32 s52, s52, 0x100
	s_addc_u32 s53, s53, 0
	s_cmp_gt_u32 s54, 13
	s_cbranch_scc0 .LBB0_1553
	s_and_b64 vcc, exec, s[14:15]
	s_cbranch_vccz .LBB0_1556
	s_barrier

.LBB0_1619:
	ds_read_b128 v[152:155], v143
	ds_read_b128 v[162:165], v143 offset:1024
	ds_read_b128 v[166:169], v143 offset:2048
	ds_read_b128 v[170:173], v143 offset:3072
	ds_read_b128 v[174:177], v158
	ds_read_b128 v[178:181], v158 offset:1024
	ds_read_b128 v[182:185], v158 offset:2048
	ds_read_b128 v[186:189], v158 offset:3072
	s_add_u32 s30, s28, 0xfffc0080
	s_addc_u32 s31, s29, -1
	s_cmp_eq_u32 s55, 12
	s_cselect_b32 s35, s19, s31
	s_cselect_b32 s34, s25, s30
	s_cselect_b32 s31, s17, s54
	s_cselect_b32 s30, s27, s53
	s_waitcnt lgkmcnt(0)
	s_add_i32 m0, s39, 0xc000
	ds_read_b128 v[190:193], v159
	ds_read_b128 v[194:197], v159 offset:1024
	ds_read_b128 v[198:201], v159 offset:2048
	ds_read_b128 v[202:205], v159 offset:3072
	ds_read_b128 v[206:209], v159 offset:4096
	ds_read_b128 v[210:213], v159 offset:5120
	ds_read_b128 v[214:217], v159 offset:6144
	ds_read_b128 v[218:221], v159 offset:7168
	global_load_lds_dwordx4 v144, s[28:29]
	s_add_i32 m0, s39, 0xe000
	s_nop 0
	global_load_lds_dwordx4 v146, s[28:29]
	s_waitcnt vmcnt(8)
	s_waitcnt lgkmcnt(0)
	s_barrier
	s_setprio 1
	s_waitcnt lgkmcnt(0)
	v_mfma_f32_16x16x32_bf16 v[116:119], v[152:155], v[190:193], v[116:119]
	v_mfma_f32_16x16x32_bf16 v[112:115], v[166:169], v[190:193], v[112:115]
	v_mfma_f32_16x16x32_bf16 v[100:103], v[152:155], v[198:201], v[100:103]
	v_mfma_f32_16x16x32_bf16 v[96:99], v[166:169], v[198:201], v[96:99]
	v_mfma_f32_16x16x32_bf16 v[88:91], v[152:155], v[206:209], v[88:91]
	v_mfma_f32_16x16x32_bf16 v[84:87], v[166:169], v[206:209], v[84:87]
	v_mfma_f32_16x16x32_bf16 v[72:75], v[152:155], v[214:217], v[72:75]
	v_mfma_f32_16x16x32_bf16 v[68:71], v[166:169], v[214:217], v[68:71]
	v_mfma_f32_16x16x32_bf16 v[116:119], v[162:165], v[194:197], v[116:119]
	v_mfma_f32_16x16x32_bf16 v[112:115], v[170:173], v[194:197], v[112:115]
	v_mfma_f32_16x16x32_bf16 v[100:103], v[162:165], v[202:205], v[100:103]
	v_mfma_f32_16x16x32_bf16 v[96:99], v[170:173], v[202:205], v[96:99]
	v_mfma_f32_16x16x32_bf16 v[88:91], v[162:165], v[210:213], v[88:91]
	v_mfma_f32_16x16x32_bf16 v[84:87], v[170:173], v[210:213], v[84:87]
	v_mfma_f32_16x16x32_bf16 v[72:75], v[162:165], v[218:221], v[72:75]
	v_mfma_f32_16x16x32_bf16 v[68:71], v[170:173], v[218:221], v[68:71]
	s_setprio 0
	s_setprio 1
	v_mfma_f32_16x16x32_bf16 v[124:127], v[174:177], v[190:193], v[124:127]
	v_mfma_f32_16x16x32_bf16 v[120:123], v[182:185], v[190:193], v[120:123]
	v_mfma_f32_16x16x32_bf16 v[108:111], v[174:177], v[198:201], v[108:111]
	v_mfma_f32_16x16x32_bf16 v[104:107], v[182:185], v[198:201], v[104:107]
	v_mfma_f32_16x16x32_bf16 v[92:95], v[174:177], v[206:209], v[92:95]
	v_mfma_f32_16x16x32_bf16 v[80:83], v[182:185], v[206:209], v[80:83]
	v_mfma_f32_16x16x32_bf16 v[76:79], v[174:177], v[214:217], v[76:79]
	v_mfma_f32_16x16x32_bf16 v[64:67], v[182:185], v[214:217], v[64:67]
	v_mfma_f32_16x16x32_bf16 v[124:127], v[178:181], v[194:197], v[124:127]
	v_mfma_f32_16x16x32_bf16 v[120:123], v[186:189], v[194:197], v[120:123]
	v_mfma_f32_16x16x32_bf16 v[108:111], v[178:181], v[202:205], v[108:111]
	v_mfma_f32_16x16x32_bf16 v[104:107], v[186:189], v[202:205], v[104:107]
	v_mfma_f32_16x16x32_bf16 v[92:95], v[178:181], v[210:213], v[92:95]
	v_mfma_f32_16x16x32_bf16 v[80:83], v[186:189], v[210:213], v[80:83]
	v_mfma_f32_16x16x32_bf16 v[76:79], v[178:181], v[218:221], v[76:79]
	v_mfma_f32_16x16x32_bf16 v[64:67], v[186:189], v[218:221], v[64:67]
	s_setprio 0
	s_barrier
	s_add_i32 s56, s49, s38
	v_lshl_add_u64 v[156:157], s[30:31], 0, v[130:131]
	s_mov_b32 m0, s56
	ds_read_b128 v[190:193], v159 offset:16384
	ds_read_b128 v[194:197], v159 offset:17408
	ds_read_b128 v[198:201], v159 offset:18432
	ds_read_b128 v[202:205], v159 offset:19456
	ds_read_b128 v[206:209], v159 offset:20480
	ds_read_b128 v[210:213], v159 offset:21504
	ds_read_b128 v[214:217], v159 offset:22528
	ds_read_b128 v[218:221], v159 offset:23552
	global_load_lds_dwordx4 v[156:157], off
	s_add_i32 m0, s56, 0x2000
	s_add_u32 s56, s30, 0x40000
	v_lshl_add_u64 v[222:223], s[30:31], 0, v[134:135]
	s_addc_u32 s57, s31, 0
	s_add_i32 s58, s50, s38
	global_load_lds_dwordx4 v[222:223], off
	s_mov_b32 m0, s58
	v_lshl_add_u64 v[226:227], s[34:35], 0, v[132:133]
	global_load_lds_dwordx4 v130, s[56:57]
	s_add_i32 m0, s58, 0x2000
	s_nop 0
	global_load_lds_dwordx4 v134, s[56:57]
	v_lshl_add_u64 v[224:225], s[34:35], 0, v[128:129]
	s_mov_b32 m0, s39
	s_nop 0
	global_load_lds_dwordx4 v[224:225], off
	s_mov_b32 m0, s40
	s_nop 0
	global_load_lds_dwordx4 v[226:227], off
	s_waitcnt vmcnt(8)
	s_waitcnt lgkmcnt(0)
	s_barrier
	s_setprio 1
	s_waitcnt lgkmcnt(0)
	v_mfma_f32_16x16x32_bf16 v[56:59], v[152:155], v[190:193], v[56:59]
	v_mfma_f32_16x16x32_bf16 v[52:55], v[166:169], v[190:193], v[52:55]
	v_mfma_f32_16x16x32_bf16 v[40:43], v[152:155], v[198:201], v[40:43]
	v_mfma_f32_16x16x32_bf16 v[36:39], v[166:169], v[198:201], v[36:39]
	v_mfma_f32_16x16x32_bf16 v[24:27], v[152:155], v[206:209], v[24:27]
	v_mfma_f32_16x16x32_bf16 v[20:23], v[166:169], v[206:209], v[20:23]
	v_mfma_f32_16x16x32_bf16 v[8:11], v[152:155], v[214:217], v[8:11]
	v_mfma_f32_16x16x32_bf16 v[4:7], v[166:169], v[214:217], v[4:7]
	v_mfma_f32_16x16x32_bf16 v[56:59], v[162:165], v[194:197], v[56:59]
	v_mfma_f32_16x16x32_bf16 v[52:55], v[170:173], v[194:197], v[52:55]
	v_mfma_f32_16x16x32_bf16 v[40:43], v[162:165], v[202:205], v[40:43]
	v_mfma_f32_16x16x32_bf16 v[36:39], v[170:173], v[202:205], v[36:39]
	v_mfma_f32_16x16x32_bf16 v[24:27], v[162:165], v[210:213], v[24:27]
	v_mfma_f32_16x16x32_bf16 v[20:23], v[170:173], v[210:213], v[20:23]
	v_mfma_f32_16x16x32_bf16 v[8:11], v[162:165], v[218:221], v[8:11]
	v_mfma_f32_16x16x32_bf16 v[4:7], v[170:173], v[218:221], v[4:7]
	s_setprio 0
	s_setprio 1
	v_mfma_f32_16x16x32_bf16 v[60:63], v[174:177], v[190:193], v[60:63]
	v_mfma_f32_16x16x32_bf16 v[48:51], v[182:185], v[190:193], v[48:51]
	v_mfma_f32_16x16x32_bf16 v[44:47], v[174:177], v[198:201], v[44:47]
	v_mfma_f32_16x16x32_bf16 v[32:35], v[182:185], v[198:201], v[32:35]
	v_mfma_f32_16x16x32_bf16 v[28:31], v[174:177], v[206:209], v[28:31]
	v_mfma_f32_16x16x32_bf16 v[16:19], v[182:185], v[206:209], v[16:19]
	v_mfma_f32_16x16x32_bf16 v[12:15], v[174:177], v[214:217], v[12:15]
	v_mfma_f32_16x16x32_bf16 v[0:3], v[182:185], v[214:217], v[0:3]
	v_mfma_f32_16x16x32_bf16 v[60:63], v[178:181], v[194:197], v[60:63]
	v_mfma_f32_16x16x32_bf16 v[48:51], v[186:189], v[194:197], v[48:51]
	v_mfma_f32_16x16x32_bf16 v[44:47], v[178:181], v[202:205], v[44:47]
	v_mfma_f32_16x16x32_bf16 v[32:35], v[186:189], v[202:205], v[32:35]
	v_mfma_f32_16x16x32_bf16 v[28:31], v[178:181], v[210:213], v[28:31]
	v_mfma_f32_16x16x32_bf16 v[16:19], v[186:189], v[210:213], v[16:19]
	v_mfma_f32_16x16x32_bf16 v[12:15], v[178:181], v[218:221], v[12:15]
	v_mfma_f32_16x16x32_bf16 v[0:3], v[186:189], v[218:221], v[0:3]
	s_setprio 0
	s_barrier
	s_add_i32 s56, 0, 0x18000
	s_add_i32 s57, 0, 0x1c000
	v_add_u32_e32 v170, s56, v141
	v_add_u32_e32 v186, s57, v141
	ds_read_b128 v[152:155], v170
	ds_read_b128 v[162:165], v170 offset:1024
	ds_read_b128 v[166:169], v170 offset:2048
	ds_read_b128 v[170:173], v170 offset:3072
	ds_read_b128 v[174:177], v186
	ds_read_b128 v[178:181], v186 offset:1024
	ds_read_b128 v[182:185], v186 offset:2048
	ds_read_b128 v[186:189], v186 offset:3072
	s_add_u32 s34, s34, 0x40000
	s_addc_u32 s35, s35, 0
	s_mov_b32 m0, s41
	ds_read_b128 v[190:193], v159 offset:32768
	ds_read_b128 v[194:197], v159 offset:33792
	ds_read_b128 v[198:201], v159 offset:34816
	ds_read_b128 v[202:205], v159 offset:35840
	ds_read_b128 v[206:209], v159 offset:36864
	ds_read_b128 v[210:213], v159 offset:37888
	ds_read_b128 v[214:217], v159 offset:38912
	ds_read_b128 v[218:221], v159 offset:39936
	global_load_lds_dwordx4 v128, s[34:35]
	v_lshl_add_u64 v[228:229], s[34:35], 0, v[132:133]
	s_mov_b32 m0, s42
	s_nop 0
	global_load_lds_dwordx4 v[228:229], off
	s_waitcnt vmcnt(8)
	s_waitcnt lgkmcnt(0)
	s_barrier
	s_setprio 1
	s_waitcnt lgkmcnt(0)
	v_mfma_f32_16x16x32_bf16 v[116:119], v[152:155], v[190:193], v[116:119]
	v_mfma_f32_16x16x32_bf16 v[112:115], v[166:169], v[190:193], v[112:115]
	v_mfma_f32_16x16x32_bf16 v[100:103], v[152:155], v[198:201], v[100:103]
	v_mfma_f32_16x16x32_bf16 v[96:99], v[166:169], v[198:201], v[96:99]
	v_mfma_f32_16x16x32_bf16 v[88:91], v[152:155], v[206:209], v[88:91]
	v_mfma_f32_16x16x32_bf16 v[84:87], v[166:169], v[206:209], v[84:87]
	v_mfma_f32_16x16x32_bf16 v[72:75], v[152:155], v[214:217], v[72:75]
	v_mfma_f32_16x16x32_bf16 v[68:71], v[166:169], v[214:217], v[68:71]
	v_mfma_f32_16x16x32_bf16 v[116:119], v[162:165], v[194:197], v[116:119]
	v_mfma_f32_16x16x32_bf16 v[112:115], v[170:173], v[194:197], v[112:115]
	v_mfma_f32_16x16x32_bf16 v[100:103], v[162:165], v[202:205], v[100:103]
	v_mfma_f32_16x16x32_bf16 v[96:99], v[170:173], v[202:205], v[96:99]
	v_mfma_f32_16x16x32_bf16 v[88:91], v[162:165], v[210:213], v[88:91]
	v_mfma_f32_16x16x32_bf16 v[84:87], v[170:173], v[210:213], v[84:87]
	v_mfma_f32_16x16x32_bf16 v[72:75], v[162:165], v[218:221], v[72:75]
	v_mfma_f32_16x16x32_bf16 v[68:71], v[170:173], v[218:221], v[68:71]
	s_setprio 0
	s_setprio 1
	v_mfma_f32_16x16x32_bf16 v[124:127], v[174:177], v[190:193], v[124:127]
	v_mfma_f32_16x16x32_bf16 v[120:123], v[182:185], v[190:193], v[120:123]
	v_mfma_f32_16x16x32_bf16 v[108:111], v[174:177], v[198:201], v[108:111]
	v_mfma_f32_16x16x32_bf16 v[104:107], v[182:185], v[198:201], v[104:107]
	v_mfma_f32_16x16x32_bf16 v[92:95], v[174:177], v[206:209], v[92:95]
	v_mfma_f32_16x16x32_bf16 v[80:83], v[182:185], v[206:209], v[80:83]
	v_mfma_f32_16x16x32_bf16 v[76:79], v[174:177], v[214:217], v[76:79]
	v_mfma_f32_16x16x32_bf16 v[64:67], v[182:185], v[214:217], v[64:67]
	v_mfma_f32_16x16x32_bf16 v[124:127], v[178:181], v[194:197], v[124:127]
	v_mfma_f32_16x16x32_bf16 v[120:123], v[186:189], v[194:197], v[120:123]
	v_mfma_f32_16x16x32_bf16 v[108:111], v[178:181], v[202:205], v[108:111]
	v_mfma_f32_16x16x32_bf16 v[104:107], v[186:189], v[202:205], v[104:107]
	v_mfma_f32_16x16x32_bf16 v[92:95], v[178:181], v[210:213], v[92:95]
	v_mfma_f32_16x16x32_bf16 v[80:83], v[186:189], v[210:213], v[80:83]
	v_mfma_f32_16x16x32_bf16 v[76:79], v[178:181], v[218:221], v[76:79]
	v_mfma_f32_16x16x32_bf16 v[64:67], v[186:189], v[218:221], v[64:67]
	s_setprio 0
	s_barrier
	s_add_i32 s34, s56, s38
	v_lshl_add_u64 v[156:157], v[156:157], 0, s[10:11]
	s_mov_b32 m0, s34
	ds_read_b128 v[190:193], v159 offset:49152
	ds_read_b128 v[194:197], v159 offset:50176
	ds_read_b128 v[198:201], v159 offset:51200
	ds_read_b128 v[202:205], v159 offset:52224
	ds_read_b128 v[206:209], v159 offset:53248
	ds_read_b128 v[210:213], v159 offset:54272
	ds_read_b128 v[214:217], v159 offset:55296
	ds_read_b128 v[218:221], v159 offset:56320
	global_load_lds_dwordx4 v[156:157], off
	s_add_i32 m0, s34, 0x2000
	s_add_u32 s30, s30, 0x40080
	v_lshl_add_u64 v[156:157], v[222:223], 0, s[10:11]
	s_addc_u32 s31, s31, 0
	s_add_i32 s34, s57, s38
	global_load_lds_dwordx4 v[156:157], off
	s_mov_b32 m0, s34
	s_nop 0
	global_load_lds_dwordx4 v130, s[30:31]
	s_add_i32 m0, s34, 0x2000
	s_nop 0
	global_load_lds_dwordx4 v134, s[30:31]
	v_lshl_add_u64 v[156:157], v[224:225], 0, s[10:11]
	s_mov_b32 m0, s43
	s_nop 0
	global_load_lds_dwordx4 v[156:157], off
	v_lshl_add_u64 v[156:157], v[226:227], 0, s[10:11]
	s_mov_b32 m0, s44
	s_nop 0
	global_load_lds_dwordx4 v[156:157], off
	s_waitcnt vmcnt(8)
	s_waitcnt lgkmcnt(0)
	s_barrier
	s_setprio 1
	s_waitcnt lgkmcnt(0)
	v_mfma_f32_16x16x32_bf16 v[56:59], v[152:155], v[190:193], v[56:59]
	v_mfma_f32_16x16x32_bf16 v[52:55], v[166:169], v[190:193], v[52:55]
	v_mfma_f32_16x16x32_bf16 v[40:43], v[152:155], v[198:201], v[40:43]
	v_mfma_f32_16x16x32_bf16 v[36:39], v[166:169], v[198:201], v[36:39]
	v_mfma_f32_16x16x32_bf16 v[24:27], v[152:155], v[206:209], v[24:27]
	v_mfma_f32_16x16x32_bf16 v[20:23], v[166:169], v[206:209], v[20:23]
	v_mfma_f32_16x16x32_bf16 v[8:11], v[152:155], v[214:217], v[8:11]
	v_mfma_f32_16x16x32_bf16 v[4:7], v[166:169], v[214:217], v[4:7]
	v_mfma_f32_16x16x32_bf16 v[56:59], v[162:165], v[194:197], v[56:59]
	v_mfma_f32_16x16x32_bf16 v[52:55], v[170:173], v[194:197], v[52:55]
	v_mfma_f32_16x16x32_bf16 v[40:43], v[162:165], v[202:205], v[40:43]
	v_mfma_f32_16x16x32_bf16 v[36:39], v[170:173], v[202:205], v[36:39]
	v_mfma_f32_16x16x32_bf16 v[24:27], v[162:165], v[210:213], v[24:27]
	v_mfma_f32_16x16x32_bf16 v[20:23], v[170:173], v[210:213], v[20:23]
	v_mfma_f32_16x16x32_bf16 v[8:11], v[162:165], v[218:221], v[8:11]
	v_mfma_f32_16x16x32_bf16 v[4:7], v[170:173], v[218:221], v[4:7]
	s_setprio 0
	s_setprio 1
	v_mfma_f32_16x16x32_bf16 v[60:63], v[174:177], v[190:193], v[60:63]
	v_mfma_f32_16x16x32_bf16 v[48:51], v[182:185], v[190:193], v[48:51]
	v_mfma_f32_16x16x32_bf16 v[44:47], v[174:177], v[198:201], v[44:47]
	v_mfma_f32_16x16x32_bf16 v[32:35], v[182:185], v[198:201], v[32:35]
	v_mfma_f32_16x16x32_bf16 v[28:31], v[174:177], v[206:209], v[28:31]
	v_mfma_f32_16x16x32_bf16 v[16:19], v[182:185], v[206:209], v[16:19]
	v_mfma_f32_16x16x32_bf16 v[12:15], v[174:177], v[214:217], v[12:15]
	v_mfma_f32_16x16x32_bf16 v[0:3], v[182:185], v[214:217], v[0:3]
	v_mfma_f32_16x16x32_bf16 v[60:63], v[178:181], v[194:197], v[60:63]
	v_mfma_f32_16x16x32_bf16 v[48:51], v[186:189], v[194:197], v[48:51]
	v_mfma_f32_16x16x32_bf16 v[44:47], v[178:181], v[202:205], v[44:47]
	v_mfma_f32_16x16x32_bf16 v[32:35], v[186:189], v[202:205], v[32:35]
	v_mfma_f32_16x16x32_bf16 v[28:31], v[178:181], v[210:213], v[28:31]
	v_mfma_f32_16x16x32_bf16 v[16:19], v[186:189], v[210:213], v[16:19]
	v_mfma_f32_16x16x32_bf16 v[12:15], v[178:181], v[218:221], v[12:15]
	v_mfma_f32_16x16x32_bf16 v[0:3], v[186:189], v[218:221], v[0:3]
	s_setprio 0
	s_barrier
	s_add_i32 s55, s55, 2
	s_add_u32 s28, s28, 0x100
	s_addc_u32 s29, s29, 0
	s_add_u32 s53, s53, 0x100
	s_addc_u32 s54, s54, 0
	s_cmp_gt_u32 s55, 13
	s_cbranch_scc0 .LBB0_1619
	s_and_b64 vcc, exec, s[12:13]
	s_cbranch_vccz .LBB0_1624
	s_barrier
	v_lshl_add_u32 v152, s26, 8, v139
	s_cmp_gt_i32 s24, 21
	s_mov_b64 s[26:27], -1
	s_cbranch_scc1 .LBB0_1625

.LBB0_1705:
	ds_read_b128 v[148:151], v145
	ds_read_b128 v[152:155], v145 offset:1024
	ds_read_b128 v[156:159], v145 offset:2048
	ds_read_b128 v[160:163], v145 offset:3072
	ds_read_b128 v[164:167], v146
	ds_read_b128 v[168:171], v146 offset:1024
	ds_read_b128 v[172:175], v146 offset:2048
	ds_read_b128 v[176:179], v146 offset:3072
	s_add_u32 s26, s24, 0x100
	s_addc_u32 s27, s25, 0
	s_cmp_eq_u32 s58, 40
	s_cselect_b32 s31, s5, s27
	s_cselect_b32 s30, s4, s26
	s_cselect_b32 s29, s23, s57
	s_cselect_b32 s28, s22, s56
	v_lshl_add_u64 v[140:141], s[24:25], 0, v[132:133]
	s_add_i32 m0, s38, 0xc000
	ds_read_b128 v[180:183], v147
	ds_read_b128 v[184:187], v147 offset:1024
	ds_read_b128 v[188:191], v147 offset:2048
	ds_read_b128 v[192:195], v147 offset:3072
	ds_read_b128 v[196:199], v147 offset:4096
	ds_read_b128 v[200:203], v147 offset:5120
	ds_read_b128 v[204:207], v147 offset:6144
	ds_read_b128 v[208:211], v147 offset:7168
	global_load_lds_dwordx4 v[140:141], off
	v_lshl_add_u64 v[140:141], s[24:25], 0, v[134:135]
	s_add_i32 m0, s38, 0xe000
	s_nop 0
	global_load_lds_dwordx4 v[140:141], off
	s_waitcnt vmcnt(8)
	s_waitcnt lgkmcnt(0)
	s_barrier
	s_setprio 1
	s_waitcnt lgkmcnt(0)
	v_mfma_f32_16x16x32_bf16 v[124:127], v[148:151], v[180:183], v[124:127]
	v_mfma_f32_16x16x32_bf16 v[120:123], v[156:159], v[180:183], v[120:123]
	v_mfma_f32_16x16x32_bf16 v[116:119], v[148:151], v[188:191], v[116:119]
	v_mfma_f32_16x16x32_bf16 v[112:115], v[156:159], v[188:191], v[112:115]
	v_mfma_f32_16x16x32_bf16 v[92:95], v[148:151], v[196:199], v[92:95]
	v_mfma_f32_16x16x32_bf16 v[88:91], v[156:159], v[196:199], v[88:91]
	v_mfma_f32_16x16x32_bf16 v[84:87], v[148:151], v[204:207], v[84:87]
	v_mfma_f32_16x16x32_bf16 v[80:83], v[156:159], v[204:207], v[80:83]
	v_mfma_f32_16x16x32_bf16 v[124:127], v[152:155], v[184:187], v[124:127]
	v_mfma_f32_16x16x32_bf16 v[120:123], v[160:163], v[184:187], v[120:123]
	v_mfma_f32_16x16x32_bf16 v[116:119], v[152:155], v[192:195], v[116:119]
	v_mfma_f32_16x16x32_bf16 v[112:115], v[160:163], v[192:195], v[112:115]
	v_mfma_f32_16x16x32_bf16 v[92:95], v[152:155], v[200:203], v[92:95]
	v_mfma_f32_16x16x32_bf16 v[88:91], v[160:163], v[200:203], v[88:91]
	v_mfma_f32_16x16x32_bf16 v[84:87], v[152:155], v[208:211], v[84:87]
	v_mfma_f32_16x16x32_bf16 v[80:83], v[160:163], v[208:211], v[80:83]
	s_setprio 0
	s_setprio 1
	v_mfma_f32_16x16x32_bf16 v[108:111], v[164:167], v[180:183], v[108:111]
	v_mfma_f32_16x16x32_bf16 v[104:107], v[172:175], v[180:183], v[104:107]
	v_mfma_f32_16x16x32_bf16 v[100:103], v[164:167], v[188:191], v[100:103]
	v_mfma_f32_16x16x32_bf16 v[96:99], v[172:175], v[188:191], v[96:99]
	v_mfma_f32_16x16x32_bf16 v[76:79], v[164:167], v[196:199], v[76:79]
	v_mfma_f32_16x16x32_bf16 v[72:75], v[172:175], v[196:199], v[72:75]
	v_mfma_f32_16x16x32_bf16 v[68:71], v[164:167], v[204:207], v[68:71]
	v_mfma_f32_16x16x32_bf16 v[64:67], v[172:175], v[204:207], v[64:67]
	v_mfma_f32_16x16x32_bf16 v[108:111], v[168:171], v[184:187], v[108:111]
	v_mfma_f32_16x16x32_bf16 v[104:107], v[176:179], v[184:187], v[104:107]
	v_mfma_f32_16x16x32_bf16 v[100:103], v[168:171], v[192:195], v[100:103]
	v_mfma_f32_16x16x32_bf16 v[96:99], v[176:179], v[192:195], v[96:99]
	v_mfma_f32_16x16x32_bf16 v[76:79], v[168:171], v[200:203], v[76:79]
	v_mfma_f32_16x16x32_bf16 v[72:75], v[176:179], v[200:203], v[72:75]
	v_mfma_f32_16x16x32_bf16 v[68:71], v[168:171], v[208:211], v[68:71]
	v_mfma_f32_16x16x32_bf16 v[64:67], v[176:179], v[208:211], v[64:67]
	s_setprio 0
	s_barrier
	s_add_i32 s24, s46, s37
	v_lshl_add_u64 v[140:141], s[28:29], 0, v[128:129]
	s_mov_b32 m0, s24
	ds_read_b128 v[180:183], v147 offset:16384
	ds_read_b128 v[184:187], v147 offset:17408
	ds_read_b128 v[188:191], v147 offset:18432
	ds_read_b128 v[192:195], v147 offset:19456
	ds_read_b128 v[196:199], v147 offset:20480
	ds_read_b128 v[200:203], v147 offset:21504
	ds_read_b128 v[204:207], v147 offset:22528
	ds_read_b128 v[208:211], v147 offset:23552
	global_load_lds_dwordx4 v[140:141], off
	s_add_i32 m0, s24, 0x2000
	s_add_u32 s24, s28, 0xb0000
	v_lshl_add_u64 v[212:213], s[28:29], 0, v[130:131]
	s_addc_u32 s25, s29, 0
	s_add_i32 s59, s47, s37
	global_load_lds_dwordx4 v[212:213], off
	v_lshl_add_u64 v[214:215], s[24:25], 0, v[128:129]
	s_mov_b32 m0, s59
	v_lshl_add_u64 v[216:217], s[30:31], 0, v[130:131]
	global_load_lds_dwordx4 v[214:215], off
	s_add_i32 m0, s59, 0x2000
	s_nop 0
	global_load_lds_dwordx4 v130, s[24:25]
	v_lshl_add_u64 v[214:215], s[30:31], 0, v[128:129]
	s_mov_b32 m0, s38
	s_nop 0
	global_load_lds_dwordx4 v[214:215], off
	s_mov_b32 m0, s39
	s_nop 0
	global_load_lds_dwordx4 v[216:217], off
	s_waitcnt vmcnt(8)
	s_waitcnt lgkmcnt(0)
	s_barrier
	s_setprio 1
	s_waitcnt lgkmcnt(0)
	v_mfma_f32_16x16x32_bf16 v[60:63], v[148:151], v[180:183], v[60:63]
	v_mfma_f32_16x16x32_bf16 v[56:59], v[156:159], v[180:183], v[56:59]
	v_mfma_f32_16x16x32_bf16 v[52:55], v[148:151], v[188:191], v[52:55]
	v_mfma_f32_16x16x32_bf16 v[48:51], v[156:159], v[188:191], v[48:51]
	v_mfma_f32_16x16x32_bf16 v[28:31], v[148:151], v[196:199], v[28:31]
	v_mfma_f32_16x16x32_bf16 v[24:27], v[156:159], v[196:199], v[24:27]
	v_mfma_f32_16x16x32_bf16 v[20:23], v[148:151], v[204:207], v[20:23]
	v_mfma_f32_16x16x32_bf16 v[16:19], v[156:159], v[204:207], v[16:19]
	v_mfma_f32_16x16x32_bf16 v[60:63], v[152:155], v[184:187], v[60:63]
	v_mfma_f32_16x16x32_bf16 v[56:59], v[160:163], v[184:187], v[56:59]
	v_mfma_f32_16x16x32_bf16 v[52:55], v[152:155], v[192:195], v[52:55]
	v_mfma_f32_16x16x32_bf16 v[48:51], v[160:163], v[192:195], v[48:51]
	v_mfma_f32_16x16x32_bf16 v[28:31], v[152:155], v[200:203], v[28:31]
	v_mfma_f32_16x16x32_bf16 v[24:27], v[160:163], v[200:203], v[24:27]
	v_mfma_f32_16x16x32_bf16 v[20:23], v[152:155], v[208:211], v[20:23]
	v_mfma_f32_16x16x32_bf16 v[16:19], v[160:163], v[208:211], v[16:19]
	s_setprio 0
	s_setprio 1
	v_mfma_f32_16x16x32_bf16 v[44:47], v[164:167], v[180:183], v[44:47]
	v_mfma_f32_16x16x32_bf16 v[40:43], v[172:175], v[180:183], v[40:43]
	v_mfma_f32_16x16x32_bf16 v[36:39], v[164:167], v[188:191], v[36:39]
	v_mfma_f32_16x16x32_bf16 v[32:35], v[172:175], v[188:191], v[32:35]
	v_mfma_f32_16x16x32_bf16 v[12:15], v[164:167], v[196:199], v[12:15]
	v_mfma_f32_16x16x32_bf16 v[8:11], v[172:175], v[196:199], v[8:11]
	v_mfma_f32_16x16x32_bf16 v[4:7], v[164:167], v[204:207], v[4:7]
	v_mfma_f32_16x16x32_bf16 v[0:3], v[172:175], v[204:207], v[0:3]
	v_mfma_f32_16x16x32_bf16 v[44:47], v[168:171], v[184:187], v[44:47]
	v_mfma_f32_16x16x32_bf16 v[40:43], v[176:179], v[184:187], v[40:43]
	v_mfma_f32_16x16x32_bf16 v[36:39], v[168:171], v[192:195], v[36:39]
	v_mfma_f32_16x16x32_bf16 v[32:35], v[176:179], v[192:195], v[32:35]
	v_mfma_f32_16x16x32_bf16 v[12:15], v[168:171], v[200:203], v[12:15]
	v_mfma_f32_16x16x32_bf16 v[8:11], v[176:179], v[200:203], v[8:11]
	v_mfma_f32_16x16x32_bf16 v[4:7], v[168:171], v[208:211], v[4:7]
	v_mfma_f32_16x16x32_bf16 v[0:3], v[176:179], v[208:211], v[0:3]
	s_setprio 0
	s_barrier
	s_add_i32 s59, 0, 0x18000
	s_add_i32 s60, 0, 0x1c000
	v_add_u32_e32 v160, s59, v143
	v_add_u32_e32 v176, s60, v143
	ds_read_b128 v[148:151], v160
	ds_read_b128 v[152:155], v160 offset:1024
	ds_read_b128 v[156:159], v160 offset:2048
	ds_read_b128 v[160:163], v160 offset:3072
	ds_read_b128 v[164:167], v176
	ds_read_b128 v[168:171], v176 offset:1024
	ds_read_b128 v[172:175], v176 offset:2048
	ds_read_b128 v[176:179], v176 offset:3072
	s_add_u32 s24, s30, 0xb0000
	s_addc_u32 s25, s31, 0
	s_mov_b32 m0, s40
	v_lshl_add_u64 v[218:219], s[24:25], 0, v[128:129]
	ds_read_b128 v[180:183], v147 offset:32768
	ds_read_b128 v[184:187], v147 offset:33792
	ds_read_b128 v[188:191], v147 offset:34816
	ds_read_b128 v[192:195], v147 offset:35840
	ds_read_b128 v[196:199], v147 offset:36864
	ds_read_b128 v[200:203], v147 offset:37888
	ds_read_b128 v[204:207], v147 offset:38912
	ds_read_b128 v[208:211], v147 offset:39936
	global_load_lds_dwordx4 v[218:219], off
	v_lshl_add_u64 v[218:219], s[24:25], 0, v[130:131]
	s_mov_b32 m0, s41
	s_nop 0
	global_load_lds_dwordx4 v[218:219], off
	s_waitcnt vmcnt(8)
	s_waitcnt lgkmcnt(0)
	s_barrier
	s_setprio 1
	s_waitcnt lgkmcnt(0)
	v_mfma_f32_16x16x32_bf16 v[124:127], v[148:151], v[180:183], v[124:127]
	v_mfma_f32_16x16x32_bf16 v[120:123], v[156:159], v[180:183], v[120:123]
	v_mfma_f32_16x16x32_bf16 v[116:119], v[148:151], v[188:191], v[116:119]
	v_mfma_f32_16x16x32_bf16 v[112:115], v[156:159], v[188:191], v[112:115]
	v_mfma_f32_16x16x32_bf16 v[92:95], v[148:151], v[196:199], v[92:95]
	v_mfma_f32_16x16x32_bf16 v[88:91], v[156:159], v[196:199], v[88:91]
	v_mfma_f32_16x16x32_bf16 v[84:87], v[148:151], v[204:207], v[84:87]
	v_mfma_f32_16x16x32_bf16 v[80:83], v[156:159], v[204:207], v[80:83]
	v_mfma_f32_16x16x32_bf16 v[124:127], v[152:155], v[184:187], v[124:127]
	v_mfma_f32_16x16x32_bf16 v[120:123], v[160:163], v[184:187], v[120:123]
	v_mfma_f32_16x16x32_bf16 v[116:119], v[152:155], v[192:195], v[116:119]
	v_mfma_f32_16x16x32_bf16 v[112:115], v[160:163], v[192:195], v[112:115]
	v_mfma_f32_16x16x32_bf16 v[92:95], v[152:155], v[200:203], v[92:95]
	v_mfma_f32_16x16x32_bf16 v[88:91], v[160:163], v[200:203], v[88:91]
	v_mfma_f32_16x16x32_bf16 v[84:87], v[152:155], v[208:211], v[84:87]
	v_mfma_f32_16x16x32_bf16 v[80:83], v[160:163], v[208:211], v[80:83]
	s_setprio 0
	s_setprio 1
	v_mfma_f32_16x16x32_bf16 v[108:111], v[164:167], v[180:183], v[108:111]
	v_mfma_f32_16x16x32_bf16 v[104:107], v[172:175], v[180:183], v[104:107]
	v_mfma_f32_16x16x32_bf16 v[100:103], v[164:167], v[188:191], v[100:103]
	v_mfma_f32_16x16x32_bf16 v[96:99], v[172:175], v[188:191], v[96:99]
	v_mfma_f32_16x16x32_bf16 v[76:79], v[164:167], v[196:199], v[76:79]
	v_mfma_f32_16x16x32_bf16 v[72:75], v[172:175], v[196:199], v[72:75]
	v_mfma_f32_16x16x32_bf16 v[68:71], v[164:167], v[204:207], v[68:71]
	v_mfma_f32_16x16x32_bf16 v[64:67], v[172:175], v[204:207], v[64:67]
	v_mfma_f32_16x16x32_bf16 v[108:111], v[168:171], v[184:187], v[108:111]
	v_mfma_f32_16x16x32_bf16 v[104:107], v[176:179], v[184:187], v[104:107]
	v_mfma_f32_16x16x32_bf16 v[100:103], v[168:171], v[192:195], v[100:103]
	v_mfma_f32_16x16x32_bf16 v[96:99], v[176:179], v[192:195], v[96:99]
	v_mfma_f32_16x16x32_bf16 v[76:79], v[168:171], v[200:203], v[76:79]
	v_mfma_f32_16x16x32_bf16 v[72:75], v[176:179], v[200:203], v[72:75]
	v_mfma_f32_16x16x32_bf16 v[68:71], v[168:171], v[208:211], v[68:71]
	v_mfma_f32_16x16x32_bf16 v[64:67], v[176:179], v[208:211], v[64:67]
	s_setprio 0
	s_barrier
	s_add_i32 s24, s59, s37
	v_lshl_add_u64 v[140:141], v[140:141], 0, s[12:13]
	s_mov_b32 m0, s24
	ds_read_b128 v[180:183], v147 offset:49152
	ds_read_b128 v[184:187], v147 offset:50176
	ds_read_b128 v[188:191], v147 offset:51200
	ds_read_b128 v[192:195], v147 offset:52224
	ds_read_b128 v[196:199], v147 offset:53248
	ds_read_b128 v[200:203], v147 offset:54272
	ds_read_b128 v[204:207], v147 offset:55296
	ds_read_b128 v[208:211], v147 offset:56320
	global_load_lds_dwordx4 v[140:141], off
	s_add_i32 m0, s24, 0x2000
	s_add_u32 s24, s28, 0xb0080
	v_lshl_add_u64 v[140:141], v[212:213], 0, s[12:13]
	s_addc_u32 s25, s29, 0
	s_add_i32 s28, s60, s37
	global_load_lds_dwordx4 v[140:141], off
	v_lshl_add_u64 v[140:141], s[24:25], 0, v[128:129]
	s_mov_b32 m0, s28
	s_nop 0
	global_load_lds_dwordx4 v[140:141], off
	s_add_i32 m0, s28, 0x2000
	s_nop 0
	global_load_lds_dwordx4 v130, s[24:25]
	v_lshl_add_u64 v[140:141], v[214:215], 0, s[12:13]
	s_mov_b32 m0, s43
	s_nop 0
	global_load_lds_dwordx4 v[140:141], off
	v_lshl_add_u64 v[140:141], v[216:217], 0, s[12:13]
	s_mov_b32 m0, s44
	s_nop 0
	global_load_lds_dwordx4 v[140:141], off
	s_waitcnt vmcnt(8)
	s_waitcnt lgkmcnt(0)
	s_barrier
	s_setprio 1
	s_waitcnt lgkmcnt(0)
	v_mfma_f32_16x16x32_bf16 v[60:63], v[148:151], v[180:183], v[60:63]
	v_mfma_f32_16x16x32_bf16 v[56:59], v[156:159], v[180:183], v[56:59]
	v_mfma_f32_16x16x32_bf16 v[52:55], v[148:151], v[188:191], v[52:55]
	v_mfma_f32_16x16x32_bf16 v[48:51], v[156:159], v[188:191], v[48:51]
	v_mfma_f32_16x16x32_bf16 v[28:31], v[148:151], v[196:199], v[28:31]
	v_mfma_f32_16x16x32_bf16 v[24:27], v[156:159], v[196:199], v[24:27]
	v_mfma_f32_16x16x32_bf16 v[20:23], v[148:151], v[204:207], v[20:23]
	v_mfma_f32_16x16x32_bf16 v[16:19], v[156:159], v[204:207], v[16:19]
	v_mfma_f32_16x16x32_bf16 v[60:63], v[152:155], v[184:187], v[60:63]
	v_mfma_f32_16x16x32_bf16 v[56:59], v[160:163], v[184:187], v[56:59]
	v_mfma_f32_16x16x32_bf16 v[52:55], v[152:155], v[192:195], v[52:55]
	v_mfma_f32_16x16x32_bf16 v[48:51], v[160:163], v[192:195], v[48:51]
	v_mfma_f32_16x16x32_bf16 v[28:31], v[152:155], v[200:203], v[28:31]
	v_mfma_f32_16x16x32_bf16 v[24:27], v[160:163], v[200:203], v[24:27]
	v_mfma_f32_16x16x32_bf16 v[20:23], v[152:155], v[208:211], v[20:23]
	v_mfma_f32_16x16x32_bf16 v[16:19], v[160:163], v[208:211], v[16:19]
	s_setprio 0
	s_setprio 1
	v_mfma_f32_16x16x32_bf16 v[44:47], v[164:167], v[180:183], v[44:47]
	v_mfma_f32_16x16x32_bf16 v[40:43], v[172:175], v[180:183], v[40:43]
	v_mfma_f32_16x16x32_bf16 v[36:39], v[164:167], v[188:191], v[36:39]
	v_mfma_f32_16x16x32_bf16 v[32:35], v[172:175], v[188:191], v[32:35]
	v_mfma_f32_16x16x32_bf16 v[12:15], v[164:167], v[196:199], v[12:15]
	v_mfma_f32_16x16x32_bf16 v[8:11], v[172:175], v[196:199], v[8:11]
	v_mfma_f32_16x16x32_bf16 v[4:7], v[164:167], v[204:207], v[4:7]
	v_mfma_f32_16x16x32_bf16 v[0:3], v[172:175], v[204:207], v[0:3]
	v_mfma_f32_16x16x32_bf16 v[44:47], v[168:171], v[184:187], v[44:47]
	v_mfma_f32_16x16x32_bf16 v[40:43], v[176:179], v[184:187], v[40:43]
	v_mfma_f32_16x16x32_bf16 v[36:39], v[168:171], v[192:195], v[36:39]
	v_mfma_f32_16x16x32_bf16 v[32:35], v[176:179], v[192:195], v[32:35]
	v_mfma_f32_16x16x32_bf16 v[12:15], v[168:171], v[200:203], v[12:15]
	v_mfma_f32_16x16x32_bf16 v[8:11], v[176:179], v[200:203], v[8:11]
	v_mfma_f32_16x16x32_bf16 v[4:7], v[168:171], v[208:211], v[4:7]
	v_mfma_f32_16x16x32_bf16 v[0:3], v[176:179], v[208:211], v[0:3]
	s_setprio 0
	s_barrier
	s_add_i32 s58, s58, 2
	s_add_u32 s56, s56, 0x100
	s_addc_u32 s57, s57, 0
	s_cmp_gt_u32 s58, 41
	s_mov_b64 s[24:25], s[26:27]
	s_cbranch_scc0 .LBB0_1705
	s_and_b64 vcc, exec, s[14:15]
	s_cbranch_vccz .LBB0_1708
	s_barrier
